# GEMM tile loops: place-holder s_nop left by the DMA-spreading / fragment-hoisting passes removed (only the M0 wait states kept)
# baseline (speedup 1.0000x reference)
.LBB0_94:
	s_ashr_i32 s0, s2, 31
	s_lshr_b32 s0, s0, 29
	s_add_i32 s0, s2, s0
	v_mov_b32_e32 v78, v133
	s_and_b32 s1, s0, 0x1fffff8
	s_lshl_b32 s0, s0, 5
	s_and_b32 s22, s0, 0xffffff00
	v_ashrrev_i32_e32 v6, 6, v78
	v_bfe_u32 v7, v78, 3, 3
	v_lshl_or_b32 v8, v6, 5, v7
	v_add_u32_e32 v0, s22, v8
	s_waitcnt lgkmcnt(0)
	v_ashrrev_i32_e32 v1, 31, v0
	v_lshlrev_b64 v[2:3], 11, v[0:1]
	v_bfe_u32 v1, v78, 4, 2
	v_readlane_b32 s20, v214, 4
	v_xor_b32_e32 v1, v1, v78
	v_readlane_b32 s21, v214, 5
	v_lshlrev_b32_e32 v1, 4, v1
	v_and_b32_e32 v64, 0x70, v1
	v_lshl_add_u64 v[2:3], s[20:21], 0, v[2:3]
	v_or_b32_e32 v1, 8, v8
	v_lshl_add_u64 v[66:67], v[2:3], 0, v[64:65]
	v_add_u32_e32 v2, s22, v1
	v_lshrrev_b32_e32 v1, 1, v1
	v_xor_b32_e32 v1, v1, v78
	v_ashrrev_i32_e32 v3, 31, v2
	v_lshlrev_b32_e32 v1, 4, v1
	v_or_b32_e32 v0, 16, v0
	v_lshlrev_b64 v[2:3], 11, v[2:3]
	v_and_b32_e32 v4, 0x70, v1
	v_ashrrev_i32_e32 v1, 31, v0
	v_lshl_add_u64 v[2:3], s[20:21], 0, v[2:3]
	v_mov_b32_e32 v5, v65
	v_lshlrev_b64 v[0:1], 11, v[0:1]
	v_lshl_add_u64 v[68:69], v[2:3], 0, v[4:5]
	v_lshl_add_u64 v[0:1], s[20:21], 0, v[0:1]
	v_or_b32_e32 v2, 24, v8
	v_lshl_add_u64 v[70:71], v[0:1], 0, v[64:65]
	v_add_u32_e32 v0, s22, v2
	v_lshrrev_b32_e32 v2, 1, v2
	v_ashrrev_i32_e32 v1, 31, v0
	v_xor_b32_e32 v2, v2, v78
	v_lshlrev_b64 v[0:1], 11, v[0:1]
	v_lshlrev_b32_e32 v2, 4, v2
	s_sub_i32 s1, s2, s1
	v_lshl_add_u64 v[0:1], s[20:21], 0, v[0:1]
	v_and_b32_e32 v2, 0x70, v2
	v_mov_b32_e32 v3, v65
	s_lshl_b32 s0, s1, 7
	v_lshl_add_u64 v[72:73], v[0:1], 0, v[2:3]
	v_lshl_or_b32 v2, v6, 4, v7
	v_add_u32_e32 v0, s0, v2
	v_lshlrev_b32_e32 v3, 12, v6
	v_ashrrev_i32_e32 v1, 31, v0
	v_add_u32_e32 v126, 0, v3
	v_lshlrev_b64 v[0:1], 11, v[0:1]
	s_waitcnt vmcnt(0)
	v_readfirstlane_b32 s38, v126
	v_add_u32_e32 v127, 0x400, v126
	v_lshl_add_u64 v[0:1], s[40:41], 0, v[0:1]
	v_or_b32_e32 v2, 8, v2
	s_waitcnt lgkmcnt(0)
	s_barrier
	s_mov_b32 m0, s38
	v_readfirstlane_b32 s39, v127
	v_add_u32_e32 v128, 0x800, v126
	v_lshlrev_b32_e32 v5, 11, v6
	v_and_b32_e32 v80, 1, v6
	v_lshl_add_u64 v[74:75], v[0:1], 0, v[64:65]
	v_add_u32_e32 v0, s0, v2
	v_lshrrev_b32_e32 v2, 1, v2
	global_load_lds_dwordx4 v[66:67], off
	s_mov_b32 m0, s39
	v_readfirstlane_b32 s48, v128
	v_add_u32_e32 v129, 0xc00, v126
	v_add_u32_e32 v6, 0, v5
	v_ashrrev_i32_e32 v1, 31, v0
	v_xor_b32_e32 v2, v2, v78
	global_load_lds_dwordx4 v[68:69], off
	s_mov_b32 m0, s48
	v_readfirstlane_b32 s49, v129
	v_add_u32_e32 v131, 0x8000, v6
	v_lshlrev_b64 v[0:1], 11, v[0:1]
	v_lshlrev_b32_e32 v2, 4, v2
	global_load_lds_dwordx4 v[70:71], off
	s_mov_b32 m0, s49
	v_readfirstlane_b32 s53, v131
	v_add_u32_e32 v130, 0x8400, v6
	v_lshl_add_u64 v[0:1], s[40:41], 0, v[0:1]
	v_and_b32_e32 v64, 0x70, v2
	global_load_lds_dwordx4 v[72:73], off
	s_mov_b32 m0, s53
	v_readfirstlane_b32 s54, v130
	v_add_u32_e32 v120, 0xc000, v126
	v_lshl_add_u64 v[76:77], v[0:1], 0, v[64:65]
	global_load_lds_dwordx4 v[74:75], off
	s_mov_b32 m0, s54
	s_mov_b64 s[20:21], 0x80
	v_readfirstlane_b32 s29, v120
	v_add_u32_e32 v121, 0xc400, v126
	global_load_lds_dwordx4 v[76:77], off
	v_lshl_add_u64 v[0:1], v[66:67], 0, s[20:21]
	s_mov_b32 m0, s29
	v_readfirstlane_b32 s33, v121
	v_add_u32_e32 v122, 0xc800, v126
	global_load_lds_dwordx4 v[0:1], off
	v_lshl_add_u64 v[0:1], v[68:69], 0, s[20:21]
	s_mov_b32 m0, s33
	v_readfirstlane_b32 s34, v122
	v_add_u32_e32 v123, 0xcc00, v126
	global_load_lds_dwordx4 v[0:1], off
	v_lshl_add_u64 v[0:1], v[70:71], 0, s[20:21]
	s_mov_b32 m0, s34
	v_readfirstlane_b32 s35, v123
	v_add_u32_e32 v124, s85, v5
	global_load_lds_dwordx4 v[0:1], off
	v_lshl_add_u64 v[0:1], v[72:73], 0, s[20:21]
	s_mov_b32 m0, s35
	v_readfirstlane_b32 s36, v124
	v_add_u32_e32 v125, 0x14400, v6
	global_load_lds_dwordx4 v[0:1], off
	v_lshl_add_u64 v[0:1], v[74:75], 0, s[20:21]
	s_mov_b32 m0, s36
	v_readfirstlane_b32 s37, v125
	global_load_lds_dwordx4 v[0:1], off
	v_lshl_add_u64 v[0:1], v[76:77], 0, s[20:21]
	s_mov_b32 m0, s37
	v_lshrrev_b32_e32 v2, 1, v78
	v_bfe_u32 v64, v78, 5, 1
	global_load_lds_dwordx4 v[0:1], off
	v_add_u32_e32 v114, s3, v3
	v_bitop3_b32 v0, v2, v64, 7 bitop3:0x6c
	s_waitcnt vmcnt(6)
	s_mov_b64 s[30:31], 0x100
	v_readfirstlane_b32 s1, v114
	v_add_u32_e32 v115, 0x400, v114
	v_lshlrev_b32_e32 v132, 4, v0
	s_waitcnt lgkmcnt(0)
	s_barrier
	v_lshl_add_u64 v[0:1], v[66:67], 0, s[30:31]
	s_mov_b32 m0, s1
	v_readfirstlane_b32 s20, v115
	v_add_u32_e32 v116, 0x800, v114
	global_load_lds_dwordx4 v[0:1], off
	v_lshl_add_u64 v[0:1], v[68:69], 0, s[30:31]
	s_mov_b32 m0, s20
	v_readfirstlane_b32 s21, v116
	v_add_u32_e32 v117, 0xc00, v114
	v_readlane_b32 s24, v212, 31
	v_and_b32_e32 v79, 31, v78
	global_load_lds_dwordx4 v[0:1], off
	v_lshl_add_u64 v[0:1], v[70:71], 0, s[30:31]
	s_mov_b32 m0, s21
	v_readfirstlane_b32 s23, v117
	v_add_u32_e32 v118, s24, v5
	v_add_u32_e32 v2, s3, v5
	v_lshlrev_b32_e32 v4, 7, v79
	global_load_lds_dwordx4 v[0:1], off
	v_lshl_add_u64 v[0:1], v[72:73], 0, s[30:31]
	s_mov_b32 m0, s23
	v_readfirstlane_b32 s24, v118
	v_add_u32_e32 v119, 0x8400, v2
	v_lshl_or_b32 v102, v80, 13, v4
	global_load_lds_dwordx4 v[0:1], off
	v_lshl_add_u64 v[0:1], v[74:75], 0, s[30:31]
	s_mov_b32 m0, s24
	v_readfirstlane_b32 s28, v119
	global_load_lds_dwordx4 v[0:1], off
	v_lshl_add_u64 v[0:1], v[76:77], 0, s[30:31]
	s_mov_b32 m0, s28
	v_add_u32_e32 v100, 0, v102
	global_load_lds_dwordx4 v[0:1], off
	v_add_u32_e32 v83, v100, v132
	v_ashrrev_i32_e32 v81, 7, v78
	ds_read_b128 a[0:3], v83 offset:32768
	ds_read_b128 a[4:7], v83 offset:36864
	v_lshl_or_b32 v134, v81, 13, v4
	v_add_u32_e32 v101, 0, v134
	v_add_u32_e32 v82, v101, v132
	ds_read_b128 a[8:11], v82
	ds_read_b128 a[12:15], v82 offset:4096
	v_lshrrev_b32_e32 v182, 6, v133
	s_nop 0
	v_readfirstlane_b32 s32, v182
	s_waitcnt lgkmcnt(1)
	v_mfma_f32_32x32x16_bf16 v[48:63], a[0:3], a[8:11], 0
	v_bfe_u32 v103, v78, 1, 3
	s_mov_b64 s[30:31], 0x180
	v_or_b32_e32 v143, 0x8000, v102
	v_or_b32_e32 v144, 0x9000, v102
	v_add_u32_e32 v145, s3, v134
	v_lshl_or_b32 v81, v81, 6, v79
	s_waitcnt vmcnt(12)
	v_mfma_f32_32x32x16_bf16 v[32:47], a[4:7], a[8:11], 0
	v_mul_lo_u32 v81, v81, s26
	s_mov_b64 s[80:81], 0x200
	s_waitcnt lgkmcnt(0)
	v_mfma_f32_32x32x16_bf16 v[16:31], a[0:3], a[12:15], 0
	v_bitop3_b32 v0, v64, v103, 2 bitop3:0x36
	v_lshlrev_b32_e32 v138, 4, v0
	v_add_u32_e32 v84, v101, v138
	ds_read_b128 a[28:31], v84 offset:4096
	ds_read_b128 a[24:27], v84
	v_add_u32_e32 v85, v100, v138
	ds_read_b128 a[20:23], v85 offset:36864
	ds_read_b128 a[16:19], v85 offset:32768
	v_mfma_f32_32x32x16_bf16 v[0:15], a[4:7], a[12:15], 0
	s_waitcnt lgkmcnt(0)
	v_mfma_f32_32x32x16_bf16 v[48:63], a[16:19], a[24:27], v[48:63]
	v_mfma_f32_32x32x16_bf16 v[32:47], a[20:23], a[24:27], v[32:47]
	v_mfma_f32_32x32x16_bf16 v[16:31], a[16:19], a[28:31], v[16:31]
	v_bitop3_b32 v86, v64, v103, 4 bitop3:0x36
	v_lshlrev_b32_e32 v139, 4, v86
	v_add_u32_e32 v86, v101, v139
	ds_read_b128 a[12:15], v86 offset:4096
	ds_read_b128 a[8:11], v86
	v_add_u32_e32 v87, v100, v139
	ds_read_b128 a[4:7], v87 offset:36864
	ds_read_b128 a[0:3], v87 offset:32768
	v_mfma_f32_32x32x16_bf16 v[0:15], a[20:23], a[28:31], v[0:15]
	s_waitcnt lgkmcnt(0)
	v_mfma_f32_32x32x16_bf16 v[48:63], a[0:3], a[8:11], v[48:63]
	v_mfma_f32_32x32x16_bf16 v[32:47], a[4:7], a[8:11], v[32:47]
	v_mfma_f32_32x32x16_bf16 v[16:31], a[0:3], a[12:15], v[16:31]
	v_bitop3_b32 v88, v64, v103, 6 bitop3:0x36
	v_lshlrev_b32_e32 v142, 4, v88
	v_add_u32_e32 v88, v101, v142
	ds_read_b128 a[28:31], v88 offset:4096
	ds_read_b128 a[24:27], v88
	v_add_u32_e32 v89, v100, v142
	ds_read_b128 a[20:23], v89 offset:36864
	ds_read_b128 a[16:19], v89 offset:32768
	v_lshlrev_b32_e32 v64, 4, v64
	v_lshl_or_b32 v64, v80, 8, v64
	v_add3_u32 v64, 0, v81, v64
	v_mfma_f32_32x32x16_bf16 v[0:15], a[4:7], a[12:15], v[0:15]
	s_waitcnt lgkmcnt(0)
	v_mfma_f32_32x32x16_bf16 v[48:63], a[16:19], a[24:27], v[48:63]
	v_mfma_f32_32x32x16_bf16 v[32:47], a[20:23], a[24:27], v[32:47]
	s_waitcnt vmcnt(6)
	s_waitcnt lgkmcnt(0)
	s_barrier
	ds_read_b128 a[12:15], v82 offset:53248
	ds_read_b128 a[8:11], v82 offset:49152
	v_mfma_f32_32x32x16_bf16 v[16:31], a[16:19], a[28:31], v[16:31]
	v_lshl_add_u64 v[158:159], v[66:67], 0, s[30:31]
	v_lshl_add_u64 v[160:161], v[68:69], 0, s[30:31]
	v_lshl_add_u64 v[162:163], v[70:71], 0, s[30:31]
	v_mfma_f32_32x32x16_bf16 v[0:15], a[20:23], a[28:31], v[0:15]
	s_and_b32 m0, s32, 7
	s_lshl_b32 m0, m0, 12
	s_add_i32 m0, m0, 0x0
	s_nop 0
	global_load_lds_dwordx4 v[158:159], off
	v_lshl_add_u64 v[164:165], v[72:73], 0, s[30:31]
	v_lshl_add_u64 v[166:167], v[74:75], 0, s[30:31]
	v_lshl_add_u64 v[168:169], v[76:77], 0, s[30:31]
	s_add_i32 s30, 0, 0xc000
	v_add_u32_e32 v90, s30, v132
	v_add_u32_e32 v92, v90, v143
	v_add_u32_e32 v90, v90, v144
	ds_read_b128 a[4:7], v90
	ds_read_b128 a[0:3], v92
	v_add_u32_e32 v91, s30, v138
	v_add_u32_e32 v93, v91, v143
	ds_read_b128 a[16:19], v93
	v_add_u32_e32 v91, v91, v144
	ds_read_b128 a[20:23], v91
	ds_read_b128 a[24:27], v84 offset:49152
	ds_read_b128 a[28:31], v84 offset:53248
	s_waitcnt lgkmcnt(4)
	v_mfma_f32_32x32x16_bf16 v[48:63], a[0:3], a[8:11], v[48:63]
	v_mfma_f32_32x32x16_bf16 v[32:47], a[4:7], a[8:11], v[32:47]
	s_and_b32 m0, s32, 7
	s_lshl_b32 m0, m0, 12
	s_add_i32 m0, m0, 0x400
	s_nop 0
	global_load_lds_dwordx4 v[160:161], off
	v_mfma_f32_32x32x16_bf16 v[16:31], a[0:3], a[12:15], v[16:31]
	v_mfma_f32_32x32x16_bf16 v[0:15], a[4:7], a[12:15], v[0:15]
	s_and_b32 m0, s32, 7
	s_lshl_b32 m0, m0, 12
	s_add_i32 m0, m0, 0x800
	s_nop 0
	global_load_lds_dwordx4 v[162:163], off
	v_add_u32_e32 v94, s30, v139
	v_add_u32_e32 v95, v94, v143
	ds_read_b128 a[0:3], v95
	v_add_u32_e32 v94, v94, v144
	ds_read_b128 a[4:7], v94
	ds_read_b128 a[8:11], v86 offset:49152
	ds_read_b128 a[12:15], v86 offset:53248
	s_waitcnt lgkmcnt(5)
	v_mfma_f32_32x32x16_bf16 v[48:63], a[16:19], a[24:27], v[48:63]
	v_mfma_f32_32x32x16_bf16 v[32:47], a[20:23], a[24:27], v[32:47]
	s_and_b32 m0, s32, 7
	s_lshl_b32 m0, m0, 12
	s_add_i32 m0, m0, 0xc00
	s_nop 0
	global_load_lds_dwordx4 v[164:165], off
	s_waitcnt lgkmcnt(4)
	v_mfma_f32_32x32x16_bf16 v[16:31], a[16:19], a[28:31], v[16:31]
	v_mfma_f32_32x32x16_bf16 v[0:15], a[20:23], a[28:31], v[0:15]
	s_and_b32 m0, s32, 7
	s_lshl_b32 m0, m0, 11
	s_add_i32 m0, m0, 0x8000
	s_nop 0
	global_load_lds_dwordx4 v[166:167], off
	v_add_u32_e32 v96, s30, v142
	v_add_u32_e32 v97, v96, v143
	ds_read_b128 a[16:19], v97
	v_add_u32_e32 v96, v96, v144
	ds_read_b128 a[20:23], v96
	ds_read_b128 a[24:27], v88 offset:49152
	ds_read_b128 a[28:31], v88 offset:53248
	s_waitcnt lgkmcnt(5)
	v_mfma_f32_32x32x16_bf16 v[48:63], a[0:3], a[8:11], v[48:63]
	v_mfma_f32_32x32x16_bf16 v[32:47], a[4:7], a[8:11], v[32:47]
	s_and_b32 m0, s32, 7
	s_lshl_b32 m0, m0, 11
	s_add_i32 m0, m0, 0x8400
	s_nop 0
	global_load_lds_dwordx4 v[168:169], off
	s_waitcnt lgkmcnt(4)
	v_mfma_f32_32x32x16_bf16 v[16:31], a[0:3], a[12:15], v[16:31]
	s_mov_b64 s[30:31], 0x200
	v_mfma_f32_32x32x16_bf16 v[0:15], a[4:7], a[12:15], v[0:15]
	s_waitcnt lgkmcnt(1)
	v_mfma_f32_32x32x16_bf16 v[48:63], a[16:19], a[24:27], v[48:63]
	v_mfma_f32_32x32x16_bf16 v[32:47], a[20:23], a[24:27], v[32:47]
	s_waitcnt vmcnt(6)
	s_waitcnt lgkmcnt(0)
	s_barrier
	v_add_u32_e32 v100, v145, v132
	ds_read_b128 a[8:11], v100
	v_add_u32_e32 v101, s3, v132
	v_add_u32_e32 v99, v101, v144
	ds_read_b128 a[4:7], v99
	v_add_u32_e32 v98, v101, v143
	v_or_b32_e32 v132, 0x1000, v134
	v_add_u32_e32 v101, v101, v132
	ds_read_b128 a[12:15], v101
	ds_read_b128 a[0:3], v98
	v_mfma_f32_32x32x16_bf16 v[16:31], a[16:19], a[28:31], v[16:31]
	v_lshl_add_u64 v[170:171], v[66:67], 0, s[30:31]
	v_lshl_add_u64 v[172:173], v[68:69], 0, s[30:31]
	v_lshl_add_u64 v[174:175], v[70:71], 0, s[30:31]
	v_mfma_f32_32x32x16_bf16 v[0:15], a[20:23], a[28:31], v[0:15]
	s_and_b32 m0, s32, 7
	s_lshl_b32 m0, m0, 12
	s_add_i32 m0, m0, 0xc000
	s_nop 0
	global_load_lds_dwordx4 v[170:171], off
	v_lshl_add_u64 v[176:177], v[72:73], 0, s[30:31]
	v_lshl_add_u64 v[178:179], v[74:75], 0, s[30:31]
	v_lshl_add_u64 v[180:181], v[76:77], 0, s[30:31]
	s_mov_b64 s[30:31], 0x280
	v_add_u32_e32 v105, s3, v138
	v_add_u32_e32 v102, v105, v143
	ds_read_b128 a[16:19], v102
	v_add_u32_e32 v103, v105, v144
	ds_read_b128 a[20:23], v103
	v_add_u32_e32 v104, v145, v138
	ds_read_b128 a[24:27], v104
	v_add_u32_e32 v105, v105, v132
	ds_read_b128 a[28:31], v105
	s_waitcnt lgkmcnt(4)
	v_mfma_f32_32x32x16_bf16 v[48:63], a[0:3], a[8:11], v[48:63]
	v_mfma_f32_32x32x16_bf16 v[32:47], a[4:7], a[8:11], v[32:47]
	s_and_b32 m0, s32, 7
	s_lshl_b32 m0, m0, 12
	s_add_i32 m0, m0, 0xc400
	s_nop 0
	global_load_lds_dwordx4 v[172:173], off
	v_mfma_f32_32x32x16_bf16 v[16:31], a[0:3], a[12:15], v[16:31]
	v_mfma_f32_32x32x16_bf16 v[0:15], a[4:7], a[12:15], v[0:15]
	s_and_b32 m0, s32, 7
	s_lshl_b32 m0, m0, 12
	s_add_i32 m0, m0, 0xc800
	s_nop 0
	global_load_lds_dwordx4 v[174:175], off
	v_add_u32_e32 v109, s3, v139
	v_add_u32_e32 v106, v109, v143
	ds_read_b128 a[0:3], v106
	v_add_u32_e32 v107, v109, v144
	ds_read_b128 a[4:7], v107
	v_add_u32_e32 v108, v145, v139
	ds_read_b128 a[8:11], v108
	v_add_u32_e32 v109, v109, v132
	ds_read_b128 a[12:15], v109
	s_waitcnt lgkmcnt(5)
	v_mfma_f32_32x32x16_bf16 v[48:63], a[16:19], a[24:27], v[48:63]
	v_mfma_f32_32x32x16_bf16 v[32:47], a[20:23], a[24:27], v[32:47]
	s_and_b32 m0, s32, 7
	s_lshl_b32 m0, m0, 12
	s_add_i32 m0, m0, 0xcc00
	s_nop 0
	global_load_lds_dwordx4 v[176:177], off
	s_waitcnt lgkmcnt(4)
	v_mfma_f32_32x32x16_bf16 v[16:31], a[16:19], a[28:31], v[16:31]
	v_mfma_f32_32x32x16_bf16 v[0:15], a[20:23], a[28:31], v[0:15]
	s_and_b32 m0, s32, 7
	s_lshl_b32 m0, m0, 11
	s_add_i32 m0, m0, 0x14000
	s_nop 0
	global_load_lds_dwordx4 v[178:179], off
	v_add_u32_e32 v113, s3, v142
	v_add_u32_e32 v110, v113, v143
	ds_read_b128 a[16:19], v110
	v_add_u32_e32 v111, v113, v144
	ds_read_b128 a[20:23], v111
	v_add_u32_e32 v112, v145, v142
	ds_read_b128 a[24:27], v112
	v_add_u32_e32 v113, v113, v132
	ds_read_b128 a[28:31], v113
	s_waitcnt lgkmcnt(5)
	v_mfma_f32_32x32x16_bf16 v[48:63], a[0:3], a[8:11], v[48:63]
	v_mfma_f32_32x32x16_bf16 v[32:47], a[4:7], a[8:11], v[32:47]
	s_and_b32 m0, s32, 7
	s_lshl_b32 m0, m0, 11
	s_add_i32 m0, m0, 0x14400
	s_nop 0
	global_load_lds_dwordx4 v[180:181], off
	s_waitcnt lgkmcnt(4)
	v_mfma_f32_32x32x16_bf16 v[16:31], a[0:3], a[12:15], v[16:31]
	v_mfma_f32_32x32x16_bf16 v[0:15], a[4:7], a[12:15], v[0:15]
	s_waitcnt lgkmcnt(1)
	v_mfma_f32_32x32x16_bf16 v[48:63], a[16:19], a[24:27], v[48:63]
	v_mfma_f32_32x32x16_bf16 v[32:47], a[20:23], a[24:27], v[32:47]
	s_waitcnt vmcnt(6)
	s_waitcnt lgkmcnt(0)
	s_barrier
	ds_read_b128 a[12:15], v82 offset:4096
	ds_read_b128 a[8:11], v82
	ds_read_b128 a[4:7], v83 offset:36864
	ds_read_b128 a[0:3], v83 offset:32768
	v_mfma_f32_32x32x16_bf16 v[16:31], a[16:19], a[28:31], v[16:31]
	v_lshl_add_u64 v[158:159], v[66:67], 0, s[30:31]
	v_lshl_add_u64 v[160:161], v[68:69], 0, s[30:31]
	v_lshl_add_u64 v[162:163], v[70:71], 0, s[30:31]
	v_mfma_f32_32x32x16_bf16 v[0:15], a[20:23], a[28:31], v[0:15]
	s_and_b32 m0, s32, 7
	s_lshl_b32 m0, m0, 12
	s_add_i32 m0, m0, 0x18000
	s_nop 0
	global_load_lds_dwordx4 v[158:159], off
	v_lshl_add_u64 v[164:165], v[72:73], 0, s[30:31]
	v_lshl_add_u64 v[166:167], v[74:75], 0, s[30:31]
	v_lshl_add_u64 v[168:169], v[76:77], 0, s[30:31]
	s_mov_b64 s[30:31], 0x300
	ds_read_b128 a[16:19], v85 offset:32768
	ds_read_b128 a[20:23], v85 offset:36864
	ds_read_b128 a[24:27], v84
	ds_read_b128 a[28:31], v84 offset:4096
	s_waitcnt lgkmcnt(4)
	v_mfma_f32_32x32x16_bf16 v[48:63], a[0:3], a[8:11], v[48:63]
	s_nop 0
	v_readfirstlane_b32 s38, v114
	v_mfma_f32_32x32x16_bf16 v[32:47], a[4:7], a[8:11], v[32:47]
	s_and_b32 m0, s32, 7
	s_lshl_b32 m0, m0, 12
	s_add_i32 m0, m0, 0x18400
	s_nop 0
	global_load_lds_dwordx4 v[160:161], off
	v_mfma_f32_32x32x16_bf16 v[16:31], a[0:3], a[12:15], v[16:31]
	v_mfma_f32_32x32x16_bf16 v[0:15], a[4:7], a[12:15], v[0:15]
	s_and_b32 m0, s32, 7
	s_lshl_b32 m0, m0, 12
	s_add_i32 m0, m0, 0x18800
	s_nop 0
	global_load_lds_dwordx4 v[162:163], off
	ds_read_b128 a[0:3], v87 offset:32768
	ds_read_b128 a[4:7], v87 offset:36864
	ds_read_b128 a[8:11], v86
	ds_read_b128 a[12:15], v86 offset:4096
	s_waitcnt lgkmcnt(5)
	v_mfma_f32_32x32x16_bf16 v[48:63], a[16:19], a[24:27], v[48:63]
	v_mfma_f32_32x32x16_bf16 v[32:47], a[20:23], a[24:27], v[32:47]
	s_and_b32 m0, s32, 7
	s_lshl_b32 m0, m0, 12
	s_add_i32 m0, m0, 0x18c00
	s_nop 0
	global_load_lds_dwordx4 v[164:165], off
	s_waitcnt lgkmcnt(4)
	v_mfma_f32_32x32x16_bf16 v[16:31], a[16:19], a[28:31], v[16:31]
	v_mfma_f32_32x32x16_bf16 v[0:15], a[20:23], a[28:31], v[0:15]
	s_and_b32 m0, s32, 7
	s_lshl_b32 m0, m0, 11
	s_add_i32 m0, m0, 0x20000
	s_nop 0
	global_load_lds_dwordx4 v[166:167], off
	ds_read_b128 a[16:19], v89 offset:32768
	ds_read_b128 a[20:23], v89 offset:36864
	ds_read_b128 a[24:27], v88
	ds_read_b128 a[28:31], v88 offset:4096
	s_waitcnt lgkmcnt(5)
	v_mfma_f32_32x32x16_bf16 v[48:63], a[0:3], a[8:11], v[48:63]
	v_mfma_f32_32x32x16_bf16 v[32:47], a[4:7], a[8:11], v[32:47]
	s_and_b32 m0, s32, 7
	s_lshl_b32 m0, m0, 11
	s_add_i32 m0, m0, 0x20400
	s_nop 0
	global_load_lds_dwordx4 v[168:169], off
	s_waitcnt lgkmcnt(4)
	v_mfma_f32_32x32x16_bf16 v[16:31], a[0:3], a[12:15], v[16:31]
	v_mfma_f32_32x32x16_bf16 v[0:15], a[4:7], a[12:15], v[0:15]
	s_waitcnt lgkmcnt(1)
	v_mfma_f32_32x32x16_bf16 v[48:63], a[16:19], a[24:27], v[48:63]
	v_mfma_f32_32x32x16_bf16 v[32:47], a[20:23], a[24:27], v[32:47]
	s_waitcnt vmcnt(6)
	s_waitcnt lgkmcnt(0)
	s_barrier
	ds_read_b128 a[12:15], v82 offset:53248
	ds_read_b128 a[8:11], v82 offset:49152
	ds_read_b128 a[4:7], v90
	ds_read_b128 a[0:3], v92
	v_mfma_f32_32x32x16_bf16 v[16:31], a[16:19], a[28:31], v[16:31]
	v_lshl_add_u64 v[170:171], v[66:67], 0, s[30:31]
	v_lshl_add_u64 v[172:173], v[68:69], 0, s[30:31]
	s_nop 0
	v_readfirstlane_b32 s39, v115
	s_nop 0
	v_lshl_add_u64 v[174:175], v[70:71], 0, s[30:31]
	s_nop 0
	v_mfma_f32_32x32x16_bf16 v[0:15], a[20:23], a[28:31], v[0:15]
	s_and_b32 m0, s32, 7
	s_lshl_b32 m0, m0, 12
	s_add_i32 m0, m0, 0x0
	s_nop 0
	global_load_lds_dwordx4 v[170:171], off
	v_lshl_add_u64 v[176:177], v[72:73], 0, s[30:31]
	s_nop 0
	v_readfirstlane_b32 s48, v116
	s_nop 0
	v_lshl_add_u64 v[178:179], v[74:75], 0, s[30:31]
	s_nop 0
	v_readfirstlane_b32 s49, v117
	s_nop 0
	v_lshl_add_u64 v[180:181], v[76:77], 0, s[30:31]
	s_nop 0
	s_mov_b64 s[30:31], 0x380
	ds_read_b128 a[16:19], v93
	ds_read_b128 a[20:23], v91
	ds_read_b128 a[24:27], v84 offset:49152
	ds_read_b128 a[28:31], v84 offset:53248
	s_waitcnt lgkmcnt(4)
	v_mfma_f32_32x32x16_bf16 v[48:63], a[0:3], a[8:11], v[48:63]
	s_nop 0
	v_readfirstlane_b32 s53, v118
	v_readfirstlane_b32 s54, v119
	v_mfma_f32_32x32x16_bf16 v[32:47], a[4:7], a[8:11], v[32:47]
	s_and_b32 m0, s32, 7
	s_lshl_b32 m0, m0, 12
	s_add_i32 m0, m0, 0x400
	s_nop 0
	global_load_lds_dwordx4 v[172:173], off
	v_mfma_f32_32x32x16_bf16 v[16:31], a[0:3], a[12:15], v[16:31]
	v_mfma_f32_32x32x16_bf16 v[0:15], a[4:7], a[12:15], v[0:15]
	s_and_b32 m0, s32, 7
	s_lshl_b32 m0, m0, 12
	s_add_i32 m0, m0, 0x800
	s_nop 0
	global_load_lds_dwordx4 v[174:175], off
	ds_read_b128 a[0:3], v95
	ds_read_b128 a[4:7], v94
	ds_read_b128 a[8:11], v86 offset:49152
	ds_read_b128 a[12:15], v86 offset:53248
	s_waitcnt lgkmcnt(5)
	v_mfma_f32_32x32x16_bf16 v[48:63], a[16:19], a[24:27], v[48:63]
	v_mfma_f32_32x32x16_bf16 v[32:47], a[20:23], a[24:27], v[32:47]
	s_and_b32 m0, s32, 7
	s_lshl_b32 m0, m0, 12
	s_add_i32 m0, m0, 0xc00
	s_nop 0
	global_load_lds_dwordx4 v[176:177], off
	s_waitcnt lgkmcnt(4)
	v_mfma_f32_32x32x16_bf16 v[16:31], a[16:19], a[28:31], v[16:31]
	v_mfma_f32_32x32x16_bf16 v[0:15], a[20:23], a[28:31], v[0:15]
	s_and_b32 m0, s32, 7
	s_lshl_b32 m0, m0, 11
	s_add_i32 m0, m0, 0x8000
	s_nop 0
	global_load_lds_dwordx4 v[178:179], off
	ds_read_b128 a[16:19], v97
	ds_read_b128 a[20:23], v96
	ds_read_b128 a[24:27], v88 offset:49152
	ds_read_b128 a[28:31], v88 offset:53248
	s_waitcnt lgkmcnt(5)
	v_mfma_f32_32x32x16_bf16 v[48:63], a[0:3], a[8:11], v[48:63]
	v_mfma_f32_32x32x16_bf16 v[32:47], a[4:7], a[8:11], v[32:47]
	s_and_b32 m0, s32, 7
	s_lshl_b32 m0, m0, 11
	s_add_i32 m0, m0, 0x8400
	s_nop 0
	global_load_lds_dwordx4 v[180:181], off
	s_waitcnt lgkmcnt(4)
	v_mfma_f32_32x32x16_bf16 v[16:31], a[0:3], a[12:15], v[16:31]
	v_mfma_f32_32x32x16_bf16 v[0:15], a[4:7], a[12:15], v[0:15]
	s_waitcnt lgkmcnt(1)
	v_mfma_f32_32x32x16_bf16 v[48:63], a[16:19], a[24:27], v[48:63]
	v_mfma_f32_32x32x16_bf16 v[32:47], a[20:23], a[24:27], v[32:47]
	s_waitcnt vmcnt(6)
	s_waitcnt lgkmcnt(0)
	s_barrier
	ds_read_b128 a[12:15], v101
	ds_read_b128 a[8:11], v100
	ds_read_b128 a[4:7], v99
	ds_read_b128 a[0:3], v98
	v_mfma_f32_32x32x16_bf16 v[16:31], a[16:19], a[28:31], v[16:31]
	v_lshl_add_u64 v[158:159], v[66:67], 0, s[30:31]
	v_lshl_add_u64 v[160:161], v[68:69], 0, s[30:31]
	s_nop 0
	v_readfirstlane_b32 s33, v121
	s_nop 0
	v_lshl_add_u64 v[162:163], v[70:71], 0, s[30:31]
	s_nop 0
	v_mfma_f32_32x32x16_bf16 v[0:15], a[20:23], a[28:31], v[0:15]
	s_and_b32 m0, s32, 7
	s_lshl_b32 m0, m0, 12
	s_add_i32 m0, m0, 0xc000
	s_nop 0
	global_load_lds_dwordx4 v[158:159], off
	v_lshl_add_u64 v[164:165], v[72:73], 0, s[30:31]
	s_nop 0
	v_readfirstlane_b32 s34, v122
	s_nop 0
	v_lshl_add_u64 v[166:167], v[74:75], 0, s[30:31]
	s_nop 0
	v_readfirstlane_b32 s35, v123
	s_nop 0
	v_lshl_add_u64 v[168:169], v[76:77], 0, s[30:31]
	s_nop 0
	s_mov_b64 s[30:31], 0x400
	ds_read_b128 a[16:19], v102
	ds_read_b128 a[20:23], v103
	ds_read_b128 a[24:27], v104
	ds_read_b128 a[28:31], v105
	s_waitcnt lgkmcnt(4)
	v_mfma_f32_32x32x16_bf16 v[48:63], a[0:3], a[8:11], v[48:63]
	s_nop 0
	v_readfirstlane_b32 s1, v126
	v_readfirstlane_b32 s36, v124
	v_readfirstlane_b32 s37, v125
	v_mfma_f32_32x32x16_bf16 v[32:47], a[4:7], a[8:11], v[32:47]
	s_and_b32 m0, s32, 7
	s_lshl_b32 m0, m0, 12
	s_add_i32 m0, m0, 0xc400
	s_nop 0
	global_load_lds_dwordx4 v[160:161], off
	v_mfma_f32_32x32x16_bf16 v[16:31], a[0:3], a[12:15], v[16:31]
	v_mfma_f32_32x32x16_bf16 v[0:15], a[4:7], a[12:15], v[0:15]
	s_and_b32 m0, s32, 7
	s_lshl_b32 m0, m0, 12
	s_add_i32 m0, m0, 0xc800
	s_nop 0
	global_load_lds_dwordx4 v[162:163], off
	ds_read_b128 a[0:3], v106
	ds_read_b128 a[4:7], v107
	ds_read_b128 a[8:11], v108
	ds_read_b128 a[12:15], v109
	s_waitcnt lgkmcnt(5)
	v_mfma_f32_32x32x16_bf16 v[48:63], a[16:19], a[24:27], v[48:63]
	v_mfma_f32_32x32x16_bf16 v[32:47], a[20:23], a[24:27], v[32:47]
	s_and_b32 m0, s32, 7
	s_lshl_b32 m0, m0, 12
	s_add_i32 m0, m0, 0xcc00
	s_nop 0
	global_load_lds_dwordx4 v[164:165], off
	s_waitcnt lgkmcnt(4)
	v_mfma_f32_32x32x16_bf16 v[16:31], a[16:19], a[28:31], v[16:31]
	v_mfma_f32_32x32x16_bf16 v[0:15], a[20:23], a[28:31], v[0:15]
	s_and_b32 m0, s32, 7
	s_lshl_b32 m0, m0, 11
	s_add_i32 m0, m0, 0x14000
	s_nop 0
	global_load_lds_dwordx4 v[166:167], off
	ds_read_b128 a[16:19], v110
	ds_read_b128 a[20:23], v111
	ds_read_b128 a[24:27], v112
	ds_read_b128 a[28:31], v113
	s_waitcnt lgkmcnt(5)
	v_mfma_f32_32x32x16_bf16 v[48:63], a[0:3], a[8:11], v[48:63]
	v_mfma_f32_32x32x16_bf16 v[32:47], a[4:7], a[8:11], v[32:47]
	s_and_b32 m0, s32, 7
	s_lshl_b32 m0, m0, 11
	s_add_i32 m0, m0, 0x14400
	s_nop 0
	global_load_lds_dwordx4 v[168:169], off
	s_waitcnt lgkmcnt(4)
	v_mfma_f32_32x32x16_bf16 v[16:31], a[0:3], a[12:15], v[16:31]
	v_mfma_f32_32x32x16_bf16 v[0:15], a[4:7], a[12:15], v[0:15]
	s_waitcnt lgkmcnt(1)
	v_mfma_f32_32x32x16_bf16 v[48:63], a[16:19], a[24:27], v[48:63]
	v_mfma_f32_32x32x16_bf16 v[32:47], a[20:23], a[24:27], v[32:47]
	s_waitcnt vmcnt(6)
	s_waitcnt lgkmcnt(0)
	s_barrier
	ds_read_b128 a[12:15], v82 offset:4096
	ds_read_b128 a[8:11], v82
	ds_read_b128 a[4:7], v83 offset:36864
	ds_read_b128 a[0:3], v83 offset:32768
	v_mfma_f32_32x32x16_bf16 v[16:31], a[16:19], a[28:31], v[16:31]
	v_lshl_add_u64 v[170:171], v[66:67], 0, s[30:31]
	v_lshl_add_u64 v[172:173], v[68:69], 0, s[30:31]
	s_nop 0
	v_readfirstlane_b32 s20, v127
	s_nop 0
	v_lshl_add_u64 v[174:175], v[70:71], 0, s[30:31]
	s_nop 0
	v_mfma_f32_32x32x16_bf16 v[0:15], a[20:23], a[28:31], v[0:15]
	s_and_b32 m0, s32, 7
	s_lshl_b32 m0, m0, 12
	s_add_i32 m0, m0, 0x18000
	s_nop 0
	global_load_lds_dwordx4 v[170:171], off
	v_lshl_add_u64 v[176:177], v[72:73], 0, s[30:31]
	s_nop 0
	v_readfirstlane_b32 s21, v128
	s_nop 0
	v_lshl_add_u64 v[178:179], v[74:75], 0, s[30:31]
	s_nop 0
	v_readfirstlane_b32 s23, v129
	s_nop 0
	v_lshl_add_u64 v[180:181], v[76:77], 0, s[30:31]
	s_nop 0
	s_mov_b64 s[28:29], 0x480
	ds_read_b128 a[16:19], v85 offset:32768
	ds_read_b128 a[20:23], v85 offset:36864
	ds_read_b128 a[24:27], v84
	ds_read_b128 a[28:31], v84 offset:4096
	s_waitcnt lgkmcnt(4)
	v_mfma_f32_32x32x16_bf16 v[48:63], a[0:3], a[8:11], v[48:63]
	s_nop 0
	v_lshl_add_u64 v[162:163], v[70:71], 0, s[28:29]
	v_readfirstlane_b32 s24, v131
	s_mov_b64 s[30:31], 0x500
	v_mfma_f32_32x32x16_bf16 v[32:47], a[4:7], a[8:11], v[32:47]
	s_and_b32 m0, s32, 7
	s_lshl_b32 m0, m0, 12
	s_add_i32 m0, m0, 0x18400
	s_nop 0
	global_load_lds_dwordx4 v[172:173], off
	v_mfma_f32_32x32x16_bf16 v[16:31], a[0:3], a[12:15], v[16:31]
	v_mfma_f32_32x32x16_bf16 v[0:15], a[4:7], a[12:15], v[0:15]
	s_and_b32 m0, s32, 7
	s_lshl_b32 m0, m0, 12
	s_add_i32 m0, m0, 0x18800
	s_nop 0
	global_load_lds_dwordx4 v[174:175], off
	ds_read_b128 a[0:3], v87 offset:32768
	ds_read_b128 a[4:7], v87 offset:36864
	ds_read_b128 a[8:11], v86
	ds_read_b128 a[12:15], v86 offset:4096
	s_waitcnt lgkmcnt(5)
	v_mfma_f32_32x32x16_bf16 v[48:63], a[16:19], a[24:27], v[48:63]
	v_mfma_f32_32x32x16_bf16 v[32:47], a[20:23], a[24:27], v[32:47]
	s_and_b32 m0, s32, 7
	s_lshl_b32 m0, m0, 12
	s_add_i32 m0, m0, 0x18c00
	s_nop 0
	global_load_lds_dwordx4 v[176:177], off
	s_waitcnt lgkmcnt(4)
	v_mfma_f32_32x32x16_bf16 v[16:31], a[16:19], a[28:31], v[16:31]
	v_mfma_f32_32x32x16_bf16 v[0:15], a[20:23], a[28:31], v[0:15]
	s_and_b32 m0, s32, 7
	s_lshl_b32 m0, m0, 11
	s_add_i32 m0, m0, 0x20000
	s_nop 0
	global_load_lds_dwordx4 v[178:179], off
	ds_read_b128 a[16:19], v89 offset:32768
	ds_read_b128 a[20:23], v89 offset:36864
	ds_read_b128 a[24:27], v88
	ds_read_b128 a[28:31], v88 offset:4096
	s_waitcnt lgkmcnt(5)
	v_mfma_f32_32x32x16_bf16 v[48:63], a[0:3], a[8:11], v[48:63]
	v_mfma_f32_32x32x16_bf16 v[32:47], a[4:7], a[8:11], v[32:47]
	s_and_b32 m0, s32, 7
	s_lshl_b32 m0, m0, 11
	s_add_i32 m0, m0, 0x20400
	s_nop 0
	global_load_lds_dwordx4 v[180:181], off
	s_waitcnt lgkmcnt(4)
	v_mfma_f32_32x32x16_bf16 v[16:31], a[0:3], a[12:15], v[16:31]
	v_mfma_f32_32x32x16_bf16 v[0:15], a[4:7], a[12:15], v[0:15]
	s_waitcnt lgkmcnt(1)
	v_mfma_f32_32x32x16_bf16 v[48:63], a[16:19], a[24:27], v[48:63]
	v_mfma_f32_32x32x16_bf16 v[32:47], a[20:23], a[24:27], v[32:47]
	s_waitcnt vmcnt(6)
	s_waitcnt lgkmcnt(0)
	s_barrier
	ds_read_b128 a[12:15], v82 offset:53248
	ds_read_b128 a[8:11], v82 offset:49152
	ds_read_b128 a[4:7], v90
	ds_read_b128 a[0:3], v92
	v_mfma_f32_32x32x16_bf16 v[16:31], a[16:19], a[28:31], v[16:31]
	v_lshl_add_u64 v[158:159], v[66:67], 0, s[28:29]
	v_lshl_add_u64 v[160:161], v[68:69], 0, s[28:29]
	v_mfma_f32_32x32x16_bf16 v[0:15], a[20:23], a[28:31], v[0:15]
	s_and_b32 m0, s32, 7
	s_lshl_b32 m0, m0, 12
	s_add_i32 m0, m0, 0x0
	s_nop 0
	global_load_lds_dwordx4 v[158:159], off
	v_lshl_add_u64 v[164:165], v[72:73], 0, s[28:29]
	v_lshl_add_u64 v[166:167], v[74:75], 0, s[28:29]
	s_nop 0
	v_lshl_add_u64 v[168:169], v[76:77], 0, s[28:29]
	v_readfirstlane_b32 s28, v130
	s_nop 0
	v_readfirstlane_b32 s29, v120
	s_nop 0
	s_nop 0
	s_nop 0
	s_nop 0
	ds_read_b128 a[16:19], v93
	ds_read_b128 a[20:23], v91
	ds_read_b128 a[24:27], v84 offset:49152
	ds_read_b128 a[28:31], v84 offset:53248
	s_waitcnt lgkmcnt(4)
	v_mfma_f32_32x32x16_bf16 v[48:63], a[0:3], a[8:11], v[48:63]
	v_lshl_add_u64 v[174:175], v[70:71], 0, s[30:31]
	v_mfma_f32_32x32x16_bf16 v[32:47], a[4:7], a[8:11], v[32:47]
	s_and_b32 m0, s32, 7
	s_lshl_b32 m0, m0, 12
	s_add_i32 m0, m0, 0x400
	s_nop 0
	global_load_lds_dwordx4 v[160:161], off
	v_mfma_f32_32x32x16_bf16 v[16:31], a[0:3], a[12:15], v[16:31]
	v_mfma_f32_32x32x16_bf16 v[0:15], a[4:7], a[12:15], v[0:15]
	s_and_b32 m0, s32, 7
	s_lshl_b32 m0, m0, 12
	s_add_i32 m0, m0, 0x800
	s_nop 0
	global_load_lds_dwordx4 v[162:163], off
	ds_read_b128 a[0:3], v95
	ds_read_b128 a[4:7], v94
	ds_read_b128 a[8:11], v86 offset:49152
	ds_read_b128 a[12:15], v86 offset:53248
	s_waitcnt lgkmcnt(5)
	v_mfma_f32_32x32x16_bf16 v[48:63], a[16:19], a[24:27], v[48:63]
	v_mfma_f32_32x32x16_bf16 v[32:47], a[20:23], a[24:27], v[32:47]
	s_and_b32 m0, s32, 7
	s_lshl_b32 m0, m0, 12
	s_add_i32 m0, m0, 0xc00
	s_nop 0
	global_load_lds_dwordx4 v[164:165], off
	s_waitcnt lgkmcnt(4)
	v_mfma_f32_32x32x16_bf16 v[16:31], a[16:19], a[28:31], v[16:31]
	v_mfma_f32_32x32x16_bf16 v[0:15], a[20:23], a[28:31], v[0:15]
	s_and_b32 m0, s32, 7
	s_lshl_b32 m0, m0, 11
	s_add_i32 m0, m0, 0x8000
	s_nop 0
	global_load_lds_dwordx4 v[166:167], off
	ds_read_b128 a[16:19], v97
	ds_read_b128 a[20:23], v96
	ds_read_b128 a[24:27], v88 offset:49152
	ds_read_b128 a[28:31], v88 offset:53248
	s_waitcnt lgkmcnt(5)
	v_mfma_f32_32x32x16_bf16 v[48:63], a[0:3], a[8:11], v[48:63]
	v_mfma_f32_32x32x16_bf16 v[32:47], a[4:7], a[8:11], v[32:47]
	s_and_b32 m0, s32, 7
	s_lshl_b32 m0, m0, 11
	s_add_i32 m0, m0, 0x8400
	s_nop 0
	global_load_lds_dwordx4 v[168:169], off
	s_waitcnt lgkmcnt(4)
	v_mfma_f32_32x32x16_bf16 v[16:31], a[0:3], a[12:15], v[16:31]
	v_mfma_f32_32x32x16_bf16 v[0:15], a[4:7], a[12:15], v[0:15]
	s_waitcnt lgkmcnt(1)
	v_mfma_f32_32x32x16_bf16 v[48:63], a[16:19], a[24:27], v[48:63]
	v_mfma_f32_32x32x16_bf16 v[32:47], a[20:23], a[24:27], v[32:47]
	s_waitcnt vmcnt(6)
	s_waitcnt lgkmcnt(0)
	s_barrier
	ds_read_b128 a[12:15], v101
	ds_read_b128 a[8:11], v100
	ds_read_b128 a[4:7], v99
	ds_read_b128 a[0:3], v98
	v_mfma_f32_32x32x16_bf16 v[16:31], a[16:19], a[28:31], v[16:31]
	v_lshl_add_u64 v[170:171], v[66:67], 0, s[30:31]
	v_lshl_add_u64 v[172:173], v[68:69], 0, s[30:31]
	v_mfma_f32_32x32x16_bf16 v[0:15], a[20:23], a[28:31], v[0:15]
	s_and_b32 m0, s32, 7
	s_lshl_b32 m0, m0, 12
	s_add_i32 m0, m0, 0xc000
	s_nop 0
	global_load_lds_dwordx4 v[170:171], off
	v_lshl_add_u64 v[176:177], v[72:73], 0, s[30:31]
	v_lshl_add_u64 v[178:179], v[74:75], 0, s[30:31]
	v_lshl_add_u64 v[180:181], v[76:77], 0, s[30:31]
	s_mov_b64 s[30:31], 0x580
	ds_read_b128 a[16:19], v102
	ds_read_b128 a[20:23], v103
	ds_read_b128 a[24:27], v104
	ds_read_b128 a[28:31], v105
	s_waitcnt lgkmcnt(4)
	v_mfma_f32_32x32x16_bf16 v[48:63], a[0:3], a[8:11], v[48:63]
	v_lshl_add_u64 v[162:163], v[70:71], 0, s[30:31]
	v_mfma_f32_32x32x16_bf16 v[32:47], a[4:7], a[8:11], v[32:47]
	s_and_b32 m0, s32, 7
	s_lshl_b32 m0, m0, 12
	s_add_i32 m0, m0, 0xc400
	s_nop 0
	global_load_lds_dwordx4 v[172:173], off
	v_mfma_f32_32x32x16_bf16 v[16:31], a[0:3], a[12:15], v[16:31]
	v_mfma_f32_32x32x16_bf16 v[0:15], a[4:7], a[12:15], v[0:15]
	s_and_b32 m0, s32, 7
	s_lshl_b32 m0, m0, 12
	s_add_i32 m0, m0, 0xc800
	s_nop 0
	global_load_lds_dwordx4 v[174:175], off
	ds_read_b128 a[0:3], v106
	ds_read_b128 a[4:7], v107
	ds_read_b128 a[8:11], v108
	ds_read_b128 a[12:15], v109
	s_waitcnt lgkmcnt(5)
	v_mfma_f32_32x32x16_bf16 v[48:63], a[16:19], a[24:27], v[48:63]
	v_mfma_f32_32x32x16_bf16 v[32:47], a[20:23], a[24:27], v[32:47]
	s_and_b32 m0, s32, 7
	s_lshl_b32 m0, m0, 12
	s_add_i32 m0, m0, 0xcc00
	s_nop 0
	global_load_lds_dwordx4 v[176:177], off
	s_waitcnt lgkmcnt(4)
	v_mfma_f32_32x32x16_bf16 v[16:31], a[16:19], a[28:31], v[16:31]
	v_mfma_f32_32x32x16_bf16 v[0:15], a[20:23], a[28:31], v[0:15]
	s_and_b32 m0, s32, 7
	s_lshl_b32 m0, m0, 11
	s_add_i32 m0, m0, 0x14000
	s_nop 0
	global_load_lds_dwordx4 v[178:179], off
	ds_read_b128 a[16:19], v110
	ds_read_b128 a[20:23], v111
	ds_read_b128 a[24:27], v112
	ds_read_b128 a[28:31], v113
	s_waitcnt lgkmcnt(5)
	v_mfma_f32_32x32x16_bf16 v[48:63], a[0:3], a[8:11], v[48:63]
	v_mfma_f32_32x32x16_bf16 v[32:47], a[4:7], a[8:11], v[32:47]
	s_and_b32 m0, s32, 7
	s_lshl_b32 m0, m0, 11
	s_add_i32 m0, m0, 0x14400
	s_nop 0
	global_load_lds_dwordx4 v[180:181], off
	s_waitcnt lgkmcnt(4)
	v_mfma_f32_32x32x16_bf16 v[16:31], a[0:3], a[12:15], v[16:31]
	v_mfma_f32_32x32x16_bf16 v[0:15], a[4:7], a[12:15], v[0:15]
	s_waitcnt lgkmcnt(1)
	v_mfma_f32_32x32x16_bf16 v[48:63], a[16:19], a[24:27], v[48:63]
	v_mfma_f32_32x32x16_bf16 v[32:47], a[20:23], a[24:27], v[32:47]
	s_waitcnt vmcnt(6)
	s_waitcnt lgkmcnt(0)
	s_barrier
	ds_read_b128 a[12:15], v82 offset:4096
	ds_read_b128 a[8:11], v82
	ds_read_b128 a[4:7], v83 offset:36864
	ds_read_b128 a[0:3], v83 offset:32768
	v_mfma_f32_32x32x16_bf16 v[16:31], a[16:19], a[28:31], v[16:31]
	v_lshl_add_u64 v[158:159], v[66:67], 0, s[30:31]
	v_lshl_add_u64 v[160:161], v[68:69], 0, s[30:31]
	v_mfma_f32_32x32x16_bf16 v[0:15], a[20:23], a[28:31], v[0:15]
	s_and_b32 m0, s32, 7
	s_lshl_b32 m0, m0, 12
	s_add_i32 m0, m0, 0x18000
	s_nop 0
	global_load_lds_dwordx4 v[158:159], off
	v_lshl_add_u64 v[164:165], v[72:73], 0, s[30:31]
	v_lshl_add_u64 v[166:167], v[74:75], 0, s[30:31]
	v_lshl_add_u64 v[168:169], v[76:77], 0, s[30:31]
	s_mov_b64 s[30:31], 0x600
	ds_read_b128 a[16:19], v85 offset:32768
	ds_read_b128 a[20:23], v85 offset:36864
	ds_read_b128 a[24:27], v84
	ds_read_b128 a[28:31], v84 offset:4096
	s_waitcnt lgkmcnt(4)
	v_mfma_f32_32x32x16_bf16 v[48:63], a[0:3], a[8:11], v[48:63]
	v_mfma_f32_32x32x16_bf16 v[32:47], a[4:7], a[8:11], v[32:47]
	s_and_b32 m0, s32, 7
	s_lshl_b32 m0, m0, 12
	s_add_i32 m0, m0, 0x18400
	s_nop 0
	global_load_lds_dwordx4 v[160:161], off
	v_mfma_f32_32x32x16_bf16 v[16:31], a[0:3], a[12:15], v[16:31]
	v_mfma_f32_32x32x16_bf16 v[0:15], a[4:7], a[12:15], v[0:15]
	s_and_b32 m0, s32, 7
	s_lshl_b32 m0, m0, 12
	s_add_i32 m0, m0, 0x18800
	s_nop 0
	global_load_lds_dwordx4 v[162:163], off
	ds_read_b128 a[0:3], v87 offset:32768
	ds_read_b128 a[4:7], v87 offset:36864
	ds_read_b128 a[8:11], v86
	ds_read_b128 a[12:15], v86 offset:4096
	s_waitcnt lgkmcnt(5)
	v_mfma_f32_32x32x16_bf16 v[48:63], a[16:19], a[24:27], v[48:63]
	v_mfma_f32_32x32x16_bf16 v[32:47], a[20:23], a[24:27], v[32:47]
	s_and_b32 m0, s32, 7
	s_lshl_b32 m0, m0, 12
	s_add_i32 m0, m0, 0x18c00
	s_nop 0
	global_load_lds_dwordx4 v[164:165], off
	s_waitcnt lgkmcnt(4)
	v_mfma_f32_32x32x16_bf16 v[16:31], a[16:19], a[28:31], v[16:31]
	v_mfma_f32_32x32x16_bf16 v[0:15], a[20:23], a[28:31], v[0:15]
	s_and_b32 m0, s32, 7
	s_lshl_b32 m0, m0, 11
	s_add_i32 m0, m0, 0x20000
	s_nop 0
	global_load_lds_dwordx4 v[166:167], off
	ds_read_b128 a[16:19], v89 offset:32768
	ds_read_b128 a[20:23], v89 offset:36864
	ds_read_b128 a[24:27], v88
	ds_read_b128 a[28:31], v88 offset:4096
	s_waitcnt lgkmcnt(5)
	v_mfma_f32_32x32x16_bf16 v[48:63], a[0:3], a[8:11], v[48:63]
	v_mfma_f32_32x32x16_bf16 v[32:47], a[4:7], a[8:11], v[32:47]
	s_and_b32 m0, s32, 7
	s_lshl_b32 m0, m0, 11
	s_add_i32 m0, m0, 0x20400
	s_nop 0
	global_load_lds_dwordx4 v[168:169], off
	s_waitcnt lgkmcnt(4)
	v_mfma_f32_32x32x16_bf16 v[16:31], a[0:3], a[12:15], v[16:31]
	v_mfma_f32_32x32x16_bf16 v[0:15], a[4:7], a[12:15], v[0:15]
	s_waitcnt lgkmcnt(1)
	v_mfma_f32_32x32x16_bf16 v[48:63], a[16:19], a[24:27], v[48:63]
	v_mfma_f32_32x32x16_bf16 v[32:47], a[20:23], a[24:27], v[32:47]
	s_waitcnt vmcnt(6)
	s_waitcnt lgkmcnt(0)
	s_barrier
	ds_read_b128 a[12:15], v82 offset:53248
	ds_read_b128 a[8:11], v82 offset:49152
	ds_read_b128 a[4:7], v90
	ds_read_b128 a[0:3], v92
	v_mfma_f32_32x32x16_bf16 v[16:31], a[16:19], a[28:31], v[16:31]
	v_lshl_add_u64 v[170:171], v[66:67], 0, s[30:31]
	v_lshl_add_u64 v[172:173], v[68:69], 0, s[30:31]
	v_lshl_add_u64 v[174:175], v[70:71], 0, s[30:31]
	v_mfma_f32_32x32x16_bf16 v[0:15], a[20:23], a[28:31], v[0:15]
	s_and_b32 m0, s32, 7
	s_lshl_b32 m0, m0, 12
	s_add_i32 m0, m0, 0x0
	s_nop 0
	global_load_lds_dwordx4 v[170:171], off
	v_lshl_add_u64 v[176:177], v[72:73], 0, s[30:31]
	v_lshl_add_u64 v[178:179], v[74:75], 0, s[30:31]
	v_lshl_add_u64 v[180:181], v[76:77], 0, s[30:31]
	s_mov_b64 s[30:31], 0x680
	ds_read_b128 a[16:19], v93
	ds_read_b128 a[20:23], v91
	ds_read_b128 a[24:27], v84 offset:49152
	ds_read_b128 a[28:31], v84 offset:53248
	s_waitcnt lgkmcnt(4)
	v_mfma_f32_32x32x16_bf16 v[48:63], a[0:3], a[8:11], v[48:63]
	v_mfma_f32_32x32x16_bf16 v[32:47], a[4:7], a[8:11], v[32:47]
	s_and_b32 m0, s32, 7
	s_lshl_b32 m0, m0, 12
	s_add_i32 m0, m0, 0x400
	s_nop 0
	global_load_lds_dwordx4 v[172:173], off
	v_mfma_f32_32x32x16_bf16 v[16:31], a[0:3], a[12:15], v[16:31]
	v_mfma_f32_32x32x16_bf16 v[0:15], a[4:7], a[12:15], v[0:15]
	s_and_b32 m0, s32, 7
	s_lshl_b32 m0, m0, 12
	s_add_i32 m0, m0, 0x800
	s_nop 0
	global_load_lds_dwordx4 v[174:175], off
	ds_read_b128 a[0:3], v95
	ds_read_b128 a[4:7], v94
	ds_read_b128 a[8:11], v86 offset:49152
	ds_read_b128 a[12:15], v86 offset:53248
	s_waitcnt lgkmcnt(5)
	v_mfma_f32_32x32x16_bf16 v[48:63], a[16:19], a[24:27], v[48:63]
	v_mfma_f32_32x32x16_bf16 v[32:47], a[20:23], a[24:27], v[32:47]
	s_and_b32 m0, s32, 7
	s_lshl_b32 m0, m0, 12
	s_add_i32 m0, m0, 0xc00
	s_nop 0
	global_load_lds_dwordx4 v[176:177], off
	s_waitcnt lgkmcnt(4)
	v_mfma_f32_32x32x16_bf16 v[16:31], a[16:19], a[28:31], v[16:31]
	v_mfma_f32_32x32x16_bf16 v[0:15], a[20:23], a[28:31], v[0:15]
	s_and_b32 m0, s32, 7
	s_lshl_b32 m0, m0, 11
	s_add_i32 m0, m0, 0x8000
	s_nop 0
	global_load_lds_dwordx4 v[178:179], off
	ds_read_b128 a[16:19], v97
	ds_read_b128 a[20:23], v96
	ds_read_b128 a[24:27], v88 offset:49152
	ds_read_b128 a[28:31], v88 offset:53248
	s_waitcnt lgkmcnt(5)
	v_mfma_f32_32x32x16_bf16 v[48:63], a[0:3], a[8:11], v[48:63]
	v_mfma_f32_32x32x16_bf16 v[32:47], a[4:7], a[8:11], v[32:47]
	s_and_b32 m0, s32, 7
	s_lshl_b32 m0, m0, 11
	s_add_i32 m0, m0, 0x8400
	s_nop 0
	global_load_lds_dwordx4 v[180:181], off
	s_waitcnt lgkmcnt(4)
	v_mfma_f32_32x32x16_bf16 v[16:31], a[0:3], a[12:15], v[16:31]
	v_mfma_f32_32x32x16_bf16 v[0:15], a[4:7], a[12:15], v[0:15]
	s_waitcnt lgkmcnt(1)
	v_mfma_f32_32x32x16_bf16 v[48:63], a[16:19], a[24:27], v[48:63]
	v_mfma_f32_32x32x16_bf16 v[32:47], a[20:23], a[24:27], v[32:47]
	s_waitcnt vmcnt(6)
	s_waitcnt lgkmcnt(0)
	s_barrier
	ds_read_b128 a[12:15], v101
	ds_read_b128 a[8:11], v100
	ds_read_b128 a[4:7], v99
	ds_read_b128 a[0:3], v98
	v_mfma_f32_32x32x16_bf16 v[16:31], a[16:19], a[28:31], v[16:31]
	v_lshl_add_u64 v[158:159], v[66:67], 0, s[30:31]
	v_lshl_add_u64 v[160:161], v[68:69], 0, s[30:31]
	v_lshl_add_u64 v[162:163], v[70:71], 0, s[30:31]
	v_mfma_f32_32x32x16_bf16 v[0:15], a[20:23], a[28:31], v[0:15]
	s_and_b32 m0, s32, 7
	s_lshl_b32 m0, m0, 12
	s_add_i32 m0, m0, 0xc000
	s_nop 0
	global_load_lds_dwordx4 v[158:159], off
	v_lshl_add_u64 v[164:165], v[72:73], 0, s[30:31]
	v_lshl_add_u64 v[166:167], v[74:75], 0, s[30:31]
	v_lshl_add_u64 v[168:169], v[76:77], 0, s[30:31]
	s_mov_b64 s[30:31], 0x700
	ds_read_b128 a[16:19], v102
	ds_read_b128 a[20:23], v103
	ds_read_b128 a[24:27], v104
	ds_read_b128 a[28:31], v105
	s_waitcnt lgkmcnt(4)
	v_mfma_f32_32x32x16_bf16 v[48:63], a[0:3], a[8:11], v[48:63]
	v_mfma_f32_32x32x16_bf16 v[32:47], a[4:7], a[8:11], v[32:47]
	s_and_b32 m0, s32, 7
	s_lshl_b32 m0, m0, 12
	s_add_i32 m0, m0, 0xc400
	s_nop 0
	global_load_lds_dwordx4 v[160:161], off
	v_mfma_f32_32x32x16_bf16 v[16:31], a[0:3], a[12:15], v[16:31]
	v_mfma_f32_32x32x16_bf16 v[0:15], a[4:7], a[12:15], v[0:15]
	s_and_b32 m0, s32, 7
	s_lshl_b32 m0, m0, 12
	s_add_i32 m0, m0, 0xc800
	s_nop 0
	global_load_lds_dwordx4 v[162:163], off
	ds_read_b128 a[0:3], v106
	ds_read_b128 a[4:7], v107
	ds_read_b128 a[8:11], v108
	ds_read_b128 a[12:15], v109
	s_waitcnt lgkmcnt(5)
	v_mfma_f32_32x32x16_bf16 v[48:63], a[16:19], a[24:27], v[48:63]
	v_mfma_f32_32x32x16_bf16 v[32:47], a[20:23], a[24:27], v[32:47]
	s_and_b32 m0, s32, 7
	s_lshl_b32 m0, m0, 12
	s_add_i32 m0, m0, 0xcc00
	s_nop 0
	global_load_lds_dwordx4 v[164:165], off
	s_waitcnt lgkmcnt(4)
	v_mfma_f32_32x32x16_bf16 v[16:31], a[16:19], a[28:31], v[16:31]
	v_mfma_f32_32x32x16_bf16 v[0:15], a[20:23], a[28:31], v[0:15]
	s_and_b32 m0, s32, 7
	s_lshl_b32 m0, m0, 11
	s_add_i32 m0, m0, 0x14000
	s_nop 0
	global_load_lds_dwordx4 v[166:167], off
	ds_read_b128 a[16:19], v110
	ds_read_b128 a[20:23], v111
	ds_read_b128 a[24:27], v112
	ds_read_b128 a[28:31], v113
	s_waitcnt lgkmcnt(5)
	v_mfma_f32_32x32x16_bf16 v[48:63], a[0:3], a[8:11], v[48:63]
	v_mfma_f32_32x32x16_bf16 v[32:47], a[4:7], a[8:11], v[32:47]
	s_and_b32 m0, s32, 7
	s_lshl_b32 m0, m0, 11
	s_add_i32 m0, m0, 0x14400
	s_nop 0
	global_load_lds_dwordx4 v[168:169], off
	s_waitcnt lgkmcnt(4)
	v_mfma_f32_32x32x16_bf16 v[16:31], a[0:3], a[12:15], v[16:31]
	v_mfma_f32_32x32x16_bf16 v[0:15], a[4:7], a[12:15], v[0:15]
	s_waitcnt lgkmcnt(1)
	v_mfma_f32_32x32x16_bf16 v[48:63], a[16:19], a[24:27], v[48:63]
	v_mfma_f32_32x32x16_bf16 v[32:47], a[20:23], a[24:27], v[32:47]
	s_waitcnt vmcnt(6)
	s_waitcnt lgkmcnt(0)
	s_barrier
	ds_read_b128 a[12:15], v82 offset:4096
	ds_read_b128 a[8:11], v82
	ds_read_b128 a[4:7], v83 offset:36864
	ds_read_b128 a[0:3], v83 offset:32768
	v_mfma_f32_32x32x16_bf16 v[16:31], a[16:19], a[28:31], v[16:31]
	v_lshl_add_u64 v[170:171], v[66:67], 0, s[30:31]
	v_lshl_add_u64 v[172:173], v[68:69], 0, s[30:31]
	v_lshl_add_u64 v[174:175], v[70:71], 0, s[30:31]
	v_mfma_f32_32x32x16_bf16 v[0:15], a[20:23], a[28:31], v[0:15]
	s_and_b32 m0, s32, 7
	s_lshl_b32 m0, m0, 12
	s_add_i32 m0, m0, 0x18000
	s_nop 0
	global_load_lds_dwordx4 v[170:171], off
	v_lshl_add_u64 v[176:177], v[72:73], 0, s[30:31]
	v_lshl_add_u64 v[178:179], v[74:75], 0, s[30:31]
	v_lshl_add_u64 v[180:181], v[76:77], 0, s[30:31]
	s_mov_b64 s[30:31], 0x780
	ds_read_b128 a[16:19], v85 offset:32768
	ds_read_b128 a[20:23], v85 offset:36864
	ds_read_b128 a[24:27], v84
	ds_read_b128 a[28:31], v84 offset:4096
	s_waitcnt lgkmcnt(4)
	v_mfma_f32_32x32x16_bf16 v[48:63], a[0:3], a[8:11], v[48:63]
	v_lshl_add_u64 v[158:159], v[66:67], 0, s[30:31]
	v_mfma_f32_32x32x16_bf16 v[32:47], a[4:7], a[8:11], v[32:47]
	s_and_b32 m0, s32, 7
	s_lshl_b32 m0, m0, 12
	s_add_i32 m0, m0, 0x18400
	s_nop 0
	global_load_lds_dwordx4 v[172:173], off
	v_mfma_f32_32x32x16_bf16 v[16:31], a[0:3], a[12:15], v[16:31]
	v_mfma_f32_32x32x16_bf16 v[0:15], a[4:7], a[12:15], v[0:15]
	s_and_b32 m0, s32, 7
	s_lshl_b32 m0, m0, 12
	s_add_i32 m0, m0, 0x18800
	s_nop 0
	global_load_lds_dwordx4 v[174:175], off
	ds_read_b128 a[0:3], v87 offset:32768
	ds_read_b128 a[4:7], v87 offset:36864
	ds_read_b128 a[8:11], v86
	ds_read_b128 a[12:15], v86 offset:4096
	s_waitcnt lgkmcnt(5)
	v_mfma_f32_32x32x16_bf16 v[48:63], a[16:19], a[24:27], v[48:63]
	v_mfma_f32_32x32x16_bf16 v[32:47], a[20:23], a[24:27], v[32:47]
	s_and_b32 m0, s32, 7
	s_lshl_b32 m0, m0, 12
	s_add_i32 m0, m0, 0x18c00
	s_nop 0
	global_load_lds_dwordx4 v[176:177], off
	s_waitcnt lgkmcnt(4)
	v_mfma_f32_32x32x16_bf16 v[16:31], a[16:19], a[28:31], v[16:31]
	v_mfma_f32_32x32x16_bf16 v[0:15], a[20:23], a[28:31], v[0:15]
	s_and_b32 m0, s32, 7
	s_lshl_b32 m0, m0, 11
	s_add_i32 m0, m0, 0x20000
	s_nop 0
	global_load_lds_dwordx4 v[178:179], off
	ds_read_b128 a[16:19], v89 offset:32768
	ds_read_b128 a[20:23], v89 offset:36864
	ds_read_b128 a[24:27], v88
	ds_read_b128 a[28:31], v88 offset:4096
	s_waitcnt lgkmcnt(5)
	v_mfma_f32_32x32x16_bf16 v[48:63], a[0:3], a[8:11], v[48:63]
	v_mfma_f32_32x32x16_bf16 v[32:47], a[4:7], a[8:11], v[32:47]
	s_and_b32 m0, s32, 7
	s_lshl_b32 m0, m0, 11
	s_add_i32 m0, m0, 0x20400
	s_nop 0
	global_load_lds_dwordx4 v[180:181], off
	s_waitcnt lgkmcnt(4)
	v_mfma_f32_32x32x16_bf16 v[16:31], a[0:3], a[12:15], v[16:31]
	v_mfma_f32_32x32x16_bf16 v[0:15], a[4:7], a[12:15], v[0:15]
	s_waitcnt lgkmcnt(1)
	v_mfma_f32_32x32x16_bf16 v[48:63], a[16:19], a[24:27], v[48:63]
	v_mfma_f32_32x32x16_bf16 v[32:47], a[20:23], a[24:27], v[32:47]
	s_waitcnt vmcnt(6)
	s_waitcnt lgkmcnt(0)
	s_barrier
	ds_read_b128 a[12:15], v82 offset:53248
	ds_read_b128 a[8:11], v82 offset:49152
	ds_read_b128 a[4:7], v90
	ds_read_b128 a[0:3], v92
	v_lshl_add_u64 v[160:161], v[68:69], 0, s[30:31]
	v_mfma_f32_32x32x16_bf16 v[16:31], a[16:19], a[28:31], v[16:31]
	v_lshl_add_u64 v[162:163], v[70:71], 0, s[30:31]
	s_nop 0
	v_readlane_b32 s20, v215, 52
	s_nop 0
	v_lshl_add_u64 v[164:165], v[72:73], 0, s[30:31]
	s_nop 0
	v_mfma_f32_32x32x16_bf16 v[0:15], a[20:23], a[28:31], v[0:15]
	s_and_b32 m0, s32, 7
	s_lshl_b32 m0, m0, 12
	s_add_i32 m0, m0, 0x0
	s_nop 0
	global_load_lds_dwordx4 v[158:159], off
	v_lshl_add_u64 v[166:167], v[74:75], 0, s[30:31]
	s_nop 0
	v_readlane_b32 s21, v215, 53
	s_nop 0
	v_lshl_add_u64 v[168:169], v[76:77], 0, s[30:31]
	s_nop 0
	s_mov_b32 s23, 0
	ds_read_b128 a[16:19], v93
	ds_read_b128 a[20:23], v91
	ds_read_b128 a[24:27], v84 offset:49152
	ds_read_b128 a[28:31], v84 offset:53248
	s_waitcnt lgkmcnt(4)
	v_mfma_f32_32x32x16_bf16 v[48:63], a[0:3], a[8:11], v[48:63]
	v_mfma_f32_32x32x16_bf16 v[32:47], a[4:7], a[8:11], v[32:47]
	s_and_b32 m0, s32, 7
	s_lshl_b32 m0, m0, 12
	s_add_i32 m0, m0, 0x400
	s_nop 0
	global_load_lds_dwordx4 v[160:161], off
	v_mfma_f32_32x32x16_bf16 v[16:31], a[0:3], a[12:15], v[16:31]
	v_mfma_f32_32x32x16_bf16 v[0:15], a[4:7], a[12:15], v[0:15]
	s_and_b32 m0, s32, 7
	s_lshl_b32 m0, m0, 12
	s_add_i32 m0, m0, 0x800
	s_nop 0
	global_load_lds_dwordx4 v[162:163], off
	ds_read_b128 a[0:3], v95
	ds_read_b128 a[4:7], v94
	ds_read_b128 a[8:11], v86 offset:49152
	ds_read_b128 a[12:15], v86 offset:53248
	s_waitcnt lgkmcnt(5)
	v_mfma_f32_32x32x16_bf16 v[48:63], a[16:19], a[24:27], v[48:63]
	v_mfma_f32_32x32x16_bf16 v[32:47], a[20:23], a[24:27], v[32:47]
	s_and_b32 m0, s32, 7
	s_lshl_b32 m0, m0, 12
	s_add_i32 m0, m0, 0xc00
	s_nop 0
	global_load_lds_dwordx4 v[164:165], off
	s_waitcnt lgkmcnt(4)
	v_mfma_f32_32x32x16_bf16 v[16:31], a[16:19], a[28:31], v[16:31]
	v_mfma_f32_32x32x16_bf16 v[0:15], a[20:23], a[28:31], v[0:15]
	s_and_b32 m0, s32, 7
	s_lshl_b32 m0, m0, 11
	s_add_i32 m0, m0, 0x8000
	s_nop 0
	global_load_lds_dwordx4 v[166:167], off
	ds_read_b128 a[16:19], v97
	ds_read_b128 a[20:23], v96
	ds_read_b128 a[24:27], v88 offset:49152
	ds_read_b128 a[28:31], v88 offset:53248
	s_waitcnt lgkmcnt(5)
	v_mfma_f32_32x32x16_bf16 v[48:63], a[0:3], a[8:11], v[48:63]
	v_mfma_f32_32x32x16_bf16 v[32:47], a[4:7], a[8:11], v[32:47]
	s_and_b32 m0, s32, 7
	s_lshl_b32 m0, m0, 11
	s_add_i32 m0, m0, 0x8400
	s_nop 0
	global_load_lds_dwordx4 v[168:169], off
	s_waitcnt lgkmcnt(4)
	v_mfma_f32_32x32x16_bf16 v[16:31], a[0:3], a[12:15], v[16:31]
	v_mfma_f32_32x32x16_bf16 v[0:15], a[4:7], a[12:15], v[0:15]
	s_waitcnt lgkmcnt(1)
	v_mfma_f32_32x32x16_bf16 v[48:63], a[16:19], a[24:27], v[48:63]
	v_mfma_f32_32x32x16_bf16 v[32:47], a[20:23], a[24:27], v[32:47]
	s_waitcnt vmcnt(6)
	s_waitcnt lgkmcnt(0)
	s_barrier
	ds_read_b128 a[12:15], v101
	ds_read_b128 a[8:11], v100
	ds_read_b128 a[4:7], v99
	ds_read_b128 a[0:3], v98
	v_mfma_f32_32x32x16_bf16 v[16:31], a[16:19], a[28:31], v[16:31]
	v_mfma_f32_32x32x16_bf16 v[0:15], a[20:23], a[28:31], v[0:15]
	ds_read_b128 a[16:19], v102
	ds_read_b128 a[20:23], v103
	ds_read_b128 a[24:27], v104
	ds_read_b128 a[28:31], v105
	s_waitcnt lgkmcnt(4)
	v_mfma_f32_32x32x16_bf16 v[48:63], a[0:3], a[8:11], v[48:63]
	v_mfma_f32_32x32x16_bf16 v[32:47], a[4:7], a[8:11], v[32:47]
	v_mfma_f32_32x32x16_bf16 v[16:31], a[0:3], a[12:15], v[16:31]
	v_mfma_f32_32x32x16_bf16 v[0:15], a[4:7], a[12:15], v[0:15]
	ds_read_b128 a[0:3], v106
	ds_read_b128 a[4:7], v107
	ds_read_b128 a[8:11], v108
	ds_read_b128 a[12:15], v109
	s_waitcnt lgkmcnt(5)
	v_mfma_f32_32x32x16_bf16 v[48:63], a[16:19], a[24:27], v[48:63]
	v_mfma_f32_32x32x16_bf16 v[32:47], a[20:23], a[24:27], v[32:47]
	s_waitcnt lgkmcnt(4)
	v_mfma_f32_32x32x16_bf16 v[16:31], a[16:19], a[28:31], v[16:31]
	v_mfma_f32_32x32x16_bf16 v[0:15], a[20:23], a[28:31], v[0:15]
	ds_read_b128 a[16:19], v110
	ds_read_b128 a[20:23], v111
	ds_read_b128 a[24:27], v112
	ds_read_b128 a[28:31], v113
	s_waitcnt lgkmcnt(5)
	v_mfma_f32_32x32x16_bf16 v[48:63], a[0:3], a[8:11], v[48:63]
	v_mfma_f32_32x32x16_bf16 v[32:47], a[4:7], a[8:11], v[32:47]
	s_waitcnt lgkmcnt(4)
	v_mfma_f32_32x32x16_bf16 v[16:31], a[0:3], a[12:15], v[16:31]
	v_mfma_f32_32x32x16_bf16 v[0:15], a[4:7], a[12:15], v[0:15]
	s_waitcnt lgkmcnt(1)
	v_mfma_f32_32x32x16_bf16 v[48:63], a[16:19], a[24:27], v[48:63]
	v_mfma_f32_32x32x16_bf16 v[32:47], a[20:23], a[24:27], v[32:47]
	s_waitcnt vmcnt(0)
	s_waitcnt lgkmcnt(0)
	s_barrier
	ds_read_b128 a[12:15], v82 offset:4096
	ds_read_b128 a[8:11], v82
	ds_read_b128 a[4:7], v83 offset:36864
	ds_read_b128 a[0:3], v83 offset:32768
	v_mfma_f32_32x32x16_bf16 v[16:31], a[16:19], a[28:31], v[16:31]
	v_mfma_f32_32x32x16_bf16 v[0:15], a[20:23], a[28:31], v[0:15]
	ds_read_b128 a[16:19], v85 offset:32768
	ds_read_b128 a[20:23], v85 offset:36864
	ds_read_b128 a[24:27], v84
	ds_read_b128 a[28:31], v84 offset:4096
	s_waitcnt lgkmcnt(4)
	v_mfma_f32_32x32x16_bf16 v[48:63], a[0:3], a[8:11], v[48:63]
	v_mfma_f32_32x32x16_bf16 v[32:47], a[4:7], a[8:11], v[32:47]
	v_mfma_f32_32x32x16_bf16 v[16:31], a[0:3], a[12:15], v[16:31]
	v_mfma_f32_32x32x16_bf16 v[0:15], a[4:7], a[12:15], v[0:15]
	ds_read_b128 a[0:3], v87 offset:32768
	ds_read_b128 a[4:7], v87 offset:36864
	ds_read_b128 a[8:11], v86
	ds_read_b128 a[12:15], v86 offset:4096
	s_waitcnt lgkmcnt(5)
	v_mfma_f32_32x32x16_bf16 v[48:63], a[16:19], a[24:27], v[48:63]
	v_mfma_f32_32x32x16_bf16 v[32:47], a[20:23], a[24:27], v[32:47]
	s_waitcnt lgkmcnt(4)
	v_mfma_f32_32x32x16_bf16 v[16:31], a[16:19], a[28:31], v[16:31]
	v_mfma_f32_32x32x16_bf16 v[0:15], a[20:23], a[28:31], v[0:15]
	s_waitcnt lgkmcnt(1)
	v_mfma_f32_32x32x16_bf16 v[48:63], a[0:3], a[8:11], v[48:63]
	v_mfma_f32_32x32x16_bf16 v[32:47], a[4:7], a[8:11], v[32:47]
	s_waitcnt lgkmcnt(0)
	v_mfma_f32_32x32x16_bf16 v[0:15], a[4:7], a[12:15], v[0:15]
	v_mfma_f32_32x32x16_bf16 v[16:31], a[0:3], a[12:15], v[16:31]
	ds_read_b128 v[66:69], v89 offset:32768
	ds_read_b128 v[70:73], v88
	ds_read_b128 v[74:77], v89 offset:36864
	ds_read_b128 v[82:85], v88 offset:4096
	s_waitcnt lgkmcnt(0)
	s_barrier
	s_waitcnt lgkmcnt(0)
	v_mfma_f32_32x32x16_bf16 v[48:63], v[66:69], v[70:73], v[48:63]
	v_mfma_f32_32x32x16_bf16 v[32:47], v[74:77], v[70:73], v[32:47]
	s_nop 10
	ds_write_b128 v64, v[48:51]
	ds_write_b128 v64, v[52:55] offset:32
	ds_write_b128 v64, v[56:59] offset:64
	ds_write_b128 v64, v[60:63] offset:96
	ds_write_b128 v64, v[32:35] offset:128
	v_mfma_f32_32x32x16_bf16 v[0:15], v[74:77], v[82:85], v[0:15]
	v_mfma_f32_32x32x16_bf16 v[16:31], v[66:69], v[82:85], v[16:31]
	ds_write_b128 v64, v[36:39] offset:160
	ds_write_b128 v64, v[40:43] offset:192
	ds_write_b128 v64, v[44:47] offset:224
	s_nop 8
	ds_write_b128 v64, v[16:19] offset:16896
	ds_write_b128 v64, v[20:23] offset:16928
	ds_write_b128 v64, v[24:27] offset:16960
	ds_write_b128 v64, v[28:31] offset:16992
	ds_write_b128 v64, v[0:3] offset:17024
	ds_write_b128 v64, v[4:7] offset:17056
	ds_write_b128 v64, v[8:11] offset:17088
	ds_write_b128 v64, v[12:15] offset:17120
	s_waitcnt lgkmcnt(0)
	s_barrier
	v_lshl_or_b32 v0, v79, 2, s0
	v_ashrrev_i32_e32 v1, 31, v0
	v_lshl_add_u32 v4, v79, 4, 0
	v_cmp_eq_u32_e64 s[0:1], 0, v79
	v_lshl_add_u64 v[6:7], v[0:1], 2, s[92:93]
	v_lshl_add_u64 v[8:9], v[0:1], 1, s[20:21]
	s_branch .LBB0_96

.LBB0_159:
	v_mov_b32_e32 v78, v133
	s_lshl_b32 s22, s2, 8
	v_ashrrev_i32_e32 v6, 6, v78
	v_bfe_u32 v7, v78, 3, 3
	v_lshl_or_b32 v8, v6, 5, v7
	v_add_u32_e32 v0, s22, v8
	s_waitcnt lgkmcnt(0)
	v_ashrrev_i32_e32 v1, 31, v0
	v_lshlrev_b64 v[2:3], 11, v[0:1]
	v_bfe_u32 v1, v78, 4, 2
	v_readlane_b32 s0, v214, 4
	v_xor_b32_e32 v1, v1, v78
	v_readlane_b32 s1, v214, 5
	v_lshlrev_b32_e32 v1, 4, v1
	v_and_b32_e32 v64, 0x70, v1
	v_lshl_add_u64 v[2:3], s[0:1], 0, v[2:3]
	v_or_b32_e32 v1, 8, v8
	v_lshl_add_u64 v[66:67], v[2:3], 0, v[64:65]
	v_add_u32_e32 v2, s22, v1
	v_lshrrev_b32_e32 v1, 1, v1
	v_xor_b32_e32 v1, v1, v78
	v_ashrrev_i32_e32 v3, 31, v2
	v_lshlrev_b32_e32 v1, 4, v1
	v_or_b32_e32 v0, 16, v0
	v_lshlrev_b64 v[2:3], 11, v[2:3]
	v_and_b32_e32 v4, 0x70, v1
	v_ashrrev_i32_e32 v1, 31, v0
	v_lshl_add_u64 v[2:3], s[0:1], 0, v[2:3]
	v_mov_b32_e32 v5, v65
	v_lshlrev_b64 v[0:1], 11, v[0:1]
	v_lshl_add_u64 v[68:69], v[2:3], 0, v[4:5]
	v_lshl_add_u64 v[0:1], s[0:1], 0, v[0:1]
	v_or_b32_e32 v2, 24, v8
	v_lshl_add_u64 v[70:71], v[0:1], 0, v[64:65]
	v_add_u32_e32 v0, s22, v2
	v_lshrrev_b32_e32 v2, 1, v2
	v_ashrrev_i32_e32 v1, 31, v0
	v_xor_b32_e32 v2, v2, v78
	v_lshlrev_b64 v[0:1], 11, v[0:1]
	v_lshlrev_b32_e32 v2, 4, v2
	v_lshl_add_u64 v[0:1], s[0:1], 0, v[0:1]
	v_and_b32_e32 v2, 0x70, v2
	v_mov_b32_e32 v3, v65
	v_lshl_add_u64 v[72:73], v[0:1], 0, v[2:3]
	v_lshl_or_b32 v2, v6, 4, v7
	v_readlane_b32 s31, v214, 58
	v_lshlrev_b32_e32 v3, 12, v6
	v_add_u32_e32 v126, 0, v3
	v_add_u32_e32 v0, s31, v2
	v_ashrrev_i32_e32 v1, 31, v0
	v_lshlrev_b64 v[0:1], 11, v[0:1]
	s_waitcnt vmcnt(0)
	v_readfirstlane_b32 s37, v126
	v_add_u32_e32 v127, 0x400, v126
	v_lshl_add_u64 v[0:1], s[40:41], 0, v[0:1]
	v_or_b32_e32 v2, 8, v2
	s_waitcnt lgkmcnt(0)
	s_barrier
	s_mov_b32 m0, s37
	v_readfirstlane_b32 s38, v127
	v_add_u32_e32 v128, 0x800, v126
	v_lshlrev_b32_e32 v5, 11, v6
	v_and_b32_e32 v80, 1, v6
	v_lshl_add_u64 v[74:75], v[0:1], 0, v[64:65]
	v_add_u32_e32 v0, s31, v2
	v_lshrrev_b32_e32 v2, 1, v2
	global_load_lds_dwordx4 v[66:67], off
	s_mov_b32 m0, s38
	v_readfirstlane_b32 s39, v128
	v_add_u32_e32 v129, 0xc00, v126
	v_add_u32_e32 v6, 0, v5
	v_ashrrev_i32_e32 v1, 31, v0
	v_xor_b32_e32 v2, v2, v78
	global_load_lds_dwordx4 v[68:69], off
	s_mov_b32 m0, s39
	v_readfirstlane_b32 s48, v129
	v_add_u32_e32 v131, 0x8000, v6
	v_lshlrev_b64 v[0:1], 11, v[0:1]
	v_lshlrev_b32_e32 v2, 4, v2
	global_load_lds_dwordx4 v[70:71], off
	s_mov_b32 m0, s48
	v_readfirstlane_b32 s49, v131
	v_add_u32_e32 v130, 0x8400, v6
	v_lshl_add_u64 v[0:1], s[40:41], 0, v[0:1]
	v_and_b32_e32 v64, 0x70, v2
	global_load_lds_dwordx4 v[72:73], off
	s_mov_b32 m0, s49
	v_readfirstlane_b32 s53, v130
	v_add_u32_e32 v120, 0xc000, v126
	v_lshl_add_u64 v[76:77], v[0:1], 0, v[64:65]
	global_load_lds_dwordx4 v[74:75], off
	s_mov_b32 m0, s53
	s_mov_b64 s[0:1], 0x80
	v_readfirstlane_b32 s28, v120
	v_add_u32_e32 v121, 0xc400, v126
	global_load_lds_dwordx4 v[76:77], off
	v_lshl_add_u64 v[0:1], v[66:67], 0, s[0:1]
	s_mov_b32 m0, s28
	v_readfirstlane_b32 s29, v121
	v_add_u32_e32 v122, 0xc800, v126
	global_load_lds_dwordx4 v[0:1], off
	v_lshl_add_u64 v[0:1], v[68:69], 0, s[0:1]
	s_mov_b32 m0, s29
	v_readfirstlane_b32 s33, v122
	v_add_u32_e32 v123, 0xcc00, v126
	global_load_lds_dwordx4 v[0:1], off
	v_lshl_add_u64 v[0:1], v[70:71], 0, s[0:1]
	s_mov_b32 m0, s33
	v_readfirstlane_b32 s34, v123
	v_add_u32_e32 v124, s85, v5
	global_load_lds_dwordx4 v[0:1], off
	v_lshl_add_u64 v[0:1], v[72:73], 0, s[0:1]
	s_mov_b32 m0, s34
	v_readfirstlane_b32 s35, v124
	v_add_u32_e32 v125, 0x14400, v6
	global_load_lds_dwordx4 v[0:1], off
	v_lshl_add_u64 v[0:1], v[74:75], 0, s[0:1]
	s_mov_b32 m0, s35
	v_readfirstlane_b32 s36, v125
	global_load_lds_dwordx4 v[0:1], off
	v_lshl_add_u64 v[0:1], v[76:77], 0, s[0:1]
	s_mov_b32 m0, s36
	v_lshrrev_b32_e32 v2, 1, v78
	v_bfe_u32 v64, v78, 5, 1
	global_load_lds_dwordx4 v[0:1], off
	v_add_u32_e32 v114, s3, v3
	v_bitop3_b32 v0, v2, v64, 7 bitop3:0x6c
	s_waitcnt vmcnt(6)
	s_mov_b64 s[46:47], 0x100
	v_readfirstlane_b32 s0, v114
	v_add_u32_e32 v115, 0x400, v114
	v_lshlrev_b32_e32 v132, 4, v0
	s_waitcnt lgkmcnt(0)
	s_barrier
	v_lshl_add_u64 v[0:1], v[66:67], 0, s[46:47]
	s_mov_b32 m0, s0
	v_readfirstlane_b32 s1, v115
	v_add_u32_e32 v116, 0x800, v114
	global_load_lds_dwordx4 v[0:1], off
	v_lshl_add_u64 v[0:1], v[68:69], 0, s[46:47]
	s_mov_b32 m0, s1
	v_readfirstlane_b32 s20, v116
	v_add_u32_e32 v117, 0xc00, v114
	v_readlane_b32 s23, v212, 31
	v_and_b32_e32 v79, 31, v78
	global_load_lds_dwordx4 v[0:1], off
	v_lshl_add_u64 v[0:1], v[70:71], 0, s[46:47]
	s_mov_b32 m0, s20
	v_readfirstlane_b32 s21, v117
	v_add_u32_e32 v118, s23, v5
	v_add_u32_e32 v2, s3, v5
	v_lshlrev_b32_e32 v4, 7, v79
	global_load_lds_dwordx4 v[0:1], off
	v_lshl_add_u64 v[0:1], v[72:73], 0, s[46:47]
	s_mov_b32 m0, s21
	v_readfirstlane_b32 s23, v118
	v_add_u32_e32 v119, 0x8400, v2
	v_lshl_or_b32 v102, v80, 13, v4
	global_load_lds_dwordx4 v[0:1], off
	v_lshl_add_u64 v[0:1], v[74:75], 0, s[46:47]
	s_mov_b32 m0, s23
	v_readfirstlane_b32 s24, v119
	global_load_lds_dwordx4 v[0:1], off
	v_lshl_add_u64 v[0:1], v[76:77], 0, s[46:47]
	s_mov_b32 m0, s24
	v_add_u32_e32 v100, 0, v102
	global_load_lds_dwordx4 v[0:1], off
	v_add_u32_e32 v83, v100, v132
	v_ashrrev_i32_e32 v81, 7, v78
	ds_read_b128 a[0:3], v83 offset:32768
	ds_read_b128 a[4:7], v83 offset:36864
	v_lshl_or_b32 v134, v81, 13, v4
	v_add_u32_e32 v101, 0, v134
	v_add_u32_e32 v82, v101, v132
	ds_read_b128 a[8:11], v82
	ds_read_b128 a[12:15], v82 offset:4096
	v_lshrrev_b32_e32 v182, 6, v133
	s_nop 0
	v_readfirstlane_b32 s32, v182
	s_waitcnt lgkmcnt(1)
	v_mfma_f32_32x32x16_bf16 v[48:63], a[0:3], a[8:11], 0
	v_bfe_u32 v103, v78, 1, 3
	s_mov_b64 s[46:47], 0x180
	s_add_i32 s30, 0, 0xc000
	v_or_b32_e32 v143, 0x8000, v102
	v_or_b32_e32 v144, 0x9000, v102
	v_add_u32_e32 v145, s3, v134
	s_waitcnt vmcnt(12)
	v_mfma_f32_32x32x16_bf16 v[32:47], a[4:7], a[8:11], 0
	v_lshl_or_b32 v81, v81, 6, v79
	v_mul_lo_u32 v81, v81, s26
	s_mov_b64 s[80:81], 0x200
	s_waitcnt lgkmcnt(0)
	v_mfma_f32_32x32x16_bf16 v[16:31], a[0:3], a[12:15], 0
	v_bitop3_b32 v0, v64, v103, 2 bitop3:0x36
	v_lshlrev_b32_e32 v138, 4, v0
	v_add_u32_e32 v84, v101, v138
	ds_read_b128 a[28:31], v84 offset:4096
	ds_read_b128 a[24:27], v84
	v_add_u32_e32 v85, v100, v138
	ds_read_b128 a[20:23], v85 offset:36864
	ds_read_b128 a[16:19], v85 offset:32768
	v_mfma_f32_32x32x16_bf16 v[0:15], a[4:7], a[12:15], 0
	s_waitcnt lgkmcnt(0)
	v_mfma_f32_32x32x16_bf16 v[48:63], a[16:19], a[24:27], v[48:63]
	v_mfma_f32_32x32x16_bf16 v[32:47], a[20:23], a[24:27], v[32:47]
	v_mfma_f32_32x32x16_bf16 v[16:31], a[16:19], a[28:31], v[16:31]
	v_bitop3_b32 v86, v64, v103, 4 bitop3:0x36
	v_lshlrev_b32_e32 v139, 4, v86
	v_add_u32_e32 v86, v101, v139
	ds_read_b128 a[12:15], v86 offset:4096
	ds_read_b128 a[8:11], v86
	v_add_u32_e32 v87, v100, v139
	ds_read_b128 a[4:7], v87 offset:36864
	ds_read_b128 a[0:3], v87 offset:32768
	v_mfma_f32_32x32x16_bf16 v[0:15], a[20:23], a[28:31], v[0:15]
	s_waitcnt lgkmcnt(0)
	v_mfma_f32_32x32x16_bf16 v[48:63], a[0:3], a[8:11], v[48:63]
	v_mfma_f32_32x32x16_bf16 v[32:47], a[4:7], a[8:11], v[32:47]
	v_mfma_f32_32x32x16_bf16 v[16:31], a[0:3], a[12:15], v[16:31]
	v_bitop3_b32 v88, v64, v103, 6 bitop3:0x36
	v_lshlrev_b32_e32 v142, 4, v88
	v_add_u32_e32 v88, v101, v142
	ds_read_b128 a[28:31], v88 offset:4096
	ds_read_b128 a[24:27], v88
	v_add_u32_e32 v89, v100, v142
	ds_read_b128 a[20:23], v89 offset:36864
	ds_read_b128 a[16:19], v89 offset:32768
	v_lshlrev_b32_e32 v64, 4, v64
	v_lshl_or_b32 v64, v80, 8, v64
	v_add3_u32 v64, 0, v81, v64
	v_mfma_f32_32x32x16_bf16 v[0:15], a[4:7], a[12:15], v[0:15]
	s_waitcnt lgkmcnt(0)
	v_mfma_f32_32x32x16_bf16 v[48:63], a[16:19], a[24:27], v[48:63]
	v_mfma_f32_32x32x16_bf16 v[32:47], a[20:23], a[24:27], v[32:47]
	s_waitcnt vmcnt(6)
	s_waitcnt lgkmcnt(0)
	s_barrier
	ds_read_b128 a[12:15], v82 offset:53248
	ds_read_b128 a[8:11], v82 offset:49152
	v_add_u32_e32 v90, s30, v132
	v_add_u32_e32 v92, v90, v143
	v_add_u32_e32 v90, v90, v144
	ds_read_b128 a[4:7], v90
	ds_read_b128 a[0:3], v92
	v_mfma_f32_32x32x16_bf16 v[16:31], a[16:19], a[28:31], v[16:31]
	v_lshl_add_u64 v[158:159], v[66:67], 0, s[46:47]
	v_lshl_add_u64 v[160:161], v[68:69], 0, s[46:47]
	v_lshl_add_u64 v[162:163], v[70:71], 0, s[46:47]
	v_mfma_f32_32x32x16_bf16 v[0:15], a[20:23], a[28:31], v[0:15]
	s_and_b32 m0, s32, 7
	s_lshl_b32 m0, m0, 12
	s_add_i32 m0, m0, 0x0
	s_nop 0
	global_load_lds_dwordx4 v[158:159], off
	v_lshl_add_u64 v[164:165], v[72:73], 0, s[46:47]
	v_lshl_add_u64 v[166:167], v[74:75], 0, s[46:47]
	v_lshl_add_u64 v[168:169], v[76:77], 0, s[46:47]
	s_mov_b64 s[46:47], 0x200
	v_add_u32_e32 v91, s30, v138
	v_add_u32_e32 v93, v91, v143
	ds_read_b128 a[16:19], v93
	v_add_u32_e32 v91, v91, v144
	ds_read_b128 a[20:23], v91
	ds_read_b128 a[24:27], v84 offset:49152
	ds_read_b128 a[28:31], v84 offset:53248
	s_waitcnt lgkmcnt(4)
	v_mfma_f32_32x32x16_bf16 v[48:63], a[0:3], a[8:11], v[48:63]
	v_mfma_f32_32x32x16_bf16 v[32:47], a[4:7], a[8:11], v[32:47]
	s_and_b32 m0, s32, 7
	s_lshl_b32 m0, m0, 12
	s_add_i32 m0, m0, 0x400
	s_nop 0
	global_load_lds_dwordx4 v[160:161], off
	v_mfma_f32_32x32x16_bf16 v[16:31], a[0:3], a[12:15], v[16:31]
	v_mfma_f32_32x32x16_bf16 v[0:15], a[4:7], a[12:15], v[0:15]
	s_and_b32 m0, s32, 7
	s_lshl_b32 m0, m0, 12
	s_add_i32 m0, m0, 0x800
	s_nop 0
	global_load_lds_dwordx4 v[162:163], off
	v_add_u32_e32 v94, s30, v139
	v_add_u32_e32 v95, v94, v143
	ds_read_b128 a[0:3], v95
	v_add_u32_e32 v94, v94, v144
	ds_read_b128 a[4:7], v94
	ds_read_b128 a[8:11], v86 offset:49152
	ds_read_b128 a[12:15], v86 offset:53248
	s_waitcnt lgkmcnt(5)
	v_mfma_f32_32x32x16_bf16 v[48:63], a[16:19], a[24:27], v[48:63]
	v_mfma_f32_32x32x16_bf16 v[32:47], a[20:23], a[24:27], v[32:47]
	s_and_b32 m0, s32, 7
	s_lshl_b32 m0, m0, 12
	s_add_i32 m0, m0, 0xc00
	s_nop 0
	global_load_lds_dwordx4 v[164:165], off
	s_waitcnt lgkmcnt(4)
	v_mfma_f32_32x32x16_bf16 v[16:31], a[16:19], a[28:31], v[16:31]
	v_mfma_f32_32x32x16_bf16 v[0:15], a[20:23], a[28:31], v[0:15]
	s_and_b32 m0, s32, 7
	s_lshl_b32 m0, m0, 11
	s_add_i32 m0, m0, 0x8000
	s_nop 0
	global_load_lds_dwordx4 v[166:167], off
	v_add_u32_e32 v96, s30, v142
	v_add_u32_e32 v97, v96, v143
	ds_read_b128 a[16:19], v97
	v_add_u32_e32 v96, v96, v144
	ds_read_b128 a[20:23], v96
	ds_read_b128 a[24:27], v88 offset:49152
	ds_read_b128 a[28:31], v88 offset:53248
	s_waitcnt lgkmcnt(5)
	v_mfma_f32_32x32x16_bf16 v[48:63], a[0:3], a[8:11], v[48:63]
	v_mfma_f32_32x32x16_bf16 v[32:47], a[4:7], a[8:11], v[32:47]
	s_and_b32 m0, s32, 7
	s_lshl_b32 m0, m0, 11
	s_add_i32 m0, m0, 0x8400
	s_nop 0
	global_load_lds_dwordx4 v[168:169], off
	s_waitcnt lgkmcnt(4)
	v_mfma_f32_32x32x16_bf16 v[16:31], a[0:3], a[12:15], v[16:31]
	v_mfma_f32_32x32x16_bf16 v[0:15], a[4:7], a[12:15], v[0:15]
	s_waitcnt lgkmcnt(1)
	v_mfma_f32_32x32x16_bf16 v[48:63], a[16:19], a[24:27], v[48:63]
	v_mfma_f32_32x32x16_bf16 v[32:47], a[20:23], a[24:27], v[32:47]
	s_waitcnt vmcnt(6)
	s_waitcnt lgkmcnt(0)
	s_barrier
	v_add_u32_e32 v100, v145, v132
	ds_read_b128 a[8:11], v100
	v_add_u32_e32 v101, s3, v132
	v_add_u32_e32 v99, v101, v144
	ds_read_b128 a[4:7], v99
	v_add_u32_e32 v98, v101, v143
	v_or_b32_e32 v132, 0x1000, v134
	v_add_u32_e32 v101, v101, v132
	ds_read_b128 a[12:15], v101
	ds_read_b128 a[0:3], v98
	v_mfma_f32_32x32x16_bf16 v[16:31], a[16:19], a[28:31], v[16:31]
	v_lshl_add_u64 v[170:171], v[66:67], 0, s[46:47]
	v_lshl_add_u64 v[172:173], v[68:69], 0, s[46:47]
	v_lshl_add_u64 v[174:175], v[70:71], 0, s[46:47]
	v_mfma_f32_32x32x16_bf16 v[0:15], a[20:23], a[28:31], v[0:15]
	s_and_b32 m0, s32, 7
	s_lshl_b32 m0, m0, 12
	s_add_i32 m0, m0, 0xc000
	s_nop 0
	global_load_lds_dwordx4 v[170:171], off
	v_lshl_add_u64 v[176:177], v[72:73], 0, s[46:47]
	v_lshl_add_u64 v[178:179], v[74:75], 0, s[46:47]
	v_lshl_add_u64 v[180:181], v[76:77], 0, s[46:47]
	s_mov_b64 s[46:47], 0x280
	v_add_u32_e32 v105, s3, v138
	v_add_u32_e32 v102, v105, v143
	ds_read_b128 a[16:19], v102
	v_add_u32_e32 v103, v105, v144
	ds_read_b128 a[20:23], v103
	v_add_u32_e32 v104, v145, v138
	ds_read_b128 a[24:27], v104
	v_add_u32_e32 v105, v105, v132
	ds_read_b128 a[28:31], v105
	s_waitcnt lgkmcnt(4)
	v_mfma_f32_32x32x16_bf16 v[48:63], a[0:3], a[8:11], v[48:63]
	v_mfma_f32_32x32x16_bf16 v[32:47], a[4:7], a[8:11], v[32:47]
	s_and_b32 m0, s32, 7
	s_lshl_b32 m0, m0, 12
	s_add_i32 m0, m0, 0xc400
	s_nop 0
	global_load_lds_dwordx4 v[172:173], off
	v_mfma_f32_32x32x16_bf16 v[16:31], a[0:3], a[12:15], v[16:31]
	v_mfma_f32_32x32x16_bf16 v[0:15], a[4:7], a[12:15], v[0:15]
	s_and_b32 m0, s32, 7
	s_lshl_b32 m0, m0, 12
	s_add_i32 m0, m0, 0xc800
	s_nop 0
	global_load_lds_dwordx4 v[174:175], off
	v_add_u32_e32 v109, s3, v139
	v_add_u32_e32 v106, v109, v143
	ds_read_b128 a[0:3], v106
	v_add_u32_e32 v107, v109, v144
	ds_read_b128 a[4:7], v107
	v_add_u32_e32 v108, v145, v139
	ds_read_b128 a[8:11], v108
	v_add_u32_e32 v109, v109, v132
	ds_read_b128 a[12:15], v109
	s_waitcnt lgkmcnt(5)
	v_mfma_f32_32x32x16_bf16 v[48:63], a[16:19], a[24:27], v[48:63]
	v_mfma_f32_32x32x16_bf16 v[32:47], a[20:23], a[24:27], v[32:47]
	s_and_b32 m0, s32, 7
	s_lshl_b32 m0, m0, 12
	s_add_i32 m0, m0, 0xcc00
	s_nop 0
	global_load_lds_dwordx4 v[176:177], off
	s_waitcnt lgkmcnt(4)
	v_mfma_f32_32x32x16_bf16 v[16:31], a[16:19], a[28:31], v[16:31]
	v_mfma_f32_32x32x16_bf16 v[0:15], a[20:23], a[28:31], v[0:15]
	s_and_b32 m0, s32, 7
	s_lshl_b32 m0, m0, 11
	s_add_i32 m0, m0, 0x14000
	s_nop 0
	global_load_lds_dwordx4 v[178:179], off
	v_add_u32_e32 v113, s3, v142
	v_add_u32_e32 v110, v113, v143
	ds_read_b128 a[16:19], v110
	v_add_u32_e32 v111, v113, v144
	ds_read_b128 a[20:23], v111
	v_add_u32_e32 v112, v145, v142
	ds_read_b128 a[24:27], v112
	v_add_u32_e32 v113, v113, v132
	ds_read_b128 a[28:31], v113
	s_waitcnt lgkmcnt(5)
	v_mfma_f32_32x32x16_bf16 v[48:63], a[0:3], a[8:11], v[48:63]
	v_mfma_f32_32x32x16_bf16 v[32:47], a[4:7], a[8:11], v[32:47]
	s_and_b32 m0, s32, 7
	s_lshl_b32 m0, m0, 11
	s_add_i32 m0, m0, 0x14400
	s_nop 0
	global_load_lds_dwordx4 v[180:181], off
	s_waitcnt lgkmcnt(4)
	v_mfma_f32_32x32x16_bf16 v[16:31], a[0:3], a[12:15], v[16:31]
	v_mfma_f32_32x32x16_bf16 v[0:15], a[4:7], a[12:15], v[0:15]
	s_waitcnt lgkmcnt(1)
	v_mfma_f32_32x32x16_bf16 v[48:63], a[16:19], a[24:27], v[48:63]
	v_mfma_f32_32x32x16_bf16 v[32:47], a[20:23], a[24:27], v[32:47]
	s_waitcnt vmcnt(6)
	s_waitcnt lgkmcnt(0)
	s_barrier
	ds_read_b128 a[12:15], v82 offset:4096
	ds_read_b128 a[8:11], v82
	ds_read_b128 a[4:7], v83 offset:36864
	ds_read_b128 a[0:3], v83 offset:32768
	v_mfma_f32_32x32x16_bf16 v[16:31], a[16:19], a[28:31], v[16:31]
	v_lshl_add_u64 v[158:159], v[66:67], 0, s[46:47]
	v_lshl_add_u64 v[160:161], v[68:69], 0, s[46:47]
	v_lshl_add_u64 v[162:163], v[70:71], 0, s[46:47]
	v_mfma_f32_32x32x16_bf16 v[0:15], a[20:23], a[28:31], v[0:15]
	s_and_b32 m0, s32, 7
	s_lshl_b32 m0, m0, 12
	s_add_i32 m0, m0, 0x18000
	s_nop 0
	global_load_lds_dwordx4 v[158:159], off
	v_lshl_add_u64 v[164:165], v[72:73], 0, s[46:47]
	v_lshl_add_u64 v[166:167], v[74:75], 0, s[46:47]
	v_lshl_add_u64 v[168:169], v[76:77], 0, s[46:47]
	s_mov_b64 s[46:47], 0x300
	ds_read_b128 a[16:19], v85 offset:32768
	ds_read_b128 a[20:23], v85 offset:36864
	ds_read_b128 a[24:27], v84
	ds_read_b128 a[28:31], v84 offset:4096
	s_waitcnt lgkmcnt(4)
	v_mfma_f32_32x32x16_bf16 v[48:63], a[0:3], a[8:11], v[48:63]
	v_mfma_f32_32x32x16_bf16 v[32:47], a[4:7], a[8:11], v[32:47]
	s_and_b32 m0, s32, 7
	s_lshl_b32 m0, m0, 12
	s_add_i32 m0, m0, 0x18400
	s_nop 0
	global_load_lds_dwordx4 v[160:161], off
	v_mfma_f32_32x32x16_bf16 v[16:31], a[0:3], a[12:15], v[16:31]
	v_mfma_f32_32x32x16_bf16 v[0:15], a[4:7], a[12:15], v[0:15]
	s_and_b32 m0, s32, 7
	s_lshl_b32 m0, m0, 12
	s_add_i32 m0, m0, 0x18800
	s_nop 0
	global_load_lds_dwordx4 v[162:163], off
	ds_read_b128 a[0:3], v87 offset:32768
	ds_read_b128 a[4:7], v87 offset:36864
	ds_read_b128 a[8:11], v86
	ds_read_b128 a[12:15], v86 offset:4096
	s_waitcnt lgkmcnt(5)
	v_mfma_f32_32x32x16_bf16 v[48:63], a[16:19], a[24:27], v[48:63]
	v_mfma_f32_32x32x16_bf16 v[32:47], a[20:23], a[24:27], v[32:47]
	s_and_b32 m0, s32, 7
	s_lshl_b32 m0, m0, 12
	s_add_i32 m0, m0, 0x18c00
	s_nop 0
	global_load_lds_dwordx4 v[164:165], off
	s_waitcnt lgkmcnt(4)
	v_mfma_f32_32x32x16_bf16 v[16:31], a[16:19], a[28:31], v[16:31]
	v_mfma_f32_32x32x16_bf16 v[0:15], a[20:23], a[28:31], v[0:15]
	s_and_b32 m0, s32, 7
	s_lshl_b32 m0, m0, 11
	s_add_i32 m0, m0, 0x20000
	s_nop 0
	global_load_lds_dwordx4 v[166:167], off
	ds_read_b128 a[16:19], v89 offset:32768
	ds_read_b128 a[20:23], v89 offset:36864
	ds_read_b128 a[24:27], v88
	ds_read_b128 a[28:31], v88 offset:4096
	s_waitcnt lgkmcnt(5)
	v_mfma_f32_32x32x16_bf16 v[48:63], a[0:3], a[8:11], v[48:63]
	v_mfma_f32_32x32x16_bf16 v[32:47], a[4:7], a[8:11], v[32:47]
	s_and_b32 m0, s32, 7
	s_lshl_b32 m0, m0, 11
	s_add_i32 m0, m0, 0x20400
	s_nop 0
	global_load_lds_dwordx4 v[168:169], off
	s_waitcnt lgkmcnt(4)
	v_mfma_f32_32x32x16_bf16 v[16:31], a[0:3], a[12:15], v[16:31]
	v_mfma_f32_32x32x16_bf16 v[0:15], a[4:7], a[12:15], v[0:15]
	s_waitcnt lgkmcnt(1)
	v_mfma_f32_32x32x16_bf16 v[48:63], a[16:19], a[24:27], v[48:63]
	v_mfma_f32_32x32x16_bf16 v[32:47], a[20:23], a[24:27], v[32:47]
	s_waitcnt vmcnt(6)
	s_waitcnt lgkmcnt(0)
	s_barrier
	ds_read_b128 a[12:15], v82 offset:53248
	ds_read_b128 a[8:11], v82 offset:49152
	ds_read_b128 a[4:7], v90
	ds_read_b128 a[0:3], v92
	v_mfma_f32_32x32x16_bf16 v[16:31], a[16:19], a[28:31], v[16:31]
	v_lshl_add_u64 v[170:171], v[66:67], 0, s[46:47]
	v_lshl_add_u64 v[172:173], v[68:69], 0, s[46:47]
	v_lshl_add_u64 v[174:175], v[70:71], 0, s[46:47]
	v_mfma_f32_32x32x16_bf16 v[0:15], a[20:23], a[28:31], v[0:15]
	s_and_b32 m0, s32, 7
	s_lshl_b32 m0, m0, 12
	s_add_i32 m0, m0, 0x0
	s_nop 0
	global_load_lds_dwordx4 v[170:171], off
	v_lshl_add_u64 v[176:177], v[72:73], 0, s[46:47]
	s_mov_b64 s[38:39], 0x380
	v_lshl_add_u64 v[178:179], v[74:75], 0, s[46:47]
	s_nop 0
	v_readfirstlane_b32 s48, v117
	s_nop 0
	v_lshl_add_u64 v[180:181], v[76:77], 0, s[46:47]
	s_nop 0
	s_mov_b64 s[46:47], 0x580
	ds_read_b128 a[16:19], v93
	ds_read_b128 a[20:23], v91
	ds_read_b128 a[24:27], v84 offset:49152
	ds_read_b128 a[28:31], v84 offset:53248
	s_waitcnt lgkmcnt(4)
	v_mfma_f32_32x32x16_bf16 v[48:63], a[0:3], a[8:11], v[48:63]
	s_nop 0
	v_readfirstlane_b32 s49, v118
	v_readfirstlane_b32 s53, v119
	v_mfma_f32_32x32x16_bf16 v[32:47], a[4:7], a[8:11], v[32:47]
	s_and_b32 m0, s32, 7
	s_lshl_b32 m0, m0, 12
	s_add_i32 m0, m0, 0x400
	s_nop 0
	global_load_lds_dwordx4 v[172:173], off
	v_mfma_f32_32x32x16_bf16 v[16:31], a[0:3], a[12:15], v[16:31]
	v_mfma_f32_32x32x16_bf16 v[0:15], a[4:7], a[12:15], v[0:15]
	s_and_b32 m0, s32, 7
	s_lshl_b32 m0, m0, 12
	s_add_i32 m0, m0, 0x800
	s_nop 0
	global_load_lds_dwordx4 v[174:175], off
	ds_read_b128 a[0:3], v95
	ds_read_b128 a[4:7], v94
	ds_read_b128 a[8:11], v86 offset:49152
	ds_read_b128 a[12:15], v86 offset:53248
	s_waitcnt lgkmcnt(5)
	v_mfma_f32_32x32x16_bf16 v[48:63], a[16:19], a[24:27], v[48:63]
	v_mfma_f32_32x32x16_bf16 v[32:47], a[20:23], a[24:27], v[32:47]
	s_and_b32 m0, s32, 7
	s_lshl_b32 m0, m0, 12
	s_add_i32 m0, m0, 0xc00
	s_nop 0
	global_load_lds_dwordx4 v[176:177], off
	s_waitcnt lgkmcnt(4)
	v_mfma_f32_32x32x16_bf16 v[16:31], a[16:19], a[28:31], v[16:31]
	v_mfma_f32_32x32x16_bf16 v[0:15], a[20:23], a[28:31], v[0:15]
	s_and_b32 m0, s32, 7
	s_lshl_b32 m0, m0, 11
	s_add_i32 m0, m0, 0x8000
	s_nop 0
	global_load_lds_dwordx4 v[178:179], off
	ds_read_b128 a[16:19], v97
	ds_read_b128 a[20:23], v96
	ds_read_b128 a[24:27], v88 offset:49152
	ds_read_b128 a[28:31], v88 offset:53248
	s_waitcnt lgkmcnt(5)
	v_mfma_f32_32x32x16_bf16 v[48:63], a[0:3], a[8:11], v[48:63]
	v_mfma_f32_32x32x16_bf16 v[32:47], a[4:7], a[8:11], v[32:47]
	s_and_b32 m0, s32, 7
	s_lshl_b32 m0, m0, 11
	s_add_i32 m0, m0, 0x8400
	s_nop 0
	global_load_lds_dwordx4 v[180:181], off
	s_waitcnt lgkmcnt(4)
	v_mfma_f32_32x32x16_bf16 v[16:31], a[0:3], a[12:15], v[16:31]
	v_mfma_f32_32x32x16_bf16 v[0:15], a[4:7], a[12:15], v[0:15]
	s_waitcnt lgkmcnt(1)
	v_mfma_f32_32x32x16_bf16 v[48:63], a[16:19], a[24:27], v[48:63]
	v_mfma_f32_32x32x16_bf16 v[32:47], a[20:23], a[24:27], v[32:47]
	s_waitcnt vmcnt(6)
	s_waitcnt lgkmcnt(0)
	s_barrier
	ds_read_b128 a[12:15], v101
	ds_read_b128 a[8:11], v100
	ds_read_b128 a[4:7], v99
	ds_read_b128 a[0:3], v98
	v_mfma_f32_32x32x16_bf16 v[16:31], a[16:19], a[28:31], v[16:31]
	v_lshl_add_u64 v[158:159], v[66:67], 0, s[38:39]
	v_lshl_add_u64 v[160:161], v[68:69], 0, s[38:39]
	s_mov_b64 s[28:29], 0x400
	v_lshl_add_u64 v[162:163], v[70:71], 0, s[38:39]
	v_mfma_f32_32x32x16_bf16 v[0:15], a[20:23], a[28:31], v[0:15]
	s_and_b32 m0, s32, 7
	s_lshl_b32 m0, m0, 12
	s_add_i32 m0, m0, 0xc000
	s_nop 0
	global_load_lds_dwordx4 v[158:159], off
	v_lshl_add_u64 v[164:165], v[72:73], 0, s[38:39]
	s_nop 0
	v_readfirstlane_b32 s33, v122
	s_nop 0
	v_lshl_add_u64 v[166:167], v[74:75], 0, s[38:39]
	s_nop 0
	v_readfirstlane_b32 s34, v123
	s_nop 0
	v_lshl_add_u64 v[168:169], v[76:77], 0, s[38:39]
	s_nop 0
	s_mov_b64 s[36:37], 0x500
	ds_read_b128 a[16:19], v102
	ds_read_b128 a[20:23], v103
	ds_read_b128 a[24:27], v104
	ds_read_b128 a[28:31], v105
	s_waitcnt lgkmcnt(4)
	v_mfma_f32_32x32x16_bf16 v[48:63], a[0:3], a[8:11], v[48:63]
	s_nop 0
	v_readfirstlane_b32 s0, v126
	v_readfirstlane_b32 s35, v124
	v_readfirstlane_b32 s38, v115
	v_readfirstlane_b32 s39, v116
	v_mfma_f32_32x32x16_bf16 v[32:47], a[4:7], a[8:11], v[32:47]
	s_and_b32 m0, s32, 7
	s_lshl_b32 m0, m0, 12
	s_add_i32 m0, m0, 0xc400
	s_nop 0
	global_load_lds_dwordx4 v[160:161], off
	v_mfma_f32_32x32x16_bf16 v[16:31], a[0:3], a[12:15], v[16:31]
	v_mfma_f32_32x32x16_bf16 v[0:15], a[4:7], a[12:15], v[0:15]
	s_and_b32 m0, s32, 7
	s_lshl_b32 m0, m0, 12
	s_add_i32 m0, m0, 0xc800
	s_nop 0
	global_load_lds_dwordx4 v[162:163], off
	ds_read_b128 a[0:3], v106
	ds_read_b128 a[4:7], v107
	ds_read_b128 a[8:11], v108
	ds_read_b128 a[12:15], v109
	s_waitcnt lgkmcnt(5)
	v_mfma_f32_32x32x16_bf16 v[48:63], a[16:19], a[24:27], v[48:63]
	v_mfma_f32_32x32x16_bf16 v[32:47], a[20:23], a[24:27], v[32:47]
	s_and_b32 m0, s32, 7
	s_lshl_b32 m0, m0, 12
	s_add_i32 m0, m0, 0xcc00
	s_nop 0
	global_load_lds_dwordx4 v[164:165], off
	s_waitcnt lgkmcnt(4)
	v_mfma_f32_32x32x16_bf16 v[16:31], a[16:19], a[28:31], v[16:31]
	v_mfma_f32_32x32x16_bf16 v[0:15], a[20:23], a[28:31], v[0:15]
	s_and_b32 m0, s32, 7
	s_lshl_b32 m0, m0, 11
	s_add_i32 m0, m0, 0x14000
	s_nop 0
	global_load_lds_dwordx4 v[166:167], off
	ds_read_b128 a[16:19], v110
	ds_read_b128 a[20:23], v111
	ds_read_b128 a[24:27], v112
	ds_read_b128 a[28:31], v113
	s_waitcnt lgkmcnt(5)
	v_mfma_f32_32x32x16_bf16 v[48:63], a[0:3], a[8:11], v[48:63]
	v_mfma_f32_32x32x16_bf16 v[32:47], a[4:7], a[8:11], v[32:47]
	s_and_b32 m0, s32, 7
	s_lshl_b32 m0, m0, 11
	s_add_i32 m0, m0, 0x14400
	s_nop 0
	global_load_lds_dwordx4 v[168:169], off
	s_waitcnt lgkmcnt(4)
	v_mfma_f32_32x32x16_bf16 v[16:31], a[0:3], a[12:15], v[16:31]
	v_mfma_f32_32x32x16_bf16 v[0:15], a[4:7], a[12:15], v[0:15]
	s_waitcnt lgkmcnt(1)
	v_mfma_f32_32x32x16_bf16 v[48:63], a[16:19], a[24:27], v[48:63]
	v_mfma_f32_32x32x16_bf16 v[32:47], a[20:23], a[24:27], v[32:47]
	s_waitcnt vmcnt(6)
	s_waitcnt lgkmcnt(0)
	s_barrier
	ds_read_b128 a[12:15], v82 offset:4096
	ds_read_b128 a[8:11], v82
	ds_read_b128 a[4:7], v83 offset:36864
	ds_read_b128 a[0:3], v83 offset:32768
	v_mfma_f32_32x32x16_bf16 v[16:31], a[16:19], a[28:31], v[16:31]
	v_lshl_add_u64 v[170:171], v[66:67], 0, s[28:29]
	v_lshl_add_u64 v[172:173], v[68:69], 0, s[28:29]
	s_nop 0
	v_readfirstlane_b32 s1, v127
	s_nop 0
	v_lshl_add_u64 v[174:175], v[70:71], 0, s[28:29]
	s_nop 0
	v_mfma_f32_32x32x16_bf16 v[0:15], a[20:23], a[28:31], v[0:15]
	s_and_b32 m0, s32, 7
	s_lshl_b32 m0, m0, 12
	s_add_i32 m0, m0, 0x18000
	s_nop 0
	global_load_lds_dwordx4 v[170:171], off
	v_lshl_add_u64 v[176:177], v[72:73], 0, s[28:29]
	s_nop 0
	v_readfirstlane_b32 s20, v128
	s_nop 0
	v_lshl_add_u64 v[178:179], v[74:75], 0, s[28:29]
	s_nop 0
	v_readfirstlane_b32 s21, v129
	s_nop 0
	v_lshl_add_u64 v[180:181], v[76:77], 0, s[28:29]
	s_nop 0
	s_mov_b64 s[28:29], 0x480
	ds_read_b128 a[16:19], v85 offset:32768
	ds_read_b128 a[20:23], v85 offset:36864
	ds_read_b128 a[24:27], v84
	ds_read_b128 a[28:31], v84 offset:4096
	s_waitcnt lgkmcnt(4)
	v_mfma_f32_32x32x16_bf16 v[48:63], a[0:3], a[8:11], v[48:63]
	s_nop 0
	v_lshl_add_u64 v[162:163], v[70:71], 0, s[28:29]
	v_readfirstlane_b32 s23, v131
	v_readfirstlane_b32 s24, v130
	v_mfma_f32_32x32x16_bf16 v[32:47], a[4:7], a[8:11], v[32:47]
	s_and_b32 m0, s32, 7
	s_lshl_b32 m0, m0, 12
	s_add_i32 m0, m0, 0x18400
	s_nop 0
	global_load_lds_dwordx4 v[172:173], off
	v_mfma_f32_32x32x16_bf16 v[16:31], a[0:3], a[12:15], v[16:31]
	v_mfma_f32_32x32x16_bf16 v[0:15], a[4:7], a[12:15], v[0:15]
	s_and_b32 m0, s32, 7
	s_lshl_b32 m0, m0, 12
	s_add_i32 m0, m0, 0x18800
	s_nop 0
	global_load_lds_dwordx4 v[174:175], off
	ds_read_b128 a[0:3], v87 offset:32768
	ds_read_b128 a[4:7], v87 offset:36864
	ds_read_b128 a[8:11], v86
	ds_read_b128 a[12:15], v86 offset:4096
	s_waitcnt lgkmcnt(5)
	v_mfma_f32_32x32x16_bf16 v[48:63], a[16:19], a[24:27], v[48:63]
	v_mfma_f32_32x32x16_bf16 v[32:47], a[20:23], a[24:27], v[32:47]
	s_and_b32 m0, s32, 7
	s_lshl_b32 m0, m0, 12
	s_add_i32 m0, m0, 0x18c00
	s_nop 0
	global_load_lds_dwordx4 v[176:177], off
	s_waitcnt lgkmcnt(4)
	v_mfma_f32_32x32x16_bf16 v[16:31], a[16:19], a[28:31], v[16:31]
	v_mfma_f32_32x32x16_bf16 v[0:15], a[20:23], a[28:31], v[0:15]
	s_and_b32 m0, s32, 7
	s_lshl_b32 m0, m0, 11
	s_add_i32 m0, m0, 0x20000
	s_nop 0
	global_load_lds_dwordx4 v[178:179], off
	ds_read_b128 a[16:19], v89 offset:32768
	ds_read_b128 a[20:23], v89 offset:36864
	ds_read_b128 a[24:27], v88
	ds_read_b128 a[28:31], v88 offset:4096
	s_waitcnt lgkmcnt(5)
	v_mfma_f32_32x32x16_bf16 v[48:63], a[0:3], a[8:11], v[48:63]
	v_mfma_f32_32x32x16_bf16 v[32:47], a[4:7], a[8:11], v[32:47]
	s_and_b32 m0, s32, 7
	s_lshl_b32 m0, m0, 11
	s_add_i32 m0, m0, 0x20400
	s_nop 0
	global_load_lds_dwordx4 v[180:181], off
	s_waitcnt lgkmcnt(4)
	v_mfma_f32_32x32x16_bf16 v[16:31], a[0:3], a[12:15], v[16:31]
	v_mfma_f32_32x32x16_bf16 v[0:15], a[4:7], a[12:15], v[0:15]
	s_waitcnt lgkmcnt(1)
	v_mfma_f32_32x32x16_bf16 v[48:63], a[16:19], a[24:27], v[48:63]
	v_mfma_f32_32x32x16_bf16 v[32:47], a[20:23], a[24:27], v[32:47]
	s_waitcnt vmcnt(6)
	s_waitcnt lgkmcnt(0)
	s_barrier
	ds_read_b128 a[12:15], v82 offset:53248
	ds_read_b128 a[8:11], v82 offset:49152
	ds_read_b128 a[4:7], v90
	ds_read_b128 a[0:3], v92
	v_mfma_f32_32x32x16_bf16 v[16:31], a[16:19], a[28:31], v[16:31]
	v_lshl_add_u64 v[158:159], v[66:67], 0, s[28:29]
	v_lshl_add_u64 v[160:161], v[68:69], 0, s[28:29]
	v_mfma_f32_32x32x16_bf16 v[0:15], a[20:23], a[28:31], v[0:15]
	s_and_b32 m0, s32, 7
	s_lshl_b32 m0, m0, 12
	s_add_i32 m0, m0, 0x0
	s_nop 0
	global_load_lds_dwordx4 v[158:159], off
	v_lshl_add_u64 v[164:165], v[72:73], 0, s[28:29]
	v_lshl_add_u64 v[166:167], v[74:75], 0, s[28:29]
	v_lshl_add_u64 v[168:169], v[76:77], 0, s[28:29]
	s_nop 0
	v_readfirstlane_b32 s28, v120
	s_nop 0
	s_nop 0
	s_nop 0
	s_nop 0
	ds_read_b128 a[16:19], v93
	ds_read_b128 a[20:23], v91
	ds_read_b128 a[24:27], v84 offset:49152
	ds_read_b128 a[28:31], v84 offset:53248
	s_waitcnt lgkmcnt(4)
	v_mfma_f32_32x32x16_bf16 v[48:63], a[0:3], a[8:11], v[48:63]
	s_nop 0
	v_readfirstlane_b32 s29, v121
	v_lshl_add_u64 v[174:175], v[70:71], 0, s[36:37]
	v_mfma_f32_32x32x16_bf16 v[32:47], a[4:7], a[8:11], v[32:47]
	s_and_b32 m0, s32, 7
	s_lshl_b32 m0, m0, 12
	s_add_i32 m0, m0, 0x400
	s_nop 0
	global_load_lds_dwordx4 v[160:161], off
	v_mfma_f32_32x32x16_bf16 v[16:31], a[0:3], a[12:15], v[16:31]
	v_mfma_f32_32x32x16_bf16 v[0:15], a[4:7], a[12:15], v[0:15]
	s_and_b32 m0, s32, 7
	s_lshl_b32 m0, m0, 12
	s_add_i32 m0, m0, 0x800
	s_nop 0
	global_load_lds_dwordx4 v[162:163], off
	ds_read_b128 a[0:3], v95
	ds_read_b128 a[4:7], v94
	ds_read_b128 a[8:11], v86 offset:49152
	ds_read_b128 a[12:15], v86 offset:53248
	s_waitcnt lgkmcnt(5)
	v_mfma_f32_32x32x16_bf16 v[48:63], a[16:19], a[24:27], v[48:63]
	v_mfma_f32_32x32x16_bf16 v[32:47], a[20:23], a[24:27], v[32:47]
	s_and_b32 m0, s32, 7
	s_lshl_b32 m0, m0, 12
	s_add_i32 m0, m0, 0xc00
	s_nop 0
	global_load_lds_dwordx4 v[164:165], off
	s_waitcnt lgkmcnt(4)
	v_mfma_f32_32x32x16_bf16 v[16:31], a[16:19], a[28:31], v[16:31]
	v_mfma_f32_32x32x16_bf16 v[0:15], a[20:23], a[28:31], v[0:15]
	s_and_b32 m0, s32, 7
	s_lshl_b32 m0, m0, 11
	s_add_i32 m0, m0, 0x8000
	s_nop 0
	global_load_lds_dwordx4 v[166:167], off
	ds_read_b128 a[16:19], v97
	ds_read_b128 a[20:23], v96
	ds_read_b128 a[24:27], v88 offset:49152
	ds_read_b128 a[28:31], v88 offset:53248
	s_waitcnt lgkmcnt(5)
	v_mfma_f32_32x32x16_bf16 v[48:63], a[0:3], a[8:11], v[48:63]
	v_mfma_f32_32x32x16_bf16 v[32:47], a[4:7], a[8:11], v[32:47]
	s_and_b32 m0, s32, 7
	s_lshl_b32 m0, m0, 11
	s_add_i32 m0, m0, 0x8400
	s_nop 0
	global_load_lds_dwordx4 v[168:169], off
	s_waitcnt lgkmcnt(4)
	v_mfma_f32_32x32x16_bf16 v[16:31], a[0:3], a[12:15], v[16:31]
	v_mfma_f32_32x32x16_bf16 v[0:15], a[4:7], a[12:15], v[0:15]
	s_waitcnt lgkmcnt(1)
	v_mfma_f32_32x32x16_bf16 v[48:63], a[16:19], a[24:27], v[48:63]
	v_mfma_f32_32x32x16_bf16 v[32:47], a[20:23], a[24:27], v[32:47]
	s_waitcnt vmcnt(6)
	s_waitcnt lgkmcnt(0)
	s_barrier
	ds_read_b128 a[12:15], v101
	ds_read_b128 a[8:11], v100
	ds_read_b128 a[4:7], v99
	ds_read_b128 a[0:3], v98
	v_mfma_f32_32x32x16_bf16 v[16:31], a[16:19], a[28:31], v[16:31]
	v_lshl_add_u64 v[170:171], v[66:67], 0, s[36:37]
	v_lshl_add_u64 v[172:173], v[68:69], 0, s[36:37]
	v_mfma_f32_32x32x16_bf16 v[0:15], a[20:23], a[28:31], v[0:15]
	s_and_b32 m0, s32, 7
	s_lshl_b32 m0, m0, 12
	s_add_i32 m0, m0, 0xc000
	s_nop 0
	global_load_lds_dwordx4 v[170:171], off
	v_lshl_add_u64 v[176:177], v[72:73], 0, s[36:37]
	v_lshl_add_u64 v[178:179], v[74:75], 0, s[36:37]
	s_nop 0
	v_lshl_add_u64 v[180:181], v[76:77], 0, s[36:37]
	v_readfirstlane_b32 s36, v125
	s_nop 0
	v_readfirstlane_b32 s37, v114
	s_nop 0
	s_nop 0
	s_nop 0
	s_nop 0
	ds_read_b128 a[16:19], v102
	ds_read_b128 a[20:23], v103
	ds_read_b128 a[24:27], v104
	ds_read_b128 a[28:31], v105
	s_waitcnt lgkmcnt(4)
	v_mfma_f32_32x32x16_bf16 v[48:63], a[0:3], a[8:11], v[48:63]
	v_lshl_add_u64 v[162:163], v[70:71], 0, s[46:47]
	v_mfma_f32_32x32x16_bf16 v[32:47], a[4:7], a[8:11], v[32:47]
	s_and_b32 m0, s32, 7
	s_lshl_b32 m0, m0, 12
	s_add_i32 m0, m0, 0xc400
	s_nop 0
	global_load_lds_dwordx4 v[172:173], off
	v_mfma_f32_32x32x16_bf16 v[16:31], a[0:3], a[12:15], v[16:31]
	v_mfma_f32_32x32x16_bf16 v[0:15], a[4:7], a[12:15], v[0:15]
	s_and_b32 m0, s32, 7
	s_lshl_b32 m0, m0, 12
	s_add_i32 m0, m0, 0xc800
	s_nop 0
	global_load_lds_dwordx4 v[174:175], off
	ds_read_b128 a[0:3], v106
	ds_read_b128 a[4:7], v107
	ds_read_b128 a[8:11], v108
	ds_read_b128 a[12:15], v109
	s_waitcnt lgkmcnt(5)
	v_mfma_f32_32x32x16_bf16 v[48:63], a[16:19], a[24:27], v[48:63]
	v_mfma_f32_32x32x16_bf16 v[32:47], a[20:23], a[24:27], v[32:47]
	s_and_b32 m0, s32, 7
	s_lshl_b32 m0, m0, 12
	s_add_i32 m0, m0, 0xcc00
	s_nop 0
	global_load_lds_dwordx4 v[176:177], off
	s_waitcnt lgkmcnt(4)
	v_mfma_f32_32x32x16_bf16 v[16:31], a[16:19], a[28:31], v[16:31]
	v_mfma_f32_32x32x16_bf16 v[0:15], a[20:23], a[28:31], v[0:15]
	s_and_b32 m0, s32, 7
	s_lshl_b32 m0, m0, 11
	s_add_i32 m0, m0, 0x14000
	s_nop 0
	global_load_lds_dwordx4 v[178:179], off
	ds_read_b128 a[16:19], v110
	ds_read_b128 a[20:23], v111
	ds_read_b128 a[24:27], v112
	ds_read_b128 a[28:31], v113
	s_waitcnt lgkmcnt(5)
	v_mfma_f32_32x32x16_bf16 v[48:63], a[0:3], a[8:11], v[48:63]
	v_mfma_f32_32x32x16_bf16 v[32:47], a[4:7], a[8:11], v[32:47]
	s_and_b32 m0, s32, 7
	s_lshl_b32 m0, m0, 11
	s_add_i32 m0, m0, 0x14400
	s_nop 0
	global_load_lds_dwordx4 v[180:181], off
	s_waitcnt lgkmcnt(4)
	v_mfma_f32_32x32x16_bf16 v[16:31], a[0:3], a[12:15], v[16:31]
	v_mfma_f32_32x32x16_bf16 v[0:15], a[4:7], a[12:15], v[0:15]
	s_waitcnt lgkmcnt(1)
	v_mfma_f32_32x32x16_bf16 v[48:63], a[16:19], a[24:27], v[48:63]
	v_mfma_f32_32x32x16_bf16 v[32:47], a[20:23], a[24:27], v[32:47]
	s_waitcnt vmcnt(6)
	s_waitcnt lgkmcnt(0)
	s_barrier
	ds_read_b128 a[12:15], v82 offset:4096
	ds_read_b128 a[8:11], v82
	ds_read_b128 a[4:7], v83 offset:36864
	ds_read_b128 a[0:3], v83 offset:32768
	v_mfma_f32_32x32x16_bf16 v[16:31], a[16:19], a[28:31], v[16:31]
	v_lshl_add_u64 v[158:159], v[66:67], 0, s[46:47]
	v_lshl_add_u64 v[160:161], v[68:69], 0, s[46:47]
	v_mfma_f32_32x32x16_bf16 v[0:15], a[20:23], a[28:31], v[0:15]
	s_and_b32 m0, s32, 7
	s_lshl_b32 m0, m0, 12
	s_add_i32 m0, m0, 0x18000
	s_nop 0
	global_load_lds_dwordx4 v[158:159], off
	v_lshl_add_u64 v[164:165], v[72:73], 0, s[46:47]
	v_lshl_add_u64 v[166:167], v[74:75], 0, s[46:47]
	v_lshl_add_u64 v[168:169], v[76:77], 0, s[46:47]
	s_mov_b64 s[46:47], 0x600
	ds_read_b128 a[16:19], v85 offset:32768
	ds_read_b128 a[20:23], v85 offset:36864
	ds_read_b128 a[24:27], v84
	ds_read_b128 a[28:31], v84 offset:4096
	s_waitcnt lgkmcnt(4)
	v_mfma_f32_32x32x16_bf16 v[48:63], a[0:3], a[8:11], v[48:63]
	v_mfma_f32_32x32x16_bf16 v[32:47], a[4:7], a[8:11], v[32:47]
	s_and_b32 m0, s32, 7
	s_lshl_b32 m0, m0, 12
	s_add_i32 m0, m0, 0x18400
	s_nop 0
	global_load_lds_dwordx4 v[160:161], off
	v_mfma_f32_32x32x16_bf16 v[16:31], a[0:3], a[12:15], v[16:31]
	v_mfma_f32_32x32x16_bf16 v[0:15], a[4:7], a[12:15], v[0:15]
	s_and_b32 m0, s32, 7
	s_lshl_b32 m0, m0, 12
	s_add_i32 m0, m0, 0x18800
	s_nop 0
	global_load_lds_dwordx4 v[162:163], off
	ds_read_b128 a[0:3], v87 offset:32768
	ds_read_b128 a[4:7], v87 offset:36864
	ds_read_b128 a[8:11], v86
	ds_read_b128 a[12:15], v86 offset:4096
	s_waitcnt lgkmcnt(5)
	v_mfma_f32_32x32x16_bf16 v[48:63], a[16:19], a[24:27], v[48:63]
	v_mfma_f32_32x32x16_bf16 v[32:47], a[20:23], a[24:27], v[32:47]
	s_and_b32 m0, s32, 7
	s_lshl_b32 m0, m0, 12
	s_add_i32 m0, m0, 0x18c00
	s_nop 0
	global_load_lds_dwordx4 v[164:165], off
	s_waitcnt lgkmcnt(4)
	v_mfma_f32_32x32x16_bf16 v[16:31], a[16:19], a[28:31], v[16:31]
	v_mfma_f32_32x32x16_bf16 v[0:15], a[20:23], a[28:31], v[0:15]
	s_and_b32 m0, s32, 7
	s_lshl_b32 m0, m0, 11
	s_add_i32 m0, m0, 0x20000
	s_nop 0
	global_load_lds_dwordx4 v[166:167], off
	ds_read_b128 a[16:19], v89 offset:32768
	ds_read_b128 a[20:23], v89 offset:36864
	ds_read_b128 a[24:27], v88
	ds_read_b128 a[28:31], v88 offset:4096
	s_waitcnt lgkmcnt(5)
	v_mfma_f32_32x32x16_bf16 v[48:63], a[0:3], a[8:11], v[48:63]
	v_mfma_f32_32x32x16_bf16 v[32:47], a[4:7], a[8:11], v[32:47]
	s_and_b32 m0, s32, 7
	s_lshl_b32 m0, m0, 11
	s_add_i32 m0, m0, 0x20400
	s_nop 0
	global_load_lds_dwordx4 v[168:169], off
	s_waitcnt lgkmcnt(4)
	v_mfma_f32_32x32x16_bf16 v[16:31], a[0:3], a[12:15], v[16:31]
	v_mfma_f32_32x32x16_bf16 v[0:15], a[4:7], a[12:15], v[0:15]
	s_waitcnt lgkmcnt(1)
	v_mfma_f32_32x32x16_bf16 v[48:63], a[16:19], a[24:27], v[48:63]
	v_mfma_f32_32x32x16_bf16 v[32:47], a[20:23], a[24:27], v[32:47]
	s_waitcnt vmcnt(6)
	s_waitcnt lgkmcnt(0)
	s_barrier
	ds_read_b128 a[12:15], v82 offset:53248
	ds_read_b128 a[8:11], v82 offset:49152
	ds_read_b128 a[4:7], v90
	ds_read_b128 a[0:3], v92
	v_mfma_f32_32x32x16_bf16 v[16:31], a[16:19], a[28:31], v[16:31]
	v_lshl_add_u64 v[170:171], v[66:67], 0, s[46:47]
	v_lshl_add_u64 v[172:173], v[68:69], 0, s[46:47]
	v_lshl_add_u64 v[174:175], v[70:71], 0, s[46:47]
	v_mfma_f32_32x32x16_bf16 v[0:15], a[20:23], a[28:31], v[0:15]
	s_and_b32 m0, s32, 7
	s_lshl_b32 m0, m0, 12
	s_add_i32 m0, m0, 0x0
	s_nop 0
	global_load_lds_dwordx4 v[170:171], off
	v_lshl_add_u64 v[176:177], v[72:73], 0, s[46:47]
	v_lshl_add_u64 v[178:179], v[74:75], 0, s[46:47]
	v_lshl_add_u64 v[180:181], v[76:77], 0, s[46:47]
	s_mov_b64 s[46:47], 0x680
	ds_read_b128 a[16:19], v93
	ds_read_b128 a[20:23], v91
	ds_read_b128 a[24:27], v84 offset:49152
	ds_read_b128 a[28:31], v84 offset:53248
	s_waitcnt lgkmcnt(4)
	v_mfma_f32_32x32x16_bf16 v[48:63], a[0:3], a[8:11], v[48:63]
	v_mfma_f32_32x32x16_bf16 v[32:47], a[4:7], a[8:11], v[32:47]
	s_and_b32 m0, s32, 7
	s_lshl_b32 m0, m0, 12
	s_add_i32 m0, m0, 0x400
	s_nop 0
	global_load_lds_dwordx4 v[172:173], off
	v_mfma_f32_32x32x16_bf16 v[16:31], a[0:3], a[12:15], v[16:31]
	v_mfma_f32_32x32x16_bf16 v[0:15], a[4:7], a[12:15], v[0:15]
	s_and_b32 m0, s32, 7
	s_lshl_b32 m0, m0, 12
	s_add_i32 m0, m0, 0x800
	s_nop 0
	global_load_lds_dwordx4 v[174:175], off
	ds_read_b128 a[0:3], v95
	ds_read_b128 a[4:7], v94
	ds_read_b128 a[8:11], v86 offset:49152
	ds_read_b128 a[12:15], v86 offset:53248
	s_waitcnt lgkmcnt(5)
	v_mfma_f32_32x32x16_bf16 v[48:63], a[16:19], a[24:27], v[48:63]
	v_mfma_f32_32x32x16_bf16 v[32:47], a[20:23], a[24:27], v[32:47]
	s_and_b32 m0, s32, 7
	s_lshl_b32 m0, m0, 12
	s_add_i32 m0, m0, 0xc00
	s_nop 0
	global_load_lds_dwordx4 v[176:177], off
	s_waitcnt lgkmcnt(4)
	v_mfma_f32_32x32x16_bf16 v[16:31], a[16:19], a[28:31], v[16:31]
	v_mfma_f32_32x32x16_bf16 v[0:15], a[20:23], a[28:31], v[0:15]
	s_and_b32 m0, s32, 7
	s_lshl_b32 m0, m0, 11
	s_add_i32 m0, m0, 0x8000
	s_nop 0
	global_load_lds_dwordx4 v[178:179], off
	ds_read_b128 a[16:19], v97
	ds_read_b128 a[20:23], v96
	ds_read_b128 a[24:27], v88 offset:49152
	ds_read_b128 a[28:31], v88 offset:53248
	s_waitcnt lgkmcnt(5)
	v_mfma_f32_32x32x16_bf16 v[48:63], a[0:3], a[8:11], v[48:63]
	v_mfma_f32_32x32x16_bf16 v[32:47], a[4:7], a[8:11], v[32:47]
	s_and_b32 m0, s32, 7
	s_lshl_b32 m0, m0, 11
	s_add_i32 m0, m0, 0x8400
	s_nop 0
	global_load_lds_dwordx4 v[180:181], off
	s_waitcnt lgkmcnt(4)
	v_mfma_f32_32x32x16_bf16 v[16:31], a[0:3], a[12:15], v[16:31]
	v_mfma_f32_32x32x16_bf16 v[0:15], a[4:7], a[12:15], v[0:15]
	s_waitcnt lgkmcnt(1)
	v_mfma_f32_32x32x16_bf16 v[48:63], a[16:19], a[24:27], v[48:63]
	v_mfma_f32_32x32x16_bf16 v[32:47], a[20:23], a[24:27], v[32:47]
	s_waitcnt vmcnt(6)
	s_waitcnt lgkmcnt(0)
	s_barrier
	ds_read_b128 a[12:15], v101
	ds_read_b128 a[8:11], v100
	ds_read_b128 a[4:7], v99
	ds_read_b128 a[0:3], v98
	v_mfma_f32_32x32x16_bf16 v[16:31], a[16:19], a[28:31], v[16:31]
	v_lshl_add_u64 v[158:159], v[66:67], 0, s[46:47]
	v_lshl_add_u64 v[160:161], v[68:69], 0, s[46:47]
	s_mov_b64 s[28:29], 0x700
	v_lshl_add_u64 v[162:163], v[70:71], 0, s[46:47]
	v_mfma_f32_32x32x16_bf16 v[0:15], a[20:23], a[28:31], v[0:15]
	s_and_b32 m0, s32, 7
	s_lshl_b32 m0, m0, 12
	s_add_i32 m0, m0, 0xc000
	s_nop 0
	global_load_lds_dwordx4 v[158:159], off
	v_lshl_add_u64 v[164:165], v[72:73], 0, s[46:47]
	v_lshl_add_u64 v[166:167], v[74:75], 0, s[46:47]
	v_lshl_add_u64 v[168:169], v[76:77], 0, s[46:47]
	ds_read_b128 a[16:19], v102
	ds_read_b128 a[20:23], v103
	ds_read_b128 a[24:27], v104
	ds_read_b128 a[28:31], v105
	s_waitcnt lgkmcnt(4)
	v_mfma_f32_32x32x16_bf16 v[48:63], a[0:3], a[8:11], v[48:63]
	v_mfma_f32_32x32x16_bf16 v[32:47], a[4:7], a[8:11], v[32:47]
	s_and_b32 m0, s32, 7
	s_lshl_b32 m0, m0, 12
	s_add_i32 m0, m0, 0xc400
	s_nop 0
	global_load_lds_dwordx4 v[160:161], off
	v_mfma_f32_32x32x16_bf16 v[16:31], a[0:3], a[12:15], v[16:31]
	v_mfma_f32_32x32x16_bf16 v[0:15], a[4:7], a[12:15], v[0:15]
	s_and_b32 m0, s32, 7
	s_lshl_b32 m0, m0, 12
	s_add_i32 m0, m0, 0xc800
	s_nop 0
	global_load_lds_dwordx4 v[162:163], off
	ds_read_b128 a[0:3], v106
	ds_read_b128 a[4:7], v107
	ds_read_b128 a[8:11], v108
	ds_read_b128 a[12:15], v109
	s_waitcnt lgkmcnt(5)
	v_mfma_f32_32x32x16_bf16 v[48:63], a[16:19], a[24:27], v[48:63]
	v_mfma_f32_32x32x16_bf16 v[32:47], a[20:23], a[24:27], v[32:47]
	s_and_b32 m0, s32, 7
	s_lshl_b32 m0, m0, 12
	s_add_i32 m0, m0, 0xcc00
	s_nop 0
	global_load_lds_dwordx4 v[164:165], off
	s_waitcnt lgkmcnt(4)
	v_mfma_f32_32x32x16_bf16 v[16:31], a[16:19], a[28:31], v[16:31]
	v_mfma_f32_32x32x16_bf16 v[0:15], a[20:23], a[28:31], v[0:15]
	s_and_b32 m0, s32, 7
	s_lshl_b32 m0, m0, 11
	s_add_i32 m0, m0, 0x14000
	s_nop 0
	global_load_lds_dwordx4 v[166:167], off
	ds_read_b128 a[16:19], v110
	ds_read_b128 a[20:23], v111
	ds_read_b128 a[24:27], v112
	ds_read_b128 a[28:31], v113
	s_waitcnt lgkmcnt(5)
	v_mfma_f32_32x32x16_bf16 v[48:63], a[0:3], a[8:11], v[48:63]
	v_mfma_f32_32x32x16_bf16 v[32:47], a[4:7], a[8:11], v[32:47]
	s_and_b32 m0, s32, 7
	s_lshl_b32 m0, m0, 11
	s_add_i32 m0, m0, 0x14400
	s_nop 0
	global_load_lds_dwordx4 v[168:169], off
	s_waitcnt lgkmcnt(4)
	v_mfma_f32_32x32x16_bf16 v[16:31], a[0:3], a[12:15], v[16:31]
	v_mfma_f32_32x32x16_bf16 v[0:15], a[4:7], a[12:15], v[0:15]
	s_waitcnt lgkmcnt(1)
	v_mfma_f32_32x32x16_bf16 v[48:63], a[16:19], a[24:27], v[48:63]
	v_mfma_f32_32x32x16_bf16 v[32:47], a[20:23], a[24:27], v[32:47]
	s_waitcnt vmcnt(6)
	s_waitcnt lgkmcnt(0)
	s_barrier
	ds_read_b128 a[12:15], v82 offset:4096
	ds_read_b128 a[8:11], v82
	ds_read_b128 a[4:7], v83 offset:36864
	ds_read_b128 a[0:3], v83 offset:32768
	v_mfma_f32_32x32x16_bf16 v[16:31], a[16:19], a[28:31], v[16:31]
	v_lshl_add_u64 v[170:171], v[66:67], 0, s[28:29]
	v_lshl_add_u64 v[172:173], v[68:69], 0, s[28:29]
	v_lshl_add_u64 v[174:175], v[70:71], 0, s[28:29]
	v_mfma_f32_32x32x16_bf16 v[0:15], a[20:23], a[28:31], v[0:15]
	s_and_b32 m0, s32, 7
	s_lshl_b32 m0, m0, 12
	s_add_i32 m0, m0, 0x18000
	s_nop 0
	global_load_lds_dwordx4 v[170:171], off
	v_lshl_add_u64 v[176:177], v[72:73], 0, s[28:29]
	v_lshl_add_u64 v[178:179], v[74:75], 0, s[28:29]
	v_lshl_add_u64 v[180:181], v[76:77], 0, s[28:29]
	s_mov_b64 s[28:29], 0x780
	ds_read_b128 a[16:19], v85 offset:32768
	ds_read_b128 a[20:23], v85 offset:36864
	ds_read_b128 a[24:27], v84
	ds_read_b128 a[28:31], v84 offset:4096
	s_waitcnt lgkmcnt(4)
	v_mfma_f32_32x32x16_bf16 v[48:63], a[0:3], a[8:11], v[48:63]
	v_lshl_add_u64 v[158:159], v[66:67], 0, s[28:29]
	v_mfma_f32_32x32x16_bf16 v[32:47], a[4:7], a[8:11], v[32:47]
	s_and_b32 m0, s32, 7
	s_lshl_b32 m0, m0, 12
	s_add_i32 m0, m0, 0x18400
	s_nop 0
	global_load_lds_dwordx4 v[172:173], off
	v_mfma_f32_32x32x16_bf16 v[16:31], a[0:3], a[12:15], v[16:31]
	v_mfma_f32_32x32x16_bf16 v[0:15], a[4:7], a[12:15], v[0:15]
	s_and_b32 m0, s32, 7
	s_lshl_b32 m0, m0, 12
	s_add_i32 m0, m0, 0x18800
	s_nop 0
	global_load_lds_dwordx4 v[174:175], off
	ds_read_b128 a[0:3], v87 offset:32768
	ds_read_b128 a[4:7], v87 offset:36864
	ds_read_b128 a[8:11], v86
	ds_read_b128 a[12:15], v86 offset:4096
	s_waitcnt lgkmcnt(5)
	v_mfma_f32_32x32x16_bf16 v[48:63], a[16:19], a[24:27], v[48:63]
	v_mfma_f32_32x32x16_bf16 v[32:47], a[20:23], a[24:27], v[32:47]
	s_and_b32 m0, s32, 7
	s_lshl_b32 m0, m0, 12
	s_add_i32 m0, m0, 0x18c00
	s_nop 0
	global_load_lds_dwordx4 v[176:177], off
	s_waitcnt lgkmcnt(4)
	v_mfma_f32_32x32x16_bf16 v[16:31], a[16:19], a[28:31], v[16:31]
	v_mfma_f32_32x32x16_bf16 v[0:15], a[20:23], a[28:31], v[0:15]
	s_and_b32 m0, s32, 7
	s_lshl_b32 m0, m0, 11
	s_add_i32 m0, m0, 0x20000
	s_nop 0
	global_load_lds_dwordx4 v[178:179], off
	ds_read_b128 a[16:19], v89 offset:32768
	ds_read_b128 a[20:23], v89 offset:36864
	ds_read_b128 a[24:27], v88
	ds_read_b128 a[28:31], v88 offset:4096
	s_waitcnt lgkmcnt(5)
	v_mfma_f32_32x32x16_bf16 v[48:63], a[0:3], a[8:11], v[48:63]
	v_mfma_f32_32x32x16_bf16 v[32:47], a[4:7], a[8:11], v[32:47]
	s_and_b32 m0, s32, 7
	s_lshl_b32 m0, m0, 11
	s_add_i32 m0, m0, 0x20400
	s_nop 0
	global_load_lds_dwordx4 v[180:181], off
	s_waitcnt lgkmcnt(4)
	v_mfma_f32_32x32x16_bf16 v[16:31], a[0:3], a[12:15], v[16:31]
	v_mfma_f32_32x32x16_bf16 v[0:15], a[4:7], a[12:15], v[0:15]
	s_waitcnt lgkmcnt(1)
	v_mfma_f32_32x32x16_bf16 v[48:63], a[16:19], a[24:27], v[48:63]
	v_mfma_f32_32x32x16_bf16 v[32:47], a[20:23], a[24:27], v[32:47]
	s_waitcnt vmcnt(6)
	s_waitcnt lgkmcnt(0)
	s_barrier
	ds_read_b128 a[12:15], v82 offset:53248
	ds_read_b128 a[8:11], v82 offset:49152
	ds_read_b128 a[4:7], v90
	ds_read_b128 a[0:3], v92
	v_lshl_add_u64 v[160:161], v[68:69], 0, s[28:29]
	v_mfma_f32_32x32x16_bf16 v[16:31], a[16:19], a[28:31], v[16:31]
	v_lshl_add_u64 v[162:163], v[70:71], 0, s[28:29]
	v_cmp_eq_u32_e64 s[0:1], 0, v79
	v_lshl_add_u64 v[164:165], v[72:73], 0, s[28:29]
	v_mfma_f32_32x32x16_bf16 v[0:15], a[20:23], a[28:31], v[0:15]
	s_and_b32 m0, s32, 7
	s_lshl_b32 m0, m0, 12
	s_add_i32 m0, m0, 0x0
	s_nop 0
	global_load_lds_dwordx4 v[158:159], off
	v_lshl_add_u64 v[166:167], v[74:75], 0, s[28:29]
	s_nop 0
	v_readlane_b32 s20, v215, 52
	s_nop 0
	v_lshl_add_u64 v[168:169], v[76:77], 0, s[28:29]
	s_nop 0
	v_readlane_b32 s21, v215, 53
	s_nop 0
	s_nop 0
	s_nop 0
	s_nop 0
	ds_read_b128 a[16:19], v93
	ds_read_b128 a[20:23], v91
	ds_read_b128 a[24:27], v84 offset:49152
	ds_read_b128 a[28:31], v84 offset:53248
	s_waitcnt lgkmcnt(4)
	v_mfma_f32_32x32x16_bf16 v[48:63], a[0:3], a[8:11], v[48:63]
	s_mov_b32 s23, 0
	v_mfma_f32_32x32x16_bf16 v[32:47], a[4:7], a[8:11], v[32:47]
	s_and_b32 m0, s32, 7
	s_lshl_b32 m0, m0, 12
	s_add_i32 m0, m0, 0x400
	s_nop 0
	global_load_lds_dwordx4 v[160:161], off
	v_mfma_f32_32x32x16_bf16 v[16:31], a[0:3], a[12:15], v[16:31]
	v_mfma_f32_32x32x16_bf16 v[0:15], a[4:7], a[12:15], v[0:15]
	s_and_b32 m0, s32, 7
	s_lshl_b32 m0, m0, 12
	s_add_i32 m0, m0, 0x800
	s_nop 0
	global_load_lds_dwordx4 v[162:163], off
	ds_read_b128 a[0:3], v95
	ds_read_b128 a[4:7], v94
	ds_read_b128 a[8:11], v86 offset:49152
	ds_read_b128 a[12:15], v86 offset:53248
	s_waitcnt lgkmcnt(5)
	v_mfma_f32_32x32x16_bf16 v[48:63], a[16:19], a[24:27], v[48:63]
	v_mfma_f32_32x32x16_bf16 v[32:47], a[20:23], a[24:27], v[32:47]
	s_and_b32 m0, s32, 7
	s_lshl_b32 m0, m0, 12
	s_add_i32 m0, m0, 0xc00
	s_nop 0
	global_load_lds_dwordx4 v[164:165], off
	s_waitcnt lgkmcnt(4)
	v_mfma_f32_32x32x16_bf16 v[16:31], a[16:19], a[28:31], v[16:31]
	v_mfma_f32_32x32x16_bf16 v[0:15], a[20:23], a[28:31], v[0:15]
	s_and_b32 m0, s32, 7
	s_lshl_b32 m0, m0, 11
	s_add_i32 m0, m0, 0x8000
	s_nop 0
	global_load_lds_dwordx4 v[166:167], off
	ds_read_b128 a[16:19], v97
	ds_read_b128 a[20:23], v96
	ds_read_b128 a[24:27], v88 offset:49152
	ds_read_b128 a[28:31], v88 offset:53248
	s_waitcnt lgkmcnt(5)
	v_mfma_f32_32x32x16_bf16 v[48:63], a[0:3], a[8:11], v[48:63]
	v_mfma_f32_32x32x16_bf16 v[32:47], a[4:7], a[8:11], v[32:47]
	s_and_b32 m0, s32, 7
	s_lshl_b32 m0, m0, 11
	s_add_i32 m0, m0, 0x8400
	s_nop 0
	global_load_lds_dwordx4 v[168:169], off
	s_waitcnt lgkmcnt(4)
	v_mfma_f32_32x32x16_bf16 v[16:31], a[0:3], a[12:15], v[16:31]
	v_mfma_f32_32x32x16_bf16 v[0:15], a[4:7], a[12:15], v[0:15]
	s_waitcnt lgkmcnt(1)
	v_mfma_f32_32x32x16_bf16 v[48:63], a[16:19], a[24:27], v[48:63]
	v_mfma_f32_32x32x16_bf16 v[32:47], a[20:23], a[24:27], v[32:47]
	s_waitcnt vmcnt(6)
	s_waitcnt lgkmcnt(0)
	s_barrier
	ds_read_b128 a[12:15], v101
	ds_read_b128 a[8:11], v100
	ds_read_b128 a[4:7], v99
	ds_read_b128 a[0:3], v98
	v_mfma_f32_32x32x16_bf16 v[16:31], a[16:19], a[28:31], v[16:31]
	v_mfma_f32_32x32x16_bf16 v[0:15], a[20:23], a[28:31], v[0:15]
	ds_read_b128 a[16:19], v102
	ds_read_b128 a[20:23], v103
	ds_read_b128 a[24:27], v104
	ds_read_b128 a[28:31], v105
	s_waitcnt lgkmcnt(4)
	v_mfma_f32_32x32x16_bf16 v[48:63], a[0:3], a[8:11], v[48:63]
	v_mfma_f32_32x32x16_bf16 v[32:47], a[4:7], a[8:11], v[32:47]
	v_mfma_f32_32x32x16_bf16 v[16:31], a[0:3], a[12:15], v[16:31]
	v_mfma_f32_32x32x16_bf16 v[0:15], a[4:7], a[12:15], v[0:15]
	ds_read_b128 a[0:3], v106
	ds_read_b128 a[4:7], v107
	ds_read_b128 a[8:11], v108
	ds_read_b128 a[12:15], v109
	s_waitcnt lgkmcnt(5)
	v_mfma_f32_32x32x16_bf16 v[48:63], a[16:19], a[24:27], v[48:63]
	v_mfma_f32_32x32x16_bf16 v[32:47], a[20:23], a[24:27], v[32:47]
	s_waitcnt lgkmcnt(4)
	v_mfma_f32_32x32x16_bf16 v[16:31], a[16:19], a[28:31], v[16:31]
	v_mfma_f32_32x32x16_bf16 v[0:15], a[20:23], a[28:31], v[0:15]
	ds_read_b128 a[16:19], v110
	ds_read_b128 a[20:23], v111
	ds_read_b128 a[24:27], v112
	ds_read_b128 a[28:31], v113
	s_waitcnt lgkmcnt(5)
	v_mfma_f32_32x32x16_bf16 v[48:63], a[0:3], a[8:11], v[48:63]
	v_mfma_f32_32x32x16_bf16 v[32:47], a[4:7], a[8:11], v[32:47]
	s_waitcnt lgkmcnt(4)
	v_mfma_f32_32x32x16_bf16 v[16:31], a[0:3], a[12:15], v[16:31]
	v_mfma_f32_32x32x16_bf16 v[0:15], a[4:7], a[12:15], v[0:15]
	s_waitcnt lgkmcnt(1)
	v_mfma_f32_32x32x16_bf16 v[48:63], a[16:19], a[24:27], v[48:63]
	v_mfma_f32_32x32x16_bf16 v[32:47], a[20:23], a[24:27], v[32:47]
	s_waitcnt vmcnt(0)
	s_waitcnt lgkmcnt(0)
	s_barrier
	ds_read_b128 a[12:15], v82 offset:4096
	ds_read_b128 a[8:11], v82
	ds_read_b128 a[4:7], v83 offset:36864
	ds_read_b128 a[0:3], v83 offset:32768
	v_mfma_f32_32x32x16_bf16 v[16:31], a[16:19], a[28:31], v[16:31]
	v_mfma_f32_32x32x16_bf16 v[0:15], a[20:23], a[28:31], v[0:15]
	ds_read_b128 a[16:19], v85 offset:32768
	ds_read_b128 a[20:23], v85 offset:36864
	ds_read_b128 a[24:27], v84
	ds_read_b128 a[28:31], v84 offset:4096
	s_waitcnt lgkmcnt(4)
	v_mfma_f32_32x32x16_bf16 v[48:63], a[0:3], a[8:11], v[48:63]
	v_mfma_f32_32x32x16_bf16 v[32:47], a[4:7], a[8:11], v[32:47]
	v_mfma_f32_32x32x16_bf16 v[16:31], a[0:3], a[12:15], v[16:31]
	v_mfma_f32_32x32x16_bf16 v[0:15], a[4:7], a[12:15], v[0:15]
	ds_read_b128 a[0:3], v87 offset:32768
	ds_read_b128 a[4:7], v87 offset:36864
	ds_read_b128 a[8:11], v86
	ds_read_b128 a[12:15], v86 offset:4096
	s_waitcnt lgkmcnt(5)
	v_mfma_f32_32x32x16_bf16 v[48:63], a[16:19], a[24:27], v[48:63]
	v_mfma_f32_32x32x16_bf16 v[32:47], a[20:23], a[24:27], v[32:47]
	s_waitcnt lgkmcnt(4)
	v_mfma_f32_32x32x16_bf16 v[16:31], a[16:19], a[28:31], v[16:31]
	v_mfma_f32_32x32x16_bf16 v[0:15], a[20:23], a[28:31], v[0:15]
	s_waitcnt lgkmcnt(1)
	v_mfma_f32_32x32x16_bf16 v[48:63], a[0:3], a[8:11], v[48:63]
	v_mfma_f32_32x32x16_bf16 v[32:47], a[4:7], a[8:11], v[32:47]
	s_waitcnt lgkmcnt(0)
	v_mfma_f32_32x32x16_bf16 v[0:15], a[4:7], a[12:15], v[0:15]
	v_mfma_f32_32x32x16_bf16 v[16:31], a[0:3], a[12:15], v[16:31]
	ds_read_b128 v[66:69], v89 offset:32768
	ds_read_b128 v[70:73], v88
	ds_read_b128 v[74:77], v89 offset:36864
	ds_read_b128 v[82:85], v88 offset:4096
	s_waitcnt lgkmcnt(0)
	s_barrier
	s_waitcnt lgkmcnt(0)
	v_mfma_f32_32x32x16_bf16 v[48:63], v[66:69], v[70:73], v[48:63]
	v_mfma_f32_32x32x16_bf16 v[32:47], v[74:77], v[70:73], v[32:47]
	s_nop 10
	ds_write_b128 v64, v[48:51]
	ds_write_b128 v64, v[52:55] offset:32
	ds_write_b128 v64, v[56:59] offset:64
	ds_write_b128 v64, v[60:63] offset:96
	ds_write_b128 v64, v[32:35] offset:128
	v_mfma_f32_32x32x16_bf16 v[0:15], v[74:77], v[82:85], v[0:15]
	v_mfma_f32_32x32x16_bf16 v[16:31], v[66:69], v[82:85], v[16:31]
	ds_write_b128 v64, v[36:39] offset:160
	ds_write_b128 v64, v[40:43] offset:192
	ds_write_b128 v64, v[44:47] offset:224
	s_nop 8
	ds_write_b128 v64, v[16:19] offset:16896
	ds_write_b128 v64, v[20:23] offset:16928
	ds_write_b128 v64, v[24:27] offset:16960
	ds_write_b128 v64, v[28:31] offset:16992
	ds_write_b128 v64, v[0:3] offset:17024
	ds_write_b128 v64, v[4:7] offset:17056
	ds_write_b128 v64, v[8:11] offset:17088
	ds_write_b128 v64, v[12:15] offset:17120
	s_waitcnt lgkmcnt(0)
	s_barrier
	v_lshl_or_b32 v0, v79, 2, s31
	v_ashrrev_i32_e32 v1, 31, v0
	v_lshl_add_u32 v4, v79, 4, 0
	v_lshl_add_u64 v[6:7], v[0:1], 2, s[92:93]
	v_lshl_add_u64 v[8:9], v[0:1], 1, s[20:21]
	s_branch .LBB0_161

.LBB0_242:
	s_or_b64 exec, exec, s[0:1]
	v_mov_b32_e32 v74, v133
	s_barrier
	v_readlane_b32 s53, v214, 24
	v_ashrrev_i32_e32 v12, 6, v74
	v_bfe_u32 v4, v74, 3, 3
	v_lshl_or_b32 v2, v12, 4, v4
	v_add_u32_e32 v0, s53, v2
	v_bfe_u32 v5, v74, 4, 2
	v_ashrrev_i32_e32 v1, 31, v0
	v_xor_b32_e32 v5, v5, v74
	v_lshlrev_b64 v[0:1], 11, v[0:1]
	v_lshlrev_b32_e32 v5, 4, v5
	v_lshl_add_u64 v[0:1], s[40:41], 0, v[0:1]
	v_or_b32_e32 v13, 8, v2
	v_lshl_or_b32 v4, v12, 5, v4
	v_and_b32_e32 v64, 0x70, v5
	v_add_u32_e32 v2, s53, v13
	v_ashrrev_i32_e32 v5, 31, v4
	v_readlane_b32 s0, v214, 4
	v_lshl_add_u64 v[70:71], v[0:1], 0, v[64:65]
	v_lshrrev_b32_e32 v0, 1, v13
	v_ashrrev_i32_e32 v3, 31, v2
	v_lshlrev_b64 v[6:7], 11, v[4:5]
	v_readlane_b32 s1, v214, 5
	v_xor_b32_e32 v0, v0, v74
	v_lshlrev_b64 v[2:3], 11, v[2:3]
	v_lshl_add_u64 v[6:7], s[0:1], 0, v[6:7]
	v_lshlrev_b32_e32 v0, 4, v0
	v_lshl_add_u64 v[2:3], s[40:41], 0, v[2:3]
	v_lshl_add_u64 v[66:67], v[6:7], 0, v[64:65]
	v_lshrrev_b32_e32 v4, 1, v4
	v_and_b32_e32 v64, 0x70, v0
	v_bitop3_b32 v4, v4, v74, 4 bitop3:0x36
	v_lshl_add_u64 v[72:73], v[2:3], 0, v[64:65]
	v_lshlrev_b32_e32 v3, 12, v12
	v_lshlrev_b32_e32 v4, 4, v4
	v_add_u32_e32 v127, 0, v3
	s_mov_b64 s[0:1], 0x2000000
	v_and_b32_e32 v4, 0x70, v4
	v_mov_b32_e32 v5, v65
	s_waitcnt vmcnt(0)
	v_readfirstlane_b32 s38, v127
	v_add_u32_e32 v126, 0x400, v127
	v_lshl_add_u64 v[8:9], v[66:67], 0, s[0:1]
	v_lshl_add_u64 v[68:69], v[6:7], 0, v[4:5]
	s_mov_b64 s[0:1], 0x2004000
	s_waitcnt lgkmcnt(0)
	s_barrier
	s_mov_b32 m0, s38
	v_readfirstlane_b32 s37, v126
	v_lshl_add_u64 v[4:5], v[68:69], 0, s[0:1]
	global_load_lds_dwordx4 v[8:9], off
	s_mov_b32 m0, s37
	v_add_u32_e32 v124, 0x800, v127
	global_load_lds_dwordx4 v[4:5], off
	v_lshlrev_b32_e32 v4, 11, v12
	s_mov_b64 s[0:1], 0x2008000
	v_readfirstlane_b32 s36, v124
	v_add_u32_e32 v122, 0xc00, v127
	v_add_u32_e32 v5, 0, v4
	v_lshl_add_u64 v[6:7], v[66:67], 0, s[0:1]
	s_mov_b64 s[0:1], 0x200c000
	s_mov_b32 m0, s36
	v_readfirstlane_b32 s35, v122
	v_add_u32_e32 v125, 0x8000, v5
	v_lshl_add_u64 v[10:11], v[68:69], 0, s[0:1]
	global_load_lds_dwordx4 v[6:7], off
	s_mov_b32 m0, s35
	v_readfirstlane_b32 s39, v125
	v_add_u32_e32 v123, 0x8400, v5
	global_load_lds_dwordx4 v[10:11], off
	s_mov_b32 m0, s39
	v_readfirstlane_b32 s40, v123
	v_add_u32_e32 v116, 0xc000, v127
	global_load_lds_dwordx4 v[70:71], off
	s_mov_b32 m0, s40
	s_mov_b64 s[0:1], 0x2000080
	v_readfirstlane_b32 s23, v116
	v_add_u32_e32 v117, 0xc400, v127
	global_load_lds_dwordx4 v[72:73], off
	v_lshl_add_u64 v[0:1], v[66:67], 0, s[0:1]
	s_mov_b32 m0, s23
	s_mov_b64 s[0:1], 0x2004080
	v_readfirstlane_b32 s24, v117
	v_add_u32_e32 v118, 0xc800, v127
	global_load_lds_dwordx4 v[0:1], off
	v_lshl_add_u64 v[0:1], v[68:69], 0, s[0:1]
	s_mov_b32 m0, s24
	s_mov_b64 s[0:1], 0x2008080
	v_readfirstlane_b32 s28, v118
	v_add_u32_e32 v119, 0xcc00, v127
	global_load_lds_dwordx4 v[0:1], off
	v_lshl_add_u64 v[0:1], v[66:67], 0, s[0:1]
	s_mov_b32 m0, s28
	s_mov_b64 s[0:1], 0x200c080
	v_readfirstlane_b32 s29, v119
	v_add_u32_e32 v120, s85, v4
	global_load_lds_dwordx4 v[0:1], off
	v_lshl_add_u64 v[0:1], v[68:69], 0, s[0:1]
	s_mov_b32 m0, s29
	s_mov_b64 s[0:1], 0x80
	v_readfirstlane_b32 s33, v120
	v_add_u32_e32 v121, 0x14400, v5
	global_load_lds_dwordx4 v[0:1], off
	v_lshl_add_u64 v[0:1], v[70:71], 0, s[0:1]
	s_mov_b32 m0, s33
	v_readfirstlane_b32 s34, v121
	v_lshrrev_b32_e32 v2, 1, v74
	v_bfe_u32 v64, v74, 5, 1
	global_load_lds_dwordx4 v[0:1], off
	v_lshl_add_u64 v[0:1], v[72:73], 0, s[0:1]
	s_mov_b32 m0, s34
	s_mov_b64 s[0:1], 0x2000100
	global_load_lds_dwordx4 v[0:1], off
	v_bitop3_b32 v0, v2, v64, 7 bitop3:0x6c
	v_add_u32_e32 v110, s3, v3
	v_lshlrev_b32_e32 v128, 4, v0
	s_waitcnt vmcnt(6)
	v_lshl_add_u64 v[0:1], v[66:67], 0, s[0:1]
	v_readfirstlane_b32 s0, v110
	v_add_u32_e32 v111, 0x400, v110
	s_waitcnt lgkmcnt(0)
	s_barrier
	s_mov_b32 m0, s0
	s_mov_b64 s[20:21], 0x2004100
	v_readfirstlane_b32 s1, v111
	v_add_u32_e32 v112, 0x800, v110
	global_load_lds_dwordx4 v[0:1], off
	v_lshl_add_u64 v[0:1], v[68:69], 0, s[20:21]
	s_mov_b32 m0, s1
	s_mov_b64 s[20:21], 0x2008100
	v_readfirstlane_b32 s2, v112
	global_load_lds_dwordx4 v[0:1], off
	v_lshl_add_u64 v[0:1], v[66:67], 0, s[20:21]
	s_mov_b32 m0, s2
	s_mov_b64 s[20:21], 0x200c100
	global_load_lds_dwordx4 v[0:1], off
	v_lshl_add_u64 v[0:1], v[68:69], 0, s[20:21]
	v_add_u32_e32 v113, 0xc00, v110
	v_readlane_b32 s21, v212, 31
	v_and_b32_e32 v75, 31, v74
	v_readfirstlane_b32 s20, v113
	v_add_u32_e32 v114, s21, v4
	v_add_u32_e32 v2, s3, v4
	v_and_b32_e32 v76, 1, v12
	v_lshlrev_b32_e32 v13, 7, v75
	s_mov_b32 m0, s20
	s_mov_b64 s[30:31], 0x100
	v_readfirstlane_b32 s21, v114
	v_add_u32_e32 v115, 0x8400, v2
	v_lshl_or_b32 v98, v76, 13, v13
	global_load_lds_dwordx4 v[0:1], off
	v_lshl_add_u64 v[0:1], v[70:71], 0, s[30:31]
	s_mov_b32 m0, s21
	v_readfirstlane_b32 s22, v115
	global_load_lds_dwordx4 v[0:1], off
	v_lshl_add_u64 v[0:1], v[72:73], 0, s[30:31]
	s_mov_b32 m0, s22
	v_add_u32_e32 v96, 0, v98
	global_load_lds_dwordx4 v[0:1], off
	v_add_u32_e32 v79, v96, v128
	v_ashrrev_i32_e32 v77, 7, v74
	ds_read_b128 a[0:3], v79 offset:32768
	ds_read_b128 a[4:7], v79 offset:36864
	v_lshl_or_b32 v129, v77, 13, v13
	v_add_u32_e32 v97, 0, v129
	v_add_u32_e32 v78, v97, v128
	ds_read_b128 a[8:11], v78
	ds_read_b128 a[12:15], v78 offset:4096
	s_waitcnt lgkmcnt(1)
	v_mfma_f32_32x32x16_bf16 v[48:63], a[0:3], a[8:11], 0
	v_bfe_u32 v99, v74, 1, 3
	s_mov_b64 s[30:31], 0x2000180
	s_mov_b32 m0, s38
	v_or_b32_e32 v139, 0x8000, v98
	v_or_b32_e32 v140, 0x9000, v98
	v_add_u32_e32 v141, s3, v129
	v_or_b32_e32 v142, 0x1000, v129
	v_mfma_f32_32x32x16_bf16 v[32:47], a[4:7], a[8:11], 0
	v_lshl_or_b32 v77, v77, 6, v75
	v_mul_lo_u32 v77, v77, s26
	s_mov_b64 s[80:81], 0x200
	s_waitcnt lgkmcnt(0)
	v_mfma_f32_32x32x16_bf16 v[16:31], a[0:3], a[12:15], 0
	v_bitop3_b32 v0, v64, v99, 2 bitop3:0x36
	v_lshlrev_b32_e32 v132, 4, v0
	v_add_u32_e32 v80, v97, v132
	ds_read_b128 a[28:31], v80 offset:4096
	ds_read_b128 a[24:27], v80
	v_add_u32_e32 v81, v96, v132
	ds_read_b128 a[20:23], v81 offset:36864
	ds_read_b128 a[16:19], v81 offset:32768
	v_mfma_f32_32x32x16_bf16 v[0:15], a[4:7], a[12:15], 0
	s_waitcnt lgkmcnt(0)
	v_mfma_f32_32x32x16_bf16 v[48:63], a[16:19], a[24:27], v[48:63]
	v_mfma_f32_32x32x16_bf16 v[32:47], a[20:23], a[24:27], v[32:47]
	v_mfma_f32_32x32x16_bf16 v[16:31], a[16:19], a[28:31], v[16:31]
	v_bitop3_b32 v82, v64, v99, 4 bitop3:0x36
	v_lshlrev_b32_e32 v134, 4, v82
	v_add_u32_e32 v82, v97, v134
	ds_read_b128 a[12:15], v82 offset:4096
	ds_read_b128 a[8:11], v82
	v_add_u32_e32 v83, v96, v134
	ds_read_b128 a[4:7], v83 offset:36864
	ds_read_b128 a[0:3], v83 offset:32768
	v_mfma_f32_32x32x16_bf16 v[0:15], a[20:23], a[28:31], v[0:15]
	s_waitcnt lgkmcnt(0)
	v_mfma_f32_32x32x16_bf16 v[48:63], a[0:3], a[8:11], v[48:63]
	v_mfma_f32_32x32x16_bf16 v[32:47], a[4:7], a[8:11], v[32:47]
	v_mfma_f32_32x32x16_bf16 v[16:31], a[0:3], a[12:15], v[16:31]
	v_bitop3_b32 v84, v64, v99, 6 bitop3:0x36
	v_lshlrev_b32_e32 v138, 4, v84
	v_add_u32_e32 v84, v97, v138
	ds_read_b128 a[28:31], v84 offset:4096
	ds_read_b128 a[24:27], v84
	v_add_u32_e32 v85, v96, v138
	ds_read_b128 a[20:23], v85 offset:36864
	ds_read_b128 a[16:19], v85 offset:32768
	v_lshlrev_b32_e32 v64, 4, v64
	v_lshl_or_b32 v64, v76, 8, v64
	v_add3_u32 v64, 0, v77, v64
	v_mfma_f32_32x32x16_bf16 v[0:15], a[4:7], a[12:15], v[0:15]
	s_waitcnt lgkmcnt(0)
	v_mfma_f32_32x32x16_bf16 v[48:63], a[16:19], a[24:27], v[48:63]
	v_mfma_f32_32x32x16_bf16 v[32:47], a[20:23], a[24:27], v[32:47]
	s_waitcnt vmcnt(6)
	s_waitcnt lgkmcnt(0)
	s_barrier
	ds_read_b128 a[12:15], v78 offset:53248
	ds_read_b128 a[8:11], v78 offset:49152
	v_mfma_f32_32x32x16_bf16 v[16:31], a[16:19], a[28:31], v[16:31]
	v_lshl_add_u64 v[86:87], v[66:67], 0, s[30:31]
	s_mov_b64 s[30:31], 0x2004180
	global_load_lds_dwordx4 v[86:87], off
	v_lshl_add_u64 v[86:87], v[68:69], 0, s[30:31]
	s_mov_b32 m0, s37
	s_mov_b64 s[30:31], 0x2008180
	global_load_lds_dwordx4 v[86:87], off
	v_lshl_add_u64 v[86:87], v[66:67], 0, s[30:31]
	s_mov_b32 m0, s36
	s_mov_b64 s[30:31], 0x200c180
	global_load_lds_dwordx4 v[86:87], off
	v_lshl_add_u64 v[86:87], v[68:69], 0, s[30:31]
	s_mov_b32 m0, s35
	s_mov_b64 s[30:31], 0x180
	global_load_lds_dwordx4 v[86:87], off
	v_lshl_add_u64 v[86:87], v[70:71], 0, s[30:31]
	s_mov_b32 m0, s39
	v_mfma_f32_32x32x16_bf16 v[0:15], a[20:23], a[28:31], v[0:15]
	global_load_lds_dwordx4 v[86:87], off
	v_lshl_add_u64 v[86:87], v[72:73], 0, s[30:31]
	s_mov_b32 m0, s40
	s_add_i32 s30, 0, 0xc000
	global_load_lds_dwordx4 v[86:87], off
	v_add_u32_e32 v86, s30, v128
	v_add_u32_e32 v88, v86, v139
	v_add_u32_e32 v86, v86, v140
	ds_read_b128 a[4:7], v86
	ds_read_b128 a[0:3], v88
	v_add_u32_e32 v87, s30, v132
	v_add_u32_e32 v89, v87, v139
	ds_read_b128 a[16:19], v89
	v_add_u32_e32 v87, v87, v140
	ds_read_b128 a[20:23], v87
	ds_read_b128 a[24:27], v80 offset:49152
	ds_read_b128 a[28:31], v80 offset:53248
	s_waitcnt lgkmcnt(4)
	v_mfma_f32_32x32x16_bf16 v[48:63], a[0:3], a[8:11], v[48:63]
	s_mov_b32 m0, s23
	v_mfma_f32_32x32x16_bf16 v[32:47], a[4:7], a[8:11], v[32:47]
	v_mfma_f32_32x32x16_bf16 v[16:31], a[0:3], a[12:15], v[16:31]
	v_mfma_f32_32x32x16_bf16 v[0:15], a[4:7], a[12:15], v[0:15]
	v_add_u32_e32 v90, s30, v134
	v_add_u32_e32 v91, v90, v139
	ds_read_b128 a[0:3], v91
	v_add_u32_e32 v90, v90, v140
	ds_read_b128 a[4:7], v90
	ds_read_b128 a[8:11], v82 offset:49152
	ds_read_b128 a[12:15], v82 offset:53248
	s_waitcnt lgkmcnt(5)
	v_mfma_f32_32x32x16_bf16 v[48:63], a[16:19], a[24:27], v[48:63]
	v_mfma_f32_32x32x16_bf16 v[32:47], a[20:23], a[24:27], v[32:47]
	s_waitcnt lgkmcnt(4)
	v_mfma_f32_32x32x16_bf16 v[16:31], a[16:19], a[28:31], v[16:31]
	v_mfma_f32_32x32x16_bf16 v[0:15], a[20:23], a[28:31], v[0:15]
	v_add_u32_e32 v92, s30, v138
	v_add_u32_e32 v93, v92, v139
	ds_read_b128 a[16:19], v93
	v_add_u32_e32 v92, v92, v140
	ds_read_b128 a[20:23], v92
	ds_read_b128 a[24:27], v84 offset:49152
	ds_read_b128 a[28:31], v84 offset:53248
	s_waitcnt lgkmcnt(5)
	v_mfma_f32_32x32x16_bf16 v[48:63], a[0:3], a[8:11], v[48:63]
	v_mfma_f32_32x32x16_bf16 v[32:47], a[4:7], a[8:11], v[32:47]
	s_waitcnt lgkmcnt(4)
	v_mfma_f32_32x32x16_bf16 v[16:31], a[0:3], a[12:15], v[16:31]
	s_mov_b64 s[30:31], 0x2000200
	v_mfma_f32_32x32x16_bf16 v[0:15], a[4:7], a[12:15], v[0:15]
	s_waitcnt lgkmcnt(1)
	v_mfma_f32_32x32x16_bf16 v[48:63], a[16:19], a[24:27], v[48:63]
	v_mfma_f32_32x32x16_bf16 v[32:47], a[20:23], a[24:27], v[32:47]
	s_waitcnt vmcnt(6)
	s_waitcnt lgkmcnt(0)
	s_barrier
	v_add_u32_e32 v96, v141, v128
	ds_read_b128 a[8:11], v96
	v_mfma_f32_32x32x16_bf16 v[16:31], a[16:19], a[28:31], v[16:31]
	v_lshl_add_u64 v[94:95], v[66:67], 0, s[30:31]
	s_mov_b64 s[30:31], 0x2004200
	global_load_lds_dwordx4 v[94:95], off
	v_lshl_add_u64 v[94:95], v[68:69], 0, s[30:31]
	s_mov_b32 m0, s24
	s_mov_b64 s[30:31], 0x2008200
	global_load_lds_dwordx4 v[94:95], off
	v_lshl_add_u64 v[94:95], v[66:67], 0, s[30:31]
	s_mov_b32 m0, s28
	s_mov_b64 s[30:31], 0x200c200
	global_load_lds_dwordx4 v[94:95], off
	v_lshl_add_u64 v[94:95], v[68:69], 0, s[30:31]
	s_mov_b32 m0, s29
	s_mov_b64 s[30:31], 0x200
	global_load_lds_dwordx4 v[94:95], off
	v_lshl_add_u64 v[94:95], v[70:71], 0, s[30:31]
	s_mov_b32 m0, s33
	v_add_u32_e32 v97, s3, v128
	global_load_lds_dwordx4 v[94:95], off
	v_lshl_add_u64 v[94:95], v[72:73], 0, s[30:31]
	s_mov_b32 m0, s34
	v_mfma_f32_32x32x16_bf16 v[0:15], a[20:23], a[28:31], v[0:15]
	global_load_lds_dwordx4 v[94:95], off
	v_add_u32_e32 v95, v97, v140
	ds_read_b128 a[4:7], v95
	v_add_u32_e32 v94, v97, v139
	v_add_u32_e32 v97, v97, v142
	ds_read_b128 a[12:15], v97
	ds_read_b128 a[0:3], v94
	v_add_u32_e32 v101, s3, v132
	v_add_u32_e32 v98, v101, v139
	ds_read_b128 a[16:19], v98
	v_add_u32_e32 v99, v101, v140
	ds_read_b128 a[20:23], v99
	v_add_u32_e32 v100, v141, v132
	ds_read_b128 a[24:27], v100
	v_add_u32_e32 v101, v101, v142
	ds_read_b128 a[28:31], v101
	s_waitcnt lgkmcnt(4)
	v_mfma_f32_32x32x16_bf16 v[48:63], a[0:3], a[8:11], v[48:63]
	s_mov_b64 s[30:31], 0x2000280
	s_mov_b32 m0, s0
	v_mfma_f32_32x32x16_bf16 v[32:47], a[4:7], a[8:11], v[32:47]
	v_mfma_f32_32x32x16_bf16 v[16:31], a[0:3], a[12:15], v[16:31]
	v_mfma_f32_32x32x16_bf16 v[0:15], a[4:7], a[12:15], v[0:15]
	v_add_u32_e32 v105, s3, v134
	v_add_u32_e32 v102, v105, v139
	ds_read_b128 a[0:3], v102
	v_add_u32_e32 v103, v105, v140
	ds_read_b128 a[4:7], v103
	v_add_u32_e32 v104, v141, v134
	ds_read_b128 a[8:11], v104
	v_add_u32_e32 v105, v105, v142
	ds_read_b128 a[12:15], v105
	s_waitcnt lgkmcnt(5)
	v_mfma_f32_32x32x16_bf16 v[48:63], a[16:19], a[24:27], v[48:63]
	v_mfma_f32_32x32x16_bf16 v[32:47], a[20:23], a[24:27], v[32:47]
	s_waitcnt lgkmcnt(4)
	v_mfma_f32_32x32x16_bf16 v[16:31], a[16:19], a[28:31], v[16:31]
	v_mfma_f32_32x32x16_bf16 v[0:15], a[20:23], a[28:31], v[0:15]
	v_add_u32_e32 v109, s3, v138
	v_add_u32_e32 v106, v109, v139
	ds_read_b128 a[16:19], v106
	v_add_u32_e32 v107, v109, v140
	ds_read_b128 a[20:23], v107
	v_add_u32_e32 v108, v141, v138
	ds_read_b128 a[24:27], v108
	v_add_u32_e32 v109, v109, v142
	ds_read_b128 a[28:31], v109
	s_waitcnt lgkmcnt(5)
	v_mfma_f32_32x32x16_bf16 v[48:63], a[0:3], a[8:11], v[48:63]
	v_mfma_f32_32x32x16_bf16 v[32:47], a[4:7], a[8:11], v[32:47]
	s_waitcnt lgkmcnt(4)
	v_mfma_f32_32x32x16_bf16 v[16:31], a[0:3], a[12:15], v[16:31]
	v_mfma_f32_32x32x16_bf16 v[0:15], a[4:7], a[12:15], v[0:15]
	s_waitcnt lgkmcnt(1)
	v_mfma_f32_32x32x16_bf16 v[48:63], a[16:19], a[24:27], v[48:63]
	v_mfma_f32_32x32x16_bf16 v[32:47], a[20:23], a[24:27], v[32:47]
	s_waitcnt vmcnt(6)
	s_waitcnt lgkmcnt(0)
	s_barrier
	ds_read_b128 a[12:15], v78 offset:4096
	ds_read_b128 a[8:11], v78
	ds_read_b128 a[4:7], v79 offset:36864
	ds_read_b128 a[0:3], v79 offset:32768
	v_mfma_f32_32x32x16_bf16 v[16:31], a[16:19], a[28:31], v[16:31]
	v_lshl_add_u64 v[128:129], v[66:67], 0, s[30:31]
	s_mov_b64 s[30:31], 0x2004280
	global_load_lds_dwordx4 v[128:129], off
	v_lshl_add_u64 v[128:129], v[68:69], 0, s[30:31]
	s_mov_b32 m0, s1
	s_mov_b64 s[30:31], 0x2008280
	global_load_lds_dwordx4 v[128:129], off
	v_lshl_add_u64 v[128:129], v[66:67], 0, s[30:31]
	s_mov_b32 m0, s2
	s_mov_b64 s[30:31], 0x200c280
	global_load_lds_dwordx4 v[128:129], off
	v_lshl_add_u64 v[128:129], v[68:69], 0, s[30:31]
	s_mov_b32 m0, s20
	s_mov_b64 s[30:31], 0x280
	global_load_lds_dwordx4 v[128:129], off
	v_lshl_add_u64 v[128:129], v[70:71], 0, s[30:31]
	s_mov_b32 m0, s21
	v_mfma_f32_32x32x16_bf16 v[0:15], a[20:23], a[28:31], v[0:15]
	global_load_lds_dwordx4 v[128:129], off
	v_lshl_add_u64 v[128:129], v[72:73], 0, s[30:31]
	s_mov_b32 m0, s22
	s_mov_b64 s[30:31], 0x2000300
	global_load_lds_dwordx4 v[128:129], off
	ds_read_b128 a[16:19], v81 offset:32768
	ds_read_b128 a[20:23], v81 offset:36864
	ds_read_b128 a[24:27], v80
	ds_read_b128 a[28:31], v80 offset:4096
	s_waitcnt lgkmcnt(4)
	v_mfma_f32_32x32x16_bf16 v[48:63], a[0:3], a[8:11], v[48:63]
	s_mov_b32 m0, s38
	v_readfirstlane_b32 s38, v113
	v_mfma_f32_32x32x16_bf16 v[32:47], a[4:7], a[8:11], v[32:47]
	v_mfma_f32_32x32x16_bf16 v[16:31], a[0:3], a[12:15], v[16:31]
	v_mfma_f32_32x32x16_bf16 v[0:15], a[4:7], a[12:15], v[0:15]
	s_nop 0
	ds_read_b128 a[0:3], v83 offset:32768
	ds_read_b128 a[4:7], v83 offset:36864
	ds_read_b128 a[8:11], v82
	ds_read_b128 a[12:15], v82 offset:4096
	s_waitcnt lgkmcnt(5)
	v_mfma_f32_32x32x16_bf16 v[48:63], a[16:19], a[24:27], v[48:63]
	v_mfma_f32_32x32x16_bf16 v[32:47], a[20:23], a[24:27], v[32:47]
	s_waitcnt lgkmcnt(4)
	v_mfma_f32_32x32x16_bf16 v[16:31], a[16:19], a[28:31], v[16:31]
	v_mfma_f32_32x32x16_bf16 v[0:15], a[20:23], a[28:31], v[0:15]
	ds_read_b128 a[16:19], v85 offset:32768
	ds_read_b128 a[20:23], v85 offset:36864
	ds_read_b128 a[24:27], v84
	ds_read_b128 a[28:31], v84 offset:4096
	s_waitcnt lgkmcnt(5)
	v_mfma_f32_32x32x16_bf16 v[48:63], a[0:3], a[8:11], v[48:63]
	v_mfma_f32_32x32x16_bf16 v[32:47], a[4:7], a[8:11], v[32:47]
	s_waitcnt lgkmcnt(4)
	v_mfma_f32_32x32x16_bf16 v[16:31], a[0:3], a[12:15], v[16:31]
	v_mfma_f32_32x32x16_bf16 v[0:15], a[4:7], a[12:15], v[0:15]
	s_waitcnt lgkmcnt(1)
	v_mfma_f32_32x32x16_bf16 v[48:63], a[16:19], a[24:27], v[48:63]
	v_mfma_f32_32x32x16_bf16 v[32:47], a[20:23], a[24:27], v[32:47]
	s_waitcnt vmcnt(6)
	s_waitcnt lgkmcnt(0)
	s_barrier
	ds_read_b128 a[12:15], v78 offset:53248
	ds_read_b128 a[8:11], v78 offset:49152
	ds_read_b128 a[4:7], v86
	ds_read_b128 a[0:3], v88
	v_mfma_f32_32x32x16_bf16 v[16:31], a[16:19], a[28:31], v[16:31]
	v_lshl_add_u64 v[128:129], v[66:67], 0, s[30:31]
	s_mov_b64 s[30:31], 0x2004300
	global_load_lds_dwordx4 v[128:129], off
	v_lshl_add_u64 v[128:129], v[68:69], 0, s[30:31]
	s_mov_b32 m0, s37
	s_mov_b64 s[30:31], 0x2008300
	global_load_lds_dwordx4 v[128:129], off
	v_lshl_add_u64 v[128:129], v[66:67], 0, s[30:31]
	s_mov_b32 m0, s36
	s_mov_b64 s[30:31], 0x200c300
	global_load_lds_dwordx4 v[128:129], off
	v_lshl_add_u64 v[128:129], v[68:69], 0, s[30:31]
	s_mov_b32 m0, s35
	s_mov_b64 s[30:31], 0x300
	global_load_lds_dwordx4 v[128:129], off
	v_lshl_add_u64 v[128:129], v[70:71], 0, s[30:31]
	s_mov_b32 m0, s39
	v_mfma_f32_32x32x16_bf16 v[0:15], a[20:23], a[28:31], v[0:15]
	global_load_lds_dwordx4 v[128:129], off
	v_lshl_add_u64 v[128:129], v[72:73], 0, s[30:31]
	s_mov_b32 m0, s40
	s_mov_b64 s[30:31], 0x2000380
	global_load_lds_dwordx4 v[128:129], off
	ds_read_b128 a[16:19], v89
	ds_read_b128 a[20:23], v87
	ds_read_b128 a[24:27], v80 offset:49152
	ds_read_b128 a[28:31], v80 offset:53248
	s_waitcnt lgkmcnt(4)
	v_mfma_f32_32x32x16_bf16 v[48:63], a[0:3], a[8:11], v[48:63]
	s_mov_b32 m0, s23
	v_readfirstlane_b32 s35, v110
	v_readfirstlane_b32 s36, v111
	v_readfirstlane_b32 s37, v112
	v_readfirstlane_b32 s39, v114
	v_readfirstlane_b32 s40, v115
	v_mfma_f32_32x32x16_bf16 v[32:47], a[4:7], a[8:11], v[32:47]
	v_mfma_f32_32x32x16_bf16 v[16:31], a[0:3], a[12:15], v[16:31]
	v_mfma_f32_32x32x16_bf16 v[0:15], a[4:7], a[12:15], v[0:15]
	s_nop 0
	ds_read_b128 a[0:3], v91
	ds_read_b128 a[4:7], v90
	ds_read_b128 a[8:11], v82 offset:49152
	ds_read_b128 a[12:15], v82 offset:53248
	s_waitcnt lgkmcnt(5)
	v_mfma_f32_32x32x16_bf16 v[48:63], a[16:19], a[24:27], v[48:63]
	v_mfma_f32_32x32x16_bf16 v[32:47], a[20:23], a[24:27], v[32:47]
	s_waitcnt lgkmcnt(4)
	v_mfma_f32_32x32x16_bf16 v[16:31], a[16:19], a[28:31], v[16:31]
	v_mfma_f32_32x32x16_bf16 v[0:15], a[20:23], a[28:31], v[0:15]
	ds_read_b128 a[16:19], v93
	ds_read_b128 a[20:23], v92
	ds_read_b128 a[24:27], v84 offset:49152
	ds_read_b128 a[28:31], v84 offset:53248
	s_waitcnt lgkmcnt(5)
	v_mfma_f32_32x32x16_bf16 v[48:63], a[0:3], a[8:11], v[48:63]
	v_mfma_f32_32x32x16_bf16 v[32:47], a[4:7], a[8:11], v[32:47]
	s_waitcnt lgkmcnt(4)
	v_mfma_f32_32x32x16_bf16 v[16:31], a[0:3], a[12:15], v[16:31]
	v_mfma_f32_32x32x16_bf16 v[0:15], a[4:7], a[12:15], v[0:15]
	s_waitcnt lgkmcnt(1)
	v_mfma_f32_32x32x16_bf16 v[48:63], a[16:19], a[24:27], v[48:63]
	v_mfma_f32_32x32x16_bf16 v[32:47], a[20:23], a[24:27], v[32:47]
	s_waitcnt vmcnt(6)
	s_waitcnt lgkmcnt(0)
	s_barrier
	ds_read_b128 a[12:15], v97
	ds_read_b128 a[8:11], v96
	ds_read_b128 a[4:7], v95
	ds_read_b128 a[0:3], v94
	v_mfma_f32_32x32x16_bf16 v[16:31], a[16:19], a[28:31], v[16:31]
	v_lshl_add_u64 v[128:129], v[66:67], 0, s[30:31]
	s_mov_b64 s[30:31], 0x2004380
	global_load_lds_dwordx4 v[128:129], off
	v_lshl_add_u64 v[128:129], v[68:69], 0, s[30:31]
	s_mov_b32 m0, s24
	s_mov_b64 s[30:31], 0x2008380
	global_load_lds_dwordx4 v[128:129], off
	v_lshl_add_u64 v[128:129], v[66:67], 0, s[30:31]
	s_mov_b32 m0, s28
	s_mov_b64 s[30:31], 0x200c380
	global_load_lds_dwordx4 v[128:129], off
	v_lshl_add_u64 v[128:129], v[68:69], 0, s[30:31]
	s_mov_b32 m0, s29
	s_mov_b64 s[28:29], 0x380
	global_load_lds_dwordx4 v[128:129], off
	v_lshl_add_u64 v[128:129], v[70:71], 0, s[28:29]
	s_mov_b32 m0, s33
	v_mfma_f32_32x32x16_bf16 v[0:15], a[20:23], a[28:31], v[0:15]
	global_load_lds_dwordx4 v[128:129], off
	v_lshl_add_u64 v[128:129], v[72:73], 0, s[28:29]
	s_mov_b32 m0, s34
	s_mov_b64 s[28:29], 0x2000400
	global_load_lds_dwordx4 v[128:129], off
	ds_read_b128 a[16:19], v98
	ds_read_b128 a[20:23], v99
	ds_read_b128 a[24:27], v100
	ds_read_b128 a[28:31], v101
	s_waitcnt lgkmcnt(4)
	v_mfma_f32_32x32x16_bf16 v[48:63], a[0:3], a[8:11], v[48:63]
	s_mov_b32 m0, s0
	v_readfirstlane_b32 s24, v117
	s_mov_b64 s[30:31], 0x200c500
	v_readfirstlane_b32 s33, v120
	v_readfirstlane_b32 s34, v121
	v_mfma_f32_32x32x16_bf16 v[32:47], a[4:7], a[8:11], v[32:47]
	v_mfma_f32_32x32x16_bf16 v[16:31], a[0:3], a[12:15], v[16:31]
	v_mfma_f32_32x32x16_bf16 v[0:15], a[4:7], a[12:15], v[0:15]
	s_nop 0
	ds_read_b128 a[0:3], v102
	ds_read_b128 a[4:7], v103
	ds_read_b128 a[8:11], v104
	ds_read_b128 a[12:15], v105
	s_waitcnt lgkmcnt(5)
	v_mfma_f32_32x32x16_bf16 v[48:63], a[16:19], a[24:27], v[48:63]
	v_mfma_f32_32x32x16_bf16 v[32:47], a[20:23], a[24:27], v[32:47]
	s_waitcnt lgkmcnt(4)
	v_mfma_f32_32x32x16_bf16 v[16:31], a[16:19], a[28:31], v[16:31]
	v_mfma_f32_32x32x16_bf16 v[0:15], a[20:23], a[28:31], v[0:15]
	ds_read_b128 a[16:19], v106
	ds_read_b128 a[20:23], v107
	ds_read_b128 a[24:27], v108
	ds_read_b128 a[28:31], v109
	s_waitcnt lgkmcnt(5)
	v_mfma_f32_32x32x16_bf16 v[48:63], a[0:3], a[8:11], v[48:63]
	v_mfma_f32_32x32x16_bf16 v[32:47], a[4:7], a[8:11], v[32:47]
	s_waitcnt lgkmcnt(4)
	v_mfma_f32_32x32x16_bf16 v[16:31], a[0:3], a[12:15], v[16:31]
	v_mfma_f32_32x32x16_bf16 v[0:15], a[4:7], a[12:15], v[0:15]
	s_waitcnt lgkmcnt(1)
	v_mfma_f32_32x32x16_bf16 v[48:63], a[16:19], a[24:27], v[48:63]
	v_mfma_f32_32x32x16_bf16 v[32:47], a[20:23], a[24:27], v[32:47]
	s_waitcnt vmcnt(6)
	s_waitcnt lgkmcnt(0)
	s_barrier
	ds_read_b128 a[12:15], v78 offset:4096
	ds_read_b128 a[8:11], v78
	ds_read_b128 a[4:7], v79 offset:36864
	ds_read_b128 a[0:3], v79 offset:32768
	v_mfma_f32_32x32x16_bf16 v[16:31], a[16:19], a[28:31], v[16:31]
	v_lshl_add_u64 v[128:129], v[66:67], 0, s[28:29]
	s_mov_b64 s[28:29], 0x2004400
	global_load_lds_dwordx4 v[128:129], off
	v_lshl_add_u64 v[128:129], v[68:69], 0, s[28:29]
	s_mov_b32 m0, s1
	s_mov_b64 s[0:1], 0x2008400
	global_load_lds_dwordx4 v[128:129], off
	v_lshl_add_u64 v[128:129], v[66:67], 0, s[0:1]
	s_mov_b32 m0, s2
	s_mov_b64 s[0:1], 0x200c400
	global_load_lds_dwordx4 v[128:129], off
	v_lshl_add_u64 v[128:129], v[68:69], 0, s[0:1]
	s_mov_b32 m0, s20
	s_mov_b64 s[0:1], 0x400
	global_load_lds_dwordx4 v[128:129], off
	v_lshl_add_u64 v[128:129], v[70:71], 0, s[0:1]
	s_mov_b32 m0, s21
	v_mfma_f32_32x32x16_bf16 v[0:15], a[20:23], a[28:31], v[0:15]
	global_load_lds_dwordx4 v[128:129], off
	v_lshl_add_u64 v[128:129], v[72:73], 0, s[0:1]
	s_mov_b32 m0, s22
	s_mov_b64 s[0:1], 0x2000480
	global_load_lds_dwordx4 v[128:129], off
	ds_read_b128 a[16:19], v81 offset:32768
	ds_read_b128 a[20:23], v81 offset:36864
	ds_read_b128 a[24:27], v80
	ds_read_b128 a[28:31], v80 offset:4096
	s_waitcnt lgkmcnt(4)
	v_mfma_f32_32x32x16_bf16 v[48:63], a[0:3], a[8:11], v[48:63]
	s_mov_b64 s[20:21], 0x2004480
	v_readfirstlane_b32 s2, v124
	s_mov_b64 s[22:23], 0x480
	s_mov_b64 s[28:29], 0x2000500
	v_mfma_f32_32x32x16_bf16 v[32:47], a[4:7], a[8:11], v[32:47]
	v_mfma_f32_32x32x16_bf16 v[16:31], a[0:3], a[12:15], v[16:31]
	v_mfma_f32_32x32x16_bf16 v[0:15], a[4:7], a[12:15], v[0:15]
	ds_read_b128 a[0:3], v83 offset:32768
	ds_read_b128 a[4:7], v83 offset:36864
	ds_read_b128 a[8:11], v82
	ds_read_b128 a[12:15], v82 offset:4096
	s_waitcnt lgkmcnt(5)
	v_mfma_f32_32x32x16_bf16 v[48:63], a[16:19], a[24:27], v[48:63]
	v_mfma_f32_32x32x16_bf16 v[32:47], a[20:23], a[24:27], v[32:47]
	s_waitcnt lgkmcnt(4)
	v_mfma_f32_32x32x16_bf16 v[16:31], a[16:19], a[28:31], v[16:31]
	v_mfma_f32_32x32x16_bf16 v[0:15], a[20:23], a[28:31], v[0:15]
	ds_read_b128 a[16:19], v85 offset:32768
	ds_read_b128 a[20:23], v85 offset:36864
	ds_read_b128 a[24:27], v84
	ds_read_b128 a[28:31], v84 offset:4096
	s_waitcnt lgkmcnt(5)
	v_mfma_f32_32x32x16_bf16 v[48:63], a[0:3], a[8:11], v[48:63]
	v_mfma_f32_32x32x16_bf16 v[32:47], a[4:7], a[8:11], v[32:47]
	s_waitcnt lgkmcnt(4)
	v_mfma_f32_32x32x16_bf16 v[16:31], a[0:3], a[12:15], v[16:31]
	v_mfma_f32_32x32x16_bf16 v[0:15], a[4:7], a[12:15], v[0:15]
	s_waitcnt lgkmcnt(1)
	v_mfma_f32_32x32x16_bf16 v[48:63], a[16:19], a[24:27], v[48:63]
	v_mfma_f32_32x32x16_bf16 v[32:47], a[20:23], a[24:27], v[32:47]
	s_waitcnt vmcnt(6)
	s_waitcnt lgkmcnt(0)
	s_barrier
	ds_read_b128 a[12:15], v78 offset:53248
	ds_read_b128 a[8:11], v78 offset:49152
	ds_read_b128 a[4:7], v86
	ds_read_b128 a[0:3], v88
	v_mfma_f32_32x32x16_bf16 v[16:31], a[16:19], a[28:31], v[16:31]
	v_lshl_add_u64 v[128:129], v[66:67], 0, s[0:1]
	v_readfirstlane_b32 s0, v127
	s_mov_b32 m0, s0
	v_readfirstlane_b32 s1, v126
	global_load_lds_dwordx4 v[128:129], off
	v_lshl_add_u64 v[128:129], v[68:69], 0, s[20:21]
	s_mov_b32 m0, s1
	s_mov_b64 s[20:21], 0x2008480
	global_load_lds_dwordx4 v[128:129], off
	v_lshl_add_u64 v[126:127], v[66:67], 0, s[20:21]
	s_mov_b32 m0, s2
	s_mov_b64 s[20:21], 0x200c480
	global_load_lds_dwordx4 v[126:127], off
	v_lshl_add_u64 v[126:127], v[68:69], 0, s[20:21]
	v_readfirstlane_b32 s20, v122
	s_mov_b32 m0, s20
	v_readfirstlane_b32 s21, v125
	global_load_lds_dwordx4 v[126:127], off
	v_lshl_add_u64 v[126:127], v[70:71], 0, s[22:23]
	s_mov_b32 m0, s21
	v_lshl_add_u64 v[124:125], v[72:73], 0, s[22:23]
	v_readfirstlane_b32 s22, v123
	global_load_lds_dwordx4 v[126:127], off
	s_mov_b32 m0, s22
	v_mfma_f32_32x32x16_bf16 v[0:15], a[20:23], a[28:31], v[0:15]
	global_load_lds_dwordx4 v[124:125], off
	s_nop 0
	s_nop 0
	v_readfirstlane_b32 s23, v116
	s_mov_b32 m0, s23
	s_nop 0
	ds_read_b128 a[16:19], v89
	ds_read_b128 a[20:23], v87
	ds_read_b128 a[24:27], v80 offset:49152
	ds_read_b128 a[28:31], v80 offset:53248
	s_waitcnt lgkmcnt(4)
	v_mfma_f32_32x32x16_bf16 v[48:63], a[0:3], a[8:11], v[48:63]
	v_mfma_f32_32x32x16_bf16 v[32:47], a[4:7], a[8:11], v[32:47]
	v_mfma_f32_32x32x16_bf16 v[16:31], a[0:3], a[12:15], v[16:31]
	v_mfma_f32_32x32x16_bf16 v[0:15], a[4:7], a[12:15], v[0:15]
	ds_read_b128 a[0:3], v91
	ds_read_b128 a[4:7], v90
	ds_read_b128 a[8:11], v82 offset:49152
	ds_read_b128 a[12:15], v82 offset:53248
	s_waitcnt lgkmcnt(5)
	v_mfma_f32_32x32x16_bf16 v[48:63], a[16:19], a[24:27], v[48:63]
	v_mfma_f32_32x32x16_bf16 v[32:47], a[20:23], a[24:27], v[32:47]
	s_waitcnt lgkmcnt(4)
	v_mfma_f32_32x32x16_bf16 v[16:31], a[16:19], a[28:31], v[16:31]
	v_mfma_f32_32x32x16_bf16 v[0:15], a[20:23], a[28:31], v[0:15]
	ds_read_b128 a[16:19], v93
	ds_read_b128 a[20:23], v92
	ds_read_b128 a[24:27], v84 offset:49152
	ds_read_b128 a[28:31], v84 offset:53248
	s_waitcnt lgkmcnt(5)
	v_mfma_f32_32x32x16_bf16 v[48:63], a[0:3], a[8:11], v[48:63]
	v_mfma_f32_32x32x16_bf16 v[32:47], a[4:7], a[8:11], v[32:47]
	s_waitcnt lgkmcnt(4)
	v_mfma_f32_32x32x16_bf16 v[16:31], a[0:3], a[12:15], v[16:31]
	v_mfma_f32_32x32x16_bf16 v[0:15], a[4:7], a[12:15], v[0:15]
	s_waitcnt lgkmcnt(1)
	v_mfma_f32_32x32x16_bf16 v[48:63], a[16:19], a[24:27], v[48:63]
	v_mfma_f32_32x32x16_bf16 v[32:47], a[20:23], a[24:27], v[32:47]
	s_waitcnt vmcnt(6)
	s_waitcnt lgkmcnt(0)
	s_barrier
	ds_read_b128 a[12:15], v97
	ds_read_b128 a[8:11], v96
	ds_read_b128 a[4:7], v95
	ds_read_b128 a[0:3], v94
	v_mfma_f32_32x32x16_bf16 v[16:31], a[16:19], a[28:31], v[16:31]
	v_lshl_add_u64 v[122:123], v[66:67], 0, s[28:29]
	s_mov_b64 s[28:29], 0x2004500
	global_load_lds_dwordx4 v[122:123], off
	v_lshl_add_u64 v[122:123], v[68:69], 0, s[28:29]
	s_mov_b64 s[28:29], 0x2008500
	s_mov_b32 m0, s24
	v_lshl_add_u64 v[116:117], v[66:67], 0, s[28:29]
	v_readfirstlane_b32 s28, v118
	global_load_lds_dwordx4 v[122:123], off
	s_mov_b32 m0, s28
	v_readfirstlane_b32 s29, v119
	global_load_lds_dwordx4 v[116:117], off
	v_lshl_add_u64 v[116:117], v[68:69], 0, s[30:31]
	s_mov_b32 m0, s29
	s_mov_b64 s[30:31], 0x500
	global_load_lds_dwordx4 v[116:117], off
	v_lshl_add_u64 v[116:117], v[70:71], 0, s[30:31]
	s_mov_b32 m0, s33
	v_mfma_f32_32x32x16_bf16 v[0:15], a[20:23], a[28:31], v[0:15]
	global_load_lds_dwordx4 v[116:117], off
	v_lshl_add_u64 v[116:117], v[72:73], 0, s[30:31]
	s_mov_b32 m0, s34
	s_mov_b64 s[30:31], 0x2000580
	global_load_lds_dwordx4 v[116:117], off
	ds_read_b128 a[16:19], v98
	ds_read_b128 a[20:23], v99
	ds_read_b128 a[24:27], v100
	ds_read_b128 a[28:31], v101
	s_waitcnt lgkmcnt(4)
	v_mfma_f32_32x32x16_bf16 v[48:63], a[0:3], a[8:11], v[48:63]
	s_mov_b32 m0, s35
	v_mfma_f32_32x32x16_bf16 v[32:47], a[4:7], a[8:11], v[32:47]
	v_mfma_f32_32x32x16_bf16 v[16:31], a[0:3], a[12:15], v[16:31]
	v_mfma_f32_32x32x16_bf16 v[0:15], a[4:7], a[12:15], v[0:15]
	ds_read_b128 a[0:3], v102
	ds_read_b128 a[4:7], v103
	ds_read_b128 a[8:11], v104
	ds_read_b128 a[12:15], v105
	s_waitcnt lgkmcnt(5)
	v_mfma_f32_32x32x16_bf16 v[48:63], a[16:19], a[24:27], v[48:63]
	v_mfma_f32_32x32x16_bf16 v[32:47], a[20:23], a[24:27], v[32:47]
	s_waitcnt lgkmcnt(4)
	v_mfma_f32_32x32x16_bf16 v[16:31], a[16:19], a[28:31], v[16:31]
	v_mfma_f32_32x32x16_bf16 v[0:15], a[20:23], a[28:31], v[0:15]
	ds_read_b128 a[16:19], v106
	ds_read_b128 a[20:23], v107
	ds_read_b128 a[24:27], v108
	ds_read_b128 a[28:31], v109
	s_waitcnt lgkmcnt(5)
	v_mfma_f32_32x32x16_bf16 v[48:63], a[0:3], a[8:11], v[48:63]
	v_mfma_f32_32x32x16_bf16 v[32:47], a[4:7], a[8:11], v[32:47]
	s_waitcnt lgkmcnt(4)
	v_mfma_f32_32x32x16_bf16 v[16:31], a[0:3], a[12:15], v[16:31]
	v_mfma_f32_32x32x16_bf16 v[0:15], a[4:7], a[12:15], v[0:15]
	s_waitcnt lgkmcnt(1)
	v_mfma_f32_32x32x16_bf16 v[48:63], a[16:19], a[24:27], v[48:63]
	v_mfma_f32_32x32x16_bf16 v[32:47], a[20:23], a[24:27], v[32:47]
	s_waitcnt vmcnt(6)
	s_waitcnt lgkmcnt(0)
	s_barrier
	ds_read_b128 a[12:15], v78 offset:4096
	ds_read_b128 a[8:11], v78
	ds_read_b128 a[4:7], v79 offset:36864
	ds_read_b128 a[0:3], v79 offset:32768
	v_mfma_f32_32x32x16_bf16 v[16:31], a[16:19], a[28:31], v[16:31]
	v_lshl_add_u64 v[116:117], v[66:67], 0, s[30:31]
	s_mov_b64 s[30:31], 0x2004580
	global_load_lds_dwordx4 v[116:117], off
	v_lshl_add_u64 v[116:117], v[68:69], 0, s[30:31]
	s_mov_b32 m0, s36
	s_mov_b64 s[30:31], 0x2008580
	global_load_lds_dwordx4 v[116:117], off
	v_lshl_add_u64 v[110:111], v[66:67], 0, s[30:31]
	s_mov_b32 m0, s37
	s_mov_b64 s[30:31], 0x200c580
	global_load_lds_dwordx4 v[110:111], off
	v_lshl_add_u64 v[110:111], v[68:69], 0, s[30:31]
	s_mov_b32 m0, s38
	s_mov_b64 s[30:31], 0x580
	global_load_lds_dwordx4 v[110:111], off
	v_lshl_add_u64 v[110:111], v[70:71], 0, s[30:31]
	s_mov_b32 m0, s39
	v_mfma_f32_32x32x16_bf16 v[0:15], a[20:23], a[28:31], v[0:15]
	global_load_lds_dwordx4 v[110:111], off
	v_lshl_add_u64 v[110:111], v[72:73], 0, s[30:31]
	s_mov_b32 m0, s40
	s_mov_b64 s[30:31], 0x2000600
	global_load_lds_dwordx4 v[110:111], off
	ds_read_b128 a[16:19], v81 offset:32768
	ds_read_b128 a[20:23], v81 offset:36864
	ds_read_b128 a[24:27], v80
	ds_read_b128 a[28:31], v80 offset:4096
	s_waitcnt lgkmcnt(4)
	v_mfma_f32_32x32x16_bf16 v[48:63], a[0:3], a[8:11], v[48:63]
	s_mov_b32 m0, s0
	v_mfma_f32_32x32x16_bf16 v[32:47], a[4:7], a[8:11], v[32:47]
	v_mfma_f32_32x32x16_bf16 v[16:31], a[0:3], a[12:15], v[16:31]
	v_mfma_f32_32x32x16_bf16 v[0:15], a[4:7], a[12:15], v[0:15]
	ds_read_b128 a[0:3], v83 offset:32768
	ds_read_b128 a[4:7], v83 offset:36864
	ds_read_b128 a[8:11], v82
	ds_read_b128 a[12:15], v82 offset:4096
	s_waitcnt lgkmcnt(5)
	v_mfma_f32_32x32x16_bf16 v[48:63], a[16:19], a[24:27], v[48:63]
	v_mfma_f32_32x32x16_bf16 v[32:47], a[20:23], a[24:27], v[32:47]
	s_waitcnt lgkmcnt(4)
	v_mfma_f32_32x32x16_bf16 v[16:31], a[16:19], a[28:31], v[16:31]
	v_mfma_f32_32x32x16_bf16 v[0:15], a[20:23], a[28:31], v[0:15]
	ds_read_b128 a[16:19], v85 offset:32768
	ds_read_b128 a[20:23], v85 offset:36864
	ds_read_b128 a[24:27], v84
	ds_read_b128 a[28:31], v84 offset:4096
	s_waitcnt lgkmcnt(5)
	v_mfma_f32_32x32x16_bf16 v[48:63], a[0:3], a[8:11], v[48:63]
	v_mfma_f32_32x32x16_bf16 v[32:47], a[4:7], a[8:11], v[32:47]
	s_waitcnt lgkmcnt(4)
	v_mfma_f32_32x32x16_bf16 v[16:31], a[0:3], a[12:15], v[16:31]
	v_mfma_f32_32x32x16_bf16 v[0:15], a[4:7], a[12:15], v[0:15]
	s_waitcnt lgkmcnt(1)
	v_mfma_f32_32x32x16_bf16 v[48:63], a[16:19], a[24:27], v[48:63]
	v_mfma_f32_32x32x16_bf16 v[32:47], a[20:23], a[24:27], v[32:47]
	s_waitcnt vmcnt(6)
	s_waitcnt lgkmcnt(0)
	s_barrier
	ds_read_b128 a[12:15], v78 offset:53248
	ds_read_b128 a[8:11], v78 offset:49152
	ds_read_b128 a[4:7], v86
	ds_read_b128 a[0:3], v88
	v_mfma_f32_32x32x16_bf16 v[16:31], a[16:19], a[28:31], v[16:31]
	v_lshl_add_u64 v[110:111], v[66:67], 0, s[30:31]
	s_mov_b64 s[30:31], 0x2004600
	global_load_lds_dwordx4 v[110:111], off
	v_lshl_add_u64 v[110:111], v[68:69], 0, s[30:31]
	s_mov_b32 m0, s1
	s_mov_b64 s[30:31], 0x2008600
	global_load_lds_dwordx4 v[110:111], off
	v_lshl_add_u64 v[110:111], v[66:67], 0, s[30:31]
	s_mov_b32 m0, s2
	s_mov_b64 s[30:31], 0x200c600
	global_load_lds_dwordx4 v[110:111], off
	v_lshl_add_u64 v[110:111], v[68:69], 0, s[30:31]
	s_mov_b32 m0, s20
	s_mov_b64 s[30:31], 0x600
	global_load_lds_dwordx4 v[110:111], off
	v_lshl_add_u64 v[110:111], v[70:71], 0, s[30:31]
	s_mov_b32 m0, s21
	v_mfma_f32_32x32x16_bf16 v[0:15], a[20:23], a[28:31], v[0:15]
	global_load_lds_dwordx4 v[110:111], off
	v_lshl_add_u64 v[110:111], v[72:73], 0, s[30:31]
	s_mov_b32 m0, s22
	s_mov_b64 s[30:31], 0x2000680
	global_load_lds_dwordx4 v[110:111], off
	ds_read_b128 a[16:19], v89
	ds_read_b128 a[20:23], v87
	ds_read_b128 a[24:27], v80 offset:49152
	ds_read_b128 a[28:31], v80 offset:53248
	s_waitcnt lgkmcnt(4)
	v_mfma_f32_32x32x16_bf16 v[48:63], a[0:3], a[8:11], v[48:63]
	s_mov_b32 m0, s23
	v_mfma_f32_32x32x16_bf16 v[32:47], a[4:7], a[8:11], v[32:47]
	v_mfma_f32_32x32x16_bf16 v[16:31], a[0:3], a[12:15], v[16:31]
	v_mfma_f32_32x32x16_bf16 v[0:15], a[4:7], a[12:15], v[0:15]
	ds_read_b128 a[0:3], v91
	ds_read_b128 a[4:7], v90
	ds_read_b128 a[8:11], v82 offset:49152
	ds_read_b128 a[12:15], v82 offset:53248
	s_waitcnt lgkmcnt(5)
	v_mfma_f32_32x32x16_bf16 v[48:63], a[16:19], a[24:27], v[48:63]
	v_mfma_f32_32x32x16_bf16 v[32:47], a[20:23], a[24:27], v[32:47]
	s_waitcnt lgkmcnt(4)
	v_mfma_f32_32x32x16_bf16 v[16:31], a[16:19], a[28:31], v[16:31]
	v_mfma_f32_32x32x16_bf16 v[0:15], a[20:23], a[28:31], v[0:15]
	ds_read_b128 a[16:19], v93
	ds_read_b128 a[20:23], v92
	ds_read_b128 a[24:27], v84 offset:49152
	ds_read_b128 a[28:31], v84 offset:53248
	s_waitcnt lgkmcnt(5)
	v_mfma_f32_32x32x16_bf16 v[48:63], a[0:3], a[8:11], v[48:63]
	v_mfma_f32_32x32x16_bf16 v[32:47], a[4:7], a[8:11], v[32:47]
	s_waitcnt lgkmcnt(4)
	v_mfma_f32_32x32x16_bf16 v[16:31], a[0:3], a[12:15], v[16:31]
	v_mfma_f32_32x32x16_bf16 v[0:15], a[4:7], a[12:15], v[0:15]
	s_waitcnt lgkmcnt(1)
	v_mfma_f32_32x32x16_bf16 v[48:63], a[16:19], a[24:27], v[48:63]
	v_mfma_f32_32x32x16_bf16 v[32:47], a[20:23], a[24:27], v[32:47]
	s_waitcnt vmcnt(6)
	s_waitcnt lgkmcnt(0)
	s_barrier
	ds_read_b128 a[12:15], v97
	ds_read_b128 a[8:11], v96
	ds_read_b128 a[4:7], v95
	ds_read_b128 a[0:3], v94
	v_mfma_f32_32x32x16_bf16 v[16:31], a[16:19], a[28:31], v[16:31]
	v_lshl_add_u64 v[110:111], v[66:67], 0, s[30:31]
	s_mov_b64 s[30:31], 0x2004680
	global_load_lds_dwordx4 v[110:111], off
	v_lshl_add_u64 v[110:111], v[68:69], 0, s[30:31]
	s_mov_b32 m0, s24
	s_mov_b64 s[30:31], 0x2008680
	global_load_lds_dwordx4 v[110:111], off
	v_lshl_add_u64 v[110:111], v[66:67], 0, s[30:31]
	s_mov_b32 m0, s28
	s_mov_b64 s[30:31], 0x200c680
	global_load_lds_dwordx4 v[110:111], off
	v_lshl_add_u64 v[110:111], v[68:69], 0, s[30:31]
	s_mov_b32 m0, s29
	s_mov_b64 s[28:29], 0x680
	global_load_lds_dwordx4 v[110:111], off
	v_lshl_add_u64 v[110:111], v[70:71], 0, s[28:29]
	s_mov_b32 m0, s33
	v_mfma_f32_32x32x16_bf16 v[0:15], a[20:23], a[28:31], v[0:15]
	global_load_lds_dwordx4 v[110:111], off
	v_lshl_add_u64 v[110:111], v[72:73], 0, s[28:29]
	s_mov_b32 m0, s34
	s_mov_b64 s[28:29], 0x2000700
	global_load_lds_dwordx4 v[110:111], off
	ds_read_b128 a[16:19], v98
	ds_read_b128 a[20:23], v99
	ds_read_b128 a[24:27], v100
	ds_read_b128 a[28:31], v101
	s_waitcnt lgkmcnt(4)
	v_mfma_f32_32x32x16_bf16 v[48:63], a[0:3], a[8:11], v[48:63]
	s_mov_b32 m0, s35
	v_mfma_f32_32x32x16_bf16 v[32:47], a[4:7], a[8:11], v[32:47]
	v_mfma_f32_32x32x16_bf16 v[16:31], a[0:3], a[12:15], v[16:31]
	v_mfma_f32_32x32x16_bf16 v[0:15], a[4:7], a[12:15], v[0:15]
	ds_read_b128 a[0:3], v102
	ds_read_b128 a[4:7], v103
	ds_read_b128 a[8:11], v104
	ds_read_b128 a[12:15], v105
	s_waitcnt lgkmcnt(5)
	v_mfma_f32_32x32x16_bf16 v[48:63], a[16:19], a[24:27], v[48:63]
	v_mfma_f32_32x32x16_bf16 v[32:47], a[20:23], a[24:27], v[32:47]
	s_waitcnt lgkmcnt(4)
	v_mfma_f32_32x32x16_bf16 v[16:31], a[16:19], a[28:31], v[16:31]
	v_mfma_f32_32x32x16_bf16 v[0:15], a[20:23], a[28:31], v[0:15]
	ds_read_b128 a[16:19], v106
	ds_read_b128 a[20:23], v107
	ds_read_b128 a[24:27], v108
	ds_read_b128 a[28:31], v109
	s_waitcnt lgkmcnt(5)
	v_mfma_f32_32x32x16_bf16 v[48:63], a[0:3], a[8:11], v[48:63]
	v_mfma_f32_32x32x16_bf16 v[32:47], a[4:7], a[8:11], v[32:47]
	s_waitcnt lgkmcnt(4)
	v_mfma_f32_32x32x16_bf16 v[16:31], a[0:3], a[12:15], v[16:31]
	v_mfma_f32_32x32x16_bf16 v[0:15], a[4:7], a[12:15], v[0:15]
	s_waitcnt lgkmcnt(1)
	v_mfma_f32_32x32x16_bf16 v[48:63], a[16:19], a[24:27], v[48:63]
	v_mfma_f32_32x32x16_bf16 v[32:47], a[20:23], a[24:27], v[32:47]
	s_waitcnt vmcnt(6)
	s_waitcnt lgkmcnt(0)
	s_barrier
	ds_read_b128 a[12:15], v78 offset:4096
	ds_read_b128 a[8:11], v78
	ds_read_b128 a[4:7], v79 offset:36864
	ds_read_b128 a[0:3], v79 offset:32768
	v_mfma_f32_32x32x16_bf16 v[16:31], a[16:19], a[28:31], v[16:31]
	v_lshl_add_u64 v[110:111], v[66:67], 0, s[28:29]
	s_mov_b64 s[28:29], 0x2004700
	global_load_lds_dwordx4 v[110:111], off
	v_lshl_add_u64 v[110:111], v[68:69], 0, s[28:29]
	s_mov_b32 m0, s36
	s_mov_b64 s[28:29], 0x2008700
	global_load_lds_dwordx4 v[110:111], off
	v_lshl_add_u64 v[110:111], v[66:67], 0, s[28:29]
	s_mov_b32 m0, s37
	s_mov_b64 s[28:29], 0x200c700
	global_load_lds_dwordx4 v[110:111], off
	v_lshl_add_u64 v[110:111], v[68:69], 0, s[28:29]
	s_mov_b32 m0, s38
	s_mov_b64 s[28:29], 0x700
	global_load_lds_dwordx4 v[110:111], off
	v_lshl_add_u64 v[110:111], v[70:71], 0, s[28:29]
	s_mov_b32 m0, s39
	v_mfma_f32_32x32x16_bf16 v[0:15], a[20:23], a[28:31], v[0:15]
	global_load_lds_dwordx4 v[110:111], off
	v_lshl_add_u64 v[110:111], v[72:73], 0, s[28:29]
	s_mov_b32 m0, s40
	s_mov_b64 s[28:29], 0x2000780
	global_load_lds_dwordx4 v[110:111], off
	ds_read_b128 a[16:19], v81 offset:32768
	ds_read_b128 a[20:23], v81 offset:36864
	ds_read_b128 a[24:27], v80
	ds_read_b128 a[28:31], v80 offset:4096
	s_waitcnt lgkmcnt(4)
	v_mfma_f32_32x32x16_bf16 v[48:63], a[0:3], a[8:11], v[48:63]
	s_mov_b32 m0, s0
	v_mfma_f32_32x32x16_bf16 v[32:47], a[4:7], a[8:11], v[32:47]
	v_mfma_f32_32x32x16_bf16 v[16:31], a[0:3], a[12:15], v[16:31]
	v_mfma_f32_32x32x16_bf16 v[0:15], a[4:7], a[12:15], v[0:15]
	ds_read_b128 a[0:3], v83 offset:32768
	ds_read_b128 a[4:7], v83 offset:36864
	ds_read_b128 a[8:11], v82
	ds_read_b128 a[12:15], v82 offset:4096
	s_waitcnt lgkmcnt(5)
	v_mfma_f32_32x32x16_bf16 v[48:63], a[16:19], a[24:27], v[48:63]
	v_mfma_f32_32x32x16_bf16 v[32:47], a[20:23], a[24:27], v[32:47]
	s_waitcnt lgkmcnt(4)
	v_mfma_f32_32x32x16_bf16 v[16:31], a[16:19], a[28:31], v[16:31]
	v_mfma_f32_32x32x16_bf16 v[0:15], a[20:23], a[28:31], v[0:15]
	ds_read_b128 a[16:19], v85 offset:32768
	ds_read_b128 a[20:23], v85 offset:36864
	ds_read_b128 a[24:27], v84
	ds_read_b128 a[28:31], v84 offset:4096
	s_waitcnt lgkmcnt(5)
	v_mfma_f32_32x32x16_bf16 v[48:63], a[0:3], a[8:11], v[48:63]
	v_mfma_f32_32x32x16_bf16 v[32:47], a[4:7], a[8:11], v[32:47]
	s_waitcnt lgkmcnt(4)
	v_mfma_f32_32x32x16_bf16 v[16:31], a[0:3], a[12:15], v[16:31]
	v_mfma_f32_32x32x16_bf16 v[0:15], a[4:7], a[12:15], v[0:15]
	s_waitcnt lgkmcnt(1)
	v_mfma_f32_32x32x16_bf16 v[48:63], a[16:19], a[24:27], v[48:63]
	v_mfma_f32_32x32x16_bf16 v[32:47], a[20:23], a[24:27], v[32:47]
	s_waitcnt vmcnt(6)
	s_waitcnt lgkmcnt(0)
	s_barrier
	ds_read_b128 a[12:15], v78 offset:53248
	ds_read_b128 a[8:11], v78 offset:49152
	ds_read_b128 a[4:7], v86
	ds_read_b128 a[0:3], v88
	v_mfma_f32_32x32x16_bf16 v[16:31], a[16:19], a[28:31], v[16:31]
	v_lshl_add_u64 v[110:111], v[66:67], 0, s[28:29]
	s_mov_b64 s[28:29], 0x2004780
	global_load_lds_dwordx4 v[110:111], off
	v_lshl_add_u64 v[110:111], v[68:69], 0, s[28:29]
	s_mov_b32 m0, s1
	s_mov_b64 s[0:1], 0x2008780
	global_load_lds_dwordx4 v[110:111], off
	v_lshl_add_u64 v[66:67], v[66:67], 0, s[0:1]
	s_mov_b32 m0, s2
	s_mov_b64 s[0:1], 0x200c780
	global_load_lds_dwordx4 v[66:67], off
	v_lshl_add_u64 v[66:67], v[68:69], 0, s[0:1]
	s_mov_b32 m0, s20
	s_mov_b64 s[0:1], 0x780
	global_load_lds_dwordx4 v[66:67], off
	v_lshl_add_u64 v[66:67], v[70:71], 0, s[0:1]
	s_mov_b32 m0, s21
	v_mfma_f32_32x32x16_bf16 v[0:15], a[20:23], a[28:31], v[0:15]
	global_load_lds_dwordx4 v[66:67], off
	v_lshl_add_u64 v[66:67], v[72:73], 0, s[0:1]
	s_mov_b32 m0, s22
	v_readlane_b32 s0, v215, 52
	global_load_lds_dwordx4 v[66:67], off
	s_nop 0
	s_nop 0
	s_nop 0
	ds_read_b128 a[16:19], v89
	ds_read_b128 a[20:23], v87
	ds_read_b128 a[24:27], v80 offset:49152
	ds_read_b128 a[28:31], v80 offset:53248
	s_waitcnt lgkmcnt(4)
	v_mfma_f32_32x32x16_bf16 v[48:63], a[0:3], a[8:11], v[48:63]
	v_readlane_b32 s1, v215, 53
	s_mov_b32 s2, 0
	v_mfma_f32_32x32x16_bf16 v[32:47], a[4:7], a[8:11], v[32:47]
	v_mfma_f32_32x32x16_bf16 v[16:31], a[0:3], a[12:15], v[16:31]
	v_mfma_f32_32x32x16_bf16 v[0:15], a[4:7], a[12:15], v[0:15]
	ds_read_b128 a[0:3], v91
	ds_read_b128 a[4:7], v90
	ds_read_b128 a[8:11], v82 offset:49152
	ds_read_b128 a[12:15], v82 offset:53248
	s_waitcnt lgkmcnt(5)
	v_mfma_f32_32x32x16_bf16 v[48:63], a[16:19], a[24:27], v[48:63]
	v_mfma_f32_32x32x16_bf16 v[32:47], a[20:23], a[24:27], v[32:47]
	s_waitcnt lgkmcnt(4)
	v_mfma_f32_32x32x16_bf16 v[16:31], a[16:19], a[28:31], v[16:31]
	v_mfma_f32_32x32x16_bf16 v[0:15], a[20:23], a[28:31], v[0:15]
	ds_read_b128 a[16:19], v93
	ds_read_b128 a[20:23], v92
	ds_read_b128 a[24:27], v84 offset:49152
	ds_read_b128 a[28:31], v84 offset:53248
	s_waitcnt lgkmcnt(5)
	v_mfma_f32_32x32x16_bf16 v[48:63], a[0:3], a[8:11], v[48:63]
	v_mfma_f32_32x32x16_bf16 v[32:47], a[4:7], a[8:11], v[32:47]
	s_waitcnt lgkmcnt(4)
	v_mfma_f32_32x32x16_bf16 v[16:31], a[0:3], a[12:15], v[16:31]
	v_mfma_f32_32x32x16_bf16 v[0:15], a[4:7], a[12:15], v[0:15]
	s_waitcnt lgkmcnt(1)
	v_mfma_f32_32x32x16_bf16 v[48:63], a[16:19], a[24:27], v[48:63]
	v_mfma_f32_32x32x16_bf16 v[32:47], a[20:23], a[24:27], v[32:47]
	s_waitcnt vmcnt(6)
	s_waitcnt lgkmcnt(0)
	s_barrier
	ds_read_b128 a[12:15], v97
	ds_read_b128 a[8:11], v96
	ds_read_b128 a[4:7], v95
	ds_read_b128 a[0:3], v94
	v_mfma_f32_32x32x16_bf16 v[16:31], a[16:19], a[28:31], v[16:31]
	v_mfma_f32_32x32x16_bf16 v[0:15], a[20:23], a[28:31], v[0:15]
	ds_read_b128 a[16:19], v98
	ds_read_b128 a[20:23], v99
	ds_read_b128 a[24:27], v100
	ds_read_b128 a[28:31], v101
	s_waitcnt lgkmcnt(4)
	v_mfma_f32_32x32x16_bf16 v[48:63], a[0:3], a[8:11], v[48:63]
	v_mfma_f32_32x32x16_bf16 v[32:47], a[4:7], a[8:11], v[32:47]
	v_mfma_f32_32x32x16_bf16 v[16:31], a[0:3], a[12:15], v[16:31]
	v_mfma_f32_32x32x16_bf16 v[0:15], a[4:7], a[12:15], v[0:15]
	ds_read_b128 a[0:3], v102
	ds_read_b128 a[4:7], v103
	ds_read_b128 a[8:11], v104
	ds_read_b128 a[12:15], v105
	s_waitcnt lgkmcnt(5)
	v_mfma_f32_32x32x16_bf16 v[48:63], a[16:19], a[24:27], v[48:63]
	v_mfma_f32_32x32x16_bf16 v[32:47], a[20:23], a[24:27], v[32:47]
	s_waitcnt lgkmcnt(4)
	v_mfma_f32_32x32x16_bf16 v[16:31], a[16:19], a[28:31], v[16:31]
	v_mfma_f32_32x32x16_bf16 v[0:15], a[20:23], a[28:31], v[0:15]
	ds_read_b128 a[16:19], v106
	ds_read_b128 a[20:23], v107
	ds_read_b128 a[24:27], v108
	ds_read_b128 a[28:31], v109
	s_waitcnt lgkmcnt(5)
	v_mfma_f32_32x32x16_bf16 v[48:63], a[0:3], a[8:11], v[48:63]
	v_mfma_f32_32x32x16_bf16 v[32:47], a[4:7], a[8:11], v[32:47]
	s_waitcnt lgkmcnt(4)
	v_mfma_f32_32x32x16_bf16 v[16:31], a[0:3], a[12:15], v[16:31]
	v_mfma_f32_32x32x16_bf16 v[0:15], a[4:7], a[12:15], v[0:15]
	s_waitcnt lgkmcnt(1)
	v_mfma_f32_32x32x16_bf16 v[48:63], a[16:19], a[24:27], v[48:63]
	v_mfma_f32_32x32x16_bf16 v[32:47], a[20:23], a[24:27], v[32:47]
	s_waitcnt vmcnt(0)
	s_waitcnt lgkmcnt(0)
	s_barrier
	ds_read_b128 a[12:15], v78 offset:4096
	ds_read_b128 a[8:11], v78
	ds_read_b128 a[4:7], v79 offset:36864
	ds_read_b128 a[0:3], v79 offset:32768
	v_mfma_f32_32x32x16_bf16 v[16:31], a[16:19], a[28:31], v[16:31]
	v_mfma_f32_32x32x16_bf16 v[0:15], a[20:23], a[28:31], v[0:15]
	ds_read_b128 a[16:19], v81 offset:32768
	ds_read_b128 a[20:23], v81 offset:36864
	ds_read_b128 a[24:27], v80
	ds_read_b128 a[28:31], v80 offset:4096
	s_waitcnt lgkmcnt(4)
	v_mfma_f32_32x32x16_bf16 v[48:63], a[0:3], a[8:11], v[48:63]
	v_mfma_f32_32x32x16_bf16 v[32:47], a[4:7], a[8:11], v[32:47]
	v_mfma_f32_32x32x16_bf16 v[16:31], a[0:3], a[12:15], v[16:31]
	v_mfma_f32_32x32x16_bf16 v[0:15], a[4:7], a[12:15], v[0:15]
	ds_read_b128 a[0:3], v83 offset:32768
	ds_read_b128 a[4:7], v83 offset:36864
	ds_read_b128 a[8:11], v82
	ds_read_b128 a[12:15], v82 offset:4096
	s_waitcnt lgkmcnt(5)
	v_mfma_f32_32x32x16_bf16 v[48:63], a[16:19], a[24:27], v[48:63]
	v_mfma_f32_32x32x16_bf16 v[32:47], a[20:23], a[24:27], v[32:47]
	s_waitcnt lgkmcnt(4)
	v_mfma_f32_32x32x16_bf16 v[16:31], a[16:19], a[28:31], v[16:31]
	v_mfma_f32_32x32x16_bf16 v[0:15], a[20:23], a[28:31], v[0:15]
	s_waitcnt lgkmcnt(1)
	v_mfma_f32_32x32x16_bf16 v[48:63], a[0:3], a[8:11], v[48:63]
	v_mfma_f32_32x32x16_bf16 v[32:47], a[4:7], a[8:11], v[32:47]
	s_waitcnt lgkmcnt(0)
	v_mfma_f32_32x32x16_bf16 v[0:15], a[4:7], a[12:15], v[0:15]
	v_mfma_f32_32x32x16_bf16 v[16:31], a[0:3], a[12:15], v[16:31]
	ds_read_b128 v[66:69], v85 offset:32768
	ds_read_b128 v[70:73], v84
	ds_read_b128 v[78:81], v85 offset:36864
	ds_read_b128 v[82:85], v84 offset:4096
	s_waitcnt lgkmcnt(0)
	s_barrier
	s_waitcnt lgkmcnt(0)
	v_mfma_f32_32x32x16_bf16 v[48:63], v[66:69], v[70:73], v[48:63]
	v_mfma_f32_32x32x16_bf16 v[32:47], v[78:81], v[70:73], v[32:47]
	s_nop 10
	ds_write_b128 v64, v[48:51]
	ds_write_b128 v64, v[52:55] offset:32
	ds_write_b128 v64, v[56:59] offset:64
	ds_write_b128 v64, v[60:63] offset:96
	ds_write_b128 v64, v[32:35] offset:128
	v_mfma_f32_32x32x16_bf16 v[0:15], v[78:81], v[82:85], v[0:15]
	v_mfma_f32_32x32x16_bf16 v[16:31], v[66:69], v[82:85], v[16:31]
	ds_write_b128 v64, v[36:39] offset:160
	ds_write_b128 v64, v[40:43] offset:192
	ds_write_b128 v64, v[44:47] offset:224
	s_nop 8
	ds_write_b128 v64, v[16:19] offset:16896
	ds_write_b128 v64, v[20:23] offset:16928
	ds_write_b128 v64, v[24:27] offset:16960
	ds_write_b128 v64, v[28:31] offset:16992
	ds_write_b128 v64, v[0:3] offset:17024
	ds_write_b128 v64, v[4:7] offset:17056
	ds_write_b128 v64, v[8:11] offset:17088
	ds_write_b128 v64, v[12:15] offset:17120
	s_waitcnt lgkmcnt(0)
	s_barrier
	v_lshl_or_b32 v0, v75, 2, s53
	v_ashrrev_i32_e32 v1, 31, v0
	v_lshl_add_u32 v4, v75, 4, 0
	v_lshl_add_u64 v[6:7], v[0:1], 2, s[92:93]
	v_lshl_add_u64 v[8:9], v[0:1], 1, s[0:1]
	v_cmp_eq_u32_e64 s[0:1], 0, v75
	s_branch .LBB0_244

.LBB0_585:
	s_and_b64 vcc, exec, s[0:1]
	s_cbranch_vccz .LBB0_518
	s_mul_hi_i32 s0, s33, 0x51eb851f
	s_lshr_b32 s1, s0, 31
	s_ashr_i32 s0, s0, 3
	v_mov_b32_e32 v78, v133
	s_add_i32 s21, s0, s1
	s_lshl_b32 s20, s21, 8
	v_ashrrev_i32_e32 v6, 6, v78
	v_bfe_u32 v7, v78, 3, 3
	v_lshl_or_b32 v8, v6, 5, v7
	v_add_u32_e32 v0, s20, v8
	s_waitcnt lgkmcnt(0)
	v_ashrrev_i32_e32 v1, 31, v0
	v_lshlrev_b64 v[2:3], 11, v[0:1]
	v_bfe_u32 v1, v78, 4, 2
	v_readlane_b32 s0, v215, 52
	v_xor_b32_e32 v1, v1, v78
	v_readlane_b32 s1, v215, 53
	v_lshlrev_b32_e32 v1, 4, v1
	v_and_b32_e32 v64, 0x70, v1
	v_lshl_add_u64 v[2:3], s[0:1], 0, v[2:3]
	v_or_b32_e32 v1, 8, v8
	v_lshl_add_u64 v[66:67], v[2:3], 0, v[64:65]
	v_add_u32_e32 v2, s20, v1
	v_lshrrev_b32_e32 v1, 1, v1
	v_xor_b32_e32 v1, v1, v78
	v_ashrrev_i32_e32 v3, 31, v2
	v_lshlrev_b32_e32 v1, 4, v1
	v_or_b32_e32 v0, 16, v0
	v_lshlrev_b64 v[2:3], 11, v[2:3]
	v_and_b32_e32 v4, 0x70, v1
	v_ashrrev_i32_e32 v1, 31, v0
	v_lshl_add_u64 v[2:3], s[0:1], 0, v[2:3]
	v_mov_b32_e32 v5, v65
	v_lshlrev_b64 v[0:1], 11, v[0:1]
	v_lshl_add_u64 v[68:69], v[2:3], 0, v[4:5]
	v_lshl_add_u64 v[0:1], s[0:1], 0, v[0:1]
	v_or_b32_e32 v2, 24, v8
	v_lshl_add_u64 v[70:71], v[0:1], 0, v[64:65]
	v_add_u32_e32 v0, s20, v2
	v_lshrrev_b32_e32 v2, 1, v2
	v_ashrrev_i32_e32 v1, 31, v0
	v_xor_b32_e32 v2, v2, v78
	v_lshlrev_b64 v[0:1], 11, v[0:1]
	v_lshlrev_b32_e32 v2, 4, v2
	v_lshl_add_u64 v[0:1], s[0:1], 0, v[0:1]
	v_and_b32_e32 v2, 0x70, v2
	v_mov_b32_e32 v3, v65
	v_lshl_or_b32 v4, v6, 4, v7
	s_mulk_i32 s21, 0xc80
	v_lshl_add_u64 v[72:73], v[0:1], 0, v[2:3]
	v_subrev_u32_e32 v0, s21, v4
	v_add_u32_e32 v0, s23, v0
	v_ashrrev_i32_e32 v1, 31, v0
	v_lshlrev_b64 v[2:3], 11, v[0:1]
	v_lshl_add_u64 v[2:3], s[96:97], 0, v[2:3]
	v_lshl_add_u64 v[74:75], v[2:3], 0, v[64:65]
	v_lshlrev_b32_e32 v3, 12, v6
	v_add_u32_e32 v126, 0, v3
	s_waitcnt vmcnt(0)
	v_add_u32_e32 v127, 0x400, v126
	v_readfirstlane_b32 s41, v126
	v_or_b32_e32 v2, 8, v4
	s_waitcnt lgkmcnt(0)
	s_barrier
	s_mov_b32 m0, s41
	v_readfirstlane_b32 s42, v127
	v_add_u32_e32 v128, 0x800, v126
	v_lshlrev_b32_e32 v5, 11, v6
	v_and_b32_e32 v79, 1, v6
	v_add_u32_e32 v0, 8, v0
	v_lshrrev_b32_e32 v2, 1, v2
	global_load_lds_dwordx4 v[66:67], off
	s_mov_b32 m0, s42
	v_readfirstlane_b32 s43, v128
	v_add_u32_e32 v129, 0xc00, v126
	v_add_u32_e32 v6, 0, v5
	v_ashrrev_i32_e32 v1, 31, v0
	v_xor_b32_e32 v2, v2, v78
	global_load_lds_dwordx4 v[68:69], off
	s_mov_b32 m0, s43
	v_readfirstlane_b32 s44, v129
	v_add_u32_e32 v131, 0x8000, v6
	v_lshlrev_b64 v[0:1], 11, v[0:1]
	v_lshlrev_b32_e32 v2, 4, v2
	global_load_lds_dwordx4 v[70:71], off
	s_mov_b32 m0, s44
	v_readfirstlane_b32 s45, v131
	v_add_u32_e32 v130, 0x8400, v6
	v_lshl_add_u64 v[0:1], s[96:97], 0, v[0:1]
	v_and_b32_e32 v64, 0x70, v2
	global_load_lds_dwordx4 v[72:73], off
	s_mov_b32 m0, s45
	v_readfirstlane_b32 s46, v130
	v_add_u32_e32 v120, 0xc000, v126
	v_lshl_add_u64 v[76:77], v[0:1], 0, v[64:65]
	global_load_lds_dwordx4 v[74:75], off
	s_mov_b32 m0, s46
	s_mov_b64 s[0:1], 0x80
	v_readfirstlane_b32 s35, v120
	v_add_u32_e32 v121, 0xc400, v126
	global_load_lds_dwordx4 v[76:77], off
	v_lshl_add_u64 v[0:1], v[66:67], 0, s[0:1]
	s_mov_b32 m0, s35
	v_readfirstlane_b32 s36, v121
	v_add_u32_e32 v122, 0xc800, v126
	global_load_lds_dwordx4 v[0:1], off
	v_lshl_add_u64 v[0:1], v[68:69], 0, s[0:1]
	s_mov_b32 m0, s36
	v_readfirstlane_b32 s37, v122
	v_add_u32_e32 v123, 0xcc00, v126
	global_load_lds_dwordx4 v[0:1], off
	v_lshl_add_u64 v[0:1], v[70:71], 0, s[0:1]
	s_mov_b32 m0, s37
	v_readfirstlane_b32 s38, v123
	v_add_u32_e32 v124, s85, v5
	global_load_lds_dwordx4 v[0:1], off
	v_lshl_add_u64 v[0:1], v[72:73], 0, s[0:1]
	s_mov_b32 m0, s38
	v_readfirstlane_b32 s39, v124
	v_add_u32_e32 v125, 0x14400, v6
	global_load_lds_dwordx4 v[0:1], off
	v_lshl_add_u64 v[0:1], v[74:75], 0, s[0:1]
	s_mov_b32 m0, s39
	v_readfirstlane_b32 s40, v125
	global_load_lds_dwordx4 v[0:1], off
	v_lshl_add_u64 v[0:1], v[76:77], 0, s[0:1]
	s_mov_b32 m0, s40
	v_lshrrev_b32_e32 v2, 1, v78
	v_bfe_u32 v64, v78, 5, 1
	global_load_lds_dwordx4 v[0:1], off
	v_add_u32_e32 v114, s3, v3
	v_bitop3_b32 v0, v2, v64, 7 bitop3:0x6c
	s_waitcnt vmcnt(6)
	s_mov_b64 s[30:31], 0x100
	v_readfirstlane_b32 s0, v114
	v_add_u32_e32 v115, 0x400, v114
	v_lshlrev_b32_e32 v132, 4, v0
	s_waitcnt lgkmcnt(0)
	s_barrier
	v_lshl_add_u64 v[0:1], v[66:67], 0, s[30:31]
	s_mov_b32 m0, s0
	v_readfirstlane_b32 s1, v115
	v_add_u32_e32 v116, 0x800, v114
	global_load_lds_dwordx4 v[0:1], off
	v_lshl_add_u64 v[0:1], v[68:69], 0, s[30:31]
	s_mov_b32 m0, s1
	v_readfirstlane_b32 s24, v116
	v_add_u32_e32 v117, 0xc00, v114
	v_readlane_b32 s29, v212, 31
	v_and_b32_e32 v81, 31, v78
	global_load_lds_dwordx4 v[0:1], off
	v_lshl_add_u64 v[0:1], v[70:71], 0, s[30:31]
	s_mov_b32 m0, s24
	v_readfirstlane_b32 s28, v117
	v_add_u32_e32 v118, s29, v5
	v_add_u32_e32 v2, s3, v5
	v_lshlrev_b32_e32 v4, 7, v81
	global_load_lds_dwordx4 v[0:1], off
	v_lshl_add_u64 v[0:1], v[72:73], 0, s[30:31]
	s_mov_b32 m0, s28
	v_readfirstlane_b32 s29, v118
	v_add_u32_e32 v119, 0x8400, v2
	v_lshl_or_b32 v102, v79, 13, v4
	global_load_lds_dwordx4 v[0:1], off
	v_lshl_add_u64 v[0:1], v[74:75], 0, s[30:31]
	s_mov_b32 m0, s29
	v_readfirstlane_b32 s34, v119
	global_load_lds_dwordx4 v[0:1], off
	v_lshl_add_u64 v[0:1], v[76:77], 0, s[30:31]
	s_mov_b32 m0, s34
	v_add_u32_e32 v100, 0, v102
	global_load_lds_dwordx4 v[0:1], off
	v_add_u32_e32 v83, v100, v132
	v_ashrrev_i32_e32 v80, 7, v78
	ds_read_b128 a[0:3], v83 offset:32768
	ds_read_b128 a[4:7], v83 offset:36864
	v_lshl_or_b32 v134, v80, 13, v4
	v_add_u32_e32 v101, 0, v134
	v_add_u32_e32 v82, v101, v132
	ds_read_b128 a[8:11], v82
	ds_read_b128 a[12:15], v82 offset:4096
	v_lshrrev_b32_e32 v182, 6, v133
	s_nop 0
	v_readfirstlane_b32 s32, v182
	s_waitcnt lgkmcnt(1)
	v_mfma_f32_32x32x16_bf16 v[48:63], a[0:3], a[8:11], 0
	v_bfe_u32 v103, v78, 1, 3
	s_mov_b64 s[30:31], 0x180
	v_or_b32_e32 v143, 0x8000, v102
	v_or_b32_e32 v144, 0x9000, v102
	v_add_u32_e32 v145, s3, v134
	s_mov_b64 s[80:81], 0x200
	s_waitcnt vmcnt(12)
	v_mfma_f32_32x32x16_bf16 v[32:47], a[4:7], a[8:11], 0
	s_waitcnt lgkmcnt(0)
	v_mfma_f32_32x32x16_bf16 v[16:31], a[0:3], a[12:15], 0
	v_bitop3_b32 v0, v64, v103, 2 bitop3:0x36
	v_lshlrev_b32_e32 v138, 4, v0
	v_add_u32_e32 v84, v101, v138
	ds_read_b128 a[28:31], v84 offset:4096
	ds_read_b128 a[24:27], v84
	v_add_u32_e32 v85, v100, v138
	ds_read_b128 a[20:23], v85 offset:36864
	ds_read_b128 a[16:19], v85 offset:32768
	v_mfma_f32_32x32x16_bf16 v[0:15], a[4:7], a[12:15], 0
	s_waitcnt lgkmcnt(0)
	v_mfma_f32_32x32x16_bf16 v[48:63], a[16:19], a[24:27], v[48:63]
	v_mfma_f32_32x32x16_bf16 v[32:47], a[20:23], a[24:27], v[32:47]
	v_mfma_f32_32x32x16_bf16 v[16:31], a[16:19], a[28:31], v[16:31]
	v_bitop3_b32 v86, v64, v103, 4 bitop3:0x36
	v_lshlrev_b32_e32 v139, 4, v86
	v_add_u32_e32 v86, v101, v139
	ds_read_b128 a[12:15], v86 offset:4096
	ds_read_b128 a[8:11], v86
	v_add_u32_e32 v87, v100, v139
	ds_read_b128 a[4:7], v87 offset:36864
	ds_read_b128 a[0:3], v87 offset:32768
	v_mfma_f32_32x32x16_bf16 v[0:15], a[20:23], a[28:31], v[0:15]
	s_waitcnt lgkmcnt(0)
	v_mfma_f32_32x32x16_bf16 v[48:63], a[0:3], a[8:11], v[48:63]
	v_mfma_f32_32x32x16_bf16 v[32:47], a[4:7], a[8:11], v[32:47]
	v_mfma_f32_32x32x16_bf16 v[16:31], a[0:3], a[12:15], v[16:31]
	v_bitop3_b32 v88, v64, v103, 6 bitop3:0x36
	v_lshlrev_b32_e32 v142, 4, v88
	v_add_u32_e32 v88, v101, v142
	ds_read_b128 a[28:31], v88 offset:4096
	ds_read_b128 a[24:27], v88
	v_add_u32_e32 v89, v100, v142
	ds_read_b128 a[20:23], v89 offset:36864
	ds_read_b128 a[16:19], v89 offset:32768
	v_mfma_f32_32x32x16_bf16 v[0:15], a[4:7], a[12:15], v[0:15]
	s_waitcnt lgkmcnt(0)
	v_mfma_f32_32x32x16_bf16 v[48:63], a[16:19], a[24:27], v[48:63]
	v_mfma_f32_32x32x16_bf16 v[32:47], a[20:23], a[24:27], v[32:47]
	s_waitcnt vmcnt(6)
	s_waitcnt lgkmcnt(0)
	s_barrier
	ds_read_b128 a[12:15], v82 offset:53248
	ds_read_b128 a[8:11], v82 offset:49152
	v_mfma_f32_32x32x16_bf16 v[16:31], a[16:19], a[28:31], v[16:31]
	v_lshl_add_u64 v[158:159], v[66:67], 0, s[30:31]
	v_lshl_add_u64 v[160:161], v[68:69], 0, s[30:31]
	v_lshl_add_u64 v[162:163], v[70:71], 0, s[30:31]
	v_mfma_f32_32x32x16_bf16 v[0:15], a[20:23], a[28:31], v[0:15]
	s_and_b32 m0, s32, 7
	s_lshl_b32 m0, m0, 12
	s_add_i32 m0, m0, 0x0
	s_nop 0
	global_load_lds_dwordx4 v[158:159], off
	v_lshl_add_u64 v[164:165], v[72:73], 0, s[30:31]
	v_lshl_add_u64 v[166:167], v[74:75], 0, s[30:31]
	v_lshl_add_u64 v[168:169], v[76:77], 0, s[30:31]
	s_add_i32 s30, 0, 0xc000
	v_add_u32_e32 v90, s30, v132
	v_add_u32_e32 v92, v90, v143
	v_add_u32_e32 v90, v90, v144
	ds_read_b128 a[4:7], v90
	ds_read_b128 a[0:3], v92
	v_add_u32_e32 v91, s30, v138
	v_add_u32_e32 v93, v91, v143
	ds_read_b128 a[16:19], v93
	v_add_u32_e32 v91, v91, v144
	ds_read_b128 a[20:23], v91
	ds_read_b128 a[24:27], v84 offset:49152
	ds_read_b128 a[28:31], v84 offset:53248
	s_waitcnt lgkmcnt(4)
	v_mfma_f32_32x32x16_bf16 v[48:63], a[0:3], a[8:11], v[48:63]
	v_mfma_f32_32x32x16_bf16 v[32:47], a[4:7], a[8:11], v[32:47]
	s_and_b32 m0, s32, 7
	s_lshl_b32 m0, m0, 12
	s_add_i32 m0, m0, 0x400
	s_nop 0
	global_load_lds_dwordx4 v[160:161], off
	v_mfma_f32_32x32x16_bf16 v[16:31], a[0:3], a[12:15], v[16:31]
	v_mfma_f32_32x32x16_bf16 v[0:15], a[4:7], a[12:15], v[0:15]
	s_and_b32 m0, s32, 7
	s_lshl_b32 m0, m0, 12
	s_add_i32 m0, m0, 0x800
	s_nop 0
	global_load_lds_dwordx4 v[162:163], off
	v_add_u32_e32 v94, s30, v139
	v_add_u32_e32 v95, v94, v143
	ds_read_b128 a[0:3], v95
	v_add_u32_e32 v94, v94, v144
	ds_read_b128 a[4:7], v94
	ds_read_b128 a[8:11], v86 offset:49152
	ds_read_b128 a[12:15], v86 offset:53248
	s_waitcnt lgkmcnt(5)
	v_mfma_f32_32x32x16_bf16 v[48:63], a[16:19], a[24:27], v[48:63]
	v_mfma_f32_32x32x16_bf16 v[32:47], a[20:23], a[24:27], v[32:47]
	s_and_b32 m0, s32, 7
	s_lshl_b32 m0, m0, 12
	s_add_i32 m0, m0, 0xc00
	s_nop 0
	global_load_lds_dwordx4 v[164:165], off
	s_waitcnt lgkmcnt(4)
	v_mfma_f32_32x32x16_bf16 v[16:31], a[16:19], a[28:31], v[16:31]
	v_mfma_f32_32x32x16_bf16 v[0:15], a[20:23], a[28:31], v[0:15]
	s_and_b32 m0, s32, 7
	s_lshl_b32 m0, m0, 11
	s_add_i32 m0, m0, 0x8000
	s_nop 0
	global_load_lds_dwordx4 v[166:167], off
	v_add_u32_e32 v96, s30, v142
	v_add_u32_e32 v97, v96, v143
	ds_read_b128 a[16:19], v97
	v_add_u32_e32 v96, v96, v144
	ds_read_b128 a[20:23], v96
	ds_read_b128 a[24:27], v88 offset:49152
	ds_read_b128 a[28:31], v88 offset:53248
	s_waitcnt lgkmcnt(5)
	v_mfma_f32_32x32x16_bf16 v[48:63], a[0:3], a[8:11], v[48:63]
	v_mfma_f32_32x32x16_bf16 v[32:47], a[4:7], a[8:11], v[32:47]
	s_and_b32 m0, s32, 7
	s_lshl_b32 m0, m0, 11
	s_add_i32 m0, m0, 0x8400
	s_nop 0
	global_load_lds_dwordx4 v[168:169], off
	s_waitcnt lgkmcnt(4)
	v_mfma_f32_32x32x16_bf16 v[16:31], a[0:3], a[12:15], v[16:31]
	s_mov_b64 s[30:31], 0x200
	v_mfma_f32_32x32x16_bf16 v[0:15], a[4:7], a[12:15], v[0:15]
	s_waitcnt lgkmcnt(1)
	v_mfma_f32_32x32x16_bf16 v[48:63], a[16:19], a[24:27], v[48:63]
	v_mfma_f32_32x32x16_bf16 v[32:47], a[20:23], a[24:27], v[32:47]
	s_waitcnt vmcnt(6)
	s_waitcnt lgkmcnt(0)
	s_barrier
	v_add_u32_e32 v100, v145, v132
	ds_read_b128 a[8:11], v100
	v_add_u32_e32 v101, s3, v132
	v_add_u32_e32 v99, v101, v144
	ds_read_b128 a[4:7], v99
	v_add_u32_e32 v98, v101, v143
	v_or_b32_e32 v132, 0x1000, v134
	v_add_u32_e32 v101, v101, v132
	ds_read_b128 a[12:15], v101
	ds_read_b128 a[0:3], v98
	v_mfma_f32_32x32x16_bf16 v[16:31], a[16:19], a[28:31], v[16:31]
	v_lshl_add_u64 v[170:171], v[66:67], 0, s[30:31]
	v_lshl_add_u64 v[172:173], v[68:69], 0, s[30:31]
	v_lshl_add_u64 v[174:175], v[70:71], 0, s[30:31]
	v_mfma_f32_32x32x16_bf16 v[0:15], a[20:23], a[28:31], v[0:15]
	s_and_b32 m0, s32, 7
	s_lshl_b32 m0, m0, 12
	s_add_i32 m0, m0, 0xc000
	s_nop 0
	global_load_lds_dwordx4 v[170:171], off
	v_lshl_add_u64 v[176:177], v[72:73], 0, s[30:31]
	v_lshl_add_u64 v[178:179], v[74:75], 0, s[30:31]
	v_lshl_add_u64 v[180:181], v[76:77], 0, s[30:31]
	s_mov_b64 s[30:31], 0x280
	v_add_u32_e32 v105, s3, v138
	v_add_u32_e32 v102, v105, v143
	ds_read_b128 a[16:19], v102
	v_add_u32_e32 v103, v105, v144
	ds_read_b128 a[20:23], v103
	v_add_u32_e32 v104, v145, v138
	ds_read_b128 a[24:27], v104
	v_add_u32_e32 v105, v105, v132
	ds_read_b128 a[28:31], v105
	s_waitcnt lgkmcnt(4)
	v_mfma_f32_32x32x16_bf16 v[48:63], a[0:3], a[8:11], v[48:63]
	v_mfma_f32_32x32x16_bf16 v[32:47], a[4:7], a[8:11], v[32:47]
	s_and_b32 m0, s32, 7
	s_lshl_b32 m0, m0, 12
	s_add_i32 m0, m0, 0xc400
	s_nop 0
	global_load_lds_dwordx4 v[172:173], off
	v_mfma_f32_32x32x16_bf16 v[16:31], a[0:3], a[12:15], v[16:31]
	v_mfma_f32_32x32x16_bf16 v[0:15], a[4:7], a[12:15], v[0:15]
	s_and_b32 m0, s32, 7
	s_lshl_b32 m0, m0, 12
	s_add_i32 m0, m0, 0xc800
	s_nop 0
	global_load_lds_dwordx4 v[174:175], off
	v_add_u32_e32 v109, s3, v139
	v_add_u32_e32 v106, v109, v143
	ds_read_b128 a[0:3], v106
	v_add_u32_e32 v107, v109, v144
	ds_read_b128 a[4:7], v107
	v_add_u32_e32 v108, v145, v139
	ds_read_b128 a[8:11], v108
	v_add_u32_e32 v109, v109, v132
	ds_read_b128 a[12:15], v109
	s_waitcnt lgkmcnt(5)
	v_mfma_f32_32x32x16_bf16 v[48:63], a[16:19], a[24:27], v[48:63]
	v_mfma_f32_32x32x16_bf16 v[32:47], a[20:23], a[24:27], v[32:47]
	s_and_b32 m0, s32, 7
	s_lshl_b32 m0, m0, 12
	s_add_i32 m0, m0, 0xcc00
	s_nop 0
	global_load_lds_dwordx4 v[176:177], off
	s_waitcnt lgkmcnt(4)
	v_mfma_f32_32x32x16_bf16 v[16:31], a[16:19], a[28:31], v[16:31]
	v_mfma_f32_32x32x16_bf16 v[0:15], a[20:23], a[28:31], v[0:15]
	s_and_b32 m0, s32, 7
	s_lshl_b32 m0, m0, 11
	s_add_i32 m0, m0, 0x14000
	s_nop 0
	global_load_lds_dwordx4 v[178:179], off
	v_add_u32_e32 v113, s3, v142
	v_add_u32_e32 v110, v113, v143
	ds_read_b128 a[16:19], v110
	v_add_u32_e32 v111, v113, v144
	ds_read_b128 a[20:23], v111
	v_add_u32_e32 v112, v145, v142
	ds_read_b128 a[24:27], v112
	v_add_u32_e32 v113, v113, v132
	ds_read_b128 a[28:31], v113
	s_waitcnt lgkmcnt(5)
	v_mfma_f32_32x32x16_bf16 v[48:63], a[0:3], a[8:11], v[48:63]
	v_mfma_f32_32x32x16_bf16 v[32:47], a[4:7], a[8:11], v[32:47]
	s_and_b32 m0, s32, 7
	s_lshl_b32 m0, m0, 11
	s_add_i32 m0, m0, 0x14400
	s_nop 0
	global_load_lds_dwordx4 v[180:181], off
	s_waitcnt lgkmcnt(4)
	v_mfma_f32_32x32x16_bf16 v[16:31], a[0:3], a[12:15], v[16:31]
	v_mfma_f32_32x32x16_bf16 v[0:15], a[4:7], a[12:15], v[0:15]
	s_waitcnt lgkmcnt(1)
	v_mfma_f32_32x32x16_bf16 v[48:63], a[16:19], a[24:27], v[48:63]
	v_mfma_f32_32x32x16_bf16 v[32:47], a[20:23], a[24:27], v[32:47]
	s_waitcnt vmcnt(6)
	s_waitcnt lgkmcnt(0)
	s_barrier
	ds_read_b128 a[12:15], v82 offset:4096
	ds_read_b128 a[8:11], v82
	ds_read_b128 a[4:7], v83 offset:36864
	ds_read_b128 a[0:3], v83 offset:32768
	v_mfma_f32_32x32x16_bf16 v[16:31], a[16:19], a[28:31], v[16:31]
	v_lshl_add_u64 v[158:159], v[66:67], 0, s[30:31]
	v_lshl_add_u64 v[160:161], v[68:69], 0, s[30:31]
	v_lshl_add_u64 v[162:163], v[70:71], 0, s[30:31]
	v_mfma_f32_32x32x16_bf16 v[0:15], a[20:23], a[28:31], v[0:15]
	s_and_b32 m0, s32, 7
	s_lshl_b32 m0, m0, 12
	s_add_i32 m0, m0, 0x18000
	s_nop 0
	global_load_lds_dwordx4 v[158:159], off
	v_lshl_add_u64 v[164:165], v[72:73], 0, s[30:31]
	v_lshl_add_u64 v[166:167], v[74:75], 0, s[30:31]
	v_lshl_add_u64 v[168:169], v[76:77], 0, s[30:31]
	s_mov_b64 s[30:31], 0x300
	ds_read_b128 a[16:19], v85 offset:32768
	ds_read_b128 a[20:23], v85 offset:36864
	ds_read_b128 a[24:27], v84
	ds_read_b128 a[28:31], v84 offset:4096
	s_waitcnt lgkmcnt(4)
	v_mfma_f32_32x32x16_bf16 v[48:63], a[0:3], a[8:11], v[48:63]
	s_nop 0
	v_readfirstlane_b32 s41, v114
	v_mfma_f32_32x32x16_bf16 v[32:47], a[4:7], a[8:11], v[32:47]
	s_and_b32 m0, s32, 7
	s_lshl_b32 m0, m0, 12
	s_add_i32 m0, m0, 0x18400
	s_nop 0
	global_load_lds_dwordx4 v[160:161], off
	v_mfma_f32_32x32x16_bf16 v[16:31], a[0:3], a[12:15], v[16:31]
	v_mfma_f32_32x32x16_bf16 v[0:15], a[4:7], a[12:15], v[0:15]
	s_and_b32 m0, s32, 7
	s_lshl_b32 m0, m0, 12
	s_add_i32 m0, m0, 0x18800
	s_nop 0
	global_load_lds_dwordx4 v[162:163], off
	ds_read_b128 a[0:3], v87 offset:32768
	ds_read_b128 a[4:7], v87 offset:36864
	ds_read_b128 a[8:11], v86
	ds_read_b128 a[12:15], v86 offset:4096
	s_waitcnt lgkmcnt(5)
	v_mfma_f32_32x32x16_bf16 v[48:63], a[16:19], a[24:27], v[48:63]
	v_mfma_f32_32x32x16_bf16 v[32:47], a[20:23], a[24:27], v[32:47]
	s_and_b32 m0, s32, 7
	s_lshl_b32 m0, m0, 12
	s_add_i32 m0, m0, 0x18c00
	s_nop 0
	global_load_lds_dwordx4 v[164:165], off
	s_waitcnt lgkmcnt(4)
	v_mfma_f32_32x32x16_bf16 v[16:31], a[16:19], a[28:31], v[16:31]
	v_mfma_f32_32x32x16_bf16 v[0:15], a[20:23], a[28:31], v[0:15]
	s_and_b32 m0, s32, 7
	s_lshl_b32 m0, m0, 11
	s_add_i32 m0, m0, 0x20000
	s_nop 0
	global_load_lds_dwordx4 v[166:167], off
	ds_read_b128 a[16:19], v89 offset:32768
	ds_read_b128 a[20:23], v89 offset:36864
	ds_read_b128 a[24:27], v88
	ds_read_b128 a[28:31], v88 offset:4096
	s_waitcnt lgkmcnt(5)
	v_mfma_f32_32x32x16_bf16 v[48:63], a[0:3], a[8:11], v[48:63]
	v_mfma_f32_32x32x16_bf16 v[32:47], a[4:7], a[8:11], v[32:47]
	s_and_b32 m0, s32, 7
	s_lshl_b32 m0, m0, 11
	s_add_i32 m0, m0, 0x20400
	s_nop 0
	global_load_lds_dwordx4 v[168:169], off
	s_waitcnt lgkmcnt(4)
	v_mfma_f32_32x32x16_bf16 v[16:31], a[0:3], a[12:15], v[16:31]
	v_mfma_f32_32x32x16_bf16 v[0:15], a[4:7], a[12:15], v[0:15]
	s_waitcnt lgkmcnt(1)
	v_mfma_f32_32x32x16_bf16 v[48:63], a[16:19], a[24:27], v[48:63]
	v_mfma_f32_32x32x16_bf16 v[32:47], a[20:23], a[24:27], v[32:47]
	s_waitcnt vmcnt(6)
	s_waitcnt lgkmcnt(0)
	s_barrier
	ds_read_b128 a[12:15], v82 offset:53248
	ds_read_b128 a[8:11], v82 offset:49152
	ds_read_b128 a[4:7], v90
	ds_read_b128 a[0:3], v92
	v_mfma_f32_32x32x16_bf16 v[16:31], a[16:19], a[28:31], v[16:31]
	v_lshl_add_u64 v[170:171], v[66:67], 0, s[30:31]
	v_lshl_add_u64 v[172:173], v[68:69], 0, s[30:31]
	s_nop 0
	v_readfirstlane_b32 s42, v115
	s_nop 0
	v_lshl_add_u64 v[174:175], v[70:71], 0, s[30:31]
	s_nop 0
	v_mfma_f32_32x32x16_bf16 v[0:15], a[20:23], a[28:31], v[0:15]
	s_and_b32 m0, s32, 7
	s_lshl_b32 m0, m0, 12
	s_add_i32 m0, m0, 0x0
	s_nop 0
	global_load_lds_dwordx4 v[170:171], off
	v_lshl_add_u64 v[176:177], v[72:73], 0, s[30:31]
	s_nop 0
	v_readfirstlane_b32 s43, v116
	s_nop 0
	v_lshl_add_u64 v[178:179], v[74:75], 0, s[30:31]
	s_nop 0
	v_readfirstlane_b32 s44, v117
	s_nop 0
	v_lshl_add_u64 v[180:181], v[76:77], 0, s[30:31]
	s_nop 0
	s_mov_b64 s[30:31], 0x380
	ds_read_b128 a[16:19], v93
	ds_read_b128 a[20:23], v91
	ds_read_b128 a[24:27], v84 offset:49152
	ds_read_b128 a[28:31], v84 offset:53248
	s_waitcnt lgkmcnt(4)
	v_mfma_f32_32x32x16_bf16 v[48:63], a[0:3], a[8:11], v[48:63]
	s_nop 0
	v_readfirstlane_b32 s35, v120
	v_readfirstlane_b32 s45, v118
	v_readfirstlane_b32 s46, v119
	v_mfma_f32_32x32x16_bf16 v[32:47], a[4:7], a[8:11], v[32:47]
	s_and_b32 m0, s32, 7
	s_lshl_b32 m0, m0, 12
	s_add_i32 m0, m0, 0x400
	s_nop 0
	global_load_lds_dwordx4 v[172:173], off
	v_mfma_f32_32x32x16_bf16 v[16:31], a[0:3], a[12:15], v[16:31]
	v_mfma_f32_32x32x16_bf16 v[0:15], a[4:7], a[12:15], v[0:15]
	s_and_b32 m0, s32, 7
	s_lshl_b32 m0, m0, 12
	s_add_i32 m0, m0, 0x800
	s_nop 0
	global_load_lds_dwordx4 v[174:175], off
	ds_read_b128 a[0:3], v95
	ds_read_b128 a[4:7], v94
	ds_read_b128 a[8:11], v86 offset:49152
	ds_read_b128 a[12:15], v86 offset:53248
	s_waitcnt lgkmcnt(5)
	v_mfma_f32_32x32x16_bf16 v[48:63], a[16:19], a[24:27], v[48:63]
	v_mfma_f32_32x32x16_bf16 v[32:47], a[20:23], a[24:27], v[32:47]
	s_and_b32 m0, s32, 7
	s_lshl_b32 m0, m0, 12
	s_add_i32 m0, m0, 0xc00
	s_nop 0
	global_load_lds_dwordx4 v[176:177], off
	s_waitcnt lgkmcnt(4)
	v_mfma_f32_32x32x16_bf16 v[16:31], a[16:19], a[28:31], v[16:31]
	v_mfma_f32_32x32x16_bf16 v[0:15], a[20:23], a[28:31], v[0:15]
	s_and_b32 m0, s32, 7
	s_lshl_b32 m0, m0, 11
	s_add_i32 m0, m0, 0x8000
	s_nop 0
	global_load_lds_dwordx4 v[178:179], off
	ds_read_b128 a[16:19], v97
	ds_read_b128 a[20:23], v96
	ds_read_b128 a[24:27], v88 offset:49152
	ds_read_b128 a[28:31], v88 offset:53248
	s_waitcnt lgkmcnt(5)
	v_mfma_f32_32x32x16_bf16 v[48:63], a[0:3], a[8:11], v[48:63]
	v_mfma_f32_32x32x16_bf16 v[32:47], a[4:7], a[8:11], v[32:47]
	s_and_b32 m0, s32, 7
	s_lshl_b32 m0, m0, 11
	s_add_i32 m0, m0, 0x8400
	s_nop 0
	global_load_lds_dwordx4 v[180:181], off
	s_waitcnt lgkmcnt(4)
	v_mfma_f32_32x32x16_bf16 v[16:31], a[0:3], a[12:15], v[16:31]
	v_mfma_f32_32x32x16_bf16 v[0:15], a[4:7], a[12:15], v[0:15]
	s_waitcnt lgkmcnt(1)
	v_mfma_f32_32x32x16_bf16 v[48:63], a[16:19], a[24:27], v[48:63]
	v_mfma_f32_32x32x16_bf16 v[32:47], a[20:23], a[24:27], v[32:47]
	s_waitcnt vmcnt(6)
	s_waitcnt lgkmcnt(0)
	s_barrier
	ds_read_b128 a[12:15], v101
	ds_read_b128 a[8:11], v100
	ds_read_b128 a[4:7], v99
	ds_read_b128 a[0:3], v98
	v_mfma_f32_32x32x16_bf16 v[16:31], a[16:19], a[28:31], v[16:31]
	v_lshl_add_u64 v[158:159], v[66:67], 0, s[30:31]
	v_lshl_add_u64 v[160:161], v[68:69], 0, s[30:31]
	s_nop 0
	v_readfirstlane_b32 s36, v121
	s_nop 0
	v_lshl_add_u64 v[162:163], v[70:71], 0, s[30:31]
	s_nop 0
	v_mfma_f32_32x32x16_bf16 v[0:15], a[20:23], a[28:31], v[0:15]
	s_and_b32 m0, s32, 7
	s_lshl_b32 m0, m0, 12
	s_add_i32 m0, m0, 0xc000
	s_nop 0
	global_load_lds_dwordx4 v[158:159], off
	v_lshl_add_u64 v[164:165], v[72:73], 0, s[30:31]
	s_nop 0
	v_readfirstlane_b32 s37, v122
	s_nop 0
	v_lshl_add_u64 v[166:167], v[74:75], 0, s[30:31]
	s_nop 0
	v_readfirstlane_b32 s38, v123
	s_nop 0
	v_lshl_add_u64 v[168:169], v[76:77], 0, s[30:31]
	s_nop 0
	s_mov_b64 s[30:31], 0x400
	ds_read_b128 a[16:19], v102
	ds_read_b128 a[20:23], v103
	ds_read_b128 a[24:27], v104
	ds_read_b128 a[28:31], v105
	s_waitcnt lgkmcnt(4)
	v_mfma_f32_32x32x16_bf16 v[48:63], a[0:3], a[8:11], v[48:63]
	s_nop 0
	v_readfirstlane_b32 s0, v126
	v_readfirstlane_b32 s39, v124
	v_readfirstlane_b32 s40, v125
	v_mfma_f32_32x32x16_bf16 v[32:47], a[4:7], a[8:11], v[32:47]
	s_and_b32 m0, s32, 7
	s_lshl_b32 m0, m0, 12
	s_add_i32 m0, m0, 0xc400
	s_nop 0
	global_load_lds_dwordx4 v[160:161], off
	v_mfma_f32_32x32x16_bf16 v[16:31], a[0:3], a[12:15], v[16:31]
	v_mfma_f32_32x32x16_bf16 v[0:15], a[4:7], a[12:15], v[0:15]
	s_and_b32 m0, s32, 7
	s_lshl_b32 m0, m0, 12
	s_add_i32 m0, m0, 0xc800
	s_nop 0
	global_load_lds_dwordx4 v[162:163], off
	ds_read_b128 a[0:3], v106
	ds_read_b128 a[4:7], v107
	ds_read_b128 a[8:11], v108
	ds_read_b128 a[12:15], v109
	s_waitcnt lgkmcnt(5)
	v_mfma_f32_32x32x16_bf16 v[48:63], a[16:19], a[24:27], v[48:63]
	v_mfma_f32_32x32x16_bf16 v[32:47], a[20:23], a[24:27], v[32:47]
	s_and_b32 m0, s32, 7
	s_lshl_b32 m0, m0, 12
	s_add_i32 m0, m0, 0xcc00
	s_nop 0
	global_load_lds_dwordx4 v[164:165], off
	s_waitcnt lgkmcnt(4)
	v_mfma_f32_32x32x16_bf16 v[16:31], a[16:19], a[28:31], v[16:31]
	v_mfma_f32_32x32x16_bf16 v[0:15], a[20:23], a[28:31], v[0:15]
	s_and_b32 m0, s32, 7
	s_lshl_b32 m0, m0, 11
	s_add_i32 m0, m0, 0x14000
	s_nop 0
	global_load_lds_dwordx4 v[166:167], off
	ds_read_b128 a[16:19], v110
	ds_read_b128 a[20:23], v111
	ds_read_b128 a[24:27], v112
	ds_read_b128 a[28:31], v113
	s_waitcnt lgkmcnt(5)
	v_mfma_f32_32x32x16_bf16 v[48:63], a[0:3], a[8:11], v[48:63]
	v_mfma_f32_32x32x16_bf16 v[32:47], a[4:7], a[8:11], v[32:47]
	s_and_b32 m0, s32, 7
	s_lshl_b32 m0, m0, 11
	s_add_i32 m0, m0, 0x14400
	s_nop 0
	global_load_lds_dwordx4 v[168:169], off
	s_waitcnt lgkmcnt(4)
	v_mfma_f32_32x32x16_bf16 v[16:31], a[0:3], a[12:15], v[16:31]
	v_mfma_f32_32x32x16_bf16 v[0:15], a[4:7], a[12:15], v[0:15]
	s_waitcnt lgkmcnt(1)
	v_mfma_f32_32x32x16_bf16 v[48:63], a[16:19], a[24:27], v[48:63]
	v_mfma_f32_32x32x16_bf16 v[32:47], a[20:23], a[24:27], v[32:47]
	s_waitcnt vmcnt(6)
	s_waitcnt lgkmcnt(0)
	s_barrier
	ds_read_b128 a[12:15], v82 offset:4096
	ds_read_b128 a[8:11], v82
	ds_read_b128 a[4:7], v83 offset:36864
	ds_read_b128 a[0:3], v83 offset:32768
	v_mfma_f32_32x32x16_bf16 v[16:31], a[16:19], a[28:31], v[16:31]
	v_lshl_add_u64 v[170:171], v[66:67], 0, s[30:31]
	v_lshl_add_u64 v[172:173], v[68:69], 0, s[30:31]
	s_nop 0
	v_readfirstlane_b32 s1, v127
	s_nop 0
	v_lshl_add_u64 v[174:175], v[70:71], 0, s[30:31]
	s_nop 0
	v_mfma_f32_32x32x16_bf16 v[0:15], a[20:23], a[28:31], v[0:15]
	s_and_b32 m0, s32, 7
	s_lshl_b32 m0, m0, 12
	s_add_i32 m0, m0, 0x18000
	s_nop 0
	global_load_lds_dwordx4 v[170:171], off
	v_lshl_add_u64 v[176:177], v[72:73], 0, s[30:31]
	s_nop 0
	v_readfirstlane_b32 s24, v128
	s_nop 0
	v_lshl_add_u64 v[178:179], v[74:75], 0, s[30:31]
	s_nop 0
	v_readfirstlane_b32 s28, v129
	s_nop 0
	v_lshl_add_u64 v[180:181], v[76:77], 0, s[30:31]
	s_nop 0
	s_mov_b64 s[30:31], 0x480
	ds_read_b128 a[16:19], v85 offset:32768
	ds_read_b128 a[20:23], v85 offset:36864
	ds_read_b128 a[24:27], v84
	ds_read_b128 a[28:31], v84 offset:4096
	s_waitcnt lgkmcnt(4)
	v_mfma_f32_32x32x16_bf16 v[48:63], a[0:3], a[8:11], v[48:63]
	s_nop 0
	v_lshl_add_u64 v[162:163], v[70:71], 0, s[30:31]
	v_readfirstlane_b32 s29, v131
	v_readfirstlane_b32 s34, v130
	v_mfma_f32_32x32x16_bf16 v[32:47], a[4:7], a[8:11], v[32:47]
	s_and_b32 m0, s32, 7
	s_lshl_b32 m0, m0, 12
	s_add_i32 m0, m0, 0x18400
	s_nop 0
	global_load_lds_dwordx4 v[172:173], off
	v_mfma_f32_32x32x16_bf16 v[16:31], a[0:3], a[12:15], v[16:31]
	v_mfma_f32_32x32x16_bf16 v[0:15], a[4:7], a[12:15], v[0:15]
	s_and_b32 m0, s32, 7
	s_lshl_b32 m0, m0, 12
	s_add_i32 m0, m0, 0x18800
	s_nop 0
	global_load_lds_dwordx4 v[174:175], off
	ds_read_b128 a[0:3], v87 offset:32768
	ds_read_b128 a[4:7], v87 offset:36864
	ds_read_b128 a[8:11], v86
	ds_read_b128 a[12:15], v86 offset:4096
	s_waitcnt lgkmcnt(5)
	v_mfma_f32_32x32x16_bf16 v[48:63], a[16:19], a[24:27], v[48:63]
	v_mfma_f32_32x32x16_bf16 v[32:47], a[20:23], a[24:27], v[32:47]
	s_and_b32 m0, s32, 7
	s_lshl_b32 m0, m0, 12
	s_add_i32 m0, m0, 0x18c00
	s_nop 0
	global_load_lds_dwordx4 v[176:177], off
	s_waitcnt lgkmcnt(4)
	v_mfma_f32_32x32x16_bf16 v[16:31], a[16:19], a[28:31], v[16:31]
	v_mfma_f32_32x32x16_bf16 v[0:15], a[20:23], a[28:31], v[0:15]
	s_and_b32 m0, s32, 7
	s_lshl_b32 m0, m0, 11
	s_add_i32 m0, m0, 0x20000
	s_nop 0
	global_load_lds_dwordx4 v[178:179], off
	ds_read_b128 a[16:19], v89 offset:32768
	ds_read_b128 a[20:23], v89 offset:36864
	ds_read_b128 a[24:27], v88
	ds_read_b128 a[28:31], v88 offset:4096
	s_waitcnt lgkmcnt(5)
	v_mfma_f32_32x32x16_bf16 v[48:63], a[0:3], a[8:11], v[48:63]
	v_mfma_f32_32x32x16_bf16 v[32:47], a[4:7], a[8:11], v[32:47]
	s_and_b32 m0, s32, 7
	s_lshl_b32 m0, m0, 11
	s_add_i32 m0, m0, 0x20400
	s_nop 0
	global_load_lds_dwordx4 v[180:181], off
	s_waitcnt lgkmcnt(4)
	v_mfma_f32_32x32x16_bf16 v[16:31], a[0:3], a[12:15], v[16:31]
	v_mfma_f32_32x32x16_bf16 v[0:15], a[4:7], a[12:15], v[0:15]
	s_waitcnt lgkmcnt(1)
	v_mfma_f32_32x32x16_bf16 v[48:63], a[16:19], a[24:27], v[48:63]
	v_mfma_f32_32x32x16_bf16 v[32:47], a[20:23], a[24:27], v[32:47]
	s_waitcnt vmcnt(6)
	s_waitcnt lgkmcnt(0)
	s_barrier
	ds_read_b128 a[12:15], v82 offset:53248
	ds_read_b128 a[8:11], v82 offset:49152
	ds_read_b128 a[4:7], v90
	ds_read_b128 a[0:3], v92
	v_mfma_f32_32x32x16_bf16 v[16:31], a[16:19], a[28:31], v[16:31]
	v_lshl_add_u64 v[158:159], v[66:67], 0, s[30:31]
	v_lshl_add_u64 v[160:161], v[68:69], 0, s[30:31]
	v_mfma_f32_32x32x16_bf16 v[0:15], a[20:23], a[28:31], v[0:15]
	s_and_b32 m0, s32, 7
	s_lshl_b32 m0, m0, 12
	s_add_i32 m0, m0, 0x0
	s_nop 0
	global_load_lds_dwordx4 v[158:159], off
	v_lshl_add_u64 v[164:165], v[72:73], 0, s[30:31]
	v_lshl_add_u64 v[166:167], v[74:75], 0, s[30:31]
	v_lshl_add_u64 v[168:169], v[76:77], 0, s[30:31]
	s_mov_b64 s[30:31], 0x500
	ds_read_b128 a[16:19], v93
	ds_read_b128 a[20:23], v91
	ds_read_b128 a[24:27], v84 offset:49152
	ds_read_b128 a[28:31], v84 offset:53248
	s_waitcnt lgkmcnt(4)
	v_mfma_f32_32x32x16_bf16 v[48:63], a[0:3], a[8:11], v[48:63]
	v_lshl_add_u64 v[174:175], v[70:71], 0, s[30:31]
	v_mfma_f32_32x32x16_bf16 v[32:47], a[4:7], a[8:11], v[32:47]
	s_and_b32 m0, s32, 7
	s_lshl_b32 m0, m0, 12
	s_add_i32 m0, m0, 0x400
	s_nop 0
	global_load_lds_dwordx4 v[160:161], off
	v_mfma_f32_32x32x16_bf16 v[16:31], a[0:3], a[12:15], v[16:31]
	v_mfma_f32_32x32x16_bf16 v[0:15], a[4:7], a[12:15], v[0:15]
	s_and_b32 m0, s32, 7
	s_lshl_b32 m0, m0, 12
	s_add_i32 m0, m0, 0x800
	s_nop 0
	global_load_lds_dwordx4 v[162:163], off
	ds_read_b128 a[0:3], v95
	ds_read_b128 a[4:7], v94
	ds_read_b128 a[8:11], v86 offset:49152
	ds_read_b128 a[12:15], v86 offset:53248
	s_waitcnt lgkmcnt(5)
	v_mfma_f32_32x32x16_bf16 v[48:63], a[16:19], a[24:27], v[48:63]
	v_mfma_f32_32x32x16_bf16 v[32:47], a[20:23], a[24:27], v[32:47]
	s_and_b32 m0, s32, 7
	s_lshl_b32 m0, m0, 12
	s_add_i32 m0, m0, 0xc00
	s_nop 0
	global_load_lds_dwordx4 v[164:165], off
	s_waitcnt lgkmcnt(4)
	v_mfma_f32_32x32x16_bf16 v[16:31], a[16:19], a[28:31], v[16:31]
	v_mfma_f32_32x32x16_bf16 v[0:15], a[20:23], a[28:31], v[0:15]
	s_and_b32 m0, s32, 7
	s_lshl_b32 m0, m0, 11
	s_add_i32 m0, m0, 0x8000
	s_nop 0
	global_load_lds_dwordx4 v[166:167], off
	ds_read_b128 a[16:19], v97
	ds_read_b128 a[20:23], v96
	ds_read_b128 a[24:27], v88 offset:49152
	ds_read_b128 a[28:31], v88 offset:53248
	s_waitcnt lgkmcnt(5)
	v_mfma_f32_32x32x16_bf16 v[48:63], a[0:3], a[8:11], v[48:63]
	v_mfma_f32_32x32x16_bf16 v[32:47], a[4:7], a[8:11], v[32:47]
	s_and_b32 m0, s32, 7
	s_lshl_b32 m0, m0, 11
	s_add_i32 m0, m0, 0x8400
	s_nop 0
	global_load_lds_dwordx4 v[168:169], off
	s_waitcnt lgkmcnt(4)
	v_mfma_f32_32x32x16_bf16 v[16:31], a[0:3], a[12:15], v[16:31]
	v_mfma_f32_32x32x16_bf16 v[0:15], a[4:7], a[12:15], v[0:15]
	s_waitcnt lgkmcnt(1)
	v_mfma_f32_32x32x16_bf16 v[48:63], a[16:19], a[24:27], v[48:63]
	v_mfma_f32_32x32x16_bf16 v[32:47], a[20:23], a[24:27], v[32:47]
	s_waitcnt vmcnt(6)
	s_waitcnt lgkmcnt(0)
	s_barrier
	ds_read_b128 a[12:15], v101
	ds_read_b128 a[8:11], v100
	ds_read_b128 a[4:7], v99
	ds_read_b128 a[0:3], v98
	v_mfma_f32_32x32x16_bf16 v[16:31], a[16:19], a[28:31], v[16:31]
	v_lshl_add_u64 v[170:171], v[66:67], 0, s[30:31]
	v_lshl_add_u64 v[172:173], v[68:69], 0, s[30:31]
	v_mfma_f32_32x32x16_bf16 v[0:15], a[20:23], a[28:31], v[0:15]
	s_and_b32 m0, s32, 7
	s_lshl_b32 m0, m0, 12
	s_add_i32 m0, m0, 0xc000
	s_nop 0
	global_load_lds_dwordx4 v[170:171], off
	v_lshl_add_u64 v[176:177], v[72:73], 0, s[30:31]
	v_lshl_add_u64 v[178:179], v[74:75], 0, s[30:31]
	v_lshl_add_u64 v[180:181], v[76:77], 0, s[30:31]
	s_mov_b64 s[30:31], 0x580
	ds_read_b128 a[16:19], v102
	ds_read_b128 a[20:23], v103
	ds_read_b128 a[24:27], v104
	ds_read_b128 a[28:31], v105
	s_waitcnt lgkmcnt(4)
	v_mfma_f32_32x32x16_bf16 v[48:63], a[0:3], a[8:11], v[48:63]
	v_lshl_add_u64 v[162:163], v[70:71], 0, s[30:31]
	v_mfma_f32_32x32x16_bf16 v[32:47], a[4:7], a[8:11], v[32:47]
	s_and_b32 m0, s32, 7
	s_lshl_b32 m0, m0, 12
	s_add_i32 m0, m0, 0xc400
	s_nop 0
	global_load_lds_dwordx4 v[172:173], off
	v_mfma_f32_32x32x16_bf16 v[16:31], a[0:3], a[12:15], v[16:31]
	v_mfma_f32_32x32x16_bf16 v[0:15], a[4:7], a[12:15], v[0:15]
	s_and_b32 m0, s32, 7
	s_lshl_b32 m0, m0, 12
	s_add_i32 m0, m0, 0xc800
	s_nop 0
	global_load_lds_dwordx4 v[174:175], off
	ds_read_b128 a[0:3], v106
	ds_read_b128 a[4:7], v107
	ds_read_b128 a[8:11], v108
	ds_read_b128 a[12:15], v109
	s_waitcnt lgkmcnt(5)
	v_mfma_f32_32x32x16_bf16 v[48:63], a[16:19], a[24:27], v[48:63]
	v_mfma_f32_32x32x16_bf16 v[32:47], a[20:23], a[24:27], v[32:47]
	s_and_b32 m0, s32, 7
	s_lshl_b32 m0, m0, 12
	s_add_i32 m0, m0, 0xcc00
	s_nop 0
	global_load_lds_dwordx4 v[176:177], off
	s_waitcnt lgkmcnt(4)
	v_mfma_f32_32x32x16_bf16 v[16:31], a[16:19], a[28:31], v[16:31]
	v_mfma_f32_32x32x16_bf16 v[0:15], a[20:23], a[28:31], v[0:15]
	s_and_b32 m0, s32, 7
	s_lshl_b32 m0, m0, 11
	s_add_i32 m0, m0, 0x14000
	s_nop 0
	global_load_lds_dwordx4 v[178:179], off
	ds_read_b128 a[16:19], v110
	ds_read_b128 a[20:23], v111
	ds_read_b128 a[24:27], v112
	ds_read_b128 a[28:31], v113
	s_waitcnt lgkmcnt(5)
	v_mfma_f32_32x32x16_bf16 v[48:63], a[0:3], a[8:11], v[48:63]
	v_mfma_f32_32x32x16_bf16 v[32:47], a[4:7], a[8:11], v[32:47]
	s_and_b32 m0, s32, 7
	s_lshl_b32 m0, m0, 11
	s_add_i32 m0, m0, 0x14400
	s_nop 0
	global_load_lds_dwordx4 v[180:181], off
	s_waitcnt lgkmcnt(4)
	v_mfma_f32_32x32x16_bf16 v[16:31], a[0:3], a[12:15], v[16:31]
	v_mfma_f32_32x32x16_bf16 v[0:15], a[4:7], a[12:15], v[0:15]
	s_waitcnt lgkmcnt(1)
	v_mfma_f32_32x32x16_bf16 v[48:63], a[16:19], a[24:27], v[48:63]
	v_mfma_f32_32x32x16_bf16 v[32:47], a[20:23], a[24:27], v[32:47]
	s_waitcnt vmcnt(6)
	s_waitcnt lgkmcnt(0)
	s_barrier
	ds_read_b128 a[12:15], v82 offset:4096
	ds_read_b128 a[8:11], v82
	ds_read_b128 a[4:7], v83 offset:36864
	ds_read_b128 a[0:3], v83 offset:32768
	v_mfma_f32_32x32x16_bf16 v[16:31], a[16:19], a[28:31], v[16:31]
	v_lshl_add_u64 v[158:159], v[66:67], 0, s[30:31]
	v_lshl_add_u64 v[160:161], v[68:69], 0, s[30:31]
	v_mfma_f32_32x32x16_bf16 v[0:15], a[20:23], a[28:31], v[0:15]
	s_and_b32 m0, s32, 7
	s_lshl_b32 m0, m0, 12
	s_add_i32 m0, m0, 0x18000
	s_nop 0
	global_load_lds_dwordx4 v[158:159], off
	v_lshl_add_u64 v[164:165], v[72:73], 0, s[30:31]
	v_lshl_add_u64 v[166:167], v[74:75], 0, s[30:31]
	v_lshl_add_u64 v[168:169], v[76:77], 0, s[30:31]
	s_mov_b64 s[30:31], 0x600
	ds_read_b128 a[16:19], v85 offset:32768
	ds_read_b128 a[20:23], v85 offset:36864
	ds_read_b128 a[24:27], v84
	ds_read_b128 a[28:31], v84 offset:4096
	s_waitcnt lgkmcnt(4)
	v_mfma_f32_32x32x16_bf16 v[48:63], a[0:3], a[8:11], v[48:63]
	v_mfma_f32_32x32x16_bf16 v[32:47], a[4:7], a[8:11], v[32:47]
	s_and_b32 m0, s32, 7
	s_lshl_b32 m0, m0, 12
	s_add_i32 m0, m0, 0x18400
	s_nop 0
	global_load_lds_dwordx4 v[160:161], off
	v_mfma_f32_32x32x16_bf16 v[16:31], a[0:3], a[12:15], v[16:31]
	v_mfma_f32_32x32x16_bf16 v[0:15], a[4:7], a[12:15], v[0:15]
	s_and_b32 m0, s32, 7
	s_lshl_b32 m0, m0, 12
	s_add_i32 m0, m0, 0x18800
	s_nop 0
	global_load_lds_dwordx4 v[162:163], off
	ds_read_b128 a[0:3], v87 offset:32768
	ds_read_b128 a[4:7], v87 offset:36864
	ds_read_b128 a[8:11], v86
	ds_read_b128 a[12:15], v86 offset:4096
	s_waitcnt lgkmcnt(5)
	v_mfma_f32_32x32x16_bf16 v[48:63], a[16:19], a[24:27], v[48:63]
	v_mfma_f32_32x32x16_bf16 v[32:47], a[20:23], a[24:27], v[32:47]
	s_and_b32 m0, s32, 7
	s_lshl_b32 m0, m0, 12
	s_add_i32 m0, m0, 0x18c00
	s_nop 0
	global_load_lds_dwordx4 v[164:165], off
	s_waitcnt lgkmcnt(4)
	v_mfma_f32_32x32x16_bf16 v[16:31], a[16:19], a[28:31], v[16:31]
	v_mfma_f32_32x32x16_bf16 v[0:15], a[20:23], a[28:31], v[0:15]
	s_and_b32 m0, s32, 7
	s_lshl_b32 m0, m0, 11
	s_add_i32 m0, m0, 0x20000
	s_nop 0
	global_load_lds_dwordx4 v[166:167], off
	ds_read_b128 a[16:19], v89 offset:32768
	ds_read_b128 a[20:23], v89 offset:36864
	ds_read_b128 a[24:27], v88
	ds_read_b128 a[28:31], v88 offset:4096
	s_waitcnt lgkmcnt(5)
	v_mfma_f32_32x32x16_bf16 v[48:63], a[0:3], a[8:11], v[48:63]
	v_mfma_f32_32x32x16_bf16 v[32:47], a[4:7], a[8:11], v[32:47]
	s_and_b32 m0, s32, 7
	s_lshl_b32 m0, m0, 11
	s_add_i32 m0, m0, 0x20400
	s_nop 0
	global_load_lds_dwordx4 v[168:169], off
	s_waitcnt lgkmcnt(4)
	v_mfma_f32_32x32x16_bf16 v[16:31], a[0:3], a[12:15], v[16:31]
	v_mfma_f32_32x32x16_bf16 v[0:15], a[4:7], a[12:15], v[0:15]
	s_waitcnt lgkmcnt(1)
	v_mfma_f32_32x32x16_bf16 v[48:63], a[16:19], a[24:27], v[48:63]
	v_mfma_f32_32x32x16_bf16 v[32:47], a[20:23], a[24:27], v[32:47]
	s_waitcnt vmcnt(6)
	s_waitcnt lgkmcnt(0)
	s_barrier
	ds_read_b128 a[12:15], v82 offset:53248
	ds_read_b128 a[8:11], v82 offset:49152
	ds_read_b128 a[4:7], v90
	ds_read_b128 a[0:3], v92
	v_mfma_f32_32x32x16_bf16 v[16:31], a[16:19], a[28:31], v[16:31]
	v_lshl_add_u64 v[170:171], v[66:67], 0, s[30:31]
	v_lshl_add_u64 v[172:173], v[68:69], 0, s[30:31]
	v_lshl_add_u64 v[174:175], v[70:71], 0, s[30:31]
	v_mfma_f32_32x32x16_bf16 v[0:15], a[20:23], a[28:31], v[0:15]
	s_and_b32 m0, s32, 7
	s_lshl_b32 m0, m0, 12
	s_add_i32 m0, m0, 0x0
	s_nop 0
	global_load_lds_dwordx4 v[170:171], off
	v_lshl_add_u64 v[176:177], v[72:73], 0, s[30:31]
	v_lshl_add_u64 v[178:179], v[74:75], 0, s[30:31]
	v_lshl_add_u64 v[180:181], v[76:77], 0, s[30:31]
	s_mov_b64 s[30:31], 0x680
	ds_read_b128 a[16:19], v93
	ds_read_b128 a[20:23], v91
	ds_read_b128 a[24:27], v84 offset:49152
	ds_read_b128 a[28:31], v84 offset:53248
	s_waitcnt lgkmcnt(4)
	v_mfma_f32_32x32x16_bf16 v[48:63], a[0:3], a[8:11], v[48:63]
	v_mfma_f32_32x32x16_bf16 v[32:47], a[4:7], a[8:11], v[32:47]
	s_and_b32 m0, s32, 7
	s_lshl_b32 m0, m0, 12
	s_add_i32 m0, m0, 0x400
	s_nop 0
	global_load_lds_dwordx4 v[172:173], off
	v_mfma_f32_32x32x16_bf16 v[16:31], a[0:3], a[12:15], v[16:31]
	v_mfma_f32_32x32x16_bf16 v[0:15], a[4:7], a[12:15], v[0:15]
	s_and_b32 m0, s32, 7
	s_lshl_b32 m0, m0, 12
	s_add_i32 m0, m0, 0x800
	s_nop 0
	global_load_lds_dwordx4 v[174:175], off
	ds_read_b128 a[0:3], v95
	ds_read_b128 a[4:7], v94
	ds_read_b128 a[8:11], v86 offset:49152
	ds_read_b128 a[12:15], v86 offset:53248
	s_waitcnt lgkmcnt(5)
	v_mfma_f32_32x32x16_bf16 v[48:63], a[16:19], a[24:27], v[48:63]
	v_mfma_f32_32x32x16_bf16 v[32:47], a[20:23], a[24:27], v[32:47]
	s_and_b32 m0, s32, 7
	s_lshl_b32 m0, m0, 12
	s_add_i32 m0, m0, 0xc00
	s_nop 0
	global_load_lds_dwordx4 v[176:177], off
	s_waitcnt lgkmcnt(4)
	v_mfma_f32_32x32x16_bf16 v[16:31], a[16:19], a[28:31], v[16:31]
	v_mfma_f32_32x32x16_bf16 v[0:15], a[20:23], a[28:31], v[0:15]
	s_and_b32 m0, s32, 7
	s_lshl_b32 m0, m0, 11
	s_add_i32 m0, m0, 0x8000
	s_nop 0
	global_load_lds_dwordx4 v[178:179], off
	ds_read_b128 a[16:19], v97
	ds_read_b128 a[20:23], v96
	ds_read_b128 a[24:27], v88 offset:49152
	ds_read_b128 a[28:31], v88 offset:53248
	s_waitcnt lgkmcnt(5)
	v_mfma_f32_32x32x16_bf16 v[48:63], a[0:3], a[8:11], v[48:63]
	v_mfma_f32_32x32x16_bf16 v[32:47], a[4:7], a[8:11], v[32:47]
	s_and_b32 m0, s32, 7
	s_lshl_b32 m0, m0, 11
	s_add_i32 m0, m0, 0x8400
	s_nop 0
	global_load_lds_dwordx4 v[180:181], off
	s_waitcnt lgkmcnt(4)
	v_mfma_f32_32x32x16_bf16 v[16:31], a[0:3], a[12:15], v[16:31]
	v_mfma_f32_32x32x16_bf16 v[0:15], a[4:7], a[12:15], v[0:15]
	s_waitcnt lgkmcnt(1)
	v_mfma_f32_32x32x16_bf16 v[48:63], a[16:19], a[24:27], v[48:63]
	v_mfma_f32_32x32x16_bf16 v[32:47], a[20:23], a[24:27], v[32:47]
	s_waitcnt vmcnt(6)
	s_waitcnt lgkmcnt(0)
	s_barrier
	ds_read_b128 a[12:15], v101
	ds_read_b128 a[8:11], v100
	ds_read_b128 a[4:7], v99
	ds_read_b128 a[0:3], v98
	v_mfma_f32_32x32x16_bf16 v[16:31], a[16:19], a[28:31], v[16:31]
	v_lshl_add_u64 v[158:159], v[66:67], 0, s[30:31]
	v_lshl_add_u64 v[160:161], v[68:69], 0, s[30:31]
	v_lshl_add_u64 v[162:163], v[70:71], 0, s[30:31]
	v_mfma_f32_32x32x16_bf16 v[0:15], a[20:23], a[28:31], v[0:15]
	s_and_b32 m0, s32, 7
	s_lshl_b32 m0, m0, 12
	s_add_i32 m0, m0, 0xc000
	s_nop 0
	global_load_lds_dwordx4 v[158:159], off
	v_lshl_add_u64 v[164:165], v[72:73], 0, s[30:31]
	v_lshl_add_u64 v[166:167], v[74:75], 0, s[30:31]
	v_lshl_add_u64 v[168:169], v[76:77], 0, s[30:31]
	s_mov_b64 s[30:31], 0x700
	ds_read_b128 a[16:19], v102
	ds_read_b128 a[20:23], v103
	ds_read_b128 a[24:27], v104
	ds_read_b128 a[28:31], v105
	s_waitcnt lgkmcnt(4)
	v_mfma_f32_32x32x16_bf16 v[48:63], a[0:3], a[8:11], v[48:63]
	v_mfma_f32_32x32x16_bf16 v[32:47], a[4:7], a[8:11], v[32:47]
	s_and_b32 m0, s32, 7
	s_lshl_b32 m0, m0, 12
	s_add_i32 m0, m0, 0xc400
	s_nop 0
	global_load_lds_dwordx4 v[160:161], off
	v_mfma_f32_32x32x16_bf16 v[16:31], a[0:3], a[12:15], v[16:31]
	v_mfma_f32_32x32x16_bf16 v[0:15], a[4:7], a[12:15], v[0:15]
	s_and_b32 m0, s32, 7
	s_lshl_b32 m0, m0, 12
	s_add_i32 m0, m0, 0xc800
	s_nop 0
	global_load_lds_dwordx4 v[162:163], off
	ds_read_b128 a[0:3], v106
	ds_read_b128 a[4:7], v107
	ds_read_b128 a[8:11], v108
	ds_read_b128 a[12:15], v109
	s_waitcnt lgkmcnt(5)
	v_mfma_f32_32x32x16_bf16 v[48:63], a[16:19], a[24:27], v[48:63]
	v_mfma_f32_32x32x16_bf16 v[32:47], a[20:23], a[24:27], v[32:47]
	s_and_b32 m0, s32, 7
	s_lshl_b32 m0, m0, 12
	s_add_i32 m0, m0, 0xcc00
	s_nop 0
	global_load_lds_dwordx4 v[164:165], off
	s_waitcnt lgkmcnt(4)
	v_mfma_f32_32x32x16_bf16 v[16:31], a[16:19], a[28:31], v[16:31]
	v_mfma_f32_32x32x16_bf16 v[0:15], a[20:23], a[28:31], v[0:15]
	s_and_b32 m0, s32, 7
	s_lshl_b32 m0, m0, 11
	s_add_i32 m0, m0, 0x14000
	s_nop 0
	global_load_lds_dwordx4 v[166:167], off
	ds_read_b128 a[16:19], v110
	ds_read_b128 a[20:23], v111
	ds_read_b128 a[24:27], v112
	ds_read_b128 a[28:31], v113
	s_waitcnt lgkmcnt(5)
	v_mfma_f32_32x32x16_bf16 v[48:63], a[0:3], a[8:11], v[48:63]
	v_mfma_f32_32x32x16_bf16 v[32:47], a[4:7], a[8:11], v[32:47]
	s_and_b32 m0, s32, 7
	s_lshl_b32 m0, m0, 11
	s_add_i32 m0, m0, 0x14400
	s_nop 0
	global_load_lds_dwordx4 v[168:169], off
	s_waitcnt lgkmcnt(4)
	v_mfma_f32_32x32x16_bf16 v[16:31], a[0:3], a[12:15], v[16:31]
	v_mfma_f32_32x32x16_bf16 v[0:15], a[4:7], a[12:15], v[0:15]
	s_waitcnt lgkmcnt(1)
	v_mfma_f32_32x32x16_bf16 v[48:63], a[16:19], a[24:27], v[48:63]
	v_mfma_f32_32x32x16_bf16 v[32:47], a[20:23], a[24:27], v[32:47]
	s_waitcnt vmcnt(6)
	s_waitcnt lgkmcnt(0)
	s_barrier
	ds_read_b128 a[12:15], v82 offset:4096
	ds_read_b128 a[8:11], v82
	ds_read_b128 a[4:7], v83 offset:36864
	ds_read_b128 a[0:3], v83 offset:32768
	v_mfma_f32_32x32x16_bf16 v[16:31], a[16:19], a[28:31], v[16:31]
	v_lshl_add_u64 v[170:171], v[66:67], 0, s[30:31]
	v_lshl_add_u64 v[172:173], v[68:69], 0, s[30:31]
	v_lshl_add_u64 v[174:175], v[70:71], 0, s[30:31]
	v_mfma_f32_32x32x16_bf16 v[0:15], a[20:23], a[28:31], v[0:15]
	s_and_b32 m0, s32, 7
	s_lshl_b32 m0, m0, 12
	s_add_i32 m0, m0, 0x18000
	s_nop 0
	global_load_lds_dwordx4 v[170:171], off
	v_lshl_add_u64 v[176:177], v[72:73], 0, s[30:31]
	v_lshl_add_u64 v[178:179], v[74:75], 0, s[30:31]
	v_lshl_add_u64 v[180:181], v[76:77], 0, s[30:31]
	s_mov_b64 s[30:31], 0x780
	ds_read_b128 a[16:19], v85 offset:32768
	ds_read_b128 a[20:23], v85 offset:36864
	ds_read_b128 a[24:27], v84
	ds_read_b128 a[28:31], v84 offset:4096
	s_waitcnt lgkmcnt(4)
	v_mfma_f32_32x32x16_bf16 v[48:63], a[0:3], a[8:11], v[48:63]
	v_lshl_add_u64 v[158:159], v[66:67], 0, s[30:31]
	v_mfma_f32_32x32x16_bf16 v[32:47], a[4:7], a[8:11], v[32:47]
	s_and_b32 m0, s32, 7
	s_lshl_b32 m0, m0, 12
	s_add_i32 m0, m0, 0x18400
	s_nop 0
	global_load_lds_dwordx4 v[172:173], off
	v_mfma_f32_32x32x16_bf16 v[16:31], a[0:3], a[12:15], v[16:31]
	v_mfma_f32_32x32x16_bf16 v[0:15], a[4:7], a[12:15], v[0:15]
	s_and_b32 m0, s32, 7
	s_lshl_b32 m0, m0, 12
	s_add_i32 m0, m0, 0x18800
	s_nop 0
	global_load_lds_dwordx4 v[174:175], off
	ds_read_b128 a[0:3], v87 offset:32768
	ds_read_b128 a[4:7], v87 offset:36864
	ds_read_b128 a[8:11], v86
	ds_read_b128 a[12:15], v86 offset:4096
	s_waitcnt lgkmcnt(5)
	v_mfma_f32_32x32x16_bf16 v[48:63], a[16:19], a[24:27], v[48:63]
	v_mfma_f32_32x32x16_bf16 v[32:47], a[20:23], a[24:27], v[32:47]
	s_and_b32 m0, s32, 7
	s_lshl_b32 m0, m0, 12
	s_add_i32 m0, m0, 0x18c00
	s_nop 0
	global_load_lds_dwordx4 v[176:177], off
	s_waitcnt lgkmcnt(4)
	v_mfma_f32_32x32x16_bf16 v[16:31], a[16:19], a[28:31], v[16:31]
	v_mfma_f32_32x32x16_bf16 v[0:15], a[20:23], a[28:31], v[0:15]
	s_and_b32 m0, s32, 7
	s_lshl_b32 m0, m0, 11
	s_add_i32 m0, m0, 0x20000
	s_nop 0
	global_load_lds_dwordx4 v[178:179], off
	ds_read_b128 a[16:19], v89 offset:32768
	ds_read_b128 a[20:23], v89 offset:36864
	ds_read_b128 a[24:27], v88
	ds_read_b128 a[28:31], v88 offset:4096
	s_waitcnt lgkmcnt(5)
	v_mfma_f32_32x32x16_bf16 v[48:63], a[0:3], a[8:11], v[48:63]
	v_mfma_f32_32x32x16_bf16 v[32:47], a[4:7], a[8:11], v[32:47]
	s_and_b32 m0, s32, 7
	s_lshl_b32 m0, m0, 11
	s_add_i32 m0, m0, 0x20400
	s_nop 0
	global_load_lds_dwordx4 v[180:181], off
	s_waitcnt lgkmcnt(4)
	v_mfma_f32_32x32x16_bf16 v[16:31], a[0:3], a[12:15], v[16:31]
	v_mfma_f32_32x32x16_bf16 v[0:15], a[4:7], a[12:15], v[0:15]
	s_waitcnt lgkmcnt(1)
	v_mfma_f32_32x32x16_bf16 v[48:63], a[16:19], a[24:27], v[48:63]
	v_mfma_f32_32x32x16_bf16 v[32:47], a[20:23], a[24:27], v[32:47]
	s_waitcnt vmcnt(6)
	s_waitcnt lgkmcnt(0)
	s_barrier
	ds_read_b128 a[12:15], v82 offset:53248
	ds_read_b128 a[8:11], v82 offset:49152
	ds_read_b128 a[4:7], v90
	ds_read_b128 a[0:3], v92
	v_lshl_add_u64 v[160:161], v[68:69], 0, s[30:31]
	v_mfma_f32_32x32x16_bf16 v[16:31], a[16:19], a[28:31], v[16:31]
	v_lshl_add_u64 v[162:163], v[70:71], 0, s[30:31]
	v_lshl_add_u64 v[164:165], v[72:73], 0, s[30:31]
	v_mfma_f32_32x32x16_bf16 v[0:15], a[20:23], a[28:31], v[0:15]
	s_and_b32 m0, s32, 7
	s_lshl_b32 m0, m0, 12
	s_add_i32 m0, m0, 0x0
	s_nop 0
	global_load_lds_dwordx4 v[158:159], off
	v_lshl_add_u64 v[166:167], v[74:75], 0, s[30:31]
	v_lshl_add_u64 v[168:169], v[76:77], 0, s[30:31]
	ds_read_b128 a[16:19], v93
	ds_read_b128 a[20:23], v91
	ds_read_b128 a[24:27], v84 offset:49152
	ds_read_b128 a[28:31], v84 offset:53248
	s_waitcnt lgkmcnt(4)
	v_mfma_f32_32x32x16_bf16 v[48:63], a[0:3], a[8:11], v[48:63]
	v_mfma_f32_32x32x16_bf16 v[32:47], a[4:7], a[8:11], v[32:47]
	s_and_b32 m0, s32, 7
	s_lshl_b32 m0, m0, 12
	s_add_i32 m0, m0, 0x400
	s_nop 0
	global_load_lds_dwordx4 v[160:161], off
	v_mfma_f32_32x32x16_bf16 v[16:31], a[0:3], a[12:15], v[16:31]
	v_mfma_f32_32x32x16_bf16 v[0:15], a[4:7], a[12:15], v[0:15]
	s_and_b32 m0, s32, 7
	s_lshl_b32 m0, m0, 12
	s_add_i32 m0, m0, 0x800
	s_nop 0
	global_load_lds_dwordx4 v[162:163], off
	ds_read_b128 a[0:3], v95
	ds_read_b128 a[4:7], v94
	ds_read_b128 a[8:11], v86 offset:49152
	ds_read_b128 a[12:15], v86 offset:53248
	s_waitcnt lgkmcnt(5)
	v_mfma_f32_32x32x16_bf16 v[48:63], a[16:19], a[24:27], v[48:63]
	v_mfma_f32_32x32x16_bf16 v[32:47], a[20:23], a[24:27], v[32:47]
	s_and_b32 m0, s32, 7
	s_lshl_b32 m0, m0, 12
	s_add_i32 m0, m0, 0xc00
	s_nop 0
	global_load_lds_dwordx4 v[164:165], off
	s_waitcnt lgkmcnt(4)
	v_mfma_f32_32x32x16_bf16 v[16:31], a[16:19], a[28:31], v[16:31]
	v_mfma_f32_32x32x16_bf16 v[0:15], a[20:23], a[28:31], v[0:15]
	s_and_b32 m0, s32, 7
	s_lshl_b32 m0, m0, 11
	s_add_i32 m0, m0, 0x8000
	s_nop 0
	global_load_lds_dwordx4 v[166:167], off
	ds_read_b128 a[16:19], v97
	ds_read_b128 a[20:23], v96
	ds_read_b128 a[24:27], v88 offset:49152
	ds_read_b128 a[28:31], v88 offset:53248
	s_waitcnt lgkmcnt(5)
	v_mfma_f32_32x32x16_bf16 v[48:63], a[0:3], a[8:11], v[48:63]
	v_mfma_f32_32x32x16_bf16 v[32:47], a[4:7], a[8:11], v[32:47]
	s_and_b32 m0, s32, 7
	s_lshl_b32 m0, m0, 11
	s_add_i32 m0, m0, 0x8400
	s_nop 0
	global_load_lds_dwordx4 v[168:169], off
	s_waitcnt lgkmcnt(4)
	v_mfma_f32_32x32x16_bf16 v[16:31], a[0:3], a[12:15], v[16:31]
	v_mfma_f32_32x32x16_bf16 v[0:15], a[4:7], a[12:15], v[0:15]
	s_waitcnt lgkmcnt(1)
	v_mfma_f32_32x32x16_bf16 v[48:63], a[16:19], a[24:27], v[48:63]
	v_mfma_f32_32x32x16_bf16 v[32:47], a[20:23], a[24:27], v[32:47]
	s_waitcnt vmcnt(6)
	s_waitcnt lgkmcnt(0)
	s_barrier
	ds_read_b128 a[12:15], v101
	ds_read_b128 a[8:11], v100
	ds_read_b128 a[4:7], v99
	ds_read_b128 a[0:3], v98
	v_mfma_f32_32x32x16_bf16 v[16:31], a[16:19], a[28:31], v[16:31]
	v_mfma_f32_32x32x16_bf16 v[0:15], a[20:23], a[28:31], v[0:15]
	ds_read_b128 a[16:19], v102
	ds_read_b128 a[20:23], v103
	ds_read_b128 a[24:27], v104
	ds_read_b128 a[28:31], v105
	s_waitcnt lgkmcnt(4)
	v_mfma_f32_32x32x16_bf16 v[48:63], a[0:3], a[8:11], v[48:63]
	v_mfma_f32_32x32x16_bf16 v[32:47], a[4:7], a[8:11], v[32:47]
	v_mfma_f32_32x32x16_bf16 v[16:31], a[0:3], a[12:15], v[16:31]
	v_mfma_f32_32x32x16_bf16 v[0:15], a[4:7], a[12:15], v[0:15]
	ds_read_b128 a[0:3], v106
	ds_read_b128 a[4:7], v107
	ds_read_b128 a[8:11], v108
	ds_read_b128 a[12:15], v109
	s_waitcnt lgkmcnt(5)
	v_mfma_f32_32x32x16_bf16 v[48:63], a[16:19], a[24:27], v[48:63]
	v_mfma_f32_32x32x16_bf16 v[32:47], a[20:23], a[24:27], v[32:47]
	s_waitcnt lgkmcnt(4)
	v_mfma_f32_32x32x16_bf16 v[16:31], a[16:19], a[28:31], v[16:31]
	v_mfma_f32_32x32x16_bf16 v[0:15], a[20:23], a[28:31], v[0:15]
	ds_read_b128 a[16:19], v110
	ds_read_b128 a[20:23], v111
	ds_read_b128 a[24:27], v112
	ds_read_b128 a[28:31], v113
	s_waitcnt lgkmcnt(5)
	v_mfma_f32_32x32x16_bf16 v[48:63], a[0:3], a[8:11], v[48:63]
	v_mfma_f32_32x32x16_bf16 v[32:47], a[4:7], a[8:11], v[32:47]
	s_waitcnt lgkmcnt(4)
	v_mfma_f32_32x32x16_bf16 v[16:31], a[0:3], a[12:15], v[16:31]
	v_mfma_f32_32x32x16_bf16 v[0:15], a[4:7], a[12:15], v[0:15]
	s_waitcnt lgkmcnt(1)
	v_mfma_f32_32x32x16_bf16 v[48:63], a[16:19], a[24:27], v[48:63]
	v_mfma_f32_32x32x16_bf16 v[32:47], a[20:23], a[24:27], v[32:47]
	s_waitcnt vmcnt(0)
	s_waitcnt lgkmcnt(0)
	s_barrier
	ds_read_b128 a[12:15], v82 offset:4096
	ds_read_b128 a[8:11], v82
	ds_read_b128 a[4:7], v83 offset:36864
	ds_read_b128 a[0:3], v83 offset:32768
	v_mfma_f32_32x32x16_bf16 v[16:31], a[16:19], a[28:31], v[16:31]
	v_mfma_f32_32x32x16_bf16 v[0:15], a[20:23], a[28:31], v[0:15]
	ds_read_b128 a[16:19], v85 offset:32768
	ds_read_b128 a[20:23], v85 offset:36864
	ds_read_b128 a[24:27], v84
	ds_read_b128 a[28:31], v84 offset:4096
	s_waitcnt lgkmcnt(4)
	v_mfma_f32_32x32x16_bf16 v[48:63], a[0:3], a[8:11], v[48:63]
	v_mfma_f32_32x32x16_bf16 v[32:47], a[4:7], a[8:11], v[32:47]
	v_mfma_f32_32x32x16_bf16 v[16:31], a[0:3], a[12:15], v[16:31]
	v_mfma_f32_32x32x16_bf16 v[0:15], a[4:7], a[12:15], v[0:15]
	ds_read_b128 a[0:3], v87 offset:32768
	ds_read_b128 a[4:7], v87 offset:36864
	ds_read_b128 a[8:11], v86
	ds_read_b128 a[12:15], v86 offset:4096
	s_waitcnt lgkmcnt(5)
	v_mfma_f32_32x32x16_bf16 v[48:63], a[16:19], a[24:27], v[48:63]
	v_mfma_f32_32x32x16_bf16 v[32:47], a[20:23], a[24:27], v[32:47]
	s_waitcnt lgkmcnt(4)
	v_mfma_f32_32x32x16_bf16 v[16:31], a[16:19], a[28:31], v[16:31]
	v_mfma_f32_32x32x16_bf16 v[0:15], a[20:23], a[28:31], v[0:15]
	s_waitcnt lgkmcnt(1)
	v_mfma_f32_32x32x16_bf16 v[48:63], a[0:3], a[8:11], v[48:63]
	v_mfma_f32_32x32x16_bf16 v[32:47], a[4:7], a[8:11], v[32:47]
	s_waitcnt lgkmcnt(0)
	v_mfma_f32_32x32x16_bf16 v[16:31], a[0:3], a[12:15], v[16:31]
	v_mfma_f32_32x32x16_bf16 v[0:15], a[4:7], a[12:15], v[0:15]
	ds_read_b128 v[66:69], v89 offset:32768
	ds_read_b128 v[70:73], v88
	ds_read_b128 v[74:77], v89 offset:36864
	ds_read_b128 v[82:85], v88 offset:4096
	s_waitcnt lgkmcnt(0)
	s_barrier
	s_waitcnt lgkmcnt(0)
	v_mfma_f32_32x32x16_bf16 v[48:63], v[66:69], v[70:73], v[48:63]
	v_mfma_f32_32x32x16_bf16 v[32:47], v[74:77], v[70:73], v[32:47]
	v_mov_b32_e32 v70, 0
	v_mfma_f32_32x32x16_bf16 v[16:31], v[66:69], v[82:85], v[16:31]
	v_lshl_or_b32 v69, v80, 6, v81
	v_add_u32_e32 v66, s20, v69
	v_cmp_gt_i32_e32 vcc, s69, v66
	v_mov_b32_e32 v68, 0
	v_ashrrev_i32_e32 v67, 31, v66
	v_mfma_f32_32x32x16_bf16 v[0:15], v[74:77], v[82:85], v[0:15]
	s_and_saveexec_b64 s[0:1], vcc
	s_cbranch_execz .LBB0_588
	v_lshl_add_u64 v[70:71], v[66:67], 2, s[76:77]
	global_load_dword v70, v[70:71], off
	s_waitcnt vmcnt(0)
	v_fmamk_f32 v70, v70, 0x3a800000, v188
	v_mul_f32_e32 v71, 0x4b800000, v70
	v_cmp_gt_f32_e32 vcc, s82, v70
	s_nop 1
	v_cndmask_b32_e32 v70, v70, v71, vcc
	v_rsq_f32_e32 v70, v70
	s_nop 0
	v_mul_f32_e32 v71, 0x45800000, v70
	v_cndmask_b32_e32 v70, v70, v71, vcc

.LBB0_612:
	v_readlane_b32 s0, v212, 1
	s_cmp_ge_i32 s56, s0
	s_mov_b64 s[0:1], -1
	s_cbranch_scc0 .LBB0_742
	s_ashr_i32 s1, s52, 31
	s_lshr_b32 s0, s1, 27
	s_add_i32 s2, s52, s0
	s_ashr_i32 s0, s2, 5
	s_and_b32 s2, s2, 0xffe0
	s_sub_i32 s2, s52, s2
	s_lshr_b32 s1, s1, 30
	s_bfe_i32 s20, s2, 0x80000
	s_add_i32 s1, s52, s1
	s_bfe_u32 s20, s20, 0x2000d
	s_and_b32 s1, s1, 0x1fffffc
	s_add_i32 s2, s2, s20
	s_sub_i32 s23, s52, s1
	s_ashr_i32 s1, s0, 31
	s_bfe_i32 s2, s2, 0x80000
	s_lshl_b64 s[20:21], s[0:1], 20
	v_readlane_b32 s22, v215, 46
	s_sext_i32_i16 s2, s2
	s_add_u32 s20, s22, s20
	v_readlane_b32 s22, v215, 47
	v_mov_b32_e32 v12, v133
	s_addc_u32 s21, s22, s21
	s_lshl_b32 s2, s2, 6
	s_and_b32 s22, s2, 0xffffff00
	v_ashrrev_i32_e32 v6, 6, v12
	v_bfe_u32 v7, v12, 3, 3
	v_lshl_or_b32 v8, v6, 5, v7
	v_add_u32_e32 v0, s22, v8
	s_waitcnt lgkmcnt(0)
	v_ashrrev_i32_e32 v1, 31, v0
	v_lshlrev_b64 v[2:3], 11, v[0:1]
	v_bfe_u32 v1, v12, 4, 2
	v_readlane_b32 s28, v215, 50
	v_xor_b32_e32 v1, v1, v12
	v_readlane_b32 s29, v215, 51
	v_lshlrev_b32_e32 v1, 4, v1
	v_and_b32_e32 v64, 0x70, v1
	v_lshl_add_u64 v[2:3], s[28:29], 0, v[2:3]
	v_or_b32_e32 v1, 8, v8
	v_lshl_add_u64 v[66:67], v[2:3], 0, v[64:65]
	v_add_u32_e32 v2, s22, v1
	v_lshrrev_b32_e32 v1, 1, v1
	v_xor_b32_e32 v1, v1, v12
	v_ashrrev_i32_e32 v3, 31, v2
	v_lshlrev_b32_e32 v1, 4, v1
	v_or_b32_e32 v0, 16, v0
	v_lshlrev_b64 v[2:3], 11, v[2:3]
	v_and_b32_e32 v4, 0x70, v1
	v_ashrrev_i32_e32 v1, 31, v0
	v_lshl_add_u64 v[2:3], s[28:29], 0, v[2:3]
	v_mov_b32_e32 v5, v65
	v_lshlrev_b64 v[0:1], 11, v[0:1]
	v_lshl_add_u64 v[68:69], v[2:3], 0, v[4:5]
	v_lshl_add_u64 v[0:1], s[28:29], 0, v[0:1]
	v_or_b32_e32 v2, 24, v8
	v_lshl_add_u64 v[70:71], v[0:1], 0, v[64:65]
	v_add_u32_e32 v0, s22, v2
	v_lshrrev_b32_e32 v2, 1, v2
	v_ashrrev_i32_e32 v1, 31, v0
	v_xor_b32_e32 v2, v2, v12
	v_lshlrev_b64 v[0:1], 11, v[0:1]
	v_lshlrev_b32_e32 v2, 4, v2
	v_lshl_add_u64 v[0:1], s[28:29], 0, v[0:1]
	v_and_b32_e32 v2, 0x70, v2
	v_mov_b32_e32 v3, v65
	s_lshl_b32 s2, s23, 7
	v_lshl_add_u64 v[72:73], v[0:1], 0, v[2:3]
	v_lshl_or_b32 v2, v6, 4, v7
	v_add_u32_e32 v0, s2, v2
	v_lshlrev_b32_e32 v3, 12, v6
	v_ashrrev_i32_e32 v1, 31, v0
	v_add_u32_e32 v125, 0, v3
	v_lshlrev_b64 v[0:1], 11, v[0:1]
	s_waitcnt vmcnt(0)
	v_readfirstlane_b32 s42, v125
	v_add_u32_e32 v126, 0x400, v125
	v_lshl_add_u64 v[0:1], s[20:21], 0, v[0:1]
	v_or_b32_e32 v2, 8, v2
	s_waitcnt lgkmcnt(0)
	s_barrier
	s_mov_b32 m0, s42
	v_readfirstlane_b32 s43, v126
	v_add_u32_e32 v127, 0x800, v125
	v_lshlrev_b32_e32 v5, 11, v6
	v_and_b32_e32 v79, 1, v6
	v_lshl_add_u64 v[74:75], v[0:1], 0, v[64:65]
	v_add_u32_e32 v0, s2, v2
	v_lshrrev_b32_e32 v2, 1, v2
	global_load_lds_dwordx4 v[66:67], off
	s_mov_b32 m0, s43
	v_readfirstlane_b32 s44, v127
	v_add_u32_e32 v128, 0xc00, v125
	v_add_u32_e32 v6, 0, v5
	v_ashrrev_i32_e32 v1, 31, v0
	v_xor_b32_e32 v2, v2, v12
	global_load_lds_dwordx4 v[68:69], off
	s_mov_b32 m0, s44
	v_readfirstlane_b32 s45, v128
	v_add_u32_e32 v130, 0x8000, v6
	v_lshlrev_b64 v[0:1], 11, v[0:1]
	v_lshlrev_b32_e32 v2, 4, v2
	global_load_lds_dwordx4 v[70:71], off
	s_mov_b32 m0, s45
	v_readfirstlane_b32 s46, v130
	v_add_u32_e32 v129, 0x8400, v6
	v_lshl_add_u64 v[0:1], s[20:21], 0, v[0:1]
	v_and_b32_e32 v64, 0x70, v2
	global_load_lds_dwordx4 v[72:73], off
	s_mov_b32 m0, s46
	v_readfirstlane_b32 s47, v129
	v_add_u32_e32 v119, 0xc000, v125
	v_lshl_add_u64 v[76:77], v[0:1], 0, v[64:65]
	global_load_lds_dwordx4 v[74:75], off
	s_mov_b32 m0, s47
	s_mov_b64 s[20:21], 0x80
	v_readfirstlane_b32 s36, v119
	v_add_u32_e32 v120, 0xc400, v125
	global_load_lds_dwordx4 v[76:77], off
	v_lshl_add_u64 v[0:1], v[66:67], 0, s[20:21]
	s_mov_b32 m0, s36
	v_readfirstlane_b32 s37, v120
	v_add_u32_e32 v121, 0xc800, v125
	global_load_lds_dwordx4 v[0:1], off
	v_lshl_add_u64 v[0:1], v[68:69], 0, s[20:21]
	s_mov_b32 m0, s37
	v_readfirstlane_b32 s38, v121
	v_add_u32_e32 v122, 0xcc00, v125
	global_load_lds_dwordx4 v[0:1], off
	v_lshl_add_u64 v[0:1], v[70:71], 0, s[20:21]
	s_mov_b32 m0, s38
	v_readfirstlane_b32 s39, v122
	v_add_u32_e32 v123, s85, v5
	global_load_lds_dwordx4 v[0:1], off
	v_lshl_add_u64 v[0:1], v[72:73], 0, s[20:21]
	s_mov_b32 m0, s39
	v_readfirstlane_b32 s40, v123
	v_add_u32_e32 v124, 0x14400, v6
	global_load_lds_dwordx4 v[0:1], off
	v_lshl_add_u64 v[0:1], v[74:75], 0, s[20:21]
	s_mov_b32 m0, s40
	v_readfirstlane_b32 s41, v124
	global_load_lds_dwordx4 v[0:1], off
	v_lshl_add_u64 v[0:1], v[76:77], 0, s[20:21]
	s_mov_b32 m0, s41
	v_lshrrev_b32_e32 v2, 1, v12
	v_bfe_u32 v64, v12, 5, 1
	global_load_lds_dwordx4 v[0:1], off
	v_add_u32_e32 v113, s3, v3
	v_bitop3_b32 v0, v2, v64, 7 bitop3:0x6c
	s_waitcnt vmcnt(6)
	s_mov_b64 s[30:31], 0x100
	v_readfirstlane_b32 s20, v113
	v_add_u32_e32 v114, 0x400, v113
	v_lshlrev_b32_e32 v110, 4, v0
	s_waitcnt lgkmcnt(0)
	s_barrier
	v_lshl_add_u64 v[0:1], v[66:67], 0, s[30:31]
	s_mov_b32 m0, s20
	v_readfirstlane_b32 s21, v114
	v_add_u32_e32 v115, 0x800, v113
	global_load_lds_dwordx4 v[0:1], off
	v_lshl_add_u64 v[0:1], v[68:69], 0, s[30:31]
	s_mov_b32 m0, s21
	v_readfirstlane_b32 s23, v115
	v_add_u32_e32 v116, 0xc00, v113
	v_readlane_b32 s29, v212, 31
	v_and_b32_e32 v80, 31, v12
	global_load_lds_dwordx4 v[0:1], off
	v_lshl_add_u64 v[0:1], v[70:71], 0, s[30:31]
	s_mov_b32 m0, s23
	v_readfirstlane_b32 s28, v116
	v_add_u32_e32 v117, s29, v5
	v_add_u32_e32 v2, s3, v5
	v_lshlrev_b32_e32 v4, 7, v80
	global_load_lds_dwordx4 v[0:1], off
	v_lshl_add_u64 v[0:1], v[72:73], 0, s[30:31]
	s_mov_b32 m0, s28
	v_readfirstlane_b32 s29, v117
	v_add_u32_e32 v118, 0x8400, v2
	v_lshl_or_b32 v102, v79, 13, v4
	global_load_lds_dwordx4 v[0:1], off
	v_lshl_add_u64 v[0:1], v[74:75], 0, s[30:31]
	s_mov_b32 m0, s29
	v_readfirstlane_b32 s33, v118
	global_load_lds_dwordx4 v[0:1], off
	v_lshl_add_u64 v[0:1], v[76:77], 0, s[30:31]
	s_mov_b32 m0, s33
	v_add_u32_e32 v100, 0, v102
	global_load_lds_dwordx4 v[0:1], off
	v_add_u32_e32 v82, v100, v110
	v_ashrrev_i32_e32 v78, 7, v12
	ds_read_b128 a[0:3], v82 offset:32768
	ds_read_b128 a[4:7], v82 offset:36864
	v_lshl_or_b32 v111, v78, 13, v4
	v_add_u32_e32 v101, 0, v111
	v_add_u32_e32 v81, v101, v110
	ds_read_b128 a[8:11], v81
	ds_read_b128 a[12:15], v81 offset:4096
	v_lshrrev_b32_e32 v182, 6, v133
	s_nop 0
	v_readfirstlane_b32 s32, v182
	s_waitcnt lgkmcnt(1)
	v_mfma_f32_32x32x16_bf16 v[48:63], a[0:3], a[8:11], 0
	v_bfe_u32 v103, v12, 1, 3
	v_bitop3_b32 v85, v64, v103, 4 bitop3:0x36
	v_lshlrev_b32_e32 v131, 4, v85
	v_add_u32_e32 v85, v101, v131
	s_mov_b64 s[30:31], 0x180
	v_or_b32_e32 v146, 0x8000, v102
	s_waitcnt vmcnt(12)
	v_mfma_f32_32x32x16_bf16 v[32:47], a[4:7], a[8:11], 0
	v_or_b32_e32 v147, 0x9000, v102
	v_add_u32_e32 v138, s3, v110
	v_add_u32_e32 v148, s3, v111
	v_or_b32_e32 v149, 0x1000, v111
	s_mov_b64 s[60:61], 0x80
	s_mov_b64 s[80:81], 0x200
	s_waitcnt lgkmcnt(0)
	v_mfma_f32_32x32x16_bf16 v[16:31], a[0:3], a[12:15], 0
	v_bitop3_b32 v0, v64, v103, 2 bitop3:0x36
	v_lshlrev_b32_e32 v112, 4, v0
	v_add_u32_e32 v83, v101, v112
	ds_read_b128 a[28:31], v83 offset:4096
	ds_read_b128 a[24:27], v83
	v_add_u32_e32 v84, v100, v112
	ds_read_b128 a[20:23], v84 offset:36864
	ds_read_b128 a[16:19], v84 offset:32768
	v_mfma_f32_32x32x16_bf16 v[0:15], a[4:7], a[12:15], 0
	v_add_u32_e32 v142, s3, v112
	v_add_u32_e32 v86, v100, v131
	ds_read_b128 a[0:3], v86 offset:32768
	ds_read_b128 a[4:7], v86 offset:36864
	ds_read_b128 a[8:11], v85
	ds_read_b128 a[12:15], v85 offset:4096
	s_waitcnt lgkmcnt(4)
	v_mfma_f32_32x32x16_bf16 v[48:63], a[16:19], a[24:27], v[48:63]
	v_mfma_f32_32x32x16_bf16 v[32:47], a[20:23], a[24:27], v[32:47]
	v_mfma_f32_32x32x16_bf16 v[16:31], a[16:19], a[28:31], v[16:31]
	v_bitop3_b32 v87, v64, v103, 6 bitop3:0x36
	v_lshlrev_b32_e32 v132, 4, v87
	v_add_u32_e32 v87, v101, v132
	v_lshlrev_b32_e32 v64, 2, v64
	v_mfma_f32_32x32x16_bf16 v[0:15], a[20:23], a[28:31], v[0:15]
	v_add_u32_e32 v88, v100, v132
	ds_read_b128 a[16:19], v88 offset:32768
	ds_read_b128 a[20:23], v88 offset:36864
	ds_read_b128 a[24:27], v87
	ds_read_b128 a[28:31], v87 offset:4096
	s_waitcnt lgkmcnt(5)
	v_mfma_f32_32x32x16_bf16 v[48:63], a[0:3], a[8:11], v[48:63]
	v_mfma_f32_32x32x16_bf16 v[32:47], a[4:7], a[8:11], v[32:47]
	s_waitcnt lgkmcnt(4)
	v_mfma_f32_32x32x16_bf16 v[16:31], a[0:3], a[12:15], v[16:31]
	v_mfma_f32_32x32x16_bf16 v[0:15], a[4:7], a[12:15], v[0:15]
	s_waitcnt lgkmcnt(1)
	v_mfma_f32_32x32x16_bf16 v[48:63], a[16:19], a[24:27], v[48:63]
	v_mfma_f32_32x32x16_bf16 v[32:47], a[20:23], a[24:27], v[32:47]
	s_waitcnt vmcnt(6)
	s_waitcnt lgkmcnt(0)
	s_barrier
	ds_read_b128 a[12:15], v81 offset:53248
	ds_read_b128 a[8:11], v81 offset:49152
	v_mfma_f32_32x32x16_bf16 v[16:31], a[16:19], a[28:31], v[16:31]
	v_lshl_add_u64 v[158:159], v[66:67], 0, s[30:31]
	v_lshl_add_u64 v[160:161], v[68:69], 0, s[30:31]
	v_lshl_add_u64 v[162:163], v[70:71], 0, s[30:31]
	v_mfma_f32_32x32x16_bf16 v[0:15], a[20:23], a[28:31], v[0:15]
	s_and_b32 m0, s32, 7
	s_lshl_b32 m0, m0, 12
	s_add_i32 m0, m0, 0x0
	s_nop 0
	global_load_lds_dwordx4 v[158:159], off
	v_lshl_add_u64 v[164:165], v[72:73], 0, s[30:31]
	v_lshl_add_u64 v[166:167], v[74:75], 0, s[30:31]
	v_lshl_add_u64 v[168:169], v[76:77], 0, s[30:31]
	s_add_i32 s30, 0, 0xc000
	v_add_u32_e32 v89, s30, v110
	v_add_u32_e32 v91, v89, v146
	v_add_u32_e32 v89, v89, v147
	ds_read_b128 a[4:7], v89
	ds_read_b128 a[0:3], v91
	v_add_u32_e32 v90, s30, v112
	v_add_u32_e32 v92, v90, v146
	ds_read_b128 a[16:19], v92
	v_add_u32_e32 v90, v90, v147
	ds_read_b128 a[20:23], v90
	ds_read_b128 a[24:27], v83 offset:49152
	ds_read_b128 a[28:31], v83 offset:53248
	s_waitcnt lgkmcnt(4)
	v_mfma_f32_32x32x16_bf16 v[48:63], a[0:3], a[8:11], v[48:63]
	v_mfma_f32_32x32x16_bf16 v[32:47], a[4:7], a[8:11], v[32:47]
	s_and_b32 m0, s32, 7
	s_lshl_b32 m0, m0, 12
	s_add_i32 m0, m0, 0x400
	s_nop 0
	global_load_lds_dwordx4 v[160:161], off
	v_mfma_f32_32x32x16_bf16 v[16:31], a[0:3], a[12:15], v[16:31]
	v_add_u32_e32 v93, s30, v131
	v_mfma_f32_32x32x16_bf16 v[0:15], a[4:7], a[12:15], v[0:15]
	s_and_b32 m0, s32, 7
	s_lshl_b32 m0, m0, 12
	s_add_i32 m0, m0, 0x800
	s_nop 0
	global_load_lds_dwordx4 v[162:163], off
	v_add_u32_e32 v94, v93, v146
	ds_read_b128 a[0:3], v94
	v_add_u32_e32 v93, v93, v147
	ds_read_b128 a[4:7], v93
	ds_read_b128 a[8:11], v85 offset:49152
	ds_read_b128 a[12:15], v85 offset:53248
	s_waitcnt lgkmcnt(5)
	v_mfma_f32_32x32x16_bf16 v[48:63], a[16:19], a[24:27], v[48:63]
	v_mfma_f32_32x32x16_bf16 v[32:47], a[20:23], a[24:27], v[32:47]
	s_and_b32 m0, s32, 7
	s_lshl_b32 m0, m0, 12
	s_add_i32 m0, m0, 0xc00
	s_nop 0
	global_load_lds_dwordx4 v[164:165], off
	s_waitcnt lgkmcnt(4)
	v_mfma_f32_32x32x16_bf16 v[16:31], a[16:19], a[28:31], v[16:31]
	v_add_u32_e32 v95, s30, v132
	s_mov_b64 s[30:31], 0x200
	v_mfma_f32_32x32x16_bf16 v[0:15], a[20:23], a[28:31], v[0:15]
	s_and_b32 m0, s32, 7
	s_lshl_b32 m0, m0, 11
	s_add_i32 m0, m0, 0x8000
	s_nop 0
	global_load_lds_dwordx4 v[166:167], off
	v_add_u32_e32 v96, v95, v146
	ds_read_b128 a[16:19], v96
	v_add_u32_e32 v95, v95, v147
	ds_read_b128 a[20:23], v95
	ds_read_b128 a[24:27], v87 offset:49152
	ds_read_b128 a[28:31], v87 offset:53248
	s_waitcnt lgkmcnt(5)
	v_mfma_f32_32x32x16_bf16 v[48:63], a[0:3], a[8:11], v[48:63]
	v_mfma_f32_32x32x16_bf16 v[32:47], a[4:7], a[8:11], v[32:47]
	s_and_b32 m0, s32, 7
	s_lshl_b32 m0, m0, 11
	s_add_i32 m0, m0, 0x8400
	s_nop 0
	global_load_lds_dwordx4 v[168:169], off
	s_waitcnt lgkmcnt(4)
	v_mfma_f32_32x32x16_bf16 v[16:31], a[0:3], a[12:15], v[16:31]
	v_add_u32_e32 v97, v138, v146
	v_mfma_f32_32x32x16_bf16 v[0:15], a[4:7], a[12:15], v[0:15]
	s_waitcnt lgkmcnt(1)
	v_mfma_f32_32x32x16_bf16 v[48:63], a[16:19], a[24:27], v[48:63]
	v_mfma_f32_32x32x16_bf16 v[32:47], a[20:23], a[24:27], v[32:47]
	s_waitcnt vmcnt(6)
	s_waitcnt lgkmcnt(0)
	s_barrier
	v_add_u32_e32 v100, v138, v149
	ds_read_b128 a[12:15], v100
	v_add_u32_e32 v99, v148, v110
	ds_read_b128 a[8:11], v99
	v_add_u32_e32 v98, v138, v147
	ds_read_b128 a[4:7], v98
	ds_read_b128 a[0:3], v97
	v_mfma_f32_32x32x16_bf16 v[16:31], a[16:19], a[28:31], v[16:31]
	v_lshl_add_u64 v[170:171], v[66:67], 0, s[30:31]
	v_lshl_add_u64 v[172:173], v[68:69], 0, s[30:31]
	v_lshl_add_u64 v[174:175], v[70:71], 0, s[30:31]
	v_mfma_f32_32x32x16_bf16 v[0:15], a[20:23], a[28:31], v[0:15]
	s_and_b32 m0, s32, 7
	s_lshl_b32 m0, m0, 12
	s_add_i32 m0, m0, 0xc000
	s_nop 0
	global_load_lds_dwordx4 v[170:171], off
	v_lshl_add_u64 v[176:177], v[72:73], 0, s[30:31]
	v_lshl_add_u64 v[178:179], v[74:75], 0, s[30:31]
	v_lshl_add_u64 v[180:181], v[76:77], 0, s[30:31]
	s_mov_b64 s[30:31], 0x280
	v_add_u32_e32 v101, v142, v146
	ds_read_b128 a[16:19], v101
	v_add_u32_e32 v102, v142, v147
	ds_read_b128 a[20:23], v102
	v_add_u32_e32 v103, v148, v112
	ds_read_b128 a[24:27], v103
	v_add_u32_e32 v104, v142, v149
	ds_read_b128 a[28:31], v104
	s_waitcnt lgkmcnt(4)
	v_mfma_f32_32x32x16_bf16 v[48:63], a[0:3], a[8:11], v[48:63]
	v_mfma_f32_32x32x16_bf16 v[32:47], a[4:7], a[8:11], v[32:47]
	s_and_b32 m0, s32, 7
	s_lshl_b32 m0, m0, 12
	s_add_i32 m0, m0, 0xc400
	s_nop 0
	global_load_lds_dwordx4 v[172:173], off
	v_add_u32_e32 v112, s3, v131
	v_mfma_f32_32x32x16_bf16 v[16:31], a[0:3], a[12:15], v[16:31]
	v_mfma_f32_32x32x16_bf16 v[0:15], a[4:7], a[12:15], v[0:15]
	s_and_b32 m0, s32, 7
	s_lshl_b32 m0, m0, 12
	s_add_i32 m0, m0, 0xc800
	s_nop 0
	global_load_lds_dwordx4 v[174:175], off
	v_add_u32_e32 v105, v112, v146
	ds_read_b128 a[0:3], v105
	v_add_u32_e32 v106, v112, v147
	ds_read_b128 a[4:7], v106
	v_add_u32_e32 v107, v148, v131
	ds_read_b128 a[8:11], v107
	v_add_u32_e32 v108, v112, v149
	ds_read_b128 a[12:15], v108
	s_waitcnt lgkmcnt(5)
	v_mfma_f32_32x32x16_bf16 v[48:63], a[16:19], a[24:27], v[48:63]
	v_mfma_f32_32x32x16_bf16 v[32:47], a[20:23], a[24:27], v[32:47]
	s_and_b32 m0, s32, 7
	s_lshl_b32 m0, m0, 12
	s_add_i32 m0, m0, 0xcc00
	s_nop 0
	global_load_lds_dwordx4 v[176:177], off
	s_waitcnt lgkmcnt(4)
	v_mfma_f32_32x32x16_bf16 v[16:31], a[16:19], a[28:31], v[16:31]
	v_mfma_f32_32x32x16_bf16 v[0:15], a[20:23], a[28:31], v[0:15]
	s_and_b32 m0, s32, 7
	s_lshl_b32 m0, m0, 11
	s_add_i32 m0, m0, 0x14000
	s_nop 0
	global_load_lds_dwordx4 v[178:179], off
	v_add_u32_e32 v112, s3, v132
	v_add_u32_e32 v109, v112, v146
	ds_read_b128 a[16:19], v109
	v_add_u32_e32 v110, v112, v147
	ds_read_b128 a[20:23], v110
	v_add_u32_e32 v111, v148, v132
	ds_read_b128 a[24:27], v111
	v_add_u32_e32 v112, v112, v149
	ds_read_b128 a[28:31], v112
	s_waitcnt lgkmcnt(5)
	v_mfma_f32_32x32x16_bf16 v[48:63], a[0:3], a[8:11], v[48:63]
	v_mfma_f32_32x32x16_bf16 v[32:47], a[4:7], a[8:11], v[32:47]
	s_and_b32 m0, s32, 7
	s_lshl_b32 m0, m0, 11
	s_add_i32 m0, m0, 0x14400
	s_nop 0
	global_load_lds_dwordx4 v[180:181], off
	s_waitcnt lgkmcnt(4)
	v_mfma_f32_32x32x16_bf16 v[16:31], a[0:3], a[12:15], v[16:31]
	v_mfma_f32_32x32x16_bf16 v[0:15], a[4:7], a[12:15], v[0:15]
	s_waitcnt lgkmcnt(1)
	v_mfma_f32_32x32x16_bf16 v[48:63], a[16:19], a[24:27], v[48:63]
	v_mfma_f32_32x32x16_bf16 v[32:47], a[20:23], a[24:27], v[32:47]
	s_waitcnt vmcnt(6)
	s_waitcnt lgkmcnt(0)
	s_barrier
	ds_read_b128 a[12:15], v81 offset:4096
	ds_read_b128 a[8:11], v81
	ds_read_b128 a[4:7], v82 offset:36864
	ds_read_b128 a[0:3], v82 offset:32768
	v_mfma_f32_32x32x16_bf16 v[16:31], a[16:19], a[28:31], v[16:31]
	v_lshl_add_u64 v[158:159], v[66:67], 0, s[30:31]
	v_lshl_add_u64 v[160:161], v[68:69], 0, s[30:31]
	v_lshl_add_u64 v[162:163], v[70:71], 0, s[30:31]
	v_mfma_f32_32x32x16_bf16 v[0:15], a[20:23], a[28:31], v[0:15]
	s_and_b32 m0, s32, 7
	s_lshl_b32 m0, m0, 12
	s_add_i32 m0, m0, 0x18000
	s_nop 0
	global_load_lds_dwordx4 v[158:159], off
	v_lshl_add_u64 v[164:165], v[72:73], 0, s[30:31]
	v_lshl_add_u64 v[166:167], v[74:75], 0, s[30:31]
	v_lshl_add_u64 v[168:169], v[76:77], 0, s[30:31]
	s_mov_b64 s[30:31], 0x300
	ds_read_b128 a[16:19], v84 offset:32768
	ds_read_b128 a[20:23], v84 offset:36864
	ds_read_b128 a[24:27], v83
	ds_read_b128 a[28:31], v83 offset:4096
	s_waitcnt lgkmcnt(4)
	v_mfma_f32_32x32x16_bf16 v[48:63], a[0:3], a[8:11], v[48:63]
	s_nop 0
	v_readfirstlane_b32 s42, v113
	v_mfma_f32_32x32x16_bf16 v[32:47], a[4:7], a[8:11], v[32:47]
	s_and_b32 m0, s32, 7
	s_lshl_b32 m0, m0, 12
	s_add_i32 m0, m0, 0x18400
	s_nop 0
	global_load_lds_dwordx4 v[160:161], off
	v_mfma_f32_32x32x16_bf16 v[16:31], a[0:3], a[12:15], v[16:31]
	v_mfma_f32_32x32x16_bf16 v[0:15], a[4:7], a[12:15], v[0:15]
	s_and_b32 m0, s32, 7
	s_lshl_b32 m0, m0, 12
	s_add_i32 m0, m0, 0x18800
	s_nop 0
	global_load_lds_dwordx4 v[162:163], off
	ds_read_b128 a[0:3], v86 offset:32768
	ds_read_b128 a[4:7], v86 offset:36864
	ds_read_b128 a[8:11], v85
	ds_read_b128 a[12:15], v85 offset:4096
	s_waitcnt lgkmcnt(5)
	v_mfma_f32_32x32x16_bf16 v[48:63], a[16:19], a[24:27], v[48:63]
	v_mfma_f32_32x32x16_bf16 v[32:47], a[20:23], a[24:27], v[32:47]
	s_and_b32 m0, s32, 7
	s_lshl_b32 m0, m0, 12
	s_add_i32 m0, m0, 0x18c00
	s_nop 0
	global_load_lds_dwordx4 v[164:165], off
	s_waitcnt lgkmcnt(4)
	v_mfma_f32_32x32x16_bf16 v[16:31], a[16:19], a[28:31], v[16:31]
	v_mfma_f32_32x32x16_bf16 v[0:15], a[20:23], a[28:31], v[0:15]
	s_and_b32 m0, s32, 7
	s_lshl_b32 m0, m0, 11
	s_add_i32 m0, m0, 0x20000
	s_nop 0
	global_load_lds_dwordx4 v[166:167], off
	ds_read_b128 a[16:19], v88 offset:32768
	ds_read_b128 a[20:23], v88 offset:36864
	ds_read_b128 a[24:27], v87
	ds_read_b128 a[28:31], v87 offset:4096
	s_waitcnt lgkmcnt(5)
	v_mfma_f32_32x32x16_bf16 v[48:63], a[0:3], a[8:11], v[48:63]
	v_mfma_f32_32x32x16_bf16 v[32:47], a[4:7], a[8:11], v[32:47]
	s_and_b32 m0, s32, 7
	s_lshl_b32 m0, m0, 11
	s_add_i32 m0, m0, 0x20400
	s_nop 0
	global_load_lds_dwordx4 v[168:169], off
	s_waitcnt lgkmcnt(4)
	v_mfma_f32_32x32x16_bf16 v[16:31], a[0:3], a[12:15], v[16:31]
	v_mfma_f32_32x32x16_bf16 v[0:15], a[4:7], a[12:15], v[0:15]
	s_waitcnt lgkmcnt(1)
	v_mfma_f32_32x32x16_bf16 v[48:63], a[16:19], a[24:27], v[48:63]
	v_mfma_f32_32x32x16_bf16 v[32:47], a[20:23], a[24:27], v[32:47]
	s_waitcnt vmcnt(6)
	s_waitcnt lgkmcnt(0)
	s_barrier
	ds_read_b128 a[12:15], v81 offset:53248
	ds_read_b128 a[8:11], v81 offset:49152
	ds_read_b128 a[4:7], v89
	ds_read_b128 a[0:3], v91
	v_mfma_f32_32x32x16_bf16 v[16:31], a[16:19], a[28:31], v[16:31]
	v_lshl_add_u64 v[170:171], v[66:67], 0, s[30:31]
	v_lshl_add_u64 v[172:173], v[68:69], 0, s[30:31]
	s_nop 0
	v_readfirstlane_b32 s43, v114
	s_nop 0
	v_lshl_add_u64 v[174:175], v[70:71], 0, s[30:31]
	s_nop 0
	v_mfma_f32_32x32x16_bf16 v[0:15], a[20:23], a[28:31], v[0:15]
	s_and_b32 m0, s32, 7
	s_lshl_b32 m0, m0, 12
	s_add_i32 m0, m0, 0x0
	s_nop 0
	global_load_lds_dwordx4 v[170:171], off
	v_lshl_add_u64 v[176:177], v[72:73], 0, s[30:31]
	s_nop 0
	v_readfirstlane_b32 s44, v115
	s_nop 0
	v_lshl_add_u64 v[178:179], v[74:75], 0, s[30:31]
	s_nop 0
	v_readfirstlane_b32 s45, v116
	s_nop 0
	v_lshl_add_u64 v[180:181], v[76:77], 0, s[30:31]
	s_nop 0
	s_mov_b64 s[30:31], 0x380
	ds_read_b128 a[16:19], v92
	ds_read_b128 a[20:23], v90
	ds_read_b128 a[24:27], v83 offset:49152
	ds_read_b128 a[28:31], v83 offset:53248
	s_waitcnt lgkmcnt(4)
	v_mfma_f32_32x32x16_bf16 v[48:63], a[0:3], a[8:11], v[48:63]
	s_nop 0
	v_readfirstlane_b32 s36, v119
	v_readfirstlane_b32 s46, v117
	v_readfirstlane_b32 s47, v118
	v_mfma_f32_32x32x16_bf16 v[32:47], a[4:7], a[8:11], v[32:47]
	s_and_b32 m0, s32, 7
	s_lshl_b32 m0, m0, 12
	s_add_i32 m0, m0, 0x400
	s_nop 0
	global_load_lds_dwordx4 v[172:173], off
	v_mfma_f32_32x32x16_bf16 v[16:31], a[0:3], a[12:15], v[16:31]
	v_mfma_f32_32x32x16_bf16 v[0:15], a[4:7], a[12:15], v[0:15]
	s_and_b32 m0, s32, 7
	s_lshl_b32 m0, m0, 12
	s_add_i32 m0, m0, 0x800
	s_nop 0
	global_load_lds_dwordx4 v[174:175], off
	ds_read_b128 a[0:3], v94
	ds_read_b128 a[4:7], v93
	ds_read_b128 a[8:11], v85 offset:49152
	ds_read_b128 a[12:15], v85 offset:53248
	s_waitcnt lgkmcnt(5)
	v_mfma_f32_32x32x16_bf16 v[48:63], a[16:19], a[24:27], v[48:63]
	v_mfma_f32_32x32x16_bf16 v[32:47], a[20:23], a[24:27], v[32:47]
	s_and_b32 m0, s32, 7
	s_lshl_b32 m0, m0, 12
	s_add_i32 m0, m0, 0xc00
	s_nop 0
	global_load_lds_dwordx4 v[176:177], off
	s_waitcnt lgkmcnt(4)
	v_mfma_f32_32x32x16_bf16 v[16:31], a[16:19], a[28:31], v[16:31]
	v_mfma_f32_32x32x16_bf16 v[0:15], a[20:23], a[28:31], v[0:15]
	s_and_b32 m0, s32, 7
	s_lshl_b32 m0, m0, 11
	s_add_i32 m0, m0, 0x8000
	s_nop 0
	global_load_lds_dwordx4 v[178:179], off
	ds_read_b128 a[16:19], v96
	ds_read_b128 a[20:23], v95
	ds_read_b128 a[24:27], v87 offset:49152
	ds_read_b128 a[28:31], v87 offset:53248
	s_waitcnt lgkmcnt(5)
	v_mfma_f32_32x32x16_bf16 v[48:63], a[0:3], a[8:11], v[48:63]
	v_mfma_f32_32x32x16_bf16 v[32:47], a[4:7], a[8:11], v[32:47]
	s_and_b32 m0, s32, 7
	s_lshl_b32 m0, m0, 11
	s_add_i32 m0, m0, 0x8400
	s_nop 0
	global_load_lds_dwordx4 v[180:181], off
	s_waitcnt lgkmcnt(4)
	v_mfma_f32_32x32x16_bf16 v[16:31], a[0:3], a[12:15], v[16:31]
	v_mfma_f32_32x32x16_bf16 v[0:15], a[4:7], a[12:15], v[0:15]
	s_waitcnt lgkmcnt(1)
	v_mfma_f32_32x32x16_bf16 v[48:63], a[16:19], a[24:27], v[48:63]
	v_mfma_f32_32x32x16_bf16 v[32:47], a[20:23], a[24:27], v[32:47]
	s_waitcnt vmcnt(6)
	s_waitcnt lgkmcnt(0)
	s_barrier
	ds_read_b128 a[12:15], v100
	ds_read_b128 a[8:11], v99
	ds_read_b128 a[4:7], v98
	ds_read_b128 a[0:3], v97
	v_mfma_f32_32x32x16_bf16 v[16:31], a[16:19], a[28:31], v[16:31]
	v_lshl_add_u64 v[158:159], v[66:67], 0, s[30:31]
	v_lshl_add_u64 v[160:161], v[68:69], 0, s[30:31]
	s_nop 0
	v_readfirstlane_b32 s37, v120
	s_nop 0
	v_lshl_add_u64 v[162:163], v[70:71], 0, s[30:31]
	s_nop 0
	v_mfma_f32_32x32x16_bf16 v[0:15], a[20:23], a[28:31], v[0:15]
	s_and_b32 m0, s32, 7
	s_lshl_b32 m0, m0, 12
	s_add_i32 m0, m0, 0xc000
	s_nop 0
	global_load_lds_dwordx4 v[158:159], off
	v_lshl_add_u64 v[164:165], v[72:73], 0, s[30:31]
	s_nop 0
	v_readfirstlane_b32 s38, v121
	s_nop 0
	v_lshl_add_u64 v[166:167], v[74:75], 0, s[30:31]
	s_nop 0
	v_readfirstlane_b32 s39, v122
	s_nop 0
	v_lshl_add_u64 v[168:169], v[76:77], 0, s[30:31]
	s_nop 0
	s_mov_b64 s[30:31], 0x400
	ds_read_b128 a[16:19], v101
	ds_read_b128 a[20:23], v102
	ds_read_b128 a[24:27], v103
	ds_read_b128 a[28:31], v104
	s_waitcnt lgkmcnt(4)
	v_mfma_f32_32x32x16_bf16 v[48:63], a[0:3], a[8:11], v[48:63]
	s_nop 0
	v_readfirstlane_b32 s20, v125
	v_readfirstlane_b32 s40, v123
	v_readfirstlane_b32 s41, v124
	v_mfma_f32_32x32x16_bf16 v[32:47], a[4:7], a[8:11], v[32:47]
	s_and_b32 m0, s32, 7
	s_lshl_b32 m0, m0, 12
	s_add_i32 m0, m0, 0xc400
	s_nop 0
	global_load_lds_dwordx4 v[160:161], off
	v_mfma_f32_32x32x16_bf16 v[16:31], a[0:3], a[12:15], v[16:31]
	v_mfma_f32_32x32x16_bf16 v[0:15], a[4:7], a[12:15], v[0:15]
	s_and_b32 m0, s32, 7
	s_lshl_b32 m0, m0, 12
	s_add_i32 m0, m0, 0xc800
	s_nop 0
	global_load_lds_dwordx4 v[162:163], off
	ds_read_b128 a[0:3], v105
	ds_read_b128 a[4:7], v106
	ds_read_b128 a[8:11], v107
	ds_read_b128 a[12:15], v108
	s_waitcnt lgkmcnt(5)
	v_mfma_f32_32x32x16_bf16 v[48:63], a[16:19], a[24:27], v[48:63]
	v_mfma_f32_32x32x16_bf16 v[32:47], a[20:23], a[24:27], v[32:47]
	s_and_b32 m0, s32, 7
	s_lshl_b32 m0, m0, 12
	s_add_i32 m0, m0, 0xcc00
	s_nop 0
	global_load_lds_dwordx4 v[164:165], off
	s_waitcnt lgkmcnt(4)
	v_mfma_f32_32x32x16_bf16 v[16:31], a[16:19], a[28:31], v[16:31]
	v_mfma_f32_32x32x16_bf16 v[0:15], a[20:23], a[28:31], v[0:15]
	s_and_b32 m0, s32, 7
	s_lshl_b32 m0, m0, 11
	s_add_i32 m0, m0, 0x14000
	s_nop 0
	global_load_lds_dwordx4 v[166:167], off
	ds_read_b128 a[16:19], v109
	ds_read_b128 a[20:23], v110
	ds_read_b128 a[24:27], v111
	ds_read_b128 a[28:31], v112
	s_waitcnt lgkmcnt(5)
	v_mfma_f32_32x32x16_bf16 v[48:63], a[0:3], a[8:11], v[48:63]
	v_mfma_f32_32x32x16_bf16 v[32:47], a[4:7], a[8:11], v[32:47]
	s_and_b32 m0, s32, 7
	s_lshl_b32 m0, m0, 11
	s_add_i32 m0, m0, 0x14400
	s_nop 0
	global_load_lds_dwordx4 v[168:169], off
	s_waitcnt lgkmcnt(4)
	v_mfma_f32_32x32x16_bf16 v[16:31], a[0:3], a[12:15], v[16:31]
	v_mfma_f32_32x32x16_bf16 v[0:15], a[4:7], a[12:15], v[0:15]
	s_waitcnt lgkmcnt(1)
	v_mfma_f32_32x32x16_bf16 v[48:63], a[16:19], a[24:27], v[48:63]
	v_mfma_f32_32x32x16_bf16 v[32:47], a[20:23], a[24:27], v[32:47]
	s_waitcnt vmcnt(6)
	s_waitcnt lgkmcnt(0)
	s_barrier
	ds_read_b128 a[12:15], v81 offset:4096
	ds_read_b128 a[8:11], v81
	ds_read_b128 a[4:7], v82 offset:36864
	ds_read_b128 a[0:3], v82 offset:32768
	v_mfma_f32_32x32x16_bf16 v[16:31], a[16:19], a[28:31], v[16:31]
	v_lshl_add_u64 v[170:171], v[66:67], 0, s[30:31]
	v_lshl_add_u64 v[172:173], v[68:69], 0, s[30:31]
	s_nop 0
	v_readfirstlane_b32 s21, v126
	s_nop 0
	v_lshl_add_u64 v[174:175], v[70:71], 0, s[30:31]
	s_nop 0
	v_mfma_f32_32x32x16_bf16 v[0:15], a[20:23], a[28:31], v[0:15]
	s_and_b32 m0, s32, 7
	s_lshl_b32 m0, m0, 12
	s_add_i32 m0, m0, 0x18000
	s_nop 0
	global_load_lds_dwordx4 v[170:171], off
	v_lshl_add_u64 v[176:177], v[72:73], 0, s[30:31]
	s_nop 0
	v_readfirstlane_b32 s23, v127
	s_nop 0
	v_lshl_add_u64 v[178:179], v[74:75], 0, s[30:31]
	s_nop 0
	v_readfirstlane_b32 s28, v128
	s_nop 0
	v_lshl_add_u64 v[180:181], v[76:77], 0, s[30:31]
	s_nop 0
	s_mov_b64 s[30:31], 0x480
	ds_read_b128 a[16:19], v84 offset:32768
	ds_read_b128 a[20:23], v84 offset:36864
	ds_read_b128 a[24:27], v83
	ds_read_b128 a[28:31], v83 offset:4096
	s_waitcnt lgkmcnt(4)
	v_mfma_f32_32x32x16_bf16 v[48:63], a[0:3], a[8:11], v[48:63]
	s_nop 0
	v_lshl_add_u64 v[164:165], v[72:73], 0, s[30:31]
	v_readfirstlane_b32 s29, v130
	v_readfirstlane_b32 s33, v129
	v_mfma_f32_32x32x16_bf16 v[32:47], a[4:7], a[8:11], v[32:47]
	s_and_b32 m0, s32, 7
	s_lshl_b32 m0, m0, 12
	s_add_i32 m0, m0, 0x18400
	s_nop 0
	global_load_lds_dwordx4 v[172:173], off
	v_mfma_f32_32x32x16_bf16 v[16:31], a[0:3], a[12:15], v[16:31]
	v_mfma_f32_32x32x16_bf16 v[0:15], a[4:7], a[12:15], v[0:15]
	s_and_b32 m0, s32, 7
	s_lshl_b32 m0, m0, 12
	s_add_i32 m0, m0, 0x18800
	s_nop 0
	global_load_lds_dwordx4 v[174:175], off
	ds_read_b128 a[0:3], v86 offset:32768
	ds_read_b128 a[4:7], v86 offset:36864
	ds_read_b128 a[8:11], v85
	ds_read_b128 a[12:15], v85 offset:4096
	s_waitcnt lgkmcnt(5)
	v_mfma_f32_32x32x16_bf16 v[48:63], a[16:19], a[24:27], v[48:63]
	v_mfma_f32_32x32x16_bf16 v[32:47], a[20:23], a[24:27], v[32:47]
	s_and_b32 m0, s32, 7
	s_lshl_b32 m0, m0, 12
	s_add_i32 m0, m0, 0x18c00
	s_nop 0
	global_load_lds_dwordx4 v[176:177], off
	s_waitcnt lgkmcnt(4)
	v_mfma_f32_32x32x16_bf16 v[16:31], a[16:19], a[28:31], v[16:31]
	v_mfma_f32_32x32x16_bf16 v[0:15], a[20:23], a[28:31], v[0:15]
	s_and_b32 m0, s32, 7
	s_lshl_b32 m0, m0, 11
	s_add_i32 m0, m0, 0x20000
	s_nop 0
	global_load_lds_dwordx4 v[178:179], off
	ds_read_b128 a[16:19], v88 offset:32768
	ds_read_b128 a[20:23], v88 offset:36864
	ds_read_b128 a[24:27], v87
	ds_read_b128 a[28:31], v87 offset:4096
	s_waitcnt lgkmcnt(5)
	v_mfma_f32_32x32x16_bf16 v[48:63], a[0:3], a[8:11], v[48:63]
	v_mfma_f32_32x32x16_bf16 v[32:47], a[4:7], a[8:11], v[32:47]
	s_and_b32 m0, s32, 7
	s_lshl_b32 m0, m0, 11
	s_add_i32 m0, m0, 0x20400
	s_nop 0
	global_load_lds_dwordx4 v[180:181], off
	s_waitcnt lgkmcnt(4)
	v_mfma_f32_32x32x16_bf16 v[16:31], a[0:3], a[12:15], v[16:31]
	v_mfma_f32_32x32x16_bf16 v[0:15], a[4:7], a[12:15], v[0:15]
	s_waitcnt lgkmcnt(1)
	v_mfma_f32_32x32x16_bf16 v[48:63], a[16:19], a[24:27], v[48:63]
	v_mfma_f32_32x32x16_bf16 v[32:47], a[20:23], a[24:27], v[32:47]
	s_waitcnt vmcnt(6)
	s_waitcnt lgkmcnt(0)
	s_barrier
	ds_read_b128 a[12:15], v81 offset:53248
	ds_read_b128 a[8:11], v81 offset:49152
	ds_read_b128 a[4:7], v89
	ds_read_b128 a[0:3], v91
	v_mfma_f32_32x32x16_bf16 v[16:31], a[16:19], a[28:31], v[16:31]
	v_lshl_add_u64 v[158:159], v[66:67], 0, s[30:31]
	v_lshl_add_u64 v[160:161], v[68:69], 0, s[30:31]
	v_lshl_add_u64 v[162:163], v[70:71], 0, s[30:31]
	v_mfma_f32_32x32x16_bf16 v[0:15], a[20:23], a[28:31], v[0:15]
	s_and_b32 m0, s32, 7
	s_lshl_b32 m0, m0, 12
	s_add_i32 m0, m0, 0x0
	s_nop 0
	global_load_lds_dwordx4 v[158:159], off
	v_lshl_add_u64 v[166:167], v[74:75], 0, s[30:31]
	v_lshl_add_u64 v[168:169], v[76:77], 0, s[30:31]
	s_mov_b64 s[30:31], 0x500
	ds_read_b128 a[16:19], v92
	ds_read_b128 a[20:23], v90
	ds_read_b128 a[24:27], v83 offset:49152
	ds_read_b128 a[28:31], v83 offset:53248
	s_waitcnt lgkmcnt(4)
	v_mfma_f32_32x32x16_bf16 v[48:63], a[0:3], a[8:11], v[48:63]
	v_lshl_add_u64 v[176:177], v[72:73], 0, s[30:31]
	v_mfma_f32_32x32x16_bf16 v[32:47], a[4:7], a[8:11], v[32:47]
	s_and_b32 m0, s32, 7
	s_lshl_b32 m0, m0, 12
	s_add_i32 m0, m0, 0x400
	s_nop 0
	global_load_lds_dwordx4 v[160:161], off
	v_mfma_f32_32x32x16_bf16 v[16:31], a[0:3], a[12:15], v[16:31]
	v_mfma_f32_32x32x16_bf16 v[0:15], a[4:7], a[12:15], v[0:15]
	s_and_b32 m0, s32, 7
	s_lshl_b32 m0, m0, 12
	s_add_i32 m0, m0, 0x800
	s_nop 0
	global_load_lds_dwordx4 v[162:163], off
	ds_read_b128 a[0:3], v94
	ds_read_b128 a[4:7], v93
	ds_read_b128 a[8:11], v85 offset:49152
	ds_read_b128 a[12:15], v85 offset:53248
	s_waitcnt lgkmcnt(5)
	v_mfma_f32_32x32x16_bf16 v[48:63], a[16:19], a[24:27], v[48:63]
	v_mfma_f32_32x32x16_bf16 v[32:47], a[20:23], a[24:27], v[32:47]
	s_and_b32 m0, s32, 7
	s_lshl_b32 m0, m0, 12
	s_add_i32 m0, m0, 0xc00
	s_nop 0
	global_load_lds_dwordx4 v[164:165], off
	s_waitcnt lgkmcnt(4)
	v_mfma_f32_32x32x16_bf16 v[16:31], a[16:19], a[28:31], v[16:31]
	v_mfma_f32_32x32x16_bf16 v[0:15], a[20:23], a[28:31], v[0:15]
	s_and_b32 m0, s32, 7
	s_lshl_b32 m0, m0, 11
	s_add_i32 m0, m0, 0x8000
	s_nop 0
	global_load_lds_dwordx4 v[166:167], off
	ds_read_b128 a[16:19], v96
	ds_read_b128 a[20:23], v95
	ds_read_b128 a[24:27], v87 offset:49152
	ds_read_b128 a[28:31], v87 offset:53248
	s_waitcnt lgkmcnt(5)
	v_mfma_f32_32x32x16_bf16 v[48:63], a[0:3], a[8:11], v[48:63]
	v_mfma_f32_32x32x16_bf16 v[32:47], a[4:7], a[8:11], v[32:47]
	s_and_b32 m0, s32, 7
	s_lshl_b32 m0, m0, 11
	s_add_i32 m0, m0, 0x8400
	s_nop 0
	global_load_lds_dwordx4 v[168:169], off
	s_waitcnt lgkmcnt(4)
	v_mfma_f32_32x32x16_bf16 v[16:31], a[0:3], a[12:15], v[16:31]
	v_mfma_f32_32x32x16_bf16 v[0:15], a[4:7], a[12:15], v[0:15]
	s_waitcnt lgkmcnt(1)
	v_mfma_f32_32x32x16_bf16 v[48:63], a[16:19], a[24:27], v[48:63]
	v_mfma_f32_32x32x16_bf16 v[32:47], a[20:23], a[24:27], v[32:47]
	s_waitcnt vmcnt(6)
	s_waitcnt lgkmcnt(0)
	s_barrier
	ds_read_b128 a[12:15], v100
	ds_read_b128 a[8:11], v99
	ds_read_b128 a[4:7], v98
	ds_read_b128 a[0:3], v97
	v_mfma_f32_32x32x16_bf16 v[16:31], a[16:19], a[28:31], v[16:31]
	v_lshl_add_u64 v[170:171], v[66:67], 0, s[30:31]
	v_lshl_add_u64 v[172:173], v[68:69], 0, s[30:31]
	v_lshl_add_u64 v[174:175], v[70:71], 0, s[30:31]
	v_mfma_f32_32x32x16_bf16 v[0:15], a[20:23], a[28:31], v[0:15]
	s_and_b32 m0, s32, 7
	s_lshl_b32 m0, m0, 12
	s_add_i32 m0, m0, 0xc000
	s_nop 0
	global_load_lds_dwordx4 v[170:171], off
	v_lshl_add_u64 v[178:179], v[74:75], 0, s[30:31]
	v_lshl_add_u64 v[180:181], v[76:77], 0, s[30:31]
	s_mov_b64 s[30:31], 0x580
	ds_read_b128 a[16:19], v101
	ds_read_b128 a[20:23], v102
	ds_read_b128 a[24:27], v103
	ds_read_b128 a[28:31], v104
	s_waitcnt lgkmcnt(4)
	v_mfma_f32_32x32x16_bf16 v[48:63], a[0:3], a[8:11], v[48:63]
	v_lshl_add_u64 v[164:165], v[72:73], 0, s[30:31]
	v_mfma_f32_32x32x16_bf16 v[32:47], a[4:7], a[8:11], v[32:47]
	s_and_b32 m0, s32, 7
	s_lshl_b32 m0, m0, 12
	s_add_i32 m0, m0, 0xc400
	s_nop 0
	global_load_lds_dwordx4 v[172:173], off
	v_mfma_f32_32x32x16_bf16 v[16:31], a[0:3], a[12:15], v[16:31]
	v_mfma_f32_32x32x16_bf16 v[0:15], a[4:7], a[12:15], v[0:15]
	s_and_b32 m0, s32, 7
	s_lshl_b32 m0, m0, 12
	s_add_i32 m0, m0, 0xc800
	s_nop 0
	global_load_lds_dwordx4 v[174:175], off
	ds_read_b128 a[0:3], v105
	ds_read_b128 a[4:7], v106
	ds_read_b128 a[8:11], v107
	ds_read_b128 a[12:15], v108
	s_waitcnt lgkmcnt(5)
	v_mfma_f32_32x32x16_bf16 v[48:63], a[16:19], a[24:27], v[48:63]
	v_mfma_f32_32x32x16_bf16 v[32:47], a[20:23], a[24:27], v[32:47]
	s_and_b32 m0, s32, 7
	s_lshl_b32 m0, m0, 12
	s_add_i32 m0, m0, 0xcc00
	s_nop 0
	global_load_lds_dwordx4 v[176:177], off
	s_waitcnt lgkmcnt(4)
	v_mfma_f32_32x32x16_bf16 v[16:31], a[16:19], a[28:31], v[16:31]
	v_mfma_f32_32x32x16_bf16 v[0:15], a[20:23], a[28:31], v[0:15]
	s_and_b32 m0, s32, 7
	s_lshl_b32 m0, m0, 11
	s_add_i32 m0, m0, 0x14000
	s_nop 0
	global_load_lds_dwordx4 v[178:179], off
	ds_read_b128 a[16:19], v109
	ds_read_b128 a[20:23], v110
	ds_read_b128 a[24:27], v111
	ds_read_b128 a[28:31], v112
	s_waitcnt lgkmcnt(5)
	v_mfma_f32_32x32x16_bf16 v[48:63], a[0:3], a[8:11], v[48:63]
	v_mfma_f32_32x32x16_bf16 v[32:47], a[4:7], a[8:11], v[32:47]
	s_and_b32 m0, s32, 7
	s_lshl_b32 m0, m0, 11
	s_add_i32 m0, m0, 0x14400
	s_nop 0
	global_load_lds_dwordx4 v[180:181], off
	s_waitcnt lgkmcnt(4)
	v_mfma_f32_32x32x16_bf16 v[16:31], a[0:3], a[12:15], v[16:31]
	v_mfma_f32_32x32x16_bf16 v[0:15], a[4:7], a[12:15], v[0:15]
	s_waitcnt lgkmcnt(1)
	v_mfma_f32_32x32x16_bf16 v[48:63], a[16:19], a[24:27], v[48:63]
	v_mfma_f32_32x32x16_bf16 v[32:47], a[20:23], a[24:27], v[32:47]
	s_waitcnt vmcnt(6)
	s_waitcnt lgkmcnt(0)
	s_barrier
	ds_read_b128 a[12:15], v81 offset:4096
	ds_read_b128 a[8:11], v81
	ds_read_b128 a[4:7], v82 offset:36864
	ds_read_b128 a[0:3], v82 offset:32768
	v_mfma_f32_32x32x16_bf16 v[16:31], a[16:19], a[28:31], v[16:31]
	v_lshl_add_u64 v[158:159], v[66:67], 0, s[30:31]
	v_lshl_add_u64 v[160:161], v[68:69], 0, s[30:31]
	v_lshl_add_u64 v[162:163], v[70:71], 0, s[30:31]
	v_mfma_f32_32x32x16_bf16 v[0:15], a[20:23], a[28:31], v[0:15]
	s_and_b32 m0, s32, 7
	s_lshl_b32 m0, m0, 12
	s_add_i32 m0, m0, 0x18000
	s_nop 0
	global_load_lds_dwordx4 v[158:159], off
	v_lshl_add_u64 v[166:167], v[74:75], 0, s[30:31]
	v_lshl_add_u64 v[168:169], v[76:77], 0, s[30:31]
	s_mov_b64 s[30:31], 0x600
	ds_read_b128 a[16:19], v84 offset:32768
	ds_read_b128 a[20:23], v84 offset:36864
	ds_read_b128 a[24:27], v83
	ds_read_b128 a[28:31], v83 offset:4096
	s_waitcnt lgkmcnt(4)
	v_mfma_f32_32x32x16_bf16 v[48:63], a[0:3], a[8:11], v[48:63]
	v_mfma_f32_32x32x16_bf16 v[32:47], a[4:7], a[8:11], v[32:47]
	s_and_b32 m0, s32, 7
	s_lshl_b32 m0, m0, 12
	s_add_i32 m0, m0, 0x18400
	s_nop 0
	global_load_lds_dwordx4 v[160:161], off
	v_mfma_f32_32x32x16_bf16 v[16:31], a[0:3], a[12:15], v[16:31]
	v_mfma_f32_32x32x16_bf16 v[0:15], a[4:7], a[12:15], v[0:15]
	s_and_b32 m0, s32, 7
	s_lshl_b32 m0, m0, 12
	s_add_i32 m0, m0, 0x18800
	s_nop 0
	global_load_lds_dwordx4 v[162:163], off
	ds_read_b128 a[0:3], v86 offset:32768
	ds_read_b128 a[4:7], v86 offset:36864
	ds_read_b128 a[8:11], v85
	ds_read_b128 a[12:15], v85 offset:4096
	s_waitcnt lgkmcnt(5)
	v_mfma_f32_32x32x16_bf16 v[48:63], a[16:19], a[24:27], v[48:63]
	v_mfma_f32_32x32x16_bf16 v[32:47], a[20:23], a[24:27], v[32:47]
	s_and_b32 m0, s32, 7
	s_lshl_b32 m0, m0, 12
	s_add_i32 m0, m0, 0x18c00
	s_nop 0
	global_load_lds_dwordx4 v[164:165], off
	s_waitcnt lgkmcnt(4)
	v_mfma_f32_32x32x16_bf16 v[16:31], a[16:19], a[28:31], v[16:31]
	v_mfma_f32_32x32x16_bf16 v[0:15], a[20:23], a[28:31], v[0:15]
	s_and_b32 m0, s32, 7
	s_lshl_b32 m0, m0, 11
	s_add_i32 m0, m0, 0x20000
	s_nop 0
	global_load_lds_dwordx4 v[166:167], off
	ds_read_b128 a[16:19], v88 offset:32768
	ds_read_b128 a[20:23], v88 offset:36864
	ds_read_b128 a[24:27], v87
	ds_read_b128 a[28:31], v87 offset:4096
	s_waitcnt lgkmcnt(5)
	v_mfma_f32_32x32x16_bf16 v[48:63], a[0:3], a[8:11], v[48:63]
	v_mfma_f32_32x32x16_bf16 v[32:47], a[4:7], a[8:11], v[32:47]
	s_and_b32 m0, s32, 7
	s_lshl_b32 m0, m0, 11
	s_add_i32 m0, m0, 0x20400
	s_nop 0
	global_load_lds_dwordx4 v[168:169], off
	s_waitcnt lgkmcnt(4)
	v_mfma_f32_32x32x16_bf16 v[16:31], a[0:3], a[12:15], v[16:31]
	v_mfma_f32_32x32x16_bf16 v[0:15], a[4:7], a[12:15], v[0:15]
	s_waitcnt lgkmcnt(1)
	v_mfma_f32_32x32x16_bf16 v[48:63], a[16:19], a[24:27], v[48:63]
	v_mfma_f32_32x32x16_bf16 v[32:47], a[20:23], a[24:27], v[32:47]
	s_waitcnt vmcnt(6)
	s_waitcnt lgkmcnt(0)
	s_barrier
	ds_read_b128 a[12:15], v81 offset:53248
	ds_read_b128 a[8:11], v81 offset:49152
	ds_read_b128 a[4:7], v89
	ds_read_b128 a[0:3], v91
	v_mfma_f32_32x32x16_bf16 v[16:31], a[16:19], a[28:31], v[16:31]
	v_lshl_add_u64 v[170:171], v[66:67], 0, s[30:31]
	v_lshl_add_u64 v[172:173], v[68:69], 0, s[30:31]
	v_lshl_add_u64 v[174:175], v[70:71], 0, s[30:31]
	v_mfma_f32_32x32x16_bf16 v[0:15], a[20:23], a[28:31], v[0:15]
	s_and_b32 m0, s32, 7
	s_lshl_b32 m0, m0, 12
	s_add_i32 m0, m0, 0x0
	s_nop 0
	global_load_lds_dwordx4 v[170:171], off
	v_lshl_add_u64 v[176:177], v[72:73], 0, s[30:31]
	v_lshl_add_u64 v[178:179], v[74:75], 0, s[30:31]
	v_lshl_add_u64 v[180:181], v[76:77], 0, s[30:31]
	s_mov_b64 s[30:31], 0x680
	ds_read_b128 a[16:19], v92
	ds_read_b128 a[20:23], v90
	ds_read_b128 a[24:27], v83 offset:49152
	ds_read_b128 a[28:31], v83 offset:53248
	s_waitcnt lgkmcnt(4)
	v_mfma_f32_32x32x16_bf16 v[48:63], a[0:3], a[8:11], v[48:63]
	v_mfma_f32_32x32x16_bf16 v[32:47], a[4:7], a[8:11], v[32:47]
	s_and_b32 m0, s32, 7
	s_lshl_b32 m0, m0, 12
	s_add_i32 m0, m0, 0x400
	s_nop 0
	global_load_lds_dwordx4 v[172:173], off
	v_mfma_f32_32x32x16_bf16 v[16:31], a[0:3], a[12:15], v[16:31]
	v_mfma_f32_32x32x16_bf16 v[0:15], a[4:7], a[12:15], v[0:15]
	s_and_b32 m0, s32, 7
	s_lshl_b32 m0, m0, 12
	s_add_i32 m0, m0, 0x800
	s_nop 0
	global_load_lds_dwordx4 v[174:175], off
	ds_read_b128 a[0:3], v94
	ds_read_b128 a[4:7], v93
	ds_read_b128 a[8:11], v85 offset:49152
	ds_read_b128 a[12:15], v85 offset:53248
	s_waitcnt lgkmcnt(5)
	v_mfma_f32_32x32x16_bf16 v[48:63], a[16:19], a[24:27], v[48:63]
	v_mfma_f32_32x32x16_bf16 v[32:47], a[20:23], a[24:27], v[32:47]
	s_and_b32 m0, s32, 7
	s_lshl_b32 m0, m0, 12
	s_add_i32 m0, m0, 0xc00
	s_nop 0
	global_load_lds_dwordx4 v[176:177], off
	s_waitcnt lgkmcnt(4)
	v_mfma_f32_32x32x16_bf16 v[16:31], a[16:19], a[28:31], v[16:31]
	v_mfma_f32_32x32x16_bf16 v[0:15], a[20:23], a[28:31], v[0:15]
	s_and_b32 m0, s32, 7
	s_lshl_b32 m0, m0, 11
	s_add_i32 m0, m0, 0x8000
	s_nop 0
	global_load_lds_dwordx4 v[178:179], off
	ds_read_b128 a[16:19], v96
	ds_read_b128 a[20:23], v95
	ds_read_b128 a[24:27], v87 offset:49152
	ds_read_b128 a[28:31], v87 offset:53248
	s_waitcnt lgkmcnt(5)
	v_mfma_f32_32x32x16_bf16 v[48:63], a[0:3], a[8:11], v[48:63]
	v_mfma_f32_32x32x16_bf16 v[32:47], a[4:7], a[8:11], v[32:47]
	s_and_b32 m0, s32, 7
	s_lshl_b32 m0, m0, 11
	s_add_i32 m0, m0, 0x8400
	s_nop 0
	global_load_lds_dwordx4 v[180:181], off
	s_waitcnt lgkmcnt(4)
	v_mfma_f32_32x32x16_bf16 v[16:31], a[0:3], a[12:15], v[16:31]
	v_mfma_f32_32x32x16_bf16 v[0:15], a[4:7], a[12:15], v[0:15]
	s_waitcnt lgkmcnt(1)
	v_mfma_f32_32x32x16_bf16 v[48:63], a[16:19], a[24:27], v[48:63]
	v_mfma_f32_32x32x16_bf16 v[32:47], a[20:23], a[24:27], v[32:47]
	s_waitcnt vmcnt(6)
	s_waitcnt lgkmcnt(0)
	s_barrier
	ds_read_b128 a[12:15], v100
	ds_read_b128 a[8:11], v99
	ds_read_b128 a[4:7], v98
	ds_read_b128 a[0:3], v97
	v_mfma_f32_32x32x16_bf16 v[16:31], a[16:19], a[28:31], v[16:31]
	v_lshl_add_u64 v[158:159], v[66:67], 0, s[30:31]
	v_lshl_add_u64 v[160:161], v[68:69], 0, s[30:31]
	v_lshl_add_u64 v[162:163], v[70:71], 0, s[30:31]
	v_mfma_f32_32x32x16_bf16 v[0:15], a[20:23], a[28:31], v[0:15]
	s_and_b32 m0, s32, 7
	s_lshl_b32 m0, m0, 12
	s_add_i32 m0, m0, 0xc000
	s_nop 0
	global_load_lds_dwordx4 v[158:159], off
	v_lshl_add_u64 v[164:165], v[72:73], 0, s[30:31]
	v_lshl_add_u64 v[166:167], v[74:75], 0, s[30:31]
	v_lshl_add_u64 v[168:169], v[76:77], 0, s[30:31]
	s_mov_b64 s[30:31], 0x700
	ds_read_b128 a[16:19], v101
	ds_read_b128 a[20:23], v102
	ds_read_b128 a[24:27], v103
	ds_read_b128 a[28:31], v104
	s_waitcnt lgkmcnt(4)
	v_mfma_f32_32x32x16_bf16 v[48:63], a[0:3], a[8:11], v[48:63]
	v_mfma_f32_32x32x16_bf16 v[32:47], a[4:7], a[8:11], v[32:47]
	s_and_b32 m0, s32, 7
	s_lshl_b32 m0, m0, 12
	s_add_i32 m0, m0, 0xc400
	s_nop 0
	global_load_lds_dwordx4 v[160:161], off
	v_mfma_f32_32x32x16_bf16 v[16:31], a[0:3], a[12:15], v[16:31]
	v_mfma_f32_32x32x16_bf16 v[0:15], a[4:7], a[12:15], v[0:15]
	s_and_b32 m0, s32, 7
	s_lshl_b32 m0, m0, 12
	s_add_i32 m0, m0, 0xc800
	s_nop 0
	global_load_lds_dwordx4 v[162:163], off
	ds_read_b128 a[0:3], v105
	ds_read_b128 a[4:7], v106
	ds_read_b128 a[8:11], v107
	ds_read_b128 a[12:15], v108
	s_waitcnt lgkmcnt(5)
	v_mfma_f32_32x32x16_bf16 v[48:63], a[16:19], a[24:27], v[48:63]
	v_mfma_f32_32x32x16_bf16 v[32:47], a[20:23], a[24:27], v[32:47]
	s_and_b32 m0, s32, 7
	s_lshl_b32 m0, m0, 12
	s_add_i32 m0, m0, 0xcc00
	s_nop 0
	global_load_lds_dwordx4 v[164:165], off
	s_waitcnt lgkmcnt(4)
	v_mfma_f32_32x32x16_bf16 v[16:31], a[16:19], a[28:31], v[16:31]
	v_mfma_f32_32x32x16_bf16 v[0:15], a[20:23], a[28:31], v[0:15]
	s_and_b32 m0, s32, 7
	s_lshl_b32 m0, m0, 11
	s_add_i32 m0, m0, 0x14000
	s_nop 0
	global_load_lds_dwordx4 v[166:167], off
	ds_read_b128 a[16:19], v109
	ds_read_b128 a[20:23], v110
	ds_read_b128 a[24:27], v111
	ds_read_b128 a[28:31], v112
	s_waitcnt lgkmcnt(5)
	v_mfma_f32_32x32x16_bf16 v[48:63], a[0:3], a[8:11], v[48:63]
	v_mfma_f32_32x32x16_bf16 v[32:47], a[4:7], a[8:11], v[32:47]
	s_and_b32 m0, s32, 7
	s_lshl_b32 m0, m0, 11
	s_add_i32 m0, m0, 0x14400
	s_nop 0
	global_load_lds_dwordx4 v[168:169], off
	s_waitcnt lgkmcnt(4)
	v_mfma_f32_32x32x16_bf16 v[16:31], a[0:3], a[12:15], v[16:31]
	v_mfma_f32_32x32x16_bf16 v[0:15], a[4:7], a[12:15], v[0:15]
	s_waitcnt lgkmcnt(1)
	v_mfma_f32_32x32x16_bf16 v[48:63], a[16:19], a[24:27], v[48:63]
	v_mfma_f32_32x32x16_bf16 v[32:47], a[20:23], a[24:27], v[32:47]
	s_waitcnt vmcnt(6)
	s_waitcnt lgkmcnt(0)
	s_barrier
	ds_read_b128 a[12:15], v81 offset:4096
	ds_read_b128 a[8:11], v81
	ds_read_b128 a[4:7], v82 offset:36864
	ds_read_b128 a[0:3], v82 offset:32768
	v_mfma_f32_32x32x16_bf16 v[16:31], a[16:19], a[28:31], v[16:31]
	v_lshl_add_u64 v[170:171], v[66:67], 0, s[30:31]
	v_lshl_add_u64 v[172:173], v[68:69], 0, s[30:31]
	v_lshl_add_u64 v[174:175], v[70:71], 0, s[30:31]
	v_mfma_f32_32x32x16_bf16 v[0:15], a[20:23], a[28:31], v[0:15]
	s_and_b32 m0, s32, 7
	s_lshl_b32 m0, m0, 12
	s_add_i32 m0, m0, 0x18000
	s_nop 0
	global_load_lds_dwordx4 v[170:171], off
	v_lshl_add_u64 v[176:177], v[72:73], 0, s[30:31]
	v_lshl_add_u64 v[178:179], v[74:75], 0, s[30:31]
	v_lshl_add_u64 v[180:181], v[76:77], 0, s[30:31]
	s_mov_b64 s[30:31], 0x780
	ds_read_b128 a[16:19], v84 offset:32768
	ds_read_b128 a[20:23], v84 offset:36864
	ds_read_b128 a[24:27], v83
	ds_read_b128 a[28:31], v83 offset:4096
	s_waitcnt lgkmcnt(4)
	v_mfma_f32_32x32x16_bf16 v[48:63], a[0:3], a[8:11], v[48:63]
	v_lshl_add_u64 v[158:159], v[66:67], 0, s[30:31]
	s_nop 0
	v_readlane_b32 s20, v214, 43
	v_mfma_f32_32x32x16_bf16 v[32:47], a[4:7], a[8:11], v[32:47]
	s_and_b32 m0, s32, 7
	s_lshl_b32 m0, m0, 12
	s_add_i32 m0, m0, 0x18400
	s_nop 0
	global_load_lds_dwordx4 v[172:173], off
	v_mfma_f32_32x32x16_bf16 v[16:31], a[0:3], a[12:15], v[16:31]
	v_mfma_f32_32x32x16_bf16 v[0:15], a[4:7], a[12:15], v[0:15]
	s_and_b32 m0, s32, 7
	s_lshl_b32 m0, m0, 12
	s_add_i32 m0, m0, 0x18800
	s_nop 0
	global_load_lds_dwordx4 v[174:175], off
	ds_read_b128 a[0:3], v86 offset:32768
	ds_read_b128 a[4:7], v86 offset:36864
	ds_read_b128 a[8:11], v85
	ds_read_b128 a[12:15], v85 offset:4096
	s_waitcnt lgkmcnt(5)
	v_mfma_f32_32x32x16_bf16 v[48:63], a[16:19], a[24:27], v[48:63]
	v_mfma_f32_32x32x16_bf16 v[32:47], a[20:23], a[24:27], v[32:47]
	s_and_b32 m0, s32, 7
	s_lshl_b32 m0, m0, 12
	s_add_i32 m0, m0, 0x18c00
	s_nop 0
	global_load_lds_dwordx4 v[176:177], off
	s_waitcnt lgkmcnt(4)
	v_mfma_f32_32x32x16_bf16 v[16:31], a[16:19], a[28:31], v[16:31]
	v_mfma_f32_32x32x16_bf16 v[0:15], a[20:23], a[28:31], v[0:15]
	s_and_b32 m0, s32, 7
	s_lshl_b32 m0, m0, 11
	s_add_i32 m0, m0, 0x20000
	s_nop 0
	global_load_lds_dwordx4 v[178:179], off
	ds_read_b128 a[16:19], v88 offset:32768
	ds_read_b128 a[20:23], v88 offset:36864
	ds_read_b128 a[24:27], v87
	ds_read_b128 a[28:31], v87 offset:4096
	s_waitcnt lgkmcnt(5)
	v_mfma_f32_32x32x16_bf16 v[48:63], a[0:3], a[8:11], v[48:63]
	v_mfma_f32_32x32x16_bf16 v[32:47], a[4:7], a[8:11], v[32:47]
	s_and_b32 m0, s32, 7
	s_lshl_b32 m0, m0, 11
	s_add_i32 m0, m0, 0x20400
	s_nop 0
	global_load_lds_dwordx4 v[180:181], off
	s_waitcnt lgkmcnt(4)
	v_mfma_f32_32x32x16_bf16 v[16:31], a[0:3], a[12:15], v[16:31]
	v_mfma_f32_32x32x16_bf16 v[0:15], a[4:7], a[12:15], v[0:15]
	s_waitcnt lgkmcnt(1)
	v_mfma_f32_32x32x16_bf16 v[48:63], a[16:19], a[24:27], v[48:63]
	v_mfma_f32_32x32x16_bf16 v[32:47], a[20:23], a[24:27], v[32:47]
	s_waitcnt vmcnt(6)
	s_waitcnt lgkmcnt(0)
	s_barrier
	ds_read_b128 a[12:15], v81 offset:53248
	ds_read_b128 a[8:11], v81 offset:49152
	ds_read_b128 a[4:7], v89
	ds_read_b128 a[0:3], v91
	v_lshl_add_u64 v[160:161], v[68:69], 0, s[30:31]
	v_mfma_f32_32x32x16_bf16 v[16:31], a[16:19], a[28:31], v[16:31]
	v_lshl_add_u64 v[162:163], v[70:71], 0, s[30:31]
	s_nop 0
	v_readlane_b32 s21, v214, 44
	s_nop 0
	v_lshl_add_u64 v[164:165], v[72:73], 0, s[30:31]
	s_nop 0
	v_mfma_f32_32x32x16_bf16 v[0:15], a[20:23], a[28:31], v[0:15]
	s_and_b32 m0, s32, 7
	s_lshl_b32 m0, m0, 12
	s_add_i32 m0, m0, 0x0
	s_nop 0
	global_load_lds_dwordx4 v[158:159], off
	v_lshl_add_u64 v[166:167], v[74:75], 0, s[30:31]
	s_lshl_b64 s[28:29], s[0:1], 21
	v_lshl_add_u64 v[168:169], v[76:77], 0, s[30:31]
	s_add_u32 s20, s20, s28
	ds_read_b128 a[16:19], v92
	ds_read_b128 a[20:23], v90
	ds_read_b128 a[24:27], v83 offset:49152
	ds_read_b128 a[28:31], v83 offset:53248
	s_waitcnt lgkmcnt(4)
	v_mfma_f32_32x32x16_bf16 v[48:63], a[0:3], a[8:11], v[48:63]
	s_addc_u32 s21, s21, s29
	v_readlane_b32 s23, v214, 41
	s_add_u32 s36, s23, s28
	v_readlane_b32 s23, v214, 42
	s_addc_u32 s37, s23, s29
	v_mfma_f32_32x32x16_bf16 v[32:47], a[4:7], a[8:11], v[32:47]
	s_and_b32 m0, s32, 7
	s_lshl_b32 m0, m0, 12
	s_add_i32 m0, m0, 0x400
	s_nop 0
	global_load_lds_dwordx4 v[160:161], off
	v_mfma_f32_32x32x16_bf16 v[16:31], a[0:3], a[12:15], v[16:31]
	v_mfma_f32_32x32x16_bf16 v[0:15], a[4:7], a[12:15], v[0:15]
	s_and_b32 m0, s32, 7
	s_lshl_b32 m0, m0, 12
	s_add_i32 m0, m0, 0x800
	s_nop 0
	global_load_lds_dwordx4 v[162:163], off
	ds_read_b128 a[0:3], v94
	ds_read_b128 a[4:7], v93
	ds_read_b128 a[8:11], v85 offset:49152
	ds_read_b128 a[12:15], v85 offset:53248
	s_waitcnt lgkmcnt(5)
	v_mfma_f32_32x32x16_bf16 v[48:63], a[16:19], a[24:27], v[48:63]
	v_mfma_f32_32x32x16_bf16 v[32:47], a[20:23], a[24:27], v[32:47]
	s_and_b32 m0, s32, 7
	s_lshl_b32 m0, m0, 12
	s_add_i32 m0, m0, 0xc00
	s_nop 0
	global_load_lds_dwordx4 v[164:165], off
	s_waitcnt lgkmcnt(4)
	v_mfma_f32_32x32x16_bf16 v[16:31], a[16:19], a[28:31], v[16:31]
	v_mfma_f32_32x32x16_bf16 v[0:15], a[20:23], a[28:31], v[0:15]
	s_and_b32 m0, s32, 7
	s_lshl_b32 m0, m0, 11
	s_add_i32 m0, m0, 0x8000
	s_nop 0
	global_load_lds_dwordx4 v[166:167], off
	ds_read_b128 a[16:19], v96
	ds_read_b128 a[20:23], v95
	ds_read_b128 a[24:27], v87 offset:49152
	ds_read_b128 a[28:31], v87 offset:53248
	s_waitcnt lgkmcnt(5)
	v_mfma_f32_32x32x16_bf16 v[48:63], a[0:3], a[8:11], v[48:63]
	v_mfma_f32_32x32x16_bf16 v[32:47], a[4:7], a[8:11], v[32:47]
	s_and_b32 m0, s32, 7
	s_lshl_b32 m0, m0, 11
	s_add_i32 m0, m0, 0x8400
	s_nop 0
	global_load_lds_dwordx4 v[168:169], off
	s_waitcnt lgkmcnt(4)
	v_mfma_f32_32x32x16_bf16 v[16:31], a[0:3], a[12:15], v[16:31]
	v_mfma_f32_32x32x16_bf16 v[0:15], a[4:7], a[12:15], v[0:15]
	s_waitcnt lgkmcnt(1)
	v_mfma_f32_32x32x16_bf16 v[48:63], a[16:19], a[24:27], v[48:63]
	v_mfma_f32_32x32x16_bf16 v[32:47], a[20:23], a[24:27], v[32:47]
	s_waitcnt vmcnt(6)
	s_waitcnt lgkmcnt(0)
	s_barrier
	ds_read_b128 a[12:15], v100
	ds_read_b128 a[8:11], v99
	ds_read_b128 a[4:7], v98
	ds_read_b128 a[0:3], v97
	v_mfma_f32_32x32x16_bf16 v[16:31], a[16:19], a[28:31], v[16:31]
	v_mfma_f32_32x32x16_bf16 v[0:15], a[20:23], a[28:31], v[0:15]
	ds_read_b128 a[16:19], v101
	ds_read_b128 a[20:23], v102
	ds_read_b128 a[24:27], v103
	ds_read_b128 a[28:31], v104
	s_waitcnt lgkmcnt(4)
	v_mfma_f32_32x32x16_bf16 v[48:63], a[0:3], a[8:11], v[48:63]
	v_mfma_f32_32x32x16_bf16 v[32:47], a[4:7], a[8:11], v[32:47]
	v_mfma_f32_32x32x16_bf16 v[16:31], a[0:3], a[12:15], v[16:31]
	v_mfma_f32_32x32x16_bf16 v[0:15], a[4:7], a[12:15], v[0:15]
	ds_read_b128 a[0:3], v105
	ds_read_b128 a[4:7], v106
	ds_read_b128 a[8:11], v107
	ds_read_b128 a[12:15], v108
	s_waitcnt lgkmcnt(5)
	v_mfma_f32_32x32x16_bf16 v[48:63], a[16:19], a[24:27], v[48:63]
	v_mfma_f32_32x32x16_bf16 v[32:47], a[20:23], a[24:27], v[32:47]
	s_waitcnt lgkmcnt(4)
	v_mfma_f32_32x32x16_bf16 v[16:31], a[16:19], a[28:31], v[16:31]
	v_mfma_f32_32x32x16_bf16 v[0:15], a[20:23], a[28:31], v[0:15]
	ds_read_b128 a[16:19], v109
	ds_read_b128 a[20:23], v110
	ds_read_b128 a[24:27], v111
	ds_read_b128 a[28:31], v112
	s_waitcnt lgkmcnt(5)
	v_mfma_f32_32x32x16_bf16 v[48:63], a[0:3], a[8:11], v[48:63]
	v_mfma_f32_32x32x16_bf16 v[32:47], a[4:7], a[8:11], v[32:47]
	s_waitcnt lgkmcnt(4)
	v_mfma_f32_32x32x16_bf16 v[16:31], a[0:3], a[12:15], v[16:31]
	v_mfma_f32_32x32x16_bf16 v[0:15], a[4:7], a[12:15], v[0:15]
	s_waitcnt lgkmcnt(1)
	v_mfma_f32_32x32x16_bf16 v[48:63], a[16:19], a[24:27], v[48:63]
	v_mfma_f32_32x32x16_bf16 v[32:47], a[20:23], a[24:27], v[32:47]
	s_waitcnt vmcnt(0)
	s_waitcnt lgkmcnt(0)
	s_barrier
	ds_read_b128 a[12:15], v81 offset:4096
	ds_read_b128 a[8:11], v81
	ds_read_b128 a[4:7], v82 offset:36864
	ds_read_b128 a[0:3], v82 offset:32768
	v_mfma_f32_32x32x16_bf16 v[16:31], a[16:19], a[28:31], v[16:31]
	v_mfma_f32_32x32x16_bf16 v[0:15], a[20:23], a[28:31], v[0:15]
	ds_read_b128 a[16:19], v84 offset:32768
	ds_read_b128 a[20:23], v84 offset:36864
	ds_read_b128 a[24:27], v83
	ds_read_b128 a[28:31], v83 offset:4096
	s_waitcnt lgkmcnt(4)
	v_mfma_f32_32x32x16_bf16 v[48:63], a[0:3], a[8:11], v[48:63]
	v_mfma_f32_32x32x16_bf16 v[32:47], a[4:7], a[8:11], v[32:47]
	v_mfma_f32_32x32x16_bf16 v[16:31], a[0:3], a[12:15], v[16:31]
	v_mfma_f32_32x32x16_bf16 v[0:15], a[4:7], a[12:15], v[0:15]
	ds_read_b128 a[0:3], v86 offset:32768
	ds_read_b128 a[4:7], v86 offset:36864
	ds_read_b128 a[8:11], v85
	ds_read_b128 a[12:15], v85 offset:4096
	s_waitcnt lgkmcnt(5)
	v_mfma_f32_32x32x16_bf16 v[48:63], a[16:19], a[24:27], v[48:63]
	v_mfma_f32_32x32x16_bf16 v[32:47], a[20:23], a[24:27], v[32:47]
	s_waitcnt lgkmcnt(4)
	v_mfma_f32_32x32x16_bf16 v[16:31], a[16:19], a[28:31], v[16:31]
	v_mfma_f32_32x32x16_bf16 v[0:15], a[20:23], a[28:31], v[0:15]
	s_waitcnt lgkmcnt(1)
	v_mfma_f32_32x32x16_bf16 v[48:63], a[0:3], a[8:11], v[48:63]
	v_mfma_f32_32x32x16_bf16 v[32:47], a[4:7], a[8:11], v[32:47]
	s_waitcnt lgkmcnt(0)
	v_mfma_f32_32x32x16_bf16 v[16:31], a[0:3], a[12:15], v[16:31]
	v_mfma_f32_32x32x16_bf16 v[0:15], a[4:7], a[12:15], v[0:15]
	ds_read_b128 v[66:69], v88 offset:32768
	ds_read_b128 v[70:73], v87
	ds_read_b128 v[74:77], v88 offset:36864
	ds_read_b128 v[82:85], v87 offset:4096
	s_waitcnt lgkmcnt(0)
	v_mfma_f32_32x32x16_bf16 v[48:63], v[66:69], v[70:73], v[48:63]
	v_mfma_f32_32x32x16_bf16 v[32:47], v[74:77], v[70:73], v[32:47]
	v_or_b32_e32 v70, s22, v80
	v_lshl_add_u32 v70, v78, 6, v70
	v_ashrrev_i32_e32 v71, 31, v70
	v_lshlrev_b64 v[72:73], 10, v[70:71]
	v_lshl_add_u64 v[86:87], s[36:37], 0, v[72:73]
	v_mfma_f32_32x32x16_bf16 v[16:31], v[66:69], v[82:85], v[16:31]
	v_lshlrev_b32_e32 v66, 6, v79
	v_or3_b32 v66, v66, v64, s2
	s_movk_i32 s2, 0xff
	v_cmp_lt_i32_e32 vcc, s2, v66
	v_mfma_f32_32x32x16_bf16 v[0:15], v[74:77], v[82:85], v[0:15]
	s_and_saveexec_b64 s[22:23], vcc
	s_xor_b64 s[28:29], exec, s[22:23]
	v_mov_b32_e32 v67, v65
	s_movk_i32 s22, 0xfc00
	v_lshl_add_u64 v[68:69], v[66:67], 2, v[86:87]
	s_mov_b32 s23, -1
	v_lshl_add_u64 v[68:69], v[68:69], 0, s[22:23]
	s_or_saveexec_b64 s[28:29], s[28:29]
	v_lshl_add_u64 v[90:91], s[20:21], 0, v[72:73]
	v_ashrrev_i32_e32 v67, 31, v66
	s_xor_b64 exec, exec, s[28:29]
	v_lshl_add_u64 v[68:69], v[66:67], 2, v[90:91]
	s_or_b64 exec, exec, s[28:29]
	s_lshl_b64 s[0:1], s[0:1], 19
	s_lshl_b64 s[22:23], s[0:1], 1
	v_readlane_b32 s0, v214, 37
	v_readlane_b32 s1, v214, 38
	s_add_u32 s0, s0, s22
	s_addc_u32 s1, s1, s23
	v_readlane_b32 s28, v214, 39
	v_readlane_b32 s29, v214, 40
	s_add_u32 s54, s28, s22
	v_and_b32_e32 v74, 0xdf, v70
	v_ashrrev_i32_e32 v71, 6, v70
	global_store_dwordx4 v[68:69], v[48:51], off
	v_add_u32_e32 v68, 0xffffff00, v66
	v_lshlrev_b32_e32 v69, 9, v66
	s_addc_u32 s55, s29, s23
	v_and_b32_e32 v71, -4, v71
	v_lshrrev_b32_e32 v92, 6, v68
	v_and_b32_e32 v72, 0x7800, v69
	v_lshlrev_b32_e32 v88, 1, v74
	s_and_saveexec_b64 s[22:23], vcc
	s_xor_b64 s[28:29], exec, s[22:23]
	s_cbranch_execz .LBB0_619
	v_add_u32_e32 v68, v92, v71
	v_ashrrev_i32_e32 v69, 31, v68
	v_lshlrev_b64 v[68:69], 15, v[68:69]
	v_lshl_add_u64 v[68:69], s[54:55], 0, v[68:69]
	v_mov_b32_e32 v73, v65
	v_lshl_add_u64 v[68:69], v[68:69], 0, v[72:73]
	v_mov_b32_e32 v89, v65
	v_bfe_u32 v73, v48, 16, 1
	v_lshl_add_u64 v[68:69], v[68:69], 0, v[88:89]
	v_add3_u32 v73, v48, v73, s27
	global_store_short_d16_hi v[68:69], v73, off
	v_bfe_u32 v73, v49, 16, 1
	v_add3_u32 v73, v49, v73, s27
	global_store_short_d16_hi v[68:69], v73, off offset:512
	v_bfe_u32 v73, v50, 16, 1
	v_add3_u32 v73, v50, v73, s27
	global_store_short_d16_hi v[68:69], v73, off offset:1024
	v_bfe_u32 v73, v51, 16, 1
	v_add3_u32 v73, v51, v73, s27
	global_store_short_d16_hi v[68:69], v73, off offset:1536

.LBB0_747:
	v_mov_b32_e32 v78, v133
	s_lshl_b32 s2, s2, 8
	v_ashrrev_i32_e32 v6, 6, v78
	v_bfe_u32 v7, v78, 3, 3
	v_lshl_or_b32 v8, v6, 5, v7
	v_add_u32_e32 v0, s2, v8
	s_waitcnt lgkmcnt(0)
	v_ashrrev_i32_e32 v1, 31, v0
	v_lshlrev_b64 v[2:3], 11, v[0:1]
	v_bfe_u32 v1, v78, 4, 2
	v_readlane_b32 s0, v215, 52
	v_xor_b32_e32 v1, v1, v78
	v_readlane_b32 s1, v215, 53
	v_lshlrev_b32_e32 v1, 4, v1
	v_and_b32_e32 v64, 0x70, v1
	v_lshl_add_u64 v[2:3], s[0:1], 0, v[2:3]
	v_or_b32_e32 v1, 8, v8
	v_lshl_add_u64 v[66:67], v[2:3], 0, v[64:65]
	v_add_u32_e32 v2, s2, v1
	v_lshrrev_b32_e32 v1, 1, v1
	v_xor_b32_e32 v1, v1, v78
	v_ashrrev_i32_e32 v3, 31, v2
	v_lshlrev_b32_e32 v1, 4, v1
	v_or_b32_e32 v0, 16, v0
	v_lshlrev_b64 v[2:3], 11, v[2:3]
	v_and_b32_e32 v4, 0x70, v1
	v_ashrrev_i32_e32 v1, 31, v0
	v_lshl_add_u64 v[2:3], s[0:1], 0, v[2:3]
	v_mov_b32_e32 v5, v65
	v_lshlrev_b64 v[0:1], 11, v[0:1]
	v_lshl_add_u64 v[68:69], v[2:3], 0, v[4:5]
	v_lshl_add_u64 v[0:1], s[0:1], 0, v[0:1]
	v_or_b32_e32 v2, 24, v8
	v_lshl_add_u64 v[70:71], v[0:1], 0, v[64:65]
	v_add_u32_e32 v0, s2, v2
	v_lshrrev_b32_e32 v2, 1, v2
	v_ashrrev_i32_e32 v1, 31, v0
	v_xor_b32_e32 v2, v2, v78
	v_lshlrev_b64 v[0:1], 11, v[0:1]
	v_lshlrev_b32_e32 v2, 4, v2
	v_lshl_add_u64 v[0:1], s[0:1], 0, v[0:1]
	v_and_b32_e32 v2, 0x70, v2
	v_mov_b32_e32 v3, v65
	v_lshl_add_u64 v[72:73], v[0:1], 0, v[2:3]
	v_lshl_or_b32 v2, v6, 4, v7
	v_add_u32_e32 v0, s20, v2
	v_lshlrev_b32_e32 v3, 12, v6
	v_ashrrev_i32_e32 v1, 31, v0
	v_add_u32_e32 v131, 0, v3
	v_lshlrev_b64 v[0:1], 11, v[0:1]
	s_waitcnt vmcnt(0)
	v_readfirstlane_b32 s40, v131
	v_add_u32_e32 v130, 0x400, v131
	v_lshl_add_u64 v[0:1], s[96:97], 0, v[0:1]
	v_or_b32_e32 v2, 8, v2
	s_waitcnt lgkmcnt(0)
	s_barrier
	s_mov_b32 m0, s40
	v_readfirstlane_b32 s41, v130
	v_add_u32_e32 v128, 0x800, v131
	v_lshlrev_b32_e32 v5, 11, v6
	v_and_b32_e32 v79, 1, v6
	v_lshl_add_u64 v[74:75], v[0:1], 0, v[64:65]
	v_add_u32_e32 v0, s20, v2
	v_lshrrev_b32_e32 v2, 1, v2
	global_load_lds_dwordx4 v[66:67], off
	s_mov_b32 m0, s41
	v_readfirstlane_b32 s42, v128
	v_add_u32_e32 v126, 0xc00, v131
	v_add_u32_e32 v6, 0, v5
	v_ashrrev_i32_e32 v1, 31, v0
	v_xor_b32_e32 v2, v2, v78
	global_load_lds_dwordx4 v[68:69], off
	s_mov_b32 m0, s42
	v_readfirstlane_b32 s43, v126
	v_add_u32_e32 v129, 0x8000, v6
	v_lshlrev_b64 v[0:1], 11, v[0:1]
	v_lshlrev_b32_e32 v2, 4, v2
	global_load_lds_dwordx4 v[70:71], off
	s_mov_b32 m0, s43
	v_readfirstlane_b32 s44, v129
	v_add_u32_e32 v127, 0x8400, v6
	v_lshl_add_u64 v[0:1], s[96:97], 0, v[0:1]
	v_and_b32_e32 v64, 0x70, v2
	global_load_lds_dwordx4 v[72:73], off
	s_mov_b32 m0, s44
	v_readfirstlane_b32 s45, v127
	v_add_u32_e32 v125, 0xc000, v131
	v_lshl_add_u64 v[76:77], v[0:1], 0, v[64:65]
	global_load_lds_dwordx4 v[74:75], off
	s_mov_b32 m0, s45
	s_mov_b64 s[0:1], 0x80
	v_readfirstlane_b32 s29, v125
	v_add_u32_e32 v120, 0xc400, v131
	global_load_lds_dwordx4 v[76:77], off
	v_lshl_add_u64 v[0:1], v[66:67], 0, s[0:1]
	s_mov_b32 m0, s29
	v_readfirstlane_b32 s33, v120
	v_add_u32_e32 v121, 0xc800, v131
	global_load_lds_dwordx4 v[0:1], off
	v_lshl_add_u64 v[0:1], v[68:69], 0, s[0:1]
	s_mov_b32 m0, s33
	v_readfirstlane_b32 s36, v121
	v_add_u32_e32 v122, 0xcc00, v131
	global_load_lds_dwordx4 v[0:1], off
	v_lshl_add_u64 v[0:1], v[70:71], 0, s[0:1]
	s_mov_b32 m0, s36
	v_readfirstlane_b32 s37, v122
	v_add_u32_e32 v123, s85, v5
	global_load_lds_dwordx4 v[0:1], off
	v_lshl_add_u64 v[0:1], v[72:73], 0, s[0:1]
	s_mov_b32 m0, s37
	v_readfirstlane_b32 s38, v123
	v_add_u32_e32 v124, 0x14400, v6
	global_load_lds_dwordx4 v[0:1], off
	v_lshl_add_u64 v[0:1], v[74:75], 0, s[0:1]
	s_mov_b32 m0, s38
	v_readfirstlane_b32 s39, v124
	global_load_lds_dwordx4 v[0:1], off
	v_lshl_add_u64 v[0:1], v[76:77], 0, s[0:1]
	s_mov_b32 m0, s39
	v_lshrrev_b32_e32 v2, 1, v78
	v_bfe_u32 v64, v78, 5, 1
	global_load_lds_dwordx4 v[0:1], off
	v_add_u32_e32 v119, s3, v3
	v_bitop3_b32 v0, v2, v64, 7 bitop3:0x6c
	s_waitcnt vmcnt(6)
	s_mov_b64 s[30:31], 0x100
	v_readfirstlane_b32 s0, v119
	v_add_u32_e32 v114, 0x400, v119
	v_lshlrev_b32_e32 v132, 4, v0
	s_waitcnt lgkmcnt(0)
	s_barrier
	v_lshl_add_u64 v[0:1], v[66:67], 0, s[30:31]
	s_mov_b32 m0, s0
	v_readfirstlane_b32 s1, v114
	v_add_u32_e32 v115, 0x800, v119
	global_load_lds_dwordx4 v[0:1], off
	v_lshl_add_u64 v[0:1], v[68:69], 0, s[30:31]
	s_mov_b32 m0, s1
	v_readfirstlane_b32 s21, v115
	v_add_u32_e32 v116, 0xc00, v119
	v_readlane_b32 s23, v212, 31
	v_and_b32_e32 v81, 31, v78
	global_load_lds_dwordx4 v[0:1], off
	v_lshl_add_u64 v[0:1], v[70:71], 0, s[30:31]
	s_mov_b32 m0, s21
	v_readfirstlane_b32 s22, v116
	v_add_u32_e32 v117, s23, v5
	v_add_u32_e32 v2, s3, v5
	v_lshlrev_b32_e32 v4, 7, v81
	global_load_lds_dwordx4 v[0:1], off
	v_lshl_add_u64 v[0:1], v[72:73], 0, s[30:31]
	s_mov_b32 m0, s22
	v_readfirstlane_b32 s23, v117
	v_add_u32_e32 v118, 0x8400, v2
	v_lshl_or_b32 v102, v79, 13, v4
	global_load_lds_dwordx4 v[0:1], off
	v_lshl_add_u64 v[0:1], v[74:75], 0, s[30:31]
	s_mov_b32 m0, s23
	v_readfirstlane_b32 s28, v118
	global_load_lds_dwordx4 v[0:1], off
	v_lshl_add_u64 v[0:1], v[76:77], 0, s[30:31]
	s_mov_b32 m0, s28
	v_add_u32_e32 v100, 0, v102
	global_load_lds_dwordx4 v[0:1], off
	v_add_u32_e32 v85, v100, v132
	v_ashrrev_i32_e32 v80, 7, v78
	ds_read_b128 v[0:3], v85 offset:32768
	ds_read_b128 v[86:89], v85 offset:36864
	v_lshl_or_b32 v134, v80, 13, v4
	v_add_u32_e32 v101, 0, v134
	v_add_u32_e32 v84, v101, v132
	ds_read_b128 v[4:7], v84
	v_bfe_u32 v103, v78, 1, 3
	s_waitcnt lgkmcnt(0)
	v_lshrrev_b32_e32 v182, 6, v133
	s_nop 0
	v_readfirstlane_b32 s32, v182
	v_mfma_f32_32x32x16_bf16 v[48:63], v[0:3], v[4:7], 0
	v_bitop3_b32 v8, v64, v103, 2 bitop3:0x36
	v_lshlrev_b32_e32 v135, 4, v8
	v_add_u32_e32 v83, v100, v135
	ds_read_b128 v[8:11], v83 offset:32768
	ds_read_b128 v[90:93], v83 offset:36864
	v_add_u32_e32 v82, v101, v135
	ds_read_b128 v[12:15], v82
	ds_read_b128 v[94:97], v82 offset:4096
	s_waitcnt vmcnt(12)
	v_mfma_f32_32x32x16_bf16 v[32:47], v[86:89], v[4:7], 0
	ds_read_b128 v[4:7], v84 offset:4096
	s_mov_b64 s[30:31], 0x180
	v_or_b32_e32 v143, 0x8000, v102
	v_or_b32_e32 v144, 0x9000, v102
	v_add_u32_e32 v145, s3, v134
	s_mov_b64 s[80:81], 0x200
	s_waitcnt lgkmcnt(0)
	v_mfma_f32_32x32x16_bf16 v[16:31], v[0:3], v[4:7], 0
	v_mfma_f32_32x32x16_bf16 v[48:63], v[8:11], v[12:15], v[48:63]
	v_mfma_f32_32x32x16_bf16 v[32:47], v[90:93], v[12:15], v[32:47]
	v_mfma_f32_32x32x16_bf16 v[16:31], v[8:11], v[94:97], v[16:31]
	v_mfma_f32_32x32x16_bf16 v[0:15], v[86:89], v[4:7], 0
	v_bitop3_b32 v86, v64, v103, 4 bitop3:0x36
	v_lshlrev_b32_e32 v138, 4, v86
	v_add_u32_e32 v87, v100, v138
	v_add_u32_e32 v86, v101, v138
	v_mfma_f32_32x32x16_bf16 v[0:15], v[90:93], v[94:97], v[0:15]
	ds_read_b128 v[88:91], v87 offset:32768
	ds_read_b128 v[92:95], v86
	ds_read_b128 v[96:99], v87 offset:36864
	s_waitcnt lgkmcnt(1)
	v_mfma_f32_32x32x16_bf16 v[48:63], v[88:91], v[92:95], v[48:63]
	s_waitcnt lgkmcnt(0)
	v_mfma_f32_32x32x16_bf16 v[32:47], v[96:99], v[92:95], v[32:47]
	ds_read_b128 v[92:95], v86 offset:4096
	s_waitcnt lgkmcnt(0)
	v_mfma_f32_32x32x16_bf16 v[16:31], v[88:91], v[92:95], v[16:31]
	v_bitop3_b32 v88, v64, v103, 6 bitop3:0x36
	v_lshlrev_b32_e32 v142, 4, v88
	v_add_u32_e32 v89, v100, v142
	v_add_u32_e32 v88, v101, v142
	v_mfma_f32_32x32x16_bf16 v[0:15], v[96:99], v[92:95], v[0:15]
	ds_read_b128 v[90:93], v89 offset:32768
	ds_read_b128 v[94:97], v88
	ds_read_b128 v[98:101], v89 offset:36864
	s_waitcnt lgkmcnt(1)
	v_mfma_f32_32x32x16_bf16 v[48:63], v[90:93], v[94:97], v[48:63]
	s_waitcnt lgkmcnt(0)
	v_mfma_f32_32x32x16_bf16 v[32:47], v[98:101], v[94:97], v[32:47]
	ds_read_b128 v[94:97], v88 offset:4096
	s_waitcnt vmcnt(6)
	s_waitcnt lgkmcnt(0)
	s_barrier
	s_waitcnt lgkmcnt(0)
	v_mfma_f32_32x32x16_bf16 v[16:31], v[90:93], v[94:97], v[16:31]
	v_lshl_add_u64 v[158:159], v[66:67], 0, s[30:31]
	v_lshl_add_u64 v[160:161], v[68:69], 0, s[30:31]
	v_lshl_add_u64 v[162:163], v[70:71], 0, s[30:31]
	v_mfma_f32_32x32x16_bf16 v[0:15], v[98:101], v[94:97], v[0:15]
	s_and_b32 m0, s32, 7
	s_lshl_b32 m0, m0, 12
	s_add_i32 m0, m0, 0x0
	s_nop 0
	global_load_lds_dwordx4 v[158:159], off
	v_lshl_add_u64 v[164:165], v[72:73], 0, s[30:31]
	v_lshl_add_u64 v[166:167], v[74:75], 0, s[30:31]
	v_lshl_add_u64 v[168:169], v[76:77], 0, s[30:31]
	s_add_i32 s30, 0, 0xc000
	v_add_u32_e32 v90, s30, v132
	v_add_u32_e32 v91, v90, v143
	v_add_u32_e32 v90, v90, v144
	ds_read_b128 v[92:95], v91
	ds_read_b128 v[96:99], v84 offset:49152
	ds_read_b128 v[100:103], v90
	ds_read_b128 v[150:153], v84 offset:53248
	s_waitcnt lgkmcnt(1)
	v_mfma_f32_32x32x16_bf16 v[48:63], v[92:95], v[96:99], v[48:63]
	v_mfma_f32_32x32x16_bf16 v[32:47], v[100:103], v[96:99], v[32:47]
	s_and_b32 m0, s32, 7
	s_lshl_b32 m0, m0, 12
	s_add_i32 m0, m0, 0x400
	s_nop 0
	global_load_lds_dwordx4 v[160:161], off
	s_waitcnt lgkmcnt(0)
	v_mfma_f32_32x32x16_bf16 v[16:31], v[92:95], v[150:153], v[16:31]
	v_add_u32_e32 v92, s30, v135
	v_add_u32_e32 v94, v92, v143
	v_add_u32_e32 v92, v92, v144
	v_add_u32_e32 v93, s30, v138
	v_add_u32_e32 v95, v93, v143
	v_add_u32_e32 v93, v93, v144
	v_mfma_f32_32x32x16_bf16 v[0:15], v[100:103], v[150:153], v[0:15]
	s_and_b32 m0, s32, 7
	s_lshl_b32 m0, m0, 12
	s_add_i32 m0, m0, 0x800
	s_nop 0
	global_load_lds_dwordx4 v[162:163], off
	ds_read_b128 v[96:99], v94
	ds_read_b128 v[100:103], v82 offset:49152
	ds_read_b128 v[104:107], v92
	ds_read_b128 v[154:157], v82 offset:53248
	s_waitcnt lgkmcnt(1)
	v_mfma_f32_32x32x16_bf16 v[48:63], v[96:99], v[100:103], v[48:63]
	v_mfma_f32_32x32x16_bf16 v[32:47], v[104:107], v[100:103], v[32:47]
	s_and_b32 m0, s32, 7
	s_lshl_b32 m0, m0, 12
	s_add_i32 m0, m0, 0xc00
	s_nop 0
	global_load_lds_dwordx4 v[164:165], off
	s_waitcnt lgkmcnt(0)
	v_mfma_f32_32x32x16_bf16 v[16:31], v[96:99], v[154:157], v[16:31]
	v_mfma_f32_32x32x16_bf16 v[0:15], v[104:107], v[154:157], v[0:15]
	s_and_b32 m0, s32, 7
	s_lshl_b32 m0, m0, 11
	s_add_i32 m0, m0, 0x8000
	s_nop 0
	global_load_lds_dwordx4 v[166:167], off
	ds_read_b128 v[96:99], v95
	ds_read_b128 v[100:103], v86 offset:49152
	ds_read_b128 v[104:107], v93
	ds_read_b128 v[150:153], v86 offset:53248
	s_waitcnt lgkmcnt(1)
	v_mfma_f32_32x32x16_bf16 v[48:63], v[96:99], v[100:103], v[48:63]
	v_mfma_f32_32x32x16_bf16 v[32:47], v[104:107], v[100:103], v[32:47]
	s_and_b32 m0, s32, 7
	s_lshl_b32 m0, m0, 11
	s_add_i32 m0, m0, 0x8400
	s_nop 0
	global_load_lds_dwordx4 v[168:169], off
	s_waitcnt lgkmcnt(0)
	v_mfma_f32_32x32x16_bf16 v[16:31], v[96:99], v[150:153], v[16:31]
	v_add_u32_e32 v96, s30, v142
	v_add_u32_e32 v97, v96, v143
	v_add_u32_e32 v96, v96, v144
	s_mov_b64 s[30:31], 0x200
	v_mfma_f32_32x32x16_bf16 v[0:15], v[104:107], v[150:153], v[0:15]
	ds_read_b128 v[98:101], v97
	ds_read_b128 v[102:105], v88 offset:49152
	ds_read_b128 v[106:109], v96
	ds_read_b128 v[154:157], v88 offset:53248
	s_waitcnt lgkmcnt(1)
	v_mfma_f32_32x32x16_bf16 v[48:63], v[98:101], v[102:105], v[48:63]
	v_mfma_f32_32x32x16_bf16 v[32:47], v[106:109], v[102:105], v[32:47]
	s_waitcnt vmcnt(6)
	s_waitcnt lgkmcnt(0)
	s_barrier
	s_waitcnt lgkmcnt(0)
	v_mfma_f32_32x32x16_bf16 v[16:31], v[98:101], v[154:157], v[16:31]
	v_lshl_add_u64 v[170:171], v[66:67], 0, s[30:31]
	v_lshl_add_u64 v[172:173], v[68:69], 0, s[30:31]
	v_add_u32_e32 v101, s3, v132
	v_lshl_add_u64 v[174:175], v[70:71], 0, s[30:31]
	v_mfma_f32_32x32x16_bf16 v[0:15], v[106:109], v[154:157], v[0:15]
	s_and_b32 m0, s32, 7
	s_lshl_b32 m0, m0, 12
	s_add_i32 m0, m0, 0xc000
	s_nop 0
	global_load_lds_dwordx4 v[170:171], off
	v_lshl_add_u64 v[176:177], v[72:73], 0, s[30:31]
	v_add_u32_e32 v100, v145, v132
	v_lshl_add_u64 v[178:179], v[74:75], 0, s[30:31]
	v_or_b32_e32 v132, 0x1000, v134
	v_lshl_add_u64 v[180:181], v[76:77], 0, s[30:31]
	s_mov_b64 s[30:31], 0x280
	v_add_u32_e32 v98, v101, v143
	v_add_u32_e32 v99, v101, v144
	ds_read_b128 v[110:113], v98
	ds_read_b128 v[106:109], v99
	ds_read_b128 v[102:105], v100
	v_add_u32_e32 v101, v101, v132
	ds_read_b128 v[150:153], v101
	s_waitcnt lgkmcnt(1)
	v_mfma_f32_32x32x16_bf16 v[48:63], v[110:113], v[102:105], v[48:63]
	v_mfma_f32_32x32x16_bf16 v[32:47], v[106:109], v[102:105], v[32:47]
	s_and_b32 m0, s32, 7
	s_lshl_b32 m0, m0, 12
	s_add_i32 m0, m0, 0xc400
	s_nop 0
	global_load_lds_dwordx4 v[172:173], off
	s_waitcnt lgkmcnt(0)
	v_mfma_f32_32x32x16_bf16 v[16:31], v[110:113], v[150:153], v[16:31]
	v_mfma_f32_32x32x16_bf16 v[0:15], v[106:109], v[150:153], v[0:15]
	s_and_b32 m0, s32, 7
	s_lshl_b32 m0, m0, 12
	s_add_i32 m0, m0, 0xc800
	s_nop 0
	global_load_lds_dwordx4 v[174:175], off
	v_add_u32_e32 v105, s3, v135
	v_add_u32_e32 v103, v105, v143
	v_add_u32_e32 v102, v105, v144
	ds_read_b128 v[106:109], v103
	v_add_u32_e32 v104, v145, v135
	ds_read_b128 v[134:137], v102
	ds_read_b128 v[110:113], v104
	v_add_u32_e32 v105, v105, v132
	ds_read_b128 v[154:157], v105
	s_waitcnt lgkmcnt(1)
	v_mfma_f32_32x32x16_bf16 v[48:63], v[106:109], v[110:113], v[48:63]
	v_mfma_f32_32x32x16_bf16 v[32:47], v[134:137], v[110:113], v[32:47]
	s_and_b32 m0, s32, 7
	s_lshl_b32 m0, m0, 12
	s_add_i32 m0, m0, 0xcc00
	s_nop 0
	global_load_lds_dwordx4 v[176:177], off
	s_waitcnt lgkmcnt(0)
	v_mfma_f32_32x32x16_bf16 v[16:31], v[106:109], v[154:157], v[16:31]
	v_add_u32_e32 v109, s3, v138
	v_add_u32_e32 v107, v109, v143
	v_add_u32_e32 v106, v109, v144
	v_add_u32_e32 v108, v145, v138
	ds_read_b128 v[138:141], v106
	v_add_u32_e32 v109, v109, v132
	v_mfma_f32_32x32x16_bf16 v[0:15], v[134:137], v[154:157], v[0:15]
	s_and_b32 m0, s32, 7
	s_lshl_b32 m0, m0, 11
	s_add_i32 m0, m0, 0x14000
	s_nop 0
	global_load_lds_dwordx4 v[178:179], off
	ds_read_b128 v[110:113], v107
	ds_read_b128 v[134:137], v108
	ds_read_b128 v[150:153], v109
	s_waitcnt lgkmcnt(1)
	v_mfma_f32_32x32x16_bf16 v[48:63], v[110:113], v[134:137], v[48:63]
	v_mfma_f32_32x32x16_bf16 v[32:47], v[138:141], v[134:137], v[32:47]
	s_and_b32 m0, s32, 7
	s_lshl_b32 m0, m0, 11
	s_add_i32 m0, m0, 0x14400
	s_nop 0
	global_load_lds_dwordx4 v[180:181], off
	s_waitcnt lgkmcnt(0)
	v_mfma_f32_32x32x16_bf16 v[16:31], v[110:113], v[150:153], v[16:31]
	v_add_u32_e32 v113, s3, v142
	v_add_u32_e32 v111, v113, v143
	v_add_u32_e32 v110, v113, v144
	v_add_u32_e32 v112, v145, v142
	ds_read_b128 v[142:145], v110
	v_add_u32_e32 v113, v113, v132
	v_mfma_f32_32x32x16_bf16 v[0:15], v[138:141], v[150:153], v[0:15]
	ds_read_b128 v[134:137], v111
	ds_read_b128 v[138:141], v112
	ds_read_b128 v[154:157], v113
	s_waitcnt lgkmcnt(1)
	v_mfma_f32_32x32x16_bf16 v[48:63], v[134:137], v[138:141], v[48:63]
	v_mfma_f32_32x32x16_bf16 v[32:47], v[142:145], v[138:141], v[32:47]
	s_waitcnt vmcnt(6)
	s_waitcnt lgkmcnt(0)
	s_barrier
	s_waitcnt lgkmcnt(0)
	v_mfma_f32_32x32x16_bf16 v[16:31], v[134:137], v[154:157], v[16:31]
	v_lshl_add_u64 v[158:159], v[66:67], 0, s[30:31]
	v_lshl_add_u64 v[160:161], v[68:69], 0, s[30:31]
	v_lshl_add_u64 v[162:163], v[70:71], 0, s[30:31]
	v_mfma_f32_32x32x16_bf16 v[0:15], v[142:145], v[154:157], v[0:15]
	s_and_b32 m0, s32, 7
	s_lshl_b32 m0, m0, 12
	s_add_i32 m0, m0, 0x18000
	s_nop 0
	global_load_lds_dwordx4 v[158:159], off
	v_lshl_add_u64 v[164:165], v[72:73], 0, s[30:31]
	v_lshl_add_u64 v[166:167], v[74:75], 0, s[30:31]
	v_lshl_add_u64 v[168:169], v[76:77], 0, s[30:31]
	s_mov_b64 s[30:31], 0x300
	ds_read_b128 v[134:137], v85 offset:32768
	ds_read_b128 v[138:141], v84
	ds_read_b128 v[142:145], v85 offset:36864
	ds_read_b128 v[150:153], v84 offset:4096
	s_waitcnt lgkmcnt(1)
	v_mfma_f32_32x32x16_bf16 v[48:63], v[134:137], v[138:141], v[48:63]
	s_nop 0
	v_readfirstlane_b32 s40, v119
	v_mfma_f32_32x32x16_bf16 v[32:47], v[142:145], v[138:141], v[32:47]
	s_and_b32 m0, s32, 7
	s_lshl_b32 m0, m0, 12
	s_add_i32 m0, m0, 0x18400
	s_nop 0
	global_load_lds_dwordx4 v[160:161], off
	s_waitcnt lgkmcnt(0)
	v_mfma_f32_32x32x16_bf16 v[16:31], v[134:137], v[150:153], v[16:31]
	v_mfma_f32_32x32x16_bf16 v[0:15], v[142:145], v[150:153], v[0:15]
	s_and_b32 m0, s32, 7
	s_lshl_b32 m0, m0, 12
	s_add_i32 m0, m0, 0x18800
	s_nop 0
	global_load_lds_dwordx4 v[162:163], off
	ds_read_b128 v[134:137], v83 offset:32768
	ds_read_b128 v[138:141], v82
	ds_read_b128 v[142:145], v83 offset:36864
	ds_read_b128 v[154:157], v82 offset:4096
	s_waitcnt lgkmcnt(1)
	v_mfma_f32_32x32x16_bf16 v[48:63], v[134:137], v[138:141], v[48:63]
	v_mfma_f32_32x32x16_bf16 v[32:47], v[142:145], v[138:141], v[32:47]
	s_and_b32 m0, s32, 7
	s_lshl_b32 m0, m0, 12
	s_add_i32 m0, m0, 0x18c00
	s_nop 0
	global_load_lds_dwordx4 v[164:165], off
	s_waitcnt lgkmcnt(0)
	v_mfma_f32_32x32x16_bf16 v[16:31], v[134:137], v[154:157], v[16:31]
	v_mfma_f32_32x32x16_bf16 v[0:15], v[142:145], v[154:157], v[0:15]
	s_and_b32 m0, s32, 7
	s_lshl_b32 m0, m0, 11
	s_add_i32 m0, m0, 0x20000
	s_nop 0
	global_load_lds_dwordx4 v[166:167], off
	ds_read_b128 v[134:137], v87 offset:32768
	ds_read_b128 v[138:141], v86
	ds_read_b128 v[142:145], v87 offset:36864
	ds_read_b128 v[150:153], v86 offset:4096
	s_waitcnt lgkmcnt(1)
	v_mfma_f32_32x32x16_bf16 v[48:63], v[134:137], v[138:141], v[48:63]
	v_mfma_f32_32x32x16_bf16 v[32:47], v[142:145], v[138:141], v[32:47]
	s_and_b32 m0, s32, 7
	s_lshl_b32 m0, m0, 11
	s_add_i32 m0, m0, 0x20400
	s_nop 0
	global_load_lds_dwordx4 v[168:169], off
	s_waitcnt lgkmcnt(0)
	v_mfma_f32_32x32x16_bf16 v[16:31], v[134:137], v[150:153], v[16:31]
	v_mfma_f32_32x32x16_bf16 v[0:15], v[142:145], v[150:153], v[0:15]
	ds_read_b128 v[134:137], v89 offset:32768
	ds_read_b128 v[138:141], v88
	ds_read_b128 v[142:145], v89 offset:36864
	ds_read_b128 v[154:157], v88 offset:4096
	s_waitcnt lgkmcnt(1)
	v_mfma_f32_32x32x16_bf16 v[48:63], v[134:137], v[138:141], v[48:63]
	v_mfma_f32_32x32x16_bf16 v[32:47], v[142:145], v[138:141], v[32:47]
	s_waitcnt vmcnt(6)
	s_waitcnt lgkmcnt(0)
	s_barrier
	s_waitcnt lgkmcnt(0)
	v_mfma_f32_32x32x16_bf16 v[16:31], v[134:137], v[154:157], v[16:31]
	v_lshl_add_u64 v[170:171], v[66:67], 0, s[30:31]
	v_lshl_add_u64 v[172:173], v[68:69], 0, s[30:31]
	s_nop 0
	v_readfirstlane_b32 s41, v114
	s_nop 0
	v_lshl_add_u64 v[174:175], v[70:71], 0, s[30:31]
	s_nop 0
	v_mfma_f32_32x32x16_bf16 v[0:15], v[142:145], v[154:157], v[0:15]
	s_and_b32 m0, s32, 7
	s_lshl_b32 m0, m0, 12
	s_add_i32 m0, m0, 0x0
	s_nop 0
	global_load_lds_dwordx4 v[170:171], off
	v_lshl_add_u64 v[176:177], v[72:73], 0, s[30:31]
	s_nop 0
	v_readfirstlane_b32 s42, v115
	s_nop 0
	v_lshl_add_u64 v[178:179], v[74:75], 0, s[30:31]
	s_nop 0
	v_readfirstlane_b32 s43, v116
	s_nop 0
	v_lshl_add_u64 v[180:181], v[76:77], 0, s[30:31]
	s_nop 0
	s_mov_b64 s[30:31], 0x380
	ds_read_b128 v[134:137], v91
	ds_read_b128 v[138:141], v84 offset:49152
	ds_read_b128 v[142:145], v90
	ds_read_b128 v[150:153], v84 offset:53248
	s_waitcnt lgkmcnt(1)
	v_mfma_f32_32x32x16_bf16 v[48:63], v[134:137], v[138:141], v[48:63]
	s_nop 0
	v_readfirstlane_b32 s29, v125
	v_readfirstlane_b32 s44, v117
	v_readfirstlane_b32 s45, v118
	v_mfma_f32_32x32x16_bf16 v[32:47], v[142:145], v[138:141], v[32:47]
	s_and_b32 m0, s32, 7
	s_lshl_b32 m0, m0, 12
	s_add_i32 m0, m0, 0x400
	s_nop 0
	global_load_lds_dwordx4 v[172:173], off
	s_waitcnt lgkmcnt(0)
	v_mfma_f32_32x32x16_bf16 v[16:31], v[134:137], v[150:153], v[16:31]
	v_mfma_f32_32x32x16_bf16 v[0:15], v[142:145], v[150:153], v[0:15]
	s_and_b32 m0, s32, 7
	s_lshl_b32 m0, m0, 12
	s_add_i32 m0, m0, 0x800
	s_nop 0
	global_load_lds_dwordx4 v[174:175], off
	ds_read_b128 v[134:137], v94
	ds_read_b128 v[138:141], v82 offset:49152
	ds_read_b128 v[142:145], v92
	ds_read_b128 v[154:157], v82 offset:53248
	s_waitcnt lgkmcnt(1)
	v_mfma_f32_32x32x16_bf16 v[48:63], v[134:137], v[138:141], v[48:63]
	v_mfma_f32_32x32x16_bf16 v[32:47], v[142:145], v[138:141], v[32:47]
	s_and_b32 m0, s32, 7
	s_lshl_b32 m0, m0, 12
	s_add_i32 m0, m0, 0xc00
	s_nop 0
	global_load_lds_dwordx4 v[176:177], off
	s_waitcnt lgkmcnt(0)
	v_mfma_f32_32x32x16_bf16 v[16:31], v[134:137], v[154:157], v[16:31]
	v_mfma_f32_32x32x16_bf16 v[0:15], v[142:145], v[154:157], v[0:15]
	s_and_b32 m0, s32, 7
	s_lshl_b32 m0, m0, 11
	s_add_i32 m0, m0, 0x8000
	s_nop 0
	global_load_lds_dwordx4 v[178:179], off
	ds_read_b128 v[134:137], v95
	ds_read_b128 v[138:141], v86 offset:49152
	ds_read_b128 v[142:145], v93
	ds_read_b128 v[150:153], v86 offset:53248
	s_waitcnt lgkmcnt(1)
	v_mfma_f32_32x32x16_bf16 v[48:63], v[134:137], v[138:141], v[48:63]
	v_mfma_f32_32x32x16_bf16 v[32:47], v[142:145], v[138:141], v[32:47]
	s_and_b32 m0, s32, 7
	s_lshl_b32 m0, m0, 11
	s_add_i32 m0, m0, 0x8400
	s_nop 0
	global_load_lds_dwordx4 v[180:181], off
	s_waitcnt lgkmcnt(0)
	v_mfma_f32_32x32x16_bf16 v[16:31], v[134:137], v[150:153], v[16:31]
	v_mfma_f32_32x32x16_bf16 v[0:15], v[142:145], v[150:153], v[0:15]
	ds_read_b128 v[134:137], v97
	ds_read_b128 v[138:141], v88 offset:49152
	ds_read_b128 v[142:145], v96
	ds_read_b128 v[154:157], v88 offset:53248
	s_waitcnt lgkmcnt(1)
	v_mfma_f32_32x32x16_bf16 v[48:63], v[134:137], v[138:141], v[48:63]
	v_mfma_f32_32x32x16_bf16 v[32:47], v[142:145], v[138:141], v[32:47]
	s_waitcnt vmcnt(6)
	s_waitcnt lgkmcnt(0)
	s_barrier
	s_waitcnt lgkmcnt(0)
	v_mfma_f32_32x32x16_bf16 v[16:31], v[134:137], v[154:157], v[16:31]
	v_lshl_add_u64 v[158:159], v[66:67], 0, s[30:31]
	v_lshl_add_u64 v[160:161], v[68:69], 0, s[30:31]
	s_nop 0
	v_readfirstlane_b32 s33, v120
	s_nop 0
	v_lshl_add_u64 v[162:163], v[70:71], 0, s[30:31]
	s_nop 0
	v_mfma_f32_32x32x16_bf16 v[0:15], v[142:145], v[154:157], v[0:15]
	s_and_b32 m0, s32, 7
	s_lshl_b32 m0, m0, 12
	s_add_i32 m0, m0, 0xc000
	s_nop 0
	global_load_lds_dwordx4 v[158:159], off
	v_lshl_add_u64 v[164:165], v[72:73], 0, s[30:31]
	s_nop 0
	v_readfirstlane_b32 s36, v121
	s_nop 0
	v_lshl_add_u64 v[166:167], v[74:75], 0, s[30:31]
	s_nop 0
	v_readfirstlane_b32 s37, v122
	s_nop 0
	v_lshl_add_u64 v[168:169], v[76:77], 0, s[30:31]
	s_nop 0
	s_mov_b64 s[30:31], 0x400
	ds_read_b128 v[134:137], v98
	ds_read_b128 v[138:141], v100
	ds_read_b128 v[142:145], v99
	ds_read_b128 v[150:153], v101
	s_waitcnt lgkmcnt(1)
	v_mfma_f32_32x32x16_bf16 v[48:63], v[134:137], v[138:141], v[48:63]
	s_nop 0
	v_readfirstlane_b32 s0, v131
	v_readfirstlane_b32 s38, v123
	v_readfirstlane_b32 s39, v124
	v_mfma_f32_32x32x16_bf16 v[32:47], v[142:145], v[138:141], v[32:47]
	s_and_b32 m0, s32, 7
	s_lshl_b32 m0, m0, 12
	s_add_i32 m0, m0, 0xc400
	s_nop 0
	global_load_lds_dwordx4 v[160:161], off
	s_waitcnt lgkmcnt(0)
	v_mfma_f32_32x32x16_bf16 v[16:31], v[134:137], v[150:153], v[16:31]
	v_mfma_f32_32x32x16_bf16 v[0:15], v[142:145], v[150:153], v[0:15]
	s_and_b32 m0, s32, 7
	s_lshl_b32 m0, m0, 12
	s_add_i32 m0, m0, 0xc800
	s_nop 0
	global_load_lds_dwordx4 v[162:163], off
	ds_read_b128 v[134:137], v103
	ds_read_b128 v[138:141], v104
	ds_read_b128 v[142:145], v102
	ds_read_b128 v[154:157], v105
	s_waitcnt lgkmcnt(1)
	v_mfma_f32_32x32x16_bf16 v[48:63], v[134:137], v[138:141], v[48:63]
	v_mfma_f32_32x32x16_bf16 v[32:47], v[142:145], v[138:141], v[32:47]
	s_and_b32 m0, s32, 7
	s_lshl_b32 m0, m0, 12
	s_add_i32 m0, m0, 0xcc00
	s_nop 0
	global_load_lds_dwordx4 v[164:165], off
	s_waitcnt lgkmcnt(0)
	v_mfma_f32_32x32x16_bf16 v[16:31], v[134:137], v[154:157], v[16:31]
	v_mfma_f32_32x32x16_bf16 v[0:15], v[142:145], v[154:157], v[0:15]
	s_and_b32 m0, s32, 7
	s_lshl_b32 m0, m0, 11
	s_add_i32 m0, m0, 0x14000
	s_nop 0
	global_load_lds_dwordx4 v[166:167], off
	ds_read_b128 v[134:137], v107
	ds_read_b128 v[138:141], v108
	ds_read_b128 v[142:145], v106
	ds_read_b128 v[150:153], v109
	s_waitcnt lgkmcnt(1)
	v_mfma_f32_32x32x16_bf16 v[48:63], v[134:137], v[138:141], v[48:63]
	v_mfma_f32_32x32x16_bf16 v[32:47], v[142:145], v[138:141], v[32:47]
	s_and_b32 m0, s32, 7
	s_lshl_b32 m0, m0, 11
	s_add_i32 m0, m0, 0x14400
	s_nop 0
	global_load_lds_dwordx4 v[168:169], off
	s_waitcnt lgkmcnt(0)
	v_mfma_f32_32x32x16_bf16 v[16:31], v[134:137], v[150:153], v[16:31]
	v_mfma_f32_32x32x16_bf16 v[0:15], v[142:145], v[150:153], v[0:15]
	ds_read_b128 v[134:137], v111
	ds_read_b128 v[138:141], v112
	ds_read_b128 v[142:145], v110
	ds_read_b128 v[154:157], v113
	s_waitcnt lgkmcnt(1)
	v_mfma_f32_32x32x16_bf16 v[48:63], v[134:137], v[138:141], v[48:63]
	v_mfma_f32_32x32x16_bf16 v[32:47], v[142:145], v[138:141], v[32:47]
	s_waitcnt vmcnt(6)
	s_waitcnt lgkmcnt(0)
	s_barrier
	s_waitcnt lgkmcnt(0)
	v_mfma_f32_32x32x16_bf16 v[16:31], v[134:137], v[154:157], v[16:31]
	v_lshl_add_u64 v[170:171], v[66:67], 0, s[30:31]
	v_lshl_add_u64 v[172:173], v[68:69], 0, s[30:31]
	s_nop 0
	v_readfirstlane_b32 s1, v130
	s_nop 0
	v_lshl_add_u64 v[174:175], v[70:71], 0, s[30:31]
	s_nop 0
	v_mfma_f32_32x32x16_bf16 v[0:15], v[142:145], v[154:157], v[0:15]
	s_and_b32 m0, s32, 7
	s_lshl_b32 m0, m0, 12
	s_add_i32 m0, m0, 0x18000
	s_nop 0
	global_load_lds_dwordx4 v[170:171], off
	v_lshl_add_u64 v[176:177], v[72:73], 0, s[30:31]
	s_nop 0
	v_readfirstlane_b32 s21, v128
	s_nop 0
	v_lshl_add_u64 v[178:179], v[74:75], 0, s[30:31]
	s_nop 0
	v_readfirstlane_b32 s22, v126
	s_nop 0
	v_lshl_add_u64 v[180:181], v[76:77], 0, s[30:31]
	s_nop 0
	s_mov_b64 s[30:31], 0x480
	ds_read_b128 v[134:137], v85 offset:32768
	ds_read_b128 v[138:141], v84
	ds_read_b128 v[142:145], v85 offset:36864
	ds_read_b128 v[150:153], v84 offset:4096
	s_waitcnt lgkmcnt(1)
	v_mfma_f32_32x32x16_bf16 v[48:63], v[134:137], v[138:141], v[48:63]
	s_nop 0
	v_lshl_add_u64 v[160:161], v[68:69], 0, s[30:31]
	v_readfirstlane_b32 s23, v129
	v_lshl_add_u64 v[166:167], v[74:75], 0, s[30:31]
	v_readfirstlane_b32 s28, v127
	v_lshl_add_u64 v[168:169], v[76:77], 0, s[30:31]
	v_mfma_f32_32x32x16_bf16 v[32:47], v[142:145], v[138:141], v[32:47]
	s_and_b32 m0, s32, 7
	s_lshl_b32 m0, m0, 12
	s_add_i32 m0, m0, 0x18400
	s_nop 0
	global_load_lds_dwordx4 v[172:173], off
	s_waitcnt lgkmcnt(0)
	v_mfma_f32_32x32x16_bf16 v[16:31], v[134:137], v[150:153], v[16:31]
	v_mfma_f32_32x32x16_bf16 v[0:15], v[142:145], v[150:153], v[0:15]
	s_and_b32 m0, s32, 7
	s_lshl_b32 m0, m0, 12
	s_add_i32 m0, m0, 0x18800
	s_nop 0
	global_load_lds_dwordx4 v[174:175], off
	ds_read_b128 v[134:137], v83 offset:32768
	ds_read_b128 v[138:141], v82
	ds_read_b128 v[142:145], v83 offset:36864
	ds_read_b128 v[154:157], v82 offset:4096
	s_waitcnt lgkmcnt(1)
	v_mfma_f32_32x32x16_bf16 v[48:63], v[134:137], v[138:141], v[48:63]
	v_mfma_f32_32x32x16_bf16 v[32:47], v[142:145], v[138:141], v[32:47]
	s_and_b32 m0, s32, 7
	s_lshl_b32 m0, m0, 12
	s_add_i32 m0, m0, 0x18c00
	s_nop 0
	global_load_lds_dwordx4 v[176:177], off
	s_waitcnt lgkmcnt(0)
	v_mfma_f32_32x32x16_bf16 v[16:31], v[134:137], v[154:157], v[16:31]
	v_mfma_f32_32x32x16_bf16 v[0:15], v[142:145], v[154:157], v[0:15]
	s_and_b32 m0, s32, 7
	s_lshl_b32 m0, m0, 11
	s_add_i32 m0, m0, 0x20000
	s_nop 0
	global_load_lds_dwordx4 v[178:179], off
	ds_read_b128 v[134:137], v87 offset:32768
	ds_read_b128 v[138:141], v86
	ds_read_b128 v[142:145], v87 offset:36864
	ds_read_b128 v[150:153], v86 offset:4096
	s_waitcnt lgkmcnt(1)
	v_mfma_f32_32x32x16_bf16 v[48:63], v[134:137], v[138:141], v[48:63]
	v_mfma_f32_32x32x16_bf16 v[32:47], v[142:145], v[138:141], v[32:47]
	s_and_b32 m0, s32, 7
	s_lshl_b32 m0, m0, 11
	s_add_i32 m0, m0, 0x20400
	s_nop 0
	global_load_lds_dwordx4 v[180:181], off
	s_waitcnt lgkmcnt(0)
	v_mfma_f32_32x32x16_bf16 v[16:31], v[134:137], v[150:153], v[16:31]
	v_mfma_f32_32x32x16_bf16 v[0:15], v[142:145], v[150:153], v[0:15]
	ds_read_b128 v[134:137], v89 offset:32768
	ds_read_b128 v[138:141], v88
	ds_read_b128 v[142:145], v89 offset:36864
	ds_read_b128 v[154:157], v88 offset:4096
	s_waitcnt lgkmcnt(1)
	v_mfma_f32_32x32x16_bf16 v[48:63], v[134:137], v[138:141], v[48:63]
	v_mfma_f32_32x32x16_bf16 v[32:47], v[142:145], v[138:141], v[32:47]
	s_waitcnt vmcnt(6)
	s_waitcnt lgkmcnt(0)
	s_barrier
	s_waitcnt lgkmcnt(0)
	v_mfma_f32_32x32x16_bf16 v[16:31], v[134:137], v[154:157], v[16:31]
	v_lshl_add_u64 v[158:159], v[66:67], 0, s[30:31]
	v_lshl_add_u64 v[162:163], v[70:71], 0, s[30:31]
	v_mfma_f32_32x32x16_bf16 v[0:15], v[142:145], v[154:157], v[0:15]
	s_and_b32 m0, s32, 7
	s_lshl_b32 m0, m0, 12
	s_add_i32 m0, m0, 0x0
	s_nop 0
	global_load_lds_dwordx4 v[158:159], off
	v_lshl_add_u64 v[164:165], v[72:73], 0, s[30:31]
	s_mov_b64 s[30:31], 0x500
	v_lshl_add_u64 v[174:175], v[70:71], 0, s[30:31]
	ds_read_b128 v[126:129], v91
	ds_read_b128 v[134:137], v84 offset:49152
	ds_read_b128 v[138:141], v90
	ds_read_b128 v[150:153], v84 offset:53248
	s_waitcnt lgkmcnt(1)
	v_mfma_f32_32x32x16_bf16 v[48:63], v[126:129], v[134:137], v[48:63]
	v_mfma_f32_32x32x16_bf16 v[32:47], v[138:141], v[134:137], v[32:47]
	s_and_b32 m0, s32, 7
	s_lshl_b32 m0, m0, 12
	s_add_i32 m0, m0, 0x400
	s_nop 0
	global_load_lds_dwordx4 v[160:161], off
	s_waitcnt lgkmcnt(0)
	v_mfma_f32_32x32x16_bf16 v[16:31], v[126:129], v[150:153], v[16:31]
	v_mfma_f32_32x32x16_bf16 v[0:15], v[138:141], v[150:153], v[0:15]
	s_and_b32 m0, s32, 7
	s_lshl_b32 m0, m0, 12
	s_add_i32 m0, m0, 0x800
	s_nop 0
	global_load_lds_dwordx4 v[162:163], off
	ds_read_b128 v[126:129], v94
	ds_read_b128 v[134:137], v82 offset:49152
	ds_read_b128 v[138:141], v92
	ds_read_b128 v[154:157], v82 offset:53248
	s_waitcnt lgkmcnt(1)
	v_mfma_f32_32x32x16_bf16 v[48:63], v[126:129], v[134:137], v[48:63]
	v_mfma_f32_32x32x16_bf16 v[32:47], v[138:141], v[134:137], v[32:47]
	s_and_b32 m0, s32, 7
	s_lshl_b32 m0, m0, 12
	s_add_i32 m0, m0, 0xc00
	s_nop 0
	global_load_lds_dwordx4 v[164:165], off
	s_waitcnt lgkmcnt(0)
	v_mfma_f32_32x32x16_bf16 v[16:31], v[126:129], v[154:157], v[16:31]
	v_mfma_f32_32x32x16_bf16 v[0:15], v[138:141], v[154:157], v[0:15]
	s_and_b32 m0, s32, 7
	s_lshl_b32 m0, m0, 11
	s_add_i32 m0, m0, 0x8000
	s_nop 0
	global_load_lds_dwordx4 v[166:167], off
	ds_read_b128 v[126:129], v95
	ds_read_b128 v[134:137], v86 offset:49152
	ds_read_b128 v[138:141], v93
	ds_read_b128 v[150:153], v86 offset:53248
	s_waitcnt lgkmcnt(1)
	v_mfma_f32_32x32x16_bf16 v[48:63], v[126:129], v[134:137], v[48:63]
	v_mfma_f32_32x32x16_bf16 v[32:47], v[138:141], v[134:137], v[32:47]
	s_and_b32 m0, s32, 7
	s_lshl_b32 m0, m0, 11
	s_add_i32 m0, m0, 0x8400
	s_nop 0
	global_load_lds_dwordx4 v[168:169], off
	s_waitcnt lgkmcnt(0)
	v_mfma_f32_32x32x16_bf16 v[16:31], v[126:129], v[150:153], v[16:31]
	v_mfma_f32_32x32x16_bf16 v[0:15], v[138:141], v[150:153], v[0:15]
	ds_read_b128 v[126:129], v97
	ds_read_b128 v[134:137], v88 offset:49152
	ds_read_b128 v[138:141], v96
	ds_read_b128 v[154:157], v88 offset:53248
	s_waitcnt lgkmcnt(1)
	v_mfma_f32_32x32x16_bf16 v[48:63], v[126:129], v[134:137], v[48:63]
	v_mfma_f32_32x32x16_bf16 v[32:47], v[138:141], v[134:137], v[32:47]
	s_waitcnt vmcnt(6)
	s_waitcnt lgkmcnt(0)
	s_barrier
	s_waitcnt lgkmcnt(0)
	v_mfma_f32_32x32x16_bf16 v[16:31], v[126:129], v[154:157], v[16:31]
	v_lshl_add_u64 v[170:171], v[66:67], 0, s[30:31]
	v_lshl_add_u64 v[172:173], v[68:69], 0, s[30:31]
	v_mfma_f32_32x32x16_bf16 v[0:15], v[138:141], v[154:157], v[0:15]
	s_and_b32 m0, s32, 7
	s_lshl_b32 m0, m0, 12
	s_add_i32 m0, m0, 0xc000
	s_nop 0
	global_load_lds_dwordx4 v[170:171], off
	v_lshl_add_u64 v[176:177], v[72:73], 0, s[30:31]
	v_lshl_add_u64 v[178:179], v[74:75], 0, s[30:31]
	v_lshl_add_u64 v[180:181], v[76:77], 0, s[30:31]
	s_mov_b64 s[30:31], 0x580
	ds_read_b128 v[120:123], v98
	ds_read_b128 v[124:127], v100
	ds_read_b128 v[128:131], v99
	ds_read_b128 v[150:153], v101
	s_waitcnt lgkmcnt(1)
	v_mfma_f32_32x32x16_bf16 v[48:63], v[120:123], v[124:127], v[48:63]
	v_lshl_add_u64 v[162:163], v[70:71], 0, s[30:31]
	v_mfma_f32_32x32x16_bf16 v[32:47], v[128:131], v[124:127], v[32:47]
	s_and_b32 m0, s32, 7
	s_lshl_b32 m0, m0, 12
	s_add_i32 m0, m0, 0xc400
	s_nop 0
	global_load_lds_dwordx4 v[172:173], off
	s_waitcnt lgkmcnt(0)
	v_mfma_f32_32x32x16_bf16 v[16:31], v[120:123], v[150:153], v[16:31]
	v_mfma_f32_32x32x16_bf16 v[0:15], v[128:131], v[150:153], v[0:15]
	s_and_b32 m0, s32, 7
	s_lshl_b32 m0, m0, 12
	s_add_i32 m0, m0, 0xc800
	s_nop 0
	global_load_lds_dwordx4 v[174:175], off
	ds_read_b128 v[120:123], v103
	ds_read_b128 v[124:127], v104
	ds_read_b128 v[128:131], v102
	ds_read_b128 v[154:157], v105
	s_waitcnt lgkmcnt(1)
	v_mfma_f32_32x32x16_bf16 v[48:63], v[120:123], v[124:127], v[48:63]
	v_mfma_f32_32x32x16_bf16 v[32:47], v[128:131], v[124:127], v[32:47]
	s_and_b32 m0, s32, 7
	s_lshl_b32 m0, m0, 12
	s_add_i32 m0, m0, 0xcc00
	s_nop 0
	global_load_lds_dwordx4 v[176:177], off
	s_waitcnt lgkmcnt(0)
	v_mfma_f32_32x32x16_bf16 v[16:31], v[120:123], v[154:157], v[16:31]
	v_mfma_f32_32x32x16_bf16 v[0:15], v[128:131], v[154:157], v[0:15]
	s_and_b32 m0, s32, 7
	s_lshl_b32 m0, m0, 11
	s_add_i32 m0, m0, 0x14000
	s_nop 0
	global_load_lds_dwordx4 v[178:179], off
	ds_read_b128 v[120:123], v107
	ds_read_b128 v[124:127], v108
	ds_read_b128 v[128:131], v106
	ds_read_b128 v[150:153], v109
	s_waitcnt lgkmcnt(1)
	v_mfma_f32_32x32x16_bf16 v[48:63], v[120:123], v[124:127], v[48:63]
	v_mfma_f32_32x32x16_bf16 v[32:47], v[128:131], v[124:127], v[32:47]
	s_and_b32 m0, s32, 7
	s_lshl_b32 m0, m0, 11
	s_add_i32 m0, m0, 0x14400
	s_nop 0
	global_load_lds_dwordx4 v[180:181], off
	s_waitcnt lgkmcnt(0)
	v_mfma_f32_32x32x16_bf16 v[16:31], v[120:123], v[150:153], v[16:31]
	v_mfma_f32_32x32x16_bf16 v[0:15], v[128:131], v[150:153], v[0:15]
	ds_read_b128 v[120:123], v111
	ds_read_b128 v[124:127], v112
	ds_read_b128 v[128:131], v110
	ds_read_b128 v[154:157], v113
	s_waitcnt lgkmcnt(1)
	v_mfma_f32_32x32x16_bf16 v[48:63], v[120:123], v[124:127], v[48:63]
	v_mfma_f32_32x32x16_bf16 v[32:47], v[128:131], v[124:127], v[32:47]
	s_waitcnt vmcnt(6)
	s_waitcnt lgkmcnt(0)
	s_barrier
	s_waitcnt lgkmcnt(0)
	v_mfma_f32_32x32x16_bf16 v[16:31], v[120:123], v[154:157], v[16:31]
	v_lshl_add_u64 v[158:159], v[66:67], 0, s[30:31]
	v_lshl_add_u64 v[160:161], v[68:69], 0, s[30:31]
	v_mfma_f32_32x32x16_bf16 v[0:15], v[128:131], v[154:157], v[0:15]
	s_and_b32 m0, s32, 7
	s_lshl_b32 m0, m0, 12
	s_add_i32 m0, m0, 0x18000
	s_nop 0
	global_load_lds_dwordx4 v[158:159], off
	v_lshl_add_u64 v[164:165], v[72:73], 0, s[30:31]
	v_lshl_add_u64 v[166:167], v[74:75], 0, s[30:31]
	v_lshl_add_u64 v[168:169], v[76:77], 0, s[30:31]
	s_mov_b64 s[30:31], 0x600
	ds_read_b128 v[114:117], v85 offset:32768
	ds_read_b128 v[118:121], v84
	ds_read_b128 v[122:125], v85 offset:36864
	ds_read_b128 v[150:153], v84 offset:4096
	s_waitcnt lgkmcnt(1)
	v_mfma_f32_32x32x16_bf16 v[48:63], v[114:117], v[118:121], v[48:63]
	v_mfma_f32_32x32x16_bf16 v[32:47], v[122:125], v[118:121], v[32:47]
	s_and_b32 m0, s32, 7
	s_lshl_b32 m0, m0, 12
	s_add_i32 m0, m0, 0x18400
	s_nop 0
	global_load_lds_dwordx4 v[160:161], off
	s_waitcnt lgkmcnt(0)
	v_mfma_f32_32x32x16_bf16 v[16:31], v[114:117], v[150:153], v[16:31]
	v_mfma_f32_32x32x16_bf16 v[0:15], v[122:125], v[150:153], v[0:15]
	s_and_b32 m0, s32, 7
	s_lshl_b32 m0, m0, 12
	s_add_i32 m0, m0, 0x18800
	s_nop 0
	global_load_lds_dwordx4 v[162:163], off
	ds_read_b128 v[114:117], v83 offset:32768
	ds_read_b128 v[118:121], v82
	ds_read_b128 v[122:125], v83 offset:36864
	ds_read_b128 v[154:157], v82 offset:4096
	s_waitcnt lgkmcnt(1)
	v_mfma_f32_32x32x16_bf16 v[48:63], v[114:117], v[118:121], v[48:63]
	v_mfma_f32_32x32x16_bf16 v[32:47], v[122:125], v[118:121], v[32:47]
	s_and_b32 m0, s32, 7
	s_lshl_b32 m0, m0, 12
	s_add_i32 m0, m0, 0x18c00
	s_nop 0
	global_load_lds_dwordx4 v[164:165], off
	s_waitcnt lgkmcnt(0)
	v_mfma_f32_32x32x16_bf16 v[16:31], v[114:117], v[154:157], v[16:31]
	v_mfma_f32_32x32x16_bf16 v[0:15], v[122:125], v[154:157], v[0:15]
	s_and_b32 m0, s32, 7
	s_lshl_b32 m0, m0, 11
	s_add_i32 m0, m0, 0x20000
	s_nop 0
	global_load_lds_dwordx4 v[166:167], off
	ds_read_b128 v[114:117], v87 offset:32768
	ds_read_b128 v[118:121], v86
	ds_read_b128 v[122:125], v87 offset:36864
	ds_read_b128 v[150:153], v86 offset:4096
	s_waitcnt lgkmcnt(1)
	v_mfma_f32_32x32x16_bf16 v[48:63], v[114:117], v[118:121], v[48:63]
	v_mfma_f32_32x32x16_bf16 v[32:47], v[122:125], v[118:121], v[32:47]
	s_and_b32 m0, s32, 7
	s_lshl_b32 m0, m0, 11
	s_add_i32 m0, m0, 0x20400
	s_nop 0
	global_load_lds_dwordx4 v[168:169], off
	s_waitcnt lgkmcnt(0)
	v_mfma_f32_32x32x16_bf16 v[16:31], v[114:117], v[150:153], v[16:31]
	v_mfma_f32_32x32x16_bf16 v[0:15], v[122:125], v[150:153], v[0:15]
	ds_read_b128 v[114:117], v89 offset:32768
	ds_read_b128 v[118:121], v88
	ds_read_b128 v[122:125], v89 offset:36864
	ds_read_b128 v[154:157], v88 offset:4096
	s_waitcnt lgkmcnt(1)
	v_mfma_f32_32x32x16_bf16 v[48:63], v[114:117], v[118:121], v[48:63]
	v_mfma_f32_32x32x16_bf16 v[32:47], v[122:125], v[118:121], v[32:47]
	s_waitcnt vmcnt(6)
	s_waitcnt lgkmcnt(0)
	s_barrier
	s_waitcnt lgkmcnt(0)
	v_mfma_f32_32x32x16_bf16 v[16:31], v[114:117], v[154:157], v[16:31]
	v_lshl_add_u64 v[170:171], v[66:67], 0, s[30:31]
	v_lshl_add_u64 v[172:173], v[68:69], 0, s[30:31]
	v_lshl_add_u64 v[174:175], v[70:71], 0, s[30:31]
	v_mfma_f32_32x32x16_bf16 v[0:15], v[122:125], v[154:157], v[0:15]
	s_and_b32 m0, s32, 7
	s_lshl_b32 m0, m0, 12
	s_add_i32 m0, m0, 0x0
	s_nop 0
	global_load_lds_dwordx4 v[170:171], off
	v_lshl_add_u64 v[176:177], v[72:73], 0, s[30:31]
	v_lshl_add_u64 v[178:179], v[74:75], 0, s[30:31]
	v_lshl_add_u64 v[180:181], v[76:77], 0, s[30:31]
	s_mov_b64 s[30:31], 0x680
	ds_read_b128 v[114:117], v91
	ds_read_b128 v[118:121], v84 offset:49152
	ds_read_b128 v[122:125], v90
	ds_read_b128 v[150:153], v84 offset:53248
	s_waitcnt lgkmcnt(1)
	v_mfma_f32_32x32x16_bf16 v[48:63], v[114:117], v[118:121], v[48:63]
	v_mfma_f32_32x32x16_bf16 v[32:47], v[122:125], v[118:121], v[32:47]
	s_and_b32 m0, s32, 7
	s_lshl_b32 m0, m0, 12
	s_add_i32 m0, m0, 0x400
	s_nop 0
	global_load_lds_dwordx4 v[172:173], off
	s_waitcnt lgkmcnt(0)
	v_mfma_f32_32x32x16_bf16 v[16:31], v[114:117], v[150:153], v[16:31]
	v_mfma_f32_32x32x16_bf16 v[0:15], v[122:125], v[150:153], v[0:15]
	s_and_b32 m0, s32, 7
	s_lshl_b32 m0, m0, 12
	s_add_i32 m0, m0, 0x800
	s_nop 0
	global_load_lds_dwordx4 v[174:175], off
	ds_read_b128 v[114:117], v94
	ds_read_b128 v[118:121], v82 offset:49152
	ds_read_b128 v[122:125], v92
	ds_read_b128 v[154:157], v82 offset:53248
	s_waitcnt lgkmcnt(1)
	v_mfma_f32_32x32x16_bf16 v[48:63], v[114:117], v[118:121], v[48:63]
	v_mfma_f32_32x32x16_bf16 v[32:47], v[122:125], v[118:121], v[32:47]
	s_and_b32 m0, s32, 7
	s_lshl_b32 m0, m0, 12
	s_add_i32 m0, m0, 0xc00
	s_nop 0
	global_load_lds_dwordx4 v[176:177], off
	s_waitcnt lgkmcnt(0)
	v_mfma_f32_32x32x16_bf16 v[16:31], v[114:117], v[154:157], v[16:31]
	v_mfma_f32_32x32x16_bf16 v[0:15], v[122:125], v[154:157], v[0:15]
	s_and_b32 m0, s32, 7
	s_lshl_b32 m0, m0, 11
	s_add_i32 m0, m0, 0x8000
	s_nop 0
	global_load_lds_dwordx4 v[178:179], off
	ds_read_b128 v[114:117], v95
	ds_read_b128 v[118:121], v86 offset:49152
	ds_read_b128 v[122:125], v93
	ds_read_b128 v[150:153], v86 offset:53248
	s_waitcnt lgkmcnt(1)
	v_mfma_f32_32x32x16_bf16 v[48:63], v[114:117], v[118:121], v[48:63]
	v_mfma_f32_32x32x16_bf16 v[32:47], v[122:125], v[118:121], v[32:47]
	s_and_b32 m0, s32, 7
	s_lshl_b32 m0, m0, 11
	s_add_i32 m0, m0, 0x8400
	s_nop 0
	global_load_lds_dwordx4 v[180:181], off
	s_waitcnt lgkmcnt(0)
	v_mfma_f32_32x32x16_bf16 v[16:31], v[114:117], v[150:153], v[16:31]
	v_mfma_f32_32x32x16_bf16 v[0:15], v[122:125], v[150:153], v[0:15]
	ds_read_b128 v[114:117], v97
	ds_read_b128 v[118:121], v88 offset:49152
	ds_read_b128 v[122:125], v96
	ds_read_b128 v[154:157], v88 offset:53248
	s_waitcnt lgkmcnt(1)
	v_mfma_f32_32x32x16_bf16 v[48:63], v[114:117], v[118:121], v[48:63]
	v_mfma_f32_32x32x16_bf16 v[32:47], v[122:125], v[118:121], v[32:47]
	s_waitcnt vmcnt(6)
	s_waitcnt lgkmcnt(0)
	s_barrier
	s_waitcnt lgkmcnt(0)
	v_mfma_f32_32x32x16_bf16 v[16:31], v[114:117], v[154:157], v[16:31]
	v_lshl_add_u64 v[158:159], v[66:67], 0, s[30:31]
	v_lshl_add_u64 v[160:161], v[68:69], 0, s[30:31]
	v_lshl_add_u64 v[162:163], v[70:71], 0, s[30:31]
	v_mfma_f32_32x32x16_bf16 v[0:15], v[122:125], v[154:157], v[0:15]
	s_and_b32 m0, s32, 7
	s_lshl_b32 m0, m0, 12
	s_add_i32 m0, m0, 0xc000
	s_nop 0
	global_load_lds_dwordx4 v[158:159], off
	v_lshl_add_u64 v[164:165], v[72:73], 0, s[30:31]
	v_lshl_add_u64 v[166:167], v[74:75], 0, s[30:31]
	v_lshl_add_u64 v[168:169], v[76:77], 0, s[30:31]
	s_mov_b64 s[30:31], 0x700
	ds_read_b128 v[114:117], v98
	ds_read_b128 v[118:121], v100
	ds_read_b128 v[122:125], v99
	ds_read_b128 v[150:153], v101
	s_waitcnt lgkmcnt(1)
	v_mfma_f32_32x32x16_bf16 v[48:63], v[114:117], v[118:121], v[48:63]
	v_mfma_f32_32x32x16_bf16 v[32:47], v[122:125], v[118:121], v[32:47]
	s_and_b32 m0, s32, 7
	s_lshl_b32 m0, m0, 12
	s_add_i32 m0, m0, 0xc400
	s_nop 0
	global_load_lds_dwordx4 v[160:161], off
	s_waitcnt lgkmcnt(0)
	v_mfma_f32_32x32x16_bf16 v[16:31], v[114:117], v[150:153], v[16:31]
	v_mfma_f32_32x32x16_bf16 v[0:15], v[122:125], v[150:153], v[0:15]
	s_and_b32 m0, s32, 7
	s_lshl_b32 m0, m0, 12
	s_add_i32 m0, m0, 0xc800
	s_nop 0
	global_load_lds_dwordx4 v[162:163], off
	ds_read_b128 v[114:117], v103
	ds_read_b128 v[118:121], v104
	ds_read_b128 v[122:125], v102
	ds_read_b128 v[154:157], v105
	s_waitcnt lgkmcnt(1)
	v_mfma_f32_32x32x16_bf16 v[48:63], v[114:117], v[118:121], v[48:63]
	v_mfma_f32_32x32x16_bf16 v[32:47], v[122:125], v[118:121], v[32:47]
	s_and_b32 m0, s32, 7
	s_lshl_b32 m0, m0, 12
	s_add_i32 m0, m0, 0xcc00
	s_nop 0
	global_load_lds_dwordx4 v[164:165], off
	s_waitcnt lgkmcnt(0)
	v_mfma_f32_32x32x16_bf16 v[16:31], v[114:117], v[154:157], v[16:31]
	v_mfma_f32_32x32x16_bf16 v[0:15], v[122:125], v[154:157], v[0:15]
	s_and_b32 m0, s32, 7
	s_lshl_b32 m0, m0, 11
	s_add_i32 m0, m0, 0x14000
	s_nop 0
	global_load_lds_dwordx4 v[166:167], off
	ds_read_b128 v[114:117], v107
	ds_read_b128 v[118:121], v108
	ds_read_b128 v[122:125], v106
	ds_read_b128 v[150:153], v109
	s_waitcnt lgkmcnt(1)
	v_mfma_f32_32x32x16_bf16 v[48:63], v[114:117], v[118:121], v[48:63]
	v_mfma_f32_32x32x16_bf16 v[32:47], v[122:125], v[118:121], v[32:47]
	s_and_b32 m0, s32, 7
	s_lshl_b32 m0, m0, 11
	s_add_i32 m0, m0, 0x14400
	s_nop 0
	global_load_lds_dwordx4 v[168:169], off
	s_waitcnt lgkmcnt(0)
	v_mfma_f32_32x32x16_bf16 v[16:31], v[114:117], v[150:153], v[16:31]
	v_mfma_f32_32x32x16_bf16 v[0:15], v[122:125], v[150:153], v[0:15]
	ds_read_b128 v[114:117], v111
	ds_read_b128 v[118:121], v112
	ds_read_b128 v[122:125], v110
	ds_read_b128 v[154:157], v113
	s_waitcnt lgkmcnt(1)
	v_mfma_f32_32x32x16_bf16 v[48:63], v[114:117], v[118:121], v[48:63]
	v_mfma_f32_32x32x16_bf16 v[32:47], v[122:125], v[118:121], v[32:47]
	s_waitcnt vmcnt(6)
	s_waitcnt lgkmcnt(0)
	s_barrier
	s_waitcnt lgkmcnt(0)
	v_mfma_f32_32x32x16_bf16 v[16:31], v[114:117], v[154:157], v[16:31]
	v_lshl_add_u64 v[170:171], v[66:67], 0, s[30:31]
	v_lshl_add_u64 v[172:173], v[68:69], 0, s[30:31]
	v_lshl_add_u64 v[174:175], v[70:71], 0, s[30:31]
	v_mfma_f32_32x32x16_bf16 v[0:15], v[122:125], v[154:157], v[0:15]
	s_and_b32 m0, s32, 7
	s_lshl_b32 m0, m0, 12
	s_add_i32 m0, m0, 0x18000
	s_nop 0
	global_load_lds_dwordx4 v[170:171], off
	v_lshl_add_u64 v[176:177], v[72:73], 0, s[30:31]
	v_lshl_add_u64 v[178:179], v[74:75], 0, s[30:31]
	v_lshl_add_u64 v[180:181], v[76:77], 0, s[30:31]
	s_mov_b64 s[30:31], 0x780
	ds_read_b128 v[114:117], v85 offset:32768
	ds_read_b128 v[118:121], v84
	ds_read_b128 v[122:125], v85 offset:36864
	ds_read_b128 v[150:153], v84 offset:4096
	s_waitcnt lgkmcnt(1)
	v_mfma_f32_32x32x16_bf16 v[48:63], v[114:117], v[118:121], v[48:63]
	v_lshl_add_u64 v[158:159], v[66:67], 0, s[30:31]
	v_mfma_f32_32x32x16_bf16 v[32:47], v[122:125], v[118:121], v[32:47]
	s_and_b32 m0, s32, 7
	s_lshl_b32 m0, m0, 12
	s_add_i32 m0, m0, 0x18400
	s_nop 0
	global_load_lds_dwordx4 v[172:173], off
	s_waitcnt lgkmcnt(0)
	v_mfma_f32_32x32x16_bf16 v[16:31], v[114:117], v[150:153], v[16:31]
	v_mfma_f32_32x32x16_bf16 v[0:15], v[122:125], v[150:153], v[0:15]
	s_and_b32 m0, s32, 7
	s_lshl_b32 m0, m0, 12
	s_add_i32 m0, m0, 0x18800
	s_nop 0
	global_load_lds_dwordx4 v[174:175], off
	ds_read_b128 v[114:117], v83 offset:32768
	ds_read_b128 v[118:121], v82
	ds_read_b128 v[122:125], v83 offset:36864
	ds_read_b128 v[154:157], v82 offset:4096
	s_waitcnt lgkmcnt(1)
	v_mfma_f32_32x32x16_bf16 v[48:63], v[114:117], v[118:121], v[48:63]
	v_mfma_f32_32x32x16_bf16 v[32:47], v[122:125], v[118:121], v[32:47]
	s_and_b32 m0, s32, 7
	s_lshl_b32 m0, m0, 12
	s_add_i32 m0, m0, 0x18c00
	s_nop 0
	global_load_lds_dwordx4 v[176:177], off
	s_waitcnt lgkmcnt(0)
	v_mfma_f32_32x32x16_bf16 v[16:31], v[114:117], v[154:157], v[16:31]
	v_mfma_f32_32x32x16_bf16 v[0:15], v[122:125], v[154:157], v[0:15]
	s_and_b32 m0, s32, 7
	s_lshl_b32 m0, m0, 11
	s_add_i32 m0, m0, 0x20000
	s_nop 0
	global_load_lds_dwordx4 v[178:179], off
	ds_read_b128 v[114:117], v87 offset:32768
	ds_read_b128 v[118:121], v86
	ds_read_b128 v[122:125], v87 offset:36864
	ds_read_b128 v[150:153], v86 offset:4096
	s_waitcnt lgkmcnt(1)
	v_mfma_f32_32x32x16_bf16 v[48:63], v[114:117], v[118:121], v[48:63]
	v_mfma_f32_32x32x16_bf16 v[32:47], v[122:125], v[118:121], v[32:47]
	s_and_b32 m0, s32, 7
	s_lshl_b32 m0, m0, 11
	s_add_i32 m0, m0, 0x20400
	s_nop 0
	global_load_lds_dwordx4 v[180:181], off
	s_waitcnt lgkmcnt(0)
	v_mfma_f32_32x32x16_bf16 v[16:31], v[114:117], v[150:153], v[16:31]
	v_mfma_f32_32x32x16_bf16 v[0:15], v[122:125], v[150:153], v[0:15]
	ds_read_b128 v[114:117], v89 offset:32768
	ds_read_b128 v[118:121], v88
	ds_read_b128 v[122:125], v89 offset:36864
	ds_read_b128 v[154:157], v88 offset:4096
	s_waitcnt lgkmcnt(1)
	v_mfma_f32_32x32x16_bf16 v[48:63], v[114:117], v[118:121], v[48:63]
	v_mfma_f32_32x32x16_bf16 v[32:47], v[122:125], v[118:121], v[32:47]
	s_waitcnt vmcnt(6)
	s_waitcnt lgkmcnt(0)
	s_barrier
	v_lshl_add_u64 v[160:161], v[68:69], 0, s[30:31]
	s_waitcnt lgkmcnt(0)
	v_mfma_f32_32x32x16_bf16 v[16:31], v[114:117], v[154:157], v[16:31]
	v_lshl_add_u64 v[162:163], v[70:71], 0, s[30:31]
	v_lshl_add_u64 v[164:165], v[72:73], 0, s[30:31]
	v_mfma_f32_32x32x16_bf16 v[0:15], v[122:125], v[154:157], v[0:15]
	s_and_b32 m0, s32, 7
	s_lshl_b32 m0, m0, 12
	s_add_i32 m0, m0, 0x0
	s_nop 0
	global_load_lds_dwordx4 v[158:159], off
	v_lshl_add_u64 v[166:167], v[74:75], 0, s[30:31]
	v_lshl_add_u64 v[168:169], v[76:77], 0, s[30:31]
	ds_read_b128 v[66:69], v91
	ds_read_b128 v[70:73], v84 offset:49152
	ds_read_b128 v[74:77], v90
	ds_read_b128 v[150:153], v84 offset:53248
	s_waitcnt lgkmcnt(1)
	v_mfma_f32_32x32x16_bf16 v[48:63], v[66:69], v[70:73], v[48:63]
	v_mfma_f32_32x32x16_bf16 v[32:47], v[74:77], v[70:73], v[32:47]
	s_and_b32 m0, s32, 7
	s_lshl_b32 m0, m0, 12
	s_add_i32 m0, m0, 0x400
	s_nop 0
	global_load_lds_dwordx4 v[160:161], off
	s_waitcnt lgkmcnt(0)
	v_mfma_f32_32x32x16_bf16 v[16:31], v[66:69], v[150:153], v[16:31]
	v_mfma_f32_32x32x16_bf16 v[0:15], v[74:77], v[150:153], v[0:15]
	s_and_b32 m0, s32, 7
	s_lshl_b32 m0, m0, 12
	s_add_i32 m0, m0, 0x800
	s_nop 0
	global_load_lds_dwordx4 v[162:163], off
	ds_read_b128 v[66:69], v94
	ds_read_b128 v[70:73], v82 offset:49152
	ds_read_b128 v[74:77], v92
	ds_read_b128 v[154:157], v82 offset:53248
	s_waitcnt lgkmcnt(1)
	v_mfma_f32_32x32x16_bf16 v[48:63], v[66:69], v[70:73], v[48:63]
	v_mfma_f32_32x32x16_bf16 v[32:47], v[74:77], v[70:73], v[32:47]
	s_and_b32 m0, s32, 7
	s_lshl_b32 m0, m0, 12
	s_add_i32 m0, m0, 0xc00
	s_nop 0
	global_load_lds_dwordx4 v[164:165], off
	s_waitcnt lgkmcnt(0)
	v_mfma_f32_32x32x16_bf16 v[16:31], v[66:69], v[154:157], v[16:31]
	v_mfma_f32_32x32x16_bf16 v[0:15], v[74:77], v[154:157], v[0:15]
	s_and_b32 m0, s32, 7
	s_lshl_b32 m0, m0, 11
	s_add_i32 m0, m0, 0x8000
	s_nop 0
	global_load_lds_dwordx4 v[166:167], off
	ds_read_b128 v[66:69], v95
	ds_read_b128 v[70:73], v86 offset:49152
	ds_read_b128 v[74:77], v93
	ds_read_b128 v[150:153], v86 offset:53248
	s_waitcnt lgkmcnt(1)
	v_mfma_f32_32x32x16_bf16 v[48:63], v[66:69], v[70:73], v[48:63]
	v_mfma_f32_32x32x16_bf16 v[32:47], v[74:77], v[70:73], v[32:47]
	s_and_b32 m0, s32, 7
	s_lshl_b32 m0, m0, 11
	s_add_i32 m0, m0, 0x8400
	s_nop 0
	global_load_lds_dwordx4 v[168:169], off
	s_waitcnt lgkmcnt(0)
	v_mfma_f32_32x32x16_bf16 v[16:31], v[66:69], v[150:153], v[16:31]
	v_mfma_f32_32x32x16_bf16 v[0:15], v[74:77], v[150:153], v[0:15]
	ds_read_b128 v[66:69], v97
	ds_read_b128 v[70:73], v88 offset:49152
	ds_read_b128 v[74:77], v96
	ds_read_b128 v[154:157], v88 offset:53248
	s_waitcnt lgkmcnt(1)
	v_mfma_f32_32x32x16_bf16 v[48:63], v[66:69], v[70:73], v[48:63]
	v_mfma_f32_32x32x16_bf16 v[32:47], v[74:77], v[70:73], v[32:47]
	s_waitcnt vmcnt(6)
	s_waitcnt lgkmcnt(0)
	s_barrier
	s_waitcnt lgkmcnt(0)
	v_mfma_f32_32x32x16_bf16 v[16:31], v[66:69], v[154:157], v[16:31]
	v_lshrrev_b32_e32 v183, 7, v133
	v_and_b32_e32 v184, 31, v133
	v_lshl_or_b32 v183, v183, 6, v184
	v_add_u32_e32 v183, s2, v183
	v_lshlrev_b32_e32 v183, 2, v183
	global_load_dword v184, v183, s[76:77]
	global_load_dword v185, v183, s[76:77] offset:128
	v_mfma_f32_32x32x16_bf16 v[0:15], v[74:77], v[154:157], v[0:15]
	ds_read_b128 v[66:69], v98
	ds_read_b128 v[70:73], v100
	ds_read_b128 v[74:77], v99
	ds_read_b128 v[150:153], v101
	s_waitcnt lgkmcnt(1)
	v_mfma_f32_32x32x16_bf16 v[48:63], v[66:69], v[70:73], v[48:63]
	v_mfma_f32_32x32x16_bf16 v[32:47], v[74:77], v[70:73], v[32:47]
	s_waitcnt lgkmcnt(0)
	v_mfma_f32_32x32x16_bf16 v[16:31], v[66:69], v[150:153], v[16:31]
	v_mfma_f32_32x32x16_bf16 v[0:15], v[74:77], v[150:153], v[0:15]
	ds_read_b128 v[66:69], v103
	ds_read_b128 v[70:73], v104
	ds_read_b128 v[74:77], v102
	ds_read_b128 v[154:157], v105
	s_waitcnt lgkmcnt(1)
	v_mfma_f32_32x32x16_bf16 v[48:63], v[66:69], v[70:73], v[48:63]
	v_mfma_f32_32x32x16_bf16 v[32:47], v[74:77], v[70:73], v[32:47]
	s_waitcnt lgkmcnt(0)
	v_mfma_f32_32x32x16_bf16 v[16:31], v[66:69], v[154:157], v[16:31]
	v_mfma_f32_32x32x16_bf16 v[0:15], v[74:77], v[154:157], v[0:15]
	ds_read_b128 v[66:69], v107
	ds_read_b128 v[70:73], v108
	ds_read_b128 v[74:77], v106
	ds_read_b128 v[150:153], v109
	s_waitcnt lgkmcnt(1)
	v_mfma_f32_32x32x16_bf16 v[48:63], v[66:69], v[70:73], v[48:63]
	v_mfma_f32_32x32x16_bf16 v[32:47], v[74:77], v[70:73], v[32:47]
	s_waitcnt lgkmcnt(0)
	v_mfma_f32_32x32x16_bf16 v[16:31], v[66:69], v[150:153], v[16:31]
	v_mfma_f32_32x32x16_bf16 v[0:15], v[74:77], v[150:153], v[0:15]
	ds_read_b128 v[66:69], v111
	ds_read_b128 v[70:73], v112
	ds_read_b128 v[74:77], v110
	ds_read_b128 v[154:157], v113
	s_waitcnt lgkmcnt(1)
	v_mfma_f32_32x32x16_bf16 v[48:63], v[66:69], v[70:73], v[48:63]
	v_mfma_f32_32x32x16_bf16 v[32:47], v[74:77], v[70:73], v[32:47]
	s_waitcnt vmcnt(0)
	s_waitcnt lgkmcnt(0)
	s_barrier
	s_waitcnt lgkmcnt(0)
	v_mfma_f32_32x32x16_bf16 v[16:31], v[66:69], v[154:157], v[16:31]
	v_mfma_f32_32x32x16_bf16 v[0:15], v[74:77], v[154:157], v[0:15]
	ds_read_b128 v[66:69], v85 offset:32768
	ds_read_b128 v[70:73], v84
	ds_read_b128 v[74:77], v85 offset:36864
	ds_read_b128 v[150:153], v84 offset:4096
	s_waitcnt lgkmcnt(1)
	v_mfma_f32_32x32x16_bf16 v[48:63], v[66:69], v[70:73], v[48:63]
	v_mfma_f32_32x32x16_bf16 v[32:47], v[74:77], v[70:73], v[32:47]
	s_waitcnt lgkmcnt(0)
	v_mfma_f32_32x32x16_bf16 v[16:31], v[66:69], v[150:153], v[16:31]
	v_mfma_f32_32x32x16_bf16 v[0:15], v[74:77], v[150:153], v[0:15]
	ds_read_b128 v[66:69], v83 offset:32768
	ds_read_b128 v[70:73], v82
	ds_read_b128 v[74:77], v83 offset:36864
	ds_read_b128 v[154:157], v82 offset:4096
	s_waitcnt lgkmcnt(1)
	v_mfma_f32_32x32x16_bf16 v[48:63], v[66:69], v[70:73], v[48:63]
	v_mfma_f32_32x32x16_bf16 v[32:47], v[74:77], v[70:73], v[32:47]
	s_waitcnt lgkmcnt(0)
	v_mfma_f32_32x32x16_bf16 v[16:31], v[66:69], v[154:157], v[16:31]
	v_mfma_f32_32x32x16_bf16 v[0:15], v[74:77], v[154:157], v[0:15]
	ds_read_b128 v[66:69], v87 offset:32768
	ds_read_b128 v[70:73], v86
	ds_read_b128 v[74:77], v87 offset:36864
	ds_read_b128 v[150:153], v86 offset:4096
	s_waitcnt lgkmcnt(1)
	v_mfma_f32_32x32x16_bf16 v[48:63], v[66:69], v[70:73], v[48:63]
	v_mfma_f32_32x32x16_bf16 v[32:47], v[74:77], v[70:73], v[32:47]
	s_waitcnt lgkmcnt(0)
	v_mfma_f32_32x32x16_bf16 v[16:31], v[66:69], v[150:153], v[16:31]
	v_mfma_f32_32x32x16_bf16 v[0:15], v[74:77], v[150:153], v[0:15]
	ds_read_b128 v[70:73], v89 offset:32768
	ds_read_b128 v[66:69], v88
	ds_read_b128 v[74:77], v89 offset:36864
	ds_read_b128 v[82:85], v88 offset:4096
	s_waitcnt lgkmcnt(0)
	s_barrier
	s_waitcnt lgkmcnt(0)
	v_mfma_f32_32x32x16_bf16 v[48:63], v[70:73], v[66:69], v[48:63]
	v_mfma_f32_32x32x16_bf16 v[32:47], v[74:77], v[66:69], v[32:47]
	v_lshl_or_b32 v69, v80, 6, v81
	v_add_u32_e32 v66, s2, v69
	v_cmp_gt_i32_e32 vcc, s69, v66
	v_ashrrev_i32_e32 v67, 31, v66
	v_mov_b32_e32 v68, 0
	v_mfma_f32_32x32x16_bf16 v[16:31], v[70:73], v[82:85], v[16:31]
	v_mov_b32_e32 v70, 0
	v_mfma_f32_32x32x16_bf16 v[0:15], v[74:77], v[82:85], v[0:15]
	s_and_saveexec_b64 s[0:1], vcc
	s_cbranch_execz .LBB0_749
	v_lshl_add_u64 v[70:71], v[66:67], 2, s[76:77]
	v_mov_b32_e32 v70, v184
	v_fmamk_f32 v70, v70, 0x3a800000, v188
	v_mul_f32_e32 v71, 0x4b800000, v70
	v_cmp_gt_f32_e32 vcc, s82, v70
	s_nop 1
	v_cndmask_b32_e32 v70, v70, v71, vcc
	v_rsq_f32_e32 v70, v70
	s_nop 0
	v_mul_f32_e32 v71, 0x45800000, v70
	v_cndmask_b32_e32 v70, v70, v71, vcc
